# static s_setprio 2 for the whole GEMM K-loop (reset after): GEMM waves win issue arbitration over the weight-prep workgroup sharing the CU in out-proj phases
# speedup vs baseline: 1.0244x; 1.0244x over previous
.LBB0_146:
	s_ashr_i32 s8, s10, 3
	s_lshl_b32 s11, s8, 1
	s_and_b32 s9, s8, -16
	s_and_b32 s11, s11, 14
	s_or_b32 s9, s11, s9
	s_bfe_u32 s11, s8, 0x10003
	s_or_b32 s9, s9, s11
	s_cmp_lt_i32 s8, 0
	s_cselect_b32 s8, s9, s8
	s_lshl_b32 s9, s10, 5
	s_and_b32 s9, s9, 0xe0
	s_add_i32 s8, s8, s9
	s_ashr_i32 s9, s8, 31
	s_lshr_b32 s9, s9, 27
	s_add_i32 s9, s8, s9
	s_and_b32 s11, s9, 0xffffffe0
	s_sub_i32 s8, s8, s11
	s_ashr_i32 s11, s8, 31
	s_lshr_b32 s11, s11, 29
	s_add_i32 s11, s8, s11
	s_ashr_i32 s12, s11, 3
	s_lshl_b32 s9, s9, 5
	s_and_b32 s9, s9, 0xfffffc00
	s_lshl_b32 s11, s12, 8
	s_add_i32 s11, s11, s9
	s_lshl_b32 s9, s12, 10
	s_lshl_b32 s8, s8, 7
	v_mov_b32_e32 v6, v188
	s_sub_i32 s12, s8, s9
	s_mov_b32 s13, 0x30000
	v_ashrrev_i32_e32 v7, 3, v6
	v_lshlrev_b32_e32 v4, 4, v6
	v_and_b32_e32 v176, 0x70, v4
	v_add_u32_e32 v4, s12, v7
	v_ashrrev_i32_e32 v5, 31, v4
	v_add_u32_e32 v0, s11, v7
	v_lshlrev_b64 v[4:5], 11, v[4:5]
	v_ashrrev_i32_e32 v1, 31, v0
	v_lshl_add_u64 v[4:5], s[4:5], 0, v[4:5]
	v_xor_b32_e32 v8, v7, v6
	v_lshlrev_b64 v[0:1], 11, v[0:1]
	v_lshl_add_u64 v[178:179], v[4:5], 0, v[176:177]
	v_lshlrev_b32_e32 v4, 4, v8
	v_lshl_add_u64 v[2:3], s[2:3], 0, v[0:1]
	v_and_b32_e32 v4, 0x70, v4
	v_lshl_add_u64 v[2:3], v[2:3], 0, v[176:177]
	v_lshl_or_b32 v176, v7, 7, v4
	v_lshrrev_b32_e32 v4, 4, v6
	v_and_b32_e32 v15, 7, v6
	v_bitop3_b32 v20, v4, v15, 3 bitop3:0x6c
	v_add_co_u32_e32 v4, vcc, s13, v178
	v_lshlrev_b32_e32 v12, 7, v6
	s_nop 0
	v_addc_co_u32_e32 v5, vcc, 0, v179, vcc
	v_bfe_u32 v14, v6, 4, 2
	v_add_co_u32_e32 v6, vcc, s14, v178
	s_mov_b32 s8, 0x70000
	s_nop 0
	v_addc_co_u32_e32 v7, vcc, 0, v179, vcc
	global_load_dwordx4 v[8:11], v[4:5], off
	global_load_dwordx4 v[16:19], v[6:7], off
	v_add_co_u32_e32 v4, vcc, s31, v178
	v_and_b32_e32 v13, 0xffffc780, v12
	s_nop 0
	v_addc_co_u32_e32 v5, vcc, 0, v179, vcc
	v_add_co_u32_e32 v6, vcc, s8, v2
	s_mov_b32 s8, 0x60000
	s_nop 0
	v_addc_co_u32_e32 v7, vcc, 0, v3, vcc
	global_load_dwordx4 v[32:35], v[4:5], off
	global_load_dwordx4 v[40:43], v[6:7], off
	v_add_co_u32_e32 v4, vcc, s8, v2
	s_mov_b32 s8, 0x50000
	s_nop 0
	v_addc_co_u32_e32 v5, vcc, 0, v3, vcc
	v_add_co_u32_e32 v6, vcc, s8, v2
	v_and_b32_e32 v12, 0x2780, v12
	s_nop 0
	v_addc_co_u32_e32 v7, vcc, 0, v3, vcc
	global_load_dwordx4 v[60:63], v[4:5], off
	global_load_dwordx4 v[68:71], v[6:7], off
	v_add_co_u32_e32 v4, vcc, 0x40000, v2
	v_bitop3_b32 v14, v14, v15, 4 bitop3:0x36
	s_nop 0
	v_addc_co_u32_e32 v5, vcc, 0, v3, vcc
	v_add_co_u32_e32 v6, vcc, s13, v2
	v_lshl_or_b32 v0, v15, 4, v0
	s_nop 0
	v_addc_co_u32_e32 v7, vcc, 0, v3, vcc
	global_load_dwordx4 v[80:83], v[4:5], off
	global_load_dwordx4 v[88:91], v[6:7], off
	v_add_co_u32_e32 v4, vcc, s14, v2
	v_mov_b32_e32 v140, 0
	s_nop 0
	v_addc_co_u32_e32 v5, vcc, 0, v3, vcc
	v_add_co_u32_e32 v6, vcc, 0x10000, v2
	v_lshl_add_u64 v[180:181], s[34:35], 0, v[0:1]
	s_nop 0
	v_addc_co_u32_e32 v7, vcc, 0, v3, vcc
	global_load_dwordx4 v[104:107], v[4:5], off
	global_load_dwordx4 v[112:115], v[6:7], off
	global_load_dwordx4 v[56:59], v[178:179], off
	global_load_dwordx4 v[116:119], v[2:3], off
	v_lshlrev_b32_e32 v2, 4, v20
	v_or_b32_e32 v185, v13, v2
	v_or_b32_e32 v184, v12, v2
	v_lshlrev_b32_e32 v2, 4, v14
	v_or_b32_e32 v183, v13, v2
	v_or_b32_e32 v182, v12, v2
	s_mov_b64 s[8:9], 0
	v_mov_b32_e32 v141, v140
	v_mov_b32_e32 v142, v140
	v_mov_b32_e32 v143, v140
	v_mov_b32_e32 v0, v140
	v_mov_b32_e32 v1, v140
	v_mov_b32_e32 v2, v140
	v_mov_b32_e32 v3, v140
	v_mov_b32_e32 v4, v140
	v_mov_b32_e32 v5, v140
	v_mov_b32_e32 v6, v140
	v_mov_b32_e32 v7, v140
	v_mov_b32_e32 v12, v140
	v_mov_b32_e32 v13, v140
	v_mov_b32_e32 v14, v140
	v_mov_b32_e32 v15, v140
	v_mov_b32_e32 v20, v140
	v_mov_b32_e32 v21, v140
	v_mov_b32_e32 v22, v140
	v_mov_b32_e32 v23, v140
	v_mov_b32_e32 v24, v140
	v_mov_b32_e32 v25, v140
	v_mov_b32_e32 v26, v140
	v_mov_b32_e32 v27, v140
	v_mov_b32_e32 v28, v140
	v_mov_b32_e32 v29, v140
	v_mov_b32_e32 v30, v140
	v_mov_b32_e32 v31, v140
	v_mov_b32_e32 v36, v140
	v_mov_b32_e32 v37, v140
	v_mov_b32_e32 v38, v140
	v_mov_b32_e32 v39, v140
	v_mov_b32_e32 v44, v140
	v_mov_b32_e32 v45, v140
	v_mov_b32_e32 v46, v140
	v_mov_b32_e32 v47, v140
	v_mov_b32_e32 v48, v140
	v_mov_b32_e32 v49, v140
	v_mov_b32_e32 v50, v140
	v_mov_b32_e32 v51, v140
	v_mov_b32_e32 v52, v140
	v_mov_b32_e32 v53, v140
	v_mov_b32_e32 v54, v140
	v_mov_b32_e32 v55, v140
	v_mov_b32_e32 v64, v140
	v_mov_b32_e32 v65, v140
	v_mov_b32_e32 v66, v140
	v_mov_b32_e32 v67, v140
	v_mov_b32_e32 v72, v140
	v_mov_b32_e32 v73, v140
	v_mov_b32_e32 v74, v140
	v_mov_b32_e32 v75, v140
	v_mov_b32_e32 v76, v140
	v_mov_b32_e32 v77, v140
	v_mov_b32_e32 v78, v140
	v_mov_b32_e32 v79, v140
	v_mov_b32_e32 v84, v140
	v_mov_b32_e32 v85, v140
	v_mov_b32_e32 v86, v140
	v_mov_b32_e32 v87, v140
	v_mov_b32_e32 v92, v140
	v_mov_b32_e32 v93, v140
	v_mov_b32_e32 v94, v140
	v_mov_b32_e32 v95, v140
	v_mov_b32_e32 v96, v140
	v_mov_b32_e32 v97, v140
	v_mov_b32_e32 v98, v140
	v_mov_b32_e32 v99, v140
	v_mov_b32_e32 v100, v140
	v_mov_b32_e32 v101, v140
	v_mov_b32_e32 v102, v140
	v_mov_b32_e32 v103, v140
	v_mov_b32_e32 v108, v140
	v_mov_b32_e32 v109, v140
	v_mov_b32_e32 v110, v140
	v_mov_b32_e32 v111, v140
	v_mov_b32_e32 v120, v140
	v_mov_b32_e32 v121, v140
	v_mov_b32_e32 v122, v140
	v_mov_b32_e32 v123, v140
	v_mov_b32_e32 v124, v140
	v_mov_b32_e32 v125, v140
	v_mov_b32_e32 v126, v140
	v_mov_b32_e32 v127, v140
	v_mov_b32_e32 v128, v140
	v_mov_b32_e32 v129, v140
	v_mov_b32_e32 v130, v140
	v_mov_b32_e32 v131, v140
	v_mov_b32_e32 v132, v140
	v_mov_b32_e32 v133, v140
	v_mov_b32_e32 v134, v140
	v_mov_b32_e32 v135, v140
	v_mov_b32_e32 v136, v140
	v_mov_b32_e32 v137, v140
	v_mov_b32_e32 v138, v140
	v_mov_b32_e32 v139, v140
	v_mov_b32_e32 v144, v140
	v_mov_b32_e32 v145, v140
	v_mov_b32_e32 v146, v140
	v_mov_b32_e32 v147, v140
	v_mov_b32_e32 v148, v140
	v_mov_b32_e32 v149, v140
	v_mov_b32_e32 v150, v140
	v_mov_b32_e32 v151, v140
	v_mov_b32_e32 v152, v140
	v_mov_b32_e32 v153, v140
	v_mov_b32_e32 v154, v140
	v_mov_b32_e32 v155, v140
	v_mov_b32_e32 v156, v140
	v_mov_b32_e32 v157, v140
	v_mov_b32_e32 v158, v140
	v_mov_b32_e32 v159, v140
	v_mov_b32_e32 v160, v140
	v_mov_b32_e32 v161, v140
	v_mov_b32_e32 v162, v140
	v_mov_b32_e32 v163, v140
	v_mov_b32_e32 v164, v140
	v_mov_b32_e32 v165, v140
	v_mov_b32_e32 v166, v140
	v_mov_b32_e32 v167, v140
	v_mov_b32_e32 v168, v140
	v_mov_b32_e32 v169, v140
	v_mov_b32_e32 v170, v140
	v_mov_b32_e32 v171, v140
	v_mov_b32_e32 v172, v140
	v_mov_b32_e32 v173, v140
	v_mov_b32_e32 v174, v140
	v_mov_b32_e32 v175, v140
	s_setprio 2
	v_readlane_b32 s98, v253, 3
	v_readlane_b32 s99, v253, 4
	v_and_b32_e32 v224, 15, v188
	v_bfe_u32 v225, v188, 4, 2
	v_lshrrev_b32_e32 v226, 2, v224
	v_sub_u32_e32 v226, 0, v226
	v_and_b32_e32 v226, 3, v226
	v_xor_b32_e32 v225, v225, v226
	v_lshlrev_b32_e32 v225, 4, v225
	v_lshl_or_b32 v225, v224, 6, v225
	v_bfe_u32 v226, v188, 7, 1
	v_lshl_or_b32 v185, v226, 13, v225
	v_bfe_u32 v226, v188, 6, 1
	v_lshl_or_b32 v184, v226, 12, v225
	v_add_u32_e32 v184, 0x4000, v184
	v_lshrrev_b32_e32 v224, 3, v188
	v_bfe_u32 v225, v188, 2, 1
	v_lshrrev_b32_e32 v226, 2, v224
	v_sub_u32_e32 v226, 0, v226
	v_and_b32_e32 v226, 3, v226
	v_and_b32_e32 v227, 3, v188
	v_xor_b32_e32 v226, v227, v226
	v_lshlrev_b32_e32 v226, 4, v226
	v_xor_b32_e32 v224, v224, v225
	v_lshl_or_b32 v226, v224, 6, v226
	v_mul_u32_u24_e32 v225, 0x6000, v225
	v_add_u32_e32 v183, v225, v226
	s_mov_b32 m0, 0
	s_sub_u32 vcc_lo, s8, s98
	v_add_u32_e32 v186, vcc_lo, v178
	v_add_u32_e32 v187, vcc_lo, v180
	s_barrier
	s_waitcnt vmcnt(0)
	ds_write_b128 v183, v[116:119]
	ds_write_b128 v183, v[112:115] offset:2048
	ds_write_b128 v183, v[104:107] offset:4096
	ds_write_b128 v183, v[88:91] offset:6144
	ds_write_b128 v183, v[80:83] offset:8192
	ds_write_b128 v183, v[68:71] offset:10240
	ds_write_b128 v183, v[60:63] offset:12288
	ds_write_b128 v183, v[40:43] offset:14336
	ds_write_b128 v183, v[56:59] offset:16384
	ds_write_b128 v183, v[32:35] offset:18432
	ds_write_b128 v183, v[16:19] offset:20480
	ds_write_b128 v183, v[8:11] offset:22528
	v_cmp_gt_u32_e32 vcc, 0x6000, v183
	v_add_u32_e32 v182, 0xc000, v183
	v_add_u32_e32 v183, 0xffffa000, v183
	s_nop 0
	v_cndmask_b32_e32 v183, v183, v182, vcc
	v_add_u32_e32 v116, s26, v187
	global_load_dwordx4 v[116:119], v116, s[98:99] offset:128
	v_add_u32_e32 v112, s27, v187
	global_load_dwordx4 v[112:115], v112, s[98:99] offset:128
	v_add_u32_e32 v104, s20, v187
	global_load_dwordx4 v[104:107], v104, s[98:99] offset:128
	v_add_u32_e32 v88, s21, v187
	global_load_dwordx4 v[88:91], v88, s[98:99] offset:128
	v_add_u32_e32 v80, s56, v187
	global_load_dwordx4 v[80:83], v80, s[98:99] offset:128
	v_add_u32_e32 v68, s57, v187
	global_load_dwordx4 v[68:71], v68, s[98:99] offset:128
	v_add_u32_e32 v60, s24, v187
	global_load_dwordx4 v[60:63], v60, s[98:99] offset:128
	v_add_u32_e32 v40, s96, v187
	global_load_dwordx4 v[40:43], v40, s[98:99] offset:128
	v_mov_b32_e32 v56, v186
	global_load_dwordx4 v[56:59], v56, s[98:99] offset:128
	v_add_u32_e32 v32, s31, v186
	global_load_dwordx4 v[32:35], v32, s[98:99] offset:128
	v_add_u32_e32 v16, s14, v186
	global_load_dwordx4 v[16:19], v16, s[98:99] offset:128
	v_add_u32_e32 v8, s13, v186
	global_load_dwordx4 v[8:11], v8, s[98:99] offset:128
	s_add_u32 s8, s8, 0x80
	s_addc_u32 s9, s9, 0
.LBB0_147:
	s_waitcnt lgkmcnt(0)
	s_barrier
	ds_read_b128 v[224:227], v184
	ds_read_b128 v[228:231], v184 offset:1024
	ds_read_b128 v[232:235], v184 offset:2048
	ds_read_b128 v[236:239], v184 offset:3072
	ds_read_b128 v[190:193], v185
	ds_read_b128 v[194:197], v185 offset:1024
	ds_read_b128 v[198:201], v185 offset:2048
	ds_read_b128 v[204:207], v185 offset:3072
	ds_read_b128 v[208:211], v185 offset:4096
	ds_read_b128 v[212:215], v185 offset:5120
	ds_read_b128 v[216:219], v185 offset:6144
	ds_read_b128 v[220:223], v185 offset:7168
	s_movk_i32 vcc_lo, 0x6000
	s_cmp_eq_u32 m0, 2
	s_cselect_b32 vcc_lo, 0xffff4000, vcc_lo
	s_add_u32 m0, m0, 1
	s_cmp_eq_u32 m0, 3
	s_cselect_b32 m0, 0, m0
	v_add_u32_e32 v185, vcc_lo, v185
	v_add_u32_e32 v184, vcc_lo, v184
	v_xor_b32_e32 v185, 64, v185
	v_xor_b32_e32 v184, 64, v184
	s_waitcnt lgkmcnt(7)
	v_mfma_f32_16x16x32_bf16 v[172:175], v[224:227], v[190:193], v[172:175]
	v_mfma_f32_16x16x32_bf16 v[168:171], v[228:231], v[190:193], v[168:171]
	v_mfma_f32_16x16x32_bf16 v[164:167], v[232:235], v[190:193], v[164:167]
	v_mfma_f32_16x16x32_bf16 v[160:163], v[236:239], v[190:193], v[160:163]
	ds_read_b128 v[190:193], v185
	s_waitcnt lgkmcnt(7)
	v_mfma_f32_16x16x32_bf16 v[156:159], v[224:227], v[194:197], v[156:159]
	v_mfma_f32_16x16x32_bf16 v[152:155], v[228:231], v[194:197], v[152:155]
	v_mfma_f32_16x16x32_bf16 v[148:151], v[232:235], v[194:197], v[148:151]
	v_mfma_f32_16x16x32_bf16 v[144:147], v[236:239], v[194:197], v[144:147]
	ds_read_b128 v[194:197], v185 offset:1024
	s_waitcnt lgkmcnt(7)
	v_mfma_f32_16x16x32_bf16 v[136:139], v[224:227], v[198:201], v[136:139]
	v_mfma_f32_16x16x32_bf16 v[132:135], v[228:231], v[198:201], v[132:135]
	v_mfma_f32_16x16x32_bf16 v[128:131], v[232:235], v[198:201], v[128:131]
	v_mfma_f32_16x16x32_bf16 v[124:127], v[236:239], v[198:201], v[124:127]
	ds_read_b128 v[198:201], v185 offset:2048
	s_waitcnt lgkmcnt(7)
	v_mfma_f32_16x16x32_bf16 v[120:123], v[224:227], v[204:207], v[120:123]
	v_mfma_f32_16x16x32_bf16 v[108:111], v[228:231], v[204:207], v[108:111]
	v_mfma_f32_16x16x32_bf16 v[100:103], v[232:235], v[204:207], v[100:103]
	v_mfma_f32_16x16x32_bf16 v[96:99], v[236:239], v[204:207], v[96:99]
	ds_read_b128 v[204:207], v185 offset:3072
	s_waitcnt lgkmcnt(7)
	v_mfma_f32_16x16x32_bf16 v[92:95], v[224:227], v[208:211], v[92:95]
	v_mfma_f32_16x16x32_bf16 v[84:87], v[228:231], v[208:211], v[84:87]
	v_mfma_f32_16x16x32_bf16 v[76:79], v[232:235], v[208:211], v[76:79]
	v_mfma_f32_16x16x32_bf16 v[72:75], v[236:239], v[208:211], v[72:75]
	ds_read_b128 v[208:211], v185 offset:4096
	s_waitcnt lgkmcnt(7)
	v_mfma_f32_16x16x32_bf16 v[64:67], v[224:227], v[212:215], v[64:67]
	v_mfma_f32_16x16x32_bf16 v[52:55], v[228:231], v[212:215], v[52:55]
	v_mfma_f32_16x16x32_bf16 v[48:51], v[232:235], v[212:215], v[48:51]
	v_mfma_f32_16x16x32_bf16 v[44:47], v[236:239], v[212:215], v[44:47]
	ds_read_b128 v[212:215], v185 offset:5120
	s_waitcnt lgkmcnt(7)
	v_mfma_f32_16x16x32_bf16 v[36:39], v[224:227], v[216:219], v[36:39]
	v_mfma_f32_16x16x32_bf16 v[28:31], v[228:231], v[216:219], v[28:31]
	v_mfma_f32_16x16x32_bf16 v[24:27], v[232:235], v[216:219], v[24:27]
	v_mfma_f32_16x16x32_bf16 v[20:23], v[236:239], v[216:219], v[20:23]
	ds_read_b128 v[216:219], v185 offset:6144
	s_waitcnt lgkmcnt(7)
	v_mfma_f32_16x16x32_bf16 v[12:15], v[224:227], v[220:223], v[12:15]
	v_mfma_f32_16x16x32_bf16 v[4:7], v[228:231], v[220:223], v[4:7]
	v_mfma_f32_16x16x32_bf16 v[0:3], v[232:235], v[220:223], v[0:3]
	v_mfma_f32_16x16x32_bf16 v[140:143], v[236:239], v[220:223], v[140:143]
	ds_read_b128 v[220:223], v185 offset:7168
	ds_read_b128 v[224:227], v184
	ds_read_b128 v[228:231], v184 offset:1024
	ds_read_b128 v[232:235], v184 offset:2048
	ds_read_b128 v[236:239], v184 offset:3072
	s_movk_i32 vcc_lo, 0x6000
	s_cmp_eq_u32 m0, 2
	s_cselect_b32 vcc_lo, 0xffff4000, vcc_lo
	s_add_u32 m0, m0, 1
	s_cmp_eq_u32 m0, 3
	s_cselect_b32 m0, 0, m0
	v_add_u32_e32 v185, vcc_lo, v185
	v_add_u32_e32 v184, vcc_lo, v184
	v_xor_b32_e32 v185, 64, v185
	v_xor_b32_e32 v184, 64, v184
	s_sub_u32 vcc_lo, s8, s98
	v_add_u32_e32 v186, vcc_lo, v178
	v_add_u32_e32 v187, vcc_lo, v180
	s_barrier
	s_waitcnt lgkmcnt(0)
	v_mfma_f32_16x16x32_bf16 v[172:175], v[224:227], v[190:193], v[172:175]
	s_waitcnt vmcnt(11)
	v_mfma_f32_16x16x32_bf16 v[168:171], v[228:231], v[190:193], v[168:171]
	ds_write_b128 v183, v[116:119]
	v_add_u32_e32 v116, s26, v187
	v_mfma_f32_16x16x32_bf16 v[164:167], v[232:235], v[190:193], v[164:167]
	global_load_dwordx4 v[116:119], v116, s[98:99] offset:128
	v_mfma_f32_16x16x32_bf16 v[160:163], v[236:239], v[190:193], v[160:163]
	s_waitcnt vmcnt(11)
	ds_write_b128 v183, v[112:115] offset:2048
	v_mfma_f32_16x16x32_bf16 v[156:159], v[224:227], v[194:197], v[156:159]
	v_add_u32_e32 v112, s27, v187
	v_mfma_f32_16x16x32_bf16 v[152:155], v[228:231], v[194:197], v[152:155]
	global_load_dwordx4 v[112:115], v112, s[98:99] offset:128
	s_waitcnt vmcnt(11)
	v_mfma_f32_16x16x32_bf16 v[148:151], v[232:235], v[194:197], v[148:151]
	ds_write_b128 v183, v[104:107] offset:4096
	v_mfma_f32_16x16x32_bf16 v[144:147], v[236:239], v[194:197], v[144:147]
	v_add_u32_e32 v104, s20, v187
	global_load_dwordx4 v[104:107], v104, s[98:99] offset:128
	v_mfma_f32_16x16x32_bf16 v[136:139], v[224:227], v[198:201], v[136:139]
	s_waitcnt vmcnt(11)
	v_mfma_f32_16x16x32_bf16 v[132:135], v[228:231], v[198:201], v[132:135]
	ds_write_b128 v183, v[88:91] offset:6144
	v_add_u32_e32 v88, s21, v187
	v_mfma_f32_16x16x32_bf16 v[128:131], v[232:235], v[198:201], v[128:131]
	global_load_dwordx4 v[88:91], v88, s[98:99] offset:128
	v_mfma_f32_16x16x32_bf16 v[124:127], v[236:239], v[198:201], v[124:127]
	s_waitcnt vmcnt(11)
	ds_write_b128 v183, v[80:83] offset:8192
	v_mfma_f32_16x16x32_bf16 v[120:123], v[224:227], v[204:207], v[120:123]
	v_add_u32_e32 v80, s56, v187
	v_mfma_f32_16x16x32_bf16 v[108:111], v[228:231], v[204:207], v[108:111]
	global_load_dwordx4 v[80:83], v80, s[98:99] offset:128
	s_waitcnt vmcnt(11)
	v_mfma_f32_16x16x32_bf16 v[100:103], v[232:235], v[204:207], v[100:103]
	ds_write_b128 v183, v[68:71] offset:10240
	v_mfma_f32_16x16x32_bf16 v[96:99], v[236:239], v[204:207], v[96:99]
	v_add_u32_e32 v68, s57, v187
	global_load_dwordx4 v[68:71], v68, s[98:99] offset:128
	v_mfma_f32_16x16x32_bf16 v[92:95], v[224:227], v[208:211], v[92:95]
	s_waitcnt vmcnt(11)
	v_mfma_f32_16x16x32_bf16 v[84:87], v[228:231], v[208:211], v[84:87]
	ds_write_b128 v183, v[60:63] offset:12288
	v_add_u32_e32 v60, s24, v187
	v_mfma_f32_16x16x32_bf16 v[76:79], v[232:235], v[208:211], v[76:79]
	global_load_dwordx4 v[60:63], v60, s[98:99] offset:128
	v_mfma_f32_16x16x32_bf16 v[72:75], v[236:239], v[208:211], v[72:75]
	s_waitcnt vmcnt(11)
	ds_write_b128 v183, v[40:43] offset:14336
	v_mfma_f32_16x16x32_bf16 v[64:67], v[224:227], v[212:215], v[64:67]
	v_add_u32_e32 v40, s96, v187
	v_mfma_f32_16x16x32_bf16 v[52:55], v[228:231], v[212:215], v[52:55]
	global_load_dwordx4 v[40:43], v40, s[98:99] offset:128
	s_waitcnt vmcnt(11)
	v_mfma_f32_16x16x32_bf16 v[48:51], v[232:235], v[212:215], v[48:51]
	ds_write_b128 v183, v[56:59] offset:16384
	v_mfma_f32_16x16x32_bf16 v[44:47], v[236:239], v[212:215], v[44:47]
	v_mov_b32_e32 v56, v186
	global_load_dwordx4 v[56:59], v56, s[98:99] offset:128
	v_mfma_f32_16x16x32_bf16 v[36:39], v[224:227], v[216:219], v[36:39]
	s_waitcnt vmcnt(11)
	v_mfma_f32_16x16x32_bf16 v[28:31], v[228:231], v[216:219], v[28:31]
	ds_write_b128 v183, v[32:35] offset:18432
	v_add_u32_e32 v32, s31, v186
	v_mfma_f32_16x16x32_bf16 v[24:27], v[232:235], v[216:219], v[24:27]
	global_load_dwordx4 v[32:35], v32, s[98:99] offset:128
	v_mfma_f32_16x16x32_bf16 v[20:23], v[236:239], v[216:219], v[20:23]
	s_waitcnt vmcnt(11)
	ds_write_b128 v183, v[16:19] offset:20480
	v_mfma_f32_16x16x32_bf16 v[12:15], v[224:227], v[220:223], v[12:15]
	v_add_u32_e32 v16, s14, v186
	v_mfma_f32_16x16x32_bf16 v[4:7], v[228:231], v[220:223], v[4:7]
	global_load_dwordx4 v[16:19], v16, s[98:99] offset:128
	s_waitcnt vmcnt(11)
	v_mfma_f32_16x16x32_bf16 v[0:3], v[232:235], v[220:223], v[0:3]
	ds_write_b128 v183, v[8:11] offset:22528
	v_mfma_f32_16x16x32_bf16 v[140:143], v[236:239], v[220:223], v[140:143]
	v_add_u32_e32 v8, s13, v186
	global_load_dwordx4 v[8:11], v8, s[98:99] offset:128
	v_cmp_gt_u32_e32 vcc, 0x6000, v183
	v_add_u32_e32 v182, 0xc000, v183
	v_add_u32_e32 v183, 0xffffa000, v183
	s_nop 0
	v_cndmask_b32_e32 v183, v183, v182, vcc
	s_add_u32 s8, s8, 0x80
	s_addc_u32 s9, s9, 0
	s_cmpk_lg_i32 s8, 0x780
	s_cbranch_scc1 .LBB0_147
	s_waitcnt lgkmcnt(0)
	s_barrier
	ds_read_b128 v[224:227], v184
	ds_read_b128 v[228:231], v184 offset:1024
	ds_read_b128 v[232:235], v184 offset:2048
	ds_read_b128 v[236:239], v184 offset:3072
	ds_read_b128 v[190:193], v185
	ds_read_b128 v[194:197], v185 offset:1024
	ds_read_b128 v[198:201], v185 offset:2048
	ds_read_b128 v[204:207], v185 offset:3072
	ds_read_b128 v[208:211], v185 offset:4096
	ds_read_b128 v[212:215], v185 offset:5120
	ds_read_b128 v[216:219], v185 offset:6144
	ds_read_b128 v[220:223], v185 offset:7168
	s_movk_i32 vcc_lo, 0x6000
	s_cmp_eq_u32 m0, 2
	s_cselect_b32 vcc_lo, 0xffff4000, vcc_lo
	s_add_u32 m0, m0, 1
	s_cmp_eq_u32 m0, 3
	s_cselect_b32 m0, 0, m0
	v_add_u32_e32 v185, vcc_lo, v185
	v_add_u32_e32 v184, vcc_lo, v184
	v_xor_b32_e32 v185, 64, v185
	v_xor_b32_e32 v184, 64, v184
	s_waitcnt lgkmcnt(7)
	v_mfma_f32_16x16x32_bf16 v[172:175], v[224:227], v[190:193], v[172:175]
	v_mfma_f32_16x16x32_bf16 v[168:171], v[228:231], v[190:193], v[168:171]
	v_mfma_f32_16x16x32_bf16 v[164:167], v[232:235], v[190:193], v[164:167]
	v_mfma_f32_16x16x32_bf16 v[160:163], v[236:239], v[190:193], v[160:163]
	ds_read_b128 v[190:193], v185
	s_waitcnt lgkmcnt(7)
	v_mfma_f32_16x16x32_bf16 v[156:159], v[224:227], v[194:197], v[156:159]
	v_mfma_f32_16x16x32_bf16 v[152:155], v[228:231], v[194:197], v[152:155]
	v_mfma_f32_16x16x32_bf16 v[148:151], v[232:235], v[194:197], v[148:151]
	v_mfma_f32_16x16x32_bf16 v[144:147], v[236:239], v[194:197], v[144:147]
	ds_read_b128 v[194:197], v185 offset:1024
	s_waitcnt lgkmcnt(7)
	v_mfma_f32_16x16x32_bf16 v[136:139], v[224:227], v[198:201], v[136:139]
	v_mfma_f32_16x16x32_bf16 v[132:135], v[228:231], v[198:201], v[132:135]
	v_mfma_f32_16x16x32_bf16 v[128:131], v[232:235], v[198:201], v[128:131]
	v_mfma_f32_16x16x32_bf16 v[124:127], v[236:239], v[198:201], v[124:127]
	ds_read_b128 v[198:201], v185 offset:2048
	s_waitcnt lgkmcnt(7)
	v_mfma_f32_16x16x32_bf16 v[120:123], v[224:227], v[204:207], v[120:123]
	v_mfma_f32_16x16x32_bf16 v[108:111], v[228:231], v[204:207], v[108:111]
	v_mfma_f32_16x16x32_bf16 v[100:103], v[232:235], v[204:207], v[100:103]
	v_mfma_f32_16x16x32_bf16 v[96:99], v[236:239], v[204:207], v[96:99]
	ds_read_b128 v[204:207], v185 offset:3072
	s_waitcnt lgkmcnt(7)
	v_mfma_f32_16x16x32_bf16 v[92:95], v[224:227], v[208:211], v[92:95]
	v_mfma_f32_16x16x32_bf16 v[84:87], v[228:231], v[208:211], v[84:87]
	v_mfma_f32_16x16x32_bf16 v[76:79], v[232:235], v[208:211], v[76:79]
	v_mfma_f32_16x16x32_bf16 v[72:75], v[236:239], v[208:211], v[72:75]
	ds_read_b128 v[208:211], v185 offset:4096
	s_waitcnt lgkmcnt(7)
	v_mfma_f32_16x16x32_bf16 v[64:67], v[224:227], v[212:215], v[64:67]
	v_mfma_f32_16x16x32_bf16 v[52:55], v[228:231], v[212:215], v[52:55]
	v_mfma_f32_16x16x32_bf16 v[48:51], v[232:235], v[212:215], v[48:51]
	v_mfma_f32_16x16x32_bf16 v[44:47], v[236:239], v[212:215], v[44:47]
	ds_read_b128 v[212:215], v185 offset:5120
	s_waitcnt lgkmcnt(7)
	v_mfma_f32_16x16x32_bf16 v[36:39], v[224:227], v[216:219], v[36:39]
	v_mfma_f32_16x16x32_bf16 v[28:31], v[228:231], v[216:219], v[28:31]
	v_mfma_f32_16x16x32_bf16 v[24:27], v[232:235], v[216:219], v[24:27]
	v_mfma_f32_16x16x32_bf16 v[20:23], v[236:239], v[216:219], v[20:23]
	ds_read_b128 v[216:219], v185 offset:6144
	s_waitcnt lgkmcnt(7)
	v_mfma_f32_16x16x32_bf16 v[12:15], v[224:227], v[220:223], v[12:15]
	v_mfma_f32_16x16x32_bf16 v[4:7], v[228:231], v[220:223], v[4:7]
	v_mfma_f32_16x16x32_bf16 v[0:3], v[232:235], v[220:223], v[0:3]
	v_mfma_f32_16x16x32_bf16 v[140:143], v[236:239], v[220:223], v[140:143]
	ds_read_b128 v[220:223], v185 offset:7168
	ds_read_b128 v[224:227], v184
	ds_read_b128 v[228:231], v184 offset:1024
	ds_read_b128 v[232:235], v184 offset:2048
	ds_read_b128 v[236:239], v184 offset:3072
	s_movk_i32 vcc_lo, 0x6000
	s_cmp_eq_u32 m0, 2
	s_cselect_b32 vcc_lo, 0xffff4000, vcc_lo
	s_add_u32 m0, m0, 1
	s_cmp_eq_u32 m0, 3
	s_cselect_b32 m0, 0, m0
	v_add_u32_e32 v185, vcc_lo, v185
	v_add_u32_e32 v184, vcc_lo, v184
	v_xor_b32_e32 v185, 64, v185
	v_xor_b32_e32 v184, 64, v184
	s_waitcnt lgkmcnt(0)
	v_mfma_f32_16x16x32_bf16 v[172:175], v[224:227], v[190:193], v[172:175]
	v_mfma_f32_16x16x32_bf16 v[168:171], v[228:231], v[190:193], v[168:171]
	v_mfma_f32_16x16x32_bf16 v[164:167], v[232:235], v[190:193], v[164:167]
	v_mfma_f32_16x16x32_bf16 v[160:163], v[236:239], v[190:193], v[160:163]
	v_mfma_f32_16x16x32_bf16 v[156:159], v[224:227], v[194:197], v[156:159]
	v_mfma_f32_16x16x32_bf16 v[152:155], v[228:231], v[194:197], v[152:155]
	v_mfma_f32_16x16x32_bf16 v[148:151], v[232:235], v[194:197], v[148:151]
	v_mfma_f32_16x16x32_bf16 v[144:147], v[236:239], v[194:197], v[144:147]
	v_mfma_f32_16x16x32_bf16 v[136:139], v[224:227], v[198:201], v[136:139]
	v_mfma_f32_16x16x32_bf16 v[132:135], v[228:231], v[198:201], v[132:135]
	v_mfma_f32_16x16x32_bf16 v[128:131], v[232:235], v[198:201], v[128:131]
	v_mfma_f32_16x16x32_bf16 v[124:127], v[236:239], v[198:201], v[124:127]
	v_mfma_f32_16x16x32_bf16 v[120:123], v[224:227], v[204:207], v[120:123]
	v_mfma_f32_16x16x32_bf16 v[108:111], v[228:231], v[204:207], v[108:111]
	v_mfma_f32_16x16x32_bf16 v[100:103], v[232:235], v[204:207], v[100:103]
	v_mfma_f32_16x16x32_bf16 v[96:99], v[236:239], v[204:207], v[96:99]
	v_mfma_f32_16x16x32_bf16 v[92:95], v[224:227], v[208:211], v[92:95]
	v_mfma_f32_16x16x32_bf16 v[84:87], v[228:231], v[208:211], v[84:87]
	v_mfma_f32_16x16x32_bf16 v[76:79], v[232:235], v[208:211], v[76:79]
	v_mfma_f32_16x16x32_bf16 v[72:75], v[236:239], v[208:211], v[72:75]
	v_mfma_f32_16x16x32_bf16 v[64:67], v[224:227], v[212:215], v[64:67]
	v_mfma_f32_16x16x32_bf16 v[52:55], v[228:231], v[212:215], v[52:55]
	v_mfma_f32_16x16x32_bf16 v[48:51], v[232:235], v[212:215], v[48:51]
	v_mfma_f32_16x16x32_bf16 v[44:47], v[236:239], v[212:215], v[44:47]
	v_mfma_f32_16x16x32_bf16 v[36:39], v[224:227], v[216:219], v[36:39]
	v_mfma_f32_16x16x32_bf16 v[28:31], v[228:231], v[216:219], v[28:31]
	v_mfma_f32_16x16x32_bf16 v[24:27], v[232:235], v[216:219], v[24:27]
	v_mfma_f32_16x16x32_bf16 v[20:23], v[236:239], v[216:219], v[20:23]
	v_mfma_f32_16x16x32_bf16 v[12:15], v[224:227], v[220:223], v[12:15]
	v_mfma_f32_16x16x32_bf16 v[4:7], v[228:231], v[220:223], v[4:7]
	v_mfma_f32_16x16x32_bf16 v[0:3], v[232:235], v[220:223], v[0:3]
	v_mfma_f32_16x16x32_bf16 v[140:143], v[236:239], v[220:223], v[140:143]
	v_lshrrev_b32_e32 v224, 4, v188
	v_and_b32_e32 v225, 7, v188
	v_bitop3_b32 v226, v224, v225, 3 bitop3:0x6c
	v_lshlrev_b32_e32 v227, 7, v188
	v_bfe_u32 v228, v188, 4, 2
	v_and_b32_e32 v229, 0xffffc780, v227
	v_and_b32_e32 v227, 0x2780, v227
	v_bitop3_b32 v228, v228, v225, 4 bitop3:0x36
	v_lshlrev_b32_e32 v226, 4, v226
	v_lshlrev_b32_e32 v228, 4, v228
	v_or_b32_e32 v185, v229, v226
	v_or_b32_e32 v184, v227, v226
	v_or_b32_e32 v183, v229, v228
	v_or_b32_e32 v182, v227, v228
	s_waitcnt vmcnt(0)
	s_setprio 0
	s_barrier
	s_waitcnt vmcnt(10)
	ds_write_b128 v176, v[116:119]
	s_waitcnt vmcnt(9)
	ds_write_b128 v176, v[112:115] offset:4096
	s_waitcnt vmcnt(8)
	ds_write_b128 v176, v[104:107] offset:8192
	s_waitcnt vmcnt(7)
	ds_write_b128 v176, v[88:91] offset:12288
	s_waitcnt vmcnt(6)
	ds_write_b128 v176, v[80:83] offset:16384
	s_waitcnt vmcnt(5)
	ds_write_b128 v176, v[68:71] offset:20480
	s_waitcnt vmcnt(4)
	ds_write_b128 v176, v[60:63] offset:24576
	s_waitcnt vmcnt(3)
	ds_write_b128 v176, v[40:43] offset:28672
	ds_write_b128 v176, v[56:59] offset:32768
	s_waitcnt vmcnt(2)
	ds_write_b128 v176, v[32:35] offset:36864
	s_waitcnt vmcnt(1)
	ds_write_b128 v176, v[16:19] offset:40960
	s_waitcnt vmcnt(0)
	ds_write_b128 v176, v[8:11] offset:45056
	s_waitcnt lgkmcnt(0)
	s_barrier
	ds_read_b128 v[8:11], v185
	ds_read_b128 v[16:19], v185 offset:2048
	ds_read_b128 v[32:35], v185 offset:4096
	ds_read_b128 v[40:43], v185 offset:6144
	ds_read_b128 v[56:59], v185 offset:8192
	ds_read_b128 v[60:63], v185 offset:10240
	ds_read_b128 v[68:71], v185 offset:12288
	ds_read_b128 v[80:83], v185 offset:14336
	ds_read_b128 v[88:91], v184 offset:32768
	ds_read_b128 v[104:107], v184 offset:34816
	ds_read_b128 v[112:115], v184 offset:36864
	ds_read_b128 v[116:119], v184 offset:38912
	s_waitcnt lgkmcnt(3)
	v_mfma_f32_16x16x32_bf16 v[172:175], v[88:91], v[8:11], v[172:175]
	s_waitcnt lgkmcnt(2)
	v_mfma_f32_16x16x32_bf16 v[168:171], v[104:107], v[8:11], v[168:171]
	s_waitcnt lgkmcnt(1)
	v_mfma_f32_16x16x32_bf16 v[164:167], v[112:115], v[8:11], v[164:167]
	s_waitcnt lgkmcnt(0)
	v_mfma_f32_16x16x32_bf16 v[8:11], v[116:119], v[8:11], v[160:163]
	v_mfma_f32_16x16x32_bf16 v[156:159], v[88:91], v[16:19], v[156:159]
	v_mfma_f32_16x16x32_bf16 v[152:155], v[104:107], v[16:19], v[152:155]
	v_mfma_f32_16x16x32_bf16 v[148:151], v[112:115], v[16:19], v[148:151]
	v_mfma_f32_16x16x32_bf16 v[16:19], v[116:119], v[16:19], v[144:147]
	v_mfma_f32_16x16x32_bf16 v[136:139], v[88:91], v[32:35], v[136:139]
	v_mfma_f32_16x16x32_bf16 v[132:135], v[104:107], v[32:35], v[132:135]
	v_mfma_f32_16x16x32_bf16 v[128:131], v[112:115], v[32:35], v[128:131]
	v_mfma_f32_16x16x32_bf16 v[32:35], v[116:119], v[32:35], v[124:127]
	v_mfma_f32_16x16x32_bf16 v[120:123], v[88:91], v[40:43], v[120:123]
	v_mfma_f32_16x16x32_bf16 v[108:111], v[104:107], v[40:43], v[108:111]
	v_mfma_f32_16x16x32_bf16 v[100:103], v[112:115], v[40:43], v[100:103]
	v_mfma_f32_16x16x32_bf16 v[40:43], v[116:119], v[40:43], v[96:99]
	v_mfma_f32_16x16x32_bf16 v[92:95], v[88:91], v[56:59], v[92:95]
	v_mfma_f32_16x16x32_bf16 v[84:87], v[104:107], v[56:59], v[84:87]
	v_mfma_f32_16x16x32_bf16 v[76:79], v[112:115], v[56:59], v[76:79]
	v_mfma_f32_16x16x32_bf16 v[56:59], v[116:119], v[56:59], v[72:75]
	v_mfma_f32_16x16x32_bf16 v[64:67], v[88:91], v[60:63], v[64:67]
	v_mfma_f32_16x16x32_bf16 v[52:55], v[104:107], v[60:63], v[52:55]
	v_mfma_f32_16x16x32_bf16 v[72:75], v[112:115], v[60:63], v[48:51]
	v_mfma_f32_16x16x32_bf16 v[60:63], v[116:119], v[60:63], v[44:47]
	v_mfma_f32_16x16x32_bf16 v[96:99], v[88:91], v[68:71], v[36:39]
	v_mfma_f32_16x16x32_bf16 v[28:31], v[104:107], v[68:71], v[28:31]
	v_mfma_f32_16x16x32_bf16 v[124:127], v[112:115], v[68:71], v[24:27]
	v_mfma_f32_16x16x32_bf16 v[20:23], v[116:119], v[68:71], v[20:23]
	v_mfma_f32_16x16x32_bf16 v[12:15], v[88:91], v[80:83], v[12:15]
	v_mfma_f32_16x16x32_bf16 v[4:7], v[104:107], v[80:83], v[4:7]
	v_mfma_f32_16x16x32_bf16 v[0:3], v[112:115], v[80:83], v[0:3]
	v_mfma_f32_16x16x32_bf16 v[68:71], v[116:119], v[80:83], v[140:143]
	ds_read_b128 v[24:27], v183
	ds_read_b128 v[36:39], v183 offset:2048
	ds_read_b128 v[44:47], v183 offset:4096
	ds_read_b128 v[80:83], v183 offset:6144
	ds_read_b128 v[88:91], v183 offset:8192
	ds_read_b128 v[104:107], v183 offset:10240
	ds_read_b128 v[112:115], v183 offset:12288
	ds_read_b128 v[116:119], v183 offset:14336
	ds_read_b128 v[140:143], v182 offset:32768
	ds_read_b128 v[144:147], v182 offset:34816
	ds_read_b128 v[160:163], v182 offset:36864
	ds_read_b128 v[178:181], v182 offset:38912
	s_waitcnt lgkmcnt(3)
	v_mfma_f32_16x16x32_bf16 v[172:175], v[140:143], v[24:27], v[172:175]
	v_mov_b32_e32 v49, v188
	v_cmp_lt_i32_e32 vcc, v189, v202
	s_waitcnt lgkmcnt(2)
	v_mfma_f32_16x16x32_bf16 v[168:171], v[144:147], v[24:27], v[168:171]
	v_mov_b32_e32 v48, v188
	v_readlane_b32 s8, v253, 24
	s_waitcnt lgkmcnt(1)
	v_mfma_f32_16x16x32_bf16 v[164:167], v[160:163], v[24:27], v[164:167]
	v_and_b32_e32 v50, 0xffffff80, v48
	v_add_u32_e32 v51, s11, v50
	v_and_or_b32 v50, v48, 64, s12
	s_waitcnt lgkmcnt(0)
	v_mfma_f32_16x16x32_bf16 v[8:11], v[178:181], v[24:27], v[8:11]
	v_bfe_u32 v26, v49, 4, 1
	v_cndmask_b32_e32 v24, v203, v189, vcc
	v_cmp_eq_u32_e32 vcc, 0, v26
	v_lshlrev_b32_e32 v186, 2, v24
	v_mfma_f32_16x16x32_bf16 v[182:185], v[178:181], v[36:39], v[16:19]
	v_and_or_b32 v48, v49, 15, v51
	v_ashrrev_i32_e32 v51, 31, v50
	v_lshl_add_u64 v[50:51], v[50:51], 1, s[6:7]
	s_nop 0
	s_nop 0
	s_nop 0
	s_nop 0
	s_nop 0
	s_nop 0
	s_nop 0
	s_nop 0
	v_lshlrev_b32_e32 v176, 5, v26
	v_lshrrev_b32_e32 v27, 1, v49
	v_lshl_add_u64 v[24:25], v[50:51], 0, v[176:177]
	v_and_b32_e32 v176, 16, v27
	v_ashrrev_i32_e32 v49, 31, v48
	v_mfma_f32_16x16x32_bf16 v[156:159], v[140:143], v[36:39], v[156:159]
	v_lshl_add_u64 v[50:51], v[24:25], 0, v[176:177]
	v_lshlrev_b64 v[24:25], 11, v[48:49]
	s_waitcnt lgkmcnt(0)
	s_nop 0
	v_mfma_f32_16x16x32_bf16 v[152:155], v[144:147], v[36:39], v[152:155]
	v_mov_b32_e32 v26, v172
	v_mov_b32_e32 v27, v168
	s_nop 1
	v_permlane16_swap_b32_e32 v26, v27
	s_waitcnt lgkmcnt(0)
	s_nop 0
	v_lshl_add_u64 v[24:25], v[50:51], 0, v[24:25]
	v_mfma_f32_16x16x32_bf16 v[148:151], v[160:163], v[36:39], v[148:151]
	v_mov_b32_e32 v16, v173
	v_mov_b32_e32 v36, v169
	s_nop 1
	v_permlane16_swap_b32_e32 v16, v36
	s_waitcnt lgkmcnt(0)
	s_nop 0
	v_cvt_pk_bf16_f32 v16, v26, v16
	v_mfma_f32_16x16x32_bf16 v[190:193], v[178:181], v[44:47], v[32:35]
	v_readlane_b32 s9, v253, 25
	s_nop 1
	v_mov_b32_e32 v17, v174
	v_mov_b32_e32 v32, v170
	s_nop 1
	v_permlane16_swap_b32_e32 v17, v32
	s_waitcnt lgkmcnt(0)
	s_nop 0
	v_mov_b32_e32 v18, v175
	v_mov_b32_e32 v19, v171
	s_nop 1
	v_permlane16_swap_b32_e32 v18, v19
	v_cvt_pk_bf16_f32 v17, v17, v18
	v_cvt_pk_bf16_f32 v18, v27, v36
	v_cvt_pk_bf16_f32 v19, v32, v19
	global_store_dwordx4 v[24:25], v[16:19], off
	v_mfma_f32_16x16x32_bf16 v[120:123], v[140:143], v[80:83], v[120:123]
	s_nop 0
	s_nop 0
	s_nop 0
	s_nop 0
	s_nop 0
	s_nop 0
	s_nop 0
	s_nop 0
	s_nop 0
	v_mfma_f32_16x16x32_bf16 v[108:111], v[144:147], v[80:83], v[108:111]
	s_waitcnt lgkmcnt(0)
	s_nop 0
	v_mov_b32_e32 v26, v164
	v_mov_b32_e32 v16, v8
	s_nop 1
	v_permlane16_swap_b32_e32 v26, v16
	s_waitcnt lgkmcnt(0)
	s_nop 0
	v_mov_b32_e32 v8, v165
	v_mov_b32_e32 v17, v9
	s_nop 1
	v_permlane16_swap_b32_e32 v8, v17
	s_waitcnt lgkmcnt(0)
	s_nop 0
	v_mov_b32_e32 v9, v166
	v_mov_b32_e32 v18, v10
	s_nop 1
	v_permlane16_swap_b32_e32 v9, v18
	s_waitcnt lgkmcnt(0)
	s_nop 0
	v_mov_b32_e32 v10, v167
	s_nop 1
	v_permlane16_swap_b32_e32 v10, v11
	v_cvt_pk_bf16_f32 v8, v26, v8
	v_cvt_pk_bf16_f32 v9, v9, v10
	v_cvt_pk_bf16_f32 v10, v16, v17
	v_cvt_pk_bf16_f32 v11, v18, v11
	global_store_dwordx4 v[24:25], v[8:11], off offset:64
	v_mfma_f32_16x16x32_bf16 v[100:103], v[160:163], v[80:83], v[100:103]
	s_nop 0
	v_or_b32_e32 v8, 16, v48
	v_ashrrev_i32_e32 v9, 31, v8
	v_lshlrev_b64 v[8:9], 11, v[8:9]
	v_mfma_f32_16x16x32_bf16 v[80:83], v[178:181], v[80:83], v[40:43]
	s_nop 0
	s_nop 0
	s_nop 0
	v_mfma_f32_16x16x32_bf16 v[40:43], v[140:143], v[104:107], v[64:67]
	s_nop 0
	s_nop 1
	v_lshl_add_u64 v[64:65], v[50:51], 0, v[8:9]
	s_nop 0
	s_nop 0
	s_nop 0
	s_nop 0
	v_mfma_f32_16x16x32_bf16 v[136:139], v[140:143], v[44:47], v[136:139]
	s_waitcnt lgkmcnt(0)
	s_nop 0
	v_mfma_f32_16x16x32_bf16 v[132:135], v[144:147], v[44:47], v[132:135]
	v_mfma_f32_16x16x32_bf16 v[128:131], v[160:163], v[44:47], v[128:131]
	v_mfma_f32_16x16x32_bf16 v[44:47], v[144:147], v[104:107], v[52:55]
	v_mfma_f32_16x16x32_bf16 v[36:39], v[178:181], v[104:107], v[60:63]
	s_nop 1
	v_mov_b32_e32 v49, v156
	v_mov_b32_e32 v54, v152
	s_nop 1
	v_permlane16_swap_b32_e32 v49, v54
	s_waitcnt lgkmcnt(0)
	s_nop 0
	v_mov_b32_e32 v8, v157
	v_mov_b32_e32 v55, v153
	s_nop 1
	v_permlane16_swap_b32_e32 v8, v55
	s_nop 0
	v_mov_b32_e32 v53, v158
	v_mov_b32_e32 v60, v154
	s_nop 1
	v_permlane16_swap_b32_e32 v53, v60
	s_nop 0
	v_mov_b32_e32 v61, v159
	v_mov_b32_e32 v62, v155
	s_nop 1
	v_permlane16_swap_b32_e32 v61, v62
	v_cvt_pk_bf16_f32 v52, v49, v8
	v_cvt_pk_bf16_f32 v53, v53, v61
	v_cvt_pk_bf16_f32 v54, v54, v55
	v_cvt_pk_bf16_f32 v55, v60, v62
	v_mfma_f32_16x16x32_bf16 v[8:11], v[140:143], v[116:119], v[12:15]
	global_store_dwordx4 v[64:65], v[52:55], off
	s_nop 0
	s_nop 0
	v_mfma_f32_16x16x32_bf16 v[12:15], v[144:147], v[116:119], v[4:7]
	s_nop 0
	s_nop 0
	s_nop 0
	v_cndmask_b32_e32 v4, v148, v182, vcc
	ds_bpermute_b32 v54, v186, v4
	s_nop 0
	s_waitcnt lgkmcnt(1)
	s_nop 0
	v_mov_b32_e32 v60, v149
	v_mov_b32_e32 v49, v183
	s_nop 1
	v_permlane16_swap_b32_e32 v60, v49
	s_waitcnt lgkmcnt(1)
	s_nop 0
	s_waitcnt lgkmcnt(0)
	v_cndmask_b32_e32 v55, v54, v148, vcc
	v_cndmask_b32_e32 v54, v182, v54, vcc
	v_mov_b32_e32 v61, v150
	v_mov_b32_e32 v62, v184
	s_nop 1
	v_permlane16_swap_b32_e32 v61, v62
	s_waitcnt lgkmcnt(0)
	s_nop 0
	v_mov_b32_e32 v63, v151
	v_mov_b32_e32 v66, v185
	s_nop 1
	v_permlane16_swap_b32_e32 v63, v66
	v_cvt_pk_bf16_f32 v52, v55, v60
	v_cvt_pk_bf16_f32 v53, v61, v63
	v_cvt_pk_bf16_f32 v54, v54, v49
	v_cvt_pk_bf16_f32 v55, v62, v66
	global_store_dwordx4 v[64:65], v[52:55], off offset:64
	s_nop 0
	s_nop 0
	v_or_b32_e32 v52, 32, v48
	v_ashrrev_i32_e32 v53, 31, v52
	v_lshlrev_b64 v[52:53], 11, v[52:53]
	v_lshl_add_u64 v[60:61], v[50:51], 0, v[52:53]
	s_nop 0
	s_nop 0
	s_nop 0
	s_nop 0
	s_nop 0
	s_nop 0
	s_waitcnt lgkmcnt(0)
	s_nop 0
	v_mov_b32_e32 v55, v136
	v_mov_b32_e32 v49, v132
	s_nop 1
	v_permlane16_swap_b32_e32 v55, v49
	s_waitcnt lgkmcnt(0)
	s_nop 0
	v_mov_b32_e32 v62, v137
	v_mov_b32_e32 v63, v133
	s_nop 1
	v_permlane16_swap_b32_e32 v62, v63
	s_waitcnt lgkmcnt(0)
	s_nop 0
	v_mov_b32_e32 v64, v138
	v_mov_b32_e32 v65, v134
	s_nop 1
	v_permlane16_swap_b32_e32 v64, v65
	s_waitcnt lgkmcnt(0)
	s_nop 0
	v_mov_b32_e32 v53, v139
	v_mov_b32_e32 v66, v135
	s_nop 1
	v_permlane16_swap_b32_e32 v53, v66
	v_cvt_pk_bf16_f32 v52, v55, v62
	v_cvt_pk_bf16_f32 v53, v64, v53
	v_cvt_pk_bf16_f32 v54, v49, v63
	v_cvt_pk_bf16_f32 v55, v65, v66
	global_store_dwordx4 v[60:61], v[52:55], off
	s_nop 0
	s_nop 0
	s_nop 0
	s_nop 0
	s_nop 0
	s_nop 0
	s_nop 0
	s_nop 0
	s_waitcnt lgkmcnt(0)
	s_nop 0
	v_mov_b32_e32 v55, v128
	v_mov_b32_e32 v49, v190
	s_nop 1
	v_permlane16_swap_b32_e32 v55, v49
	s_waitcnt lgkmcnt(0)
	s_nop 0
	v_mov_b32_e32 v62, v129
	v_mov_b32_e32 v63, v191
	s_nop 1
	v_permlane16_swap_b32_e32 v62, v63
	s_waitcnt lgkmcnt(0)
	s_nop 0
	v_mov_b32_e32 v64, v130
	v_mov_b32_e32 v65, v192
	s_nop 1
	v_permlane16_swap_b32_e32 v64, v65
	s_waitcnt lgkmcnt(0)
	s_nop 0
	v_mov_b32_e32 v53, v131
	v_mov_b32_e32 v66, v193
	s_nop 1
	v_permlane16_swap_b32_e32 v53, v66
	v_cvt_pk_bf16_f32 v52, v55, v62
	v_cvt_pk_bf16_f32 v53, v64, v53
	v_cvt_pk_bf16_f32 v54, v49, v63
	v_cvt_pk_bf16_f32 v55, v65, v66
	global_store_dwordx4 v[60:61], v[52:55], off offset:64
	s_nop 0
	s_nop 0
	v_or_b32_e32 v52, 48, v48
	v_ashrrev_i32_e32 v53, 31, v52
	v_lshlrev_b64 v[52:53], 11, v[52:53]
	v_lshl_add_u64 v[60:61], v[50:51], 0, v[52:53]
	s_nop 0
	s_nop 0
	s_nop 0
	s_nop 0
	s_nop 0
	s_nop 0
	s_waitcnt lgkmcnt(0)
	s_nop 0
	v_mov_b32_e32 v55, v120
	v_mov_b32_e32 v49, v108
	s_nop 1
	v_permlane16_swap_b32_e32 v55, v49
	s_waitcnt lgkmcnt(0)
	s_nop 0
	v_mov_b32_e32 v62, v121
	v_mov_b32_e32 v63, v109
	s_nop 1
	v_permlane16_swap_b32_e32 v62, v63
	s_waitcnt lgkmcnt(0)
	s_nop 0
	v_mov_b32_e32 v64, v122
	v_mov_b32_e32 v65, v110
	s_nop 1
	v_permlane16_swap_b32_e32 v64, v65
	s_waitcnt lgkmcnt(0)
	s_nop 0
	v_mov_b32_e32 v53, v123
	v_mov_b32_e32 v66, v111
	s_nop 1
	v_permlane16_swap_b32_e32 v53, v66
	v_cvt_pk_bf16_f32 v52, v55, v62
	v_cvt_pk_bf16_f32 v53, v64, v53
	v_cvt_pk_bf16_f32 v54, v49, v63
	v_cvt_pk_bf16_f32 v55, v65, v66
	global_store_dwordx4 v[60:61], v[52:55], off
	s_nop 0
	s_nop 0
	s_nop 0
	s_nop 0
	s_nop 0
	s_nop 0
	s_nop 0
	s_nop 0
	s_waitcnt lgkmcnt(0)
	s_nop 0
	v_mov_b32_e32 v55, v100
	v_mov_b32_e32 v49, v80
	s_nop 1
	v_permlane16_swap_b32_e32 v55, v49
	s_waitcnt lgkmcnt(0)
	s_nop 0
	v_mov_b32_e32 v62, v101
	v_mov_b32_e32 v63, v81
	s_nop 1
	v_permlane16_swap_b32_e32 v62, v63
	s_waitcnt lgkmcnt(0)
	s_nop 0
	v_mov_b32_e32 v64, v102
	v_mov_b32_e32 v65, v82
	s_nop 1
	v_permlane16_swap_b32_e32 v64, v65
	s_waitcnt lgkmcnt(0)
	s_nop 0
	v_mov_b32_e32 v53, v103
	v_mov_b32_e32 v66, v83
	s_nop 1
	v_permlane16_swap_b32_e32 v53, v66
	v_mfma_f32_16x16x32_bf16 v[92:95], v[140:143], v[88:91], v[92:95]
	v_cvt_pk_bf16_f32 v52, v55, v62
	v_cvt_pk_bf16_f32 v53, v64, v53
	v_cvt_pk_bf16_f32 v54, v49, v63
	v_mfma_f32_16x16x32_bf16 v[84:87], v[144:147], v[88:91], v[84:87]
	v_cvt_pk_bf16_f32 v55, v65, v66
	global_store_dwordx4 v[60:61], v[52:55], off offset:64
	v_mfma_f32_16x16x32_bf16 v[76:79], v[160:163], v[88:91], v[76:79]
	s_nop 0
	v_or_b32_e32 v52, 64, v48
	v_ashrrev_i32_e32 v53, 31, v52
	v_lshlrev_b64 v[52:53], 11, v[52:53]
	v_lshl_add_u64 v[60:61], v[50:51], 0, v[52:53]
	s_nop 0
	s_nop 0
	s_nop 0
	s_nop 0
	s_nop 0
	s_nop 0
	s_nop 0
	s_nop 0
	v_mfma_f32_16x16x32_bf16 v[56:59], v[178:181], v[88:91], v[56:59]
	s_waitcnt lgkmcnt(0)
	s_nop 0
	v_mov_b32_e32 v55, v92
	v_mov_b32_e32 v49, v84
	s_nop 1
	v_permlane16_swap_b32_e32 v55, v49
	s_waitcnt lgkmcnt(0)
	s_nop 0
	v_mov_b32_e32 v62, v93
	v_mov_b32_e32 v63, v85
	s_nop 1
	v_permlane16_swap_b32_e32 v62, v63
	s_waitcnt lgkmcnt(0)
	s_nop 0
	v_mov_b32_e32 v64, v94
	v_mov_b32_e32 v65, v86
	s_nop 1
	v_permlane16_swap_b32_e32 v64, v65
	s_waitcnt lgkmcnt(0)
	s_nop 0
	v_mov_b32_e32 v53, v95
	v_mov_b32_e32 v66, v87
	s_nop 1
	v_permlane16_swap_b32_e32 v53, v66
	v_cvt_pk_bf16_f32 v52, v55, v62
	v_cvt_pk_bf16_f32 v53, v64, v53
	v_cvt_pk_bf16_f32 v54, v49, v63
	v_cvt_pk_bf16_f32 v55, v65, v66
	global_store_dwordx4 v[60:61], v[52:55], off
	s_nop 0
	s_nop 0
	s_nop 0
	s_nop 0
	s_nop 0
	s_nop 0
	s_nop 0
	s_nop 0
	s_waitcnt lgkmcnt(0)
	s_nop 0
	v_mov_b32_e32 v55, v76
	v_mov_b32_e32 v49, v56
	s_nop 1
	v_permlane16_swap_b32_e32 v55, v49
	s_waitcnt lgkmcnt(0)
	s_nop 0
	v_mov_b32_e32 v56, v77
	s_nop 1
	v_permlane16_swap_b32_e32 v56, v57
	s_waitcnt lgkmcnt(0)
	s_nop 0
	v_mov_b32_e32 v62, v78
	s_nop 1
	v_permlane16_swap_b32_e32 v62, v58
	s_waitcnt lgkmcnt(0)
	s_nop 0
	v_mov_b32_e32 v53, v79
	s_nop 1
	v_permlane16_swap_b32_e32 v53, v59
	v_cvt_pk_bf16_f32 v52, v55, v56
	v_cvt_pk_bf16_f32 v53, v62, v53
	v_cvt_pk_bf16_f32 v54, v49, v57
	v_cvt_pk_bf16_f32 v55, v58, v59
	global_store_dwordx4 v[60:61], v[52:55], off offset:64
	s_nop 0
	s_nop 0
	s_nop 0
	s_nop 0
	s_nop 0
	s_nop 0
	s_nop 0
	s_nop 0
	v_mfma_f32_16x16x32_bf16 v[32:35], v[160:163], v[104:107], v[72:75]
	v_or_b32_e32 v52, 0x50, v48
	v_ashrrev_i32_e32 v53, 31, v52
	v_lshlrev_b64 v[52:53], 11, v[52:53]
	s_waitcnt lgkmcnt(0)
	s_nop 0
	s_nop 1
	v_permlane16_swap_b32_e32 v40, v44
	s_waitcnt lgkmcnt(0)
	s_nop 0
	s_nop 1
	v_permlane16_swap_b32_e32 v41, v45
	s_waitcnt lgkmcnt(0)
	s_nop 0
	s_nop 1
	v_permlane16_swap_b32_e32 v42, v46
	s_waitcnt lgkmcnt(0)
	s_nop 0
	s_nop 1
	v_permlane16_swap_b32_e32 v43, v47
	v_lshl_add_u64 v[52:53], v[50:51], 0, v[52:53]
	v_cvt_pk_bf16_f32 v40, v40, v41
	v_cvt_pk_bf16_f32 v41, v42, v43
	v_cvt_pk_bf16_f32 v42, v44, v45
	v_cvt_pk_bf16_f32 v43, v46, v47
	global_store_dwordx4 v[52:53], v[40:43], off
	v_mfma_f32_16x16x32_bf16 v[24:27], v[140:143], v[112:115], v[96:99]
	s_nop 0
	s_nop 0
	s_nop 0
	s_nop 0
	s_nop 0
	s_nop 0
	s_nop 0
	s_nop 0
	s_nop 0
	v_mfma_f32_16x16x32_bf16 v[28:31], v[144:147], v[112:115], v[28:31]
	s_waitcnt lgkmcnt(0)
	s_nop 0
	s_nop 1
	v_permlane16_swap_b32_e32 v32, v36
	s_waitcnt lgkmcnt(0)
	s_nop 0
	s_nop 1
	v_permlane16_swap_b32_e32 v33, v37
	s_waitcnt lgkmcnt(0)
	s_nop 0
	s_nop 1
	v_permlane16_swap_b32_e32 v34, v38
	s_waitcnt lgkmcnt(0)
	s_nop 0
	s_nop 1
	v_permlane16_swap_b32_e32 v35, v39
	v_cvt_pk_bf16_f32 v32, v32, v33
	v_cvt_pk_bf16_f32 v33, v34, v35
	v_cvt_pk_bf16_f32 v34, v36, v37
	v_cvt_pk_bf16_f32 v35, v38, v39
	global_store_dwordx4 v[52:53], v[32:35], off offset:64
	s_nop 0
	s_nop 0
	s_nop 0
	s_nop 0
	s_nop 0
	s_nop 0
	s_nop 0
	s_nop 0
	v_mfma_f32_16x16x32_bf16 v[16:19], v[160:163], v[112:115], v[124:127]
	v_or_b32_e32 v32, 0x60, v48
	v_ashrrev_i32_e32 v33, 31, v32
	v_lshlrev_b64 v[32:33], 11, v[32:33]
	v_mfma_f32_16x16x32_bf16 v[20:23], v[178:181], v[112:115], v[20:23]
	s_waitcnt lgkmcnt(0)
	s_nop 0
	s_nop 1
	v_permlane16_swap_b32_e32 v24, v28
	s_waitcnt lgkmcnt(0)
	s_nop 0
	s_nop 1
	v_permlane16_swap_b32_e32 v25, v29
	s_waitcnt lgkmcnt(0)
	s_nop 0
	s_nop 1
	v_permlane16_swap_b32_e32 v26, v30
	s_waitcnt lgkmcnt(0)
	s_nop 0
	s_nop 1
	v_permlane16_swap_b32_e32 v27, v31
	v_lshl_add_u64 v[32:33], v[50:51], 0, v[32:33]
	v_cvt_pk_bf16_f32 v24, v24, v25
	v_cvt_pk_bf16_f32 v25, v26, v27
	v_cvt_pk_bf16_f32 v26, v28, v29
	v_cvt_pk_bf16_f32 v27, v30, v31
	global_store_dwordx4 v[32:33], v[24:27], off
	v_mfma_f32_16x16x32_bf16 v[0:3], v[160:163], v[116:119], v[0:3]
	s_nop 0
	s_nop 0
	s_nop 0
	s_nop 0
	s_nop 0
	s_nop 0
	s_nop 0
	s_nop 0
	s_nop 0
	v_mfma_f32_16x16x32_bf16 v[4:7], v[178:181], v[116:119], v[68:71]
	s_waitcnt lgkmcnt(0)
	s_nop 0
	s_nop 1
	v_permlane16_swap_b32_e32 v16, v20
	s_waitcnt lgkmcnt(0)
	s_nop 0
	s_nop 1
	v_permlane16_swap_b32_e32 v17, v21
	s_waitcnt lgkmcnt(0)
	s_nop 0
	s_nop 1
	v_permlane16_swap_b32_e32 v18, v22
	s_waitcnt lgkmcnt(0)
	s_nop 0
	s_nop 1
	v_permlane16_swap_b32_e32 v19, v23
	v_cvt_pk_bf16_f32 v16, v16, v17
	v_cvt_pk_bf16_f32 v17, v18, v19
	v_cvt_pk_bf16_f32 v18, v20, v21
	v_cvt_pk_bf16_f32 v19, v22, v23
	global_store_dwordx4 v[32:33], v[16:19], off offset:64
	s_nop 0
	s_nop 0
	s_nop 0
	s_nop 0
	s_nop 0
	s_nop 0
	s_nop 0
	s_nop 0
	v_or_b32_e32 v16, 0x70, v48
	v_ashrrev_i32_e32 v17, 31, v16
	v_lshlrev_b64 v[16:17], 11, v[16:17]
	s_waitcnt lgkmcnt(0)
	s_nop 0
	s_nop 1
	v_permlane16_swap_b32_e32 v8, v12
	s_waitcnt lgkmcnt(0)
	s_nop 0
	s_nop 1
	v_permlane16_swap_b32_e32 v9, v13
	s_waitcnt lgkmcnt(0)
	s_nop 0
	s_nop 1
	v_permlane16_swap_b32_e32 v10, v14
	s_waitcnt lgkmcnt(0)
	s_nop 0
	s_nop 1
	v_permlane16_swap_b32_e32 v11, v15
	v_lshl_add_u64 v[16:17], v[50:51], 0, v[16:17]
	v_cvt_pk_bf16_f32 v8, v8, v9
	v_cvt_pk_bf16_f32 v9, v10, v11
	v_cvt_pk_bf16_f32 v10, v12, v13
	v_cvt_pk_bf16_f32 v11, v14, v15
	global_store_dwordx4 v[16:17], v[8:11], off
	s_nop 1
	s_nop 0
	s_nop 0
	s_nop 0
	s_nop 0
	s_nop 0
	s_nop 0
	s_nop 0
	s_nop 0
	s_waitcnt lgkmcnt(0)
	s_nop 0
	s_nop 1
	v_permlane16_swap_b32_e32 v0, v4
	s_waitcnt lgkmcnt(0)
	s_nop 0
	s_nop 1
	v_permlane16_swap_b32_e32 v1, v5
	s_waitcnt lgkmcnt(0)
	s_nop 0
	s_nop 1
	v_permlane16_swap_b32_e32 v2, v6
	s_waitcnt lgkmcnt(0)
	s_nop 0
	s_nop 1
	v_permlane16_swap_b32_e32 v3, v7
	v_cvt_pk_bf16_f32 v0, v0, v1
	v_cvt_pk_bf16_f32 v1, v2, v3
	v_cvt_pk_bf16_f32 v2, v4, v5
	v_cvt_pk_bf16_f32 v3, v6, v7
	global_store_dwordx4 v[16:17], v[0:3], off offset:64
	s_load_dword s8, s[8:9], 0x0
	s_waitcnt lgkmcnt(0)
	s_add_i32 s10, s8, s10
	s_cmpk_gt_i32 s10, 0xff
	s_cbranch_scc0 .LBB0_146

.LBB0_398:
	s_andn2_b64 vcc, exec, s[0:1]
	s_cbranch_vccnz .LBB0_418
	s_add_i32 s0, s7, 0xfffffdc0
	s_and_b32 s1, s7, 7
	s_lshr_b32 s0, s0, 3
	s_mul_i32 s1, s1, 48
	s_add_i32 s1, s1, s0
	s_and_b32 s0, s1, 0xffff
	s_mul_i32 s0, s0, 0xaaab
	s_lshr_b32 s8, s0, 20
	s_mul_i32 s9, s8, 0xffffffe8
	s_add_i32 s1, s9, s1
	s_mul_i32 s9, s1, 0x2aab
	s_lshr_b32 s30, s9, 31
	s_lshr_b32 s9, s9, 16
	s_lshr_b32 s0, s0, 21
	s_add_i32 s9, s9, s30
	s_sext_i32_i16 s9, s9
	s_lshl_b32 s30, s0, 1
	s_add_i32 s30, s30, s9
	s_lshl_b32 s0, s0, 10
	s_lshl_b32 s9, s9, 8
	v_mov_b32_e32 v8, v188
	s_sub_i32 s8, s8, s30
	s_add_i32 s9, s9, s0
	s_mul_i32 s8, s8, 6
	v_ashrrev_i32_e32 v9, 3, v8
	v_add_u32_e32 v4, s9, v9
	s_movk_i32 s30, 0x300
	s_add_i32 s8, s8, s1
	v_mad_i64_i32 v[0:1], s[0:1], v4, s30, 0
	v_readlane_b32 s0, v255, 49
	v_readlane_b32 s1, v255, 50
	s_lshl_b32 s8, s8, 7
	v_add_u32_e32 v10, s8, v9
	v_mov_b64_e32 v[2:3], s[0:1]
	v_mad_i64_i32 v[2:3], s[0:1], v4, s30, v[2:3]
	v_lshlrev_b32_e32 v4, 4, v8
	v_and_b32_e32 v176, 0x70, v4
	v_mad_i64_i32 v[4:5], s[0:1], v10, s30, 0
	v_readlane_b32 s0, v255, 51
	v_readlane_b32 s1, v255, 52
	v_lshl_add_u64 v[2:3], v[2:3], 0, v[176:177]
	v_lshlrev_b32_e32 v12, 7, v8
	v_mov_b64_e32 v[6:7], s[0:1]
	v_mad_i64_i32 v[6:7], s[0:1], v10, s30, v[6:7]
	v_xor_b32_e32 v10, v9, v8
	v_lshlrev_b32_e32 v10, 4, v10
	v_lshl_add_u64 v[6:7], v[6:7], 0, v[176:177]
	v_and_b32_e32 v10, 0x70, v10
	v_lshl_or_b32 v176, v9, 7, v10
	v_lshrrev_b32_e32 v9, 4, v8
	v_bfe_u32 v14, v8, 4, 2
	v_and_b32_e32 v15, 7, v8
	v_add_co_u32_e32 v8, vcc, s77, v6
	v_bitop3_b32 v16, v9, v15, 3 bitop3:0x6c
	s_nop 0
	v_addc_co_u32_e32 v9, vcc, 0, v7, vcc
	v_add_co_u32_e32 v10, vcc, s28, v6
	s_mov_b32 s0, 0x2a000
	s_nop 0
	v_addc_co_u32_e32 v11, vcc, 0, v7, vcc
	global_load_dwordx4 v[68:71], v[8:9], off
	global_load_dwordx4 v[72:75], v[10:11], off
	v_add_co_u32_e32 v8, vcc, s54, v6
	v_and_b32_e32 v13, 0xffffc780, v12
	s_nop 0
	v_addc_co_u32_e32 v9, vcc, 0, v7, vcc
	v_add_co_u32_e32 v10, vcc, s0, v2
	s_mov_b32 s0, 0x24000
	s_nop 0
	v_addc_co_u32_e32 v11, vcc, 0, v3, vcc
	global_load_dwordx4 v[88:91], v[8:9], off
	global_load_dwordx4 v[96:99], v[10:11], off
	v_add_co_u32_e32 v8, vcc, s0, v2
	s_mov_b32 s0, 0x1e000
	s_nop 0
	v_addc_co_u32_e32 v9, vcc, 0, v3, vcc
	v_add_co_u32_e32 v10, vcc, s0, v2
	s_mov_b32 s0, 0x18000
	s_nop 0
	v_addc_co_u32_e32 v11, vcc, 0, v3, vcc
	global_load_dwordx4 v[108:111], v[8:9], off
	global_load_dwordx4 v[120:123], v[10:11], off
	v_add_co_u32_e32 v8, vcc, s0, v2
	v_and_b32_e32 v12, 0x2780, v12
	s_nop 0
	v_addc_co_u32_e32 v9, vcc, 0, v3, vcc
	v_add_co_u32_e32 v10, vcc, s77, v2
	v_bitop3_b32 v14, v14, v15, 4 bitop3:0x36
	s_nop 0
	v_addc_co_u32_e32 v11, vcc, 0, v3, vcc
	global_load_dwordx4 v[132:135], v[8:9], off
	global_load_dwordx4 v[136:139], v[10:11], off
	v_add_co_u32_e32 v8, vcc, s28, v2
	v_mov_b32_e32 v112, 0
	s_nop 0
	v_addc_co_u32_e32 v9, vcc, 0, v3, vcc
	v_add_co_u32_e32 v10, vcc, s54, v2
	s_mov_b64 s[0:1], 0
	s_nop 0
	v_addc_co_u32_e32 v11, vcc, 0, v3, vcc
	global_load_dwordx4 v[152:155], v[8:9], off
	global_load_dwordx4 v[160:163], v[10:11], off
	global_load_dwordx4 v[148:151], v[6:7], off
	global_load_dwordx4 v[168:171], v[2:3], off
	v_lshlrev_b32_e32 v2, 4, v16
	v_or_b32_e32 v185, v13, v2
	v_or_b32_e32 v184, v12, v2
	v_lshlrev_b32_e32 v2, 4, v14
	v_or_b32_e32 v183, v13, v2
	v_or_b32_e32 v182, v12, v2
	v_lshlrev_b32_e32 v2, 4, v15
	v_or_b32_e32 v0, v0, v2
	v_or_b32_e32 v4, v4, v2
	v_lshl_add_u64 v[178:179], s[34:35], 0, v[0:1]
	v_lshl_add_u64 v[180:181], s[84:85], 0, v[4:5]
	v_mov_b32_e32 v113, v112
	v_mov_b32_e32 v114, v112
	v_mov_b32_e32 v115, v112
	v_mov_b32_e32 v0, v112
	v_mov_b32_e32 v1, v112
	v_mov_b32_e32 v2, v112
	v_mov_b32_e32 v3, v112
	v_mov_b32_e32 v4, v112
	v_mov_b32_e32 v5, v112
	v_mov_b32_e32 v6, v112
	v_mov_b32_e32 v7, v112
	v_mov_b32_e32 v8, v112
	v_mov_b32_e32 v9, v112
	v_mov_b32_e32 v10, v112
	v_mov_b32_e32 v11, v112
	v_mov_b32_e32 v12, v112
	v_mov_b32_e32 v13, v112
	v_mov_b32_e32 v14, v112
	v_mov_b32_e32 v15, v112
	v_mov_b32_e32 v16, v112
	v_mov_b32_e32 v17, v112
	v_mov_b32_e32 v18, v112
	v_mov_b32_e32 v19, v112
	v_mov_b32_e32 v20, v112
	v_mov_b32_e32 v21, v112
	v_mov_b32_e32 v22, v112
	v_mov_b32_e32 v23, v112
	v_mov_b32_e32 v24, v112
	v_mov_b32_e32 v25, v112
	v_mov_b32_e32 v26, v112
	v_mov_b32_e32 v27, v112
	v_mov_b32_e32 v28, v112
	v_mov_b32_e32 v29, v112
	v_mov_b32_e32 v30, v112
	v_mov_b32_e32 v31, v112
	v_mov_b32_e32 v32, v112
	v_mov_b32_e32 v33, v112
	v_mov_b32_e32 v34, v112
	v_mov_b32_e32 v35, v112
	v_mov_b32_e32 v36, v112
	v_mov_b32_e32 v37, v112
	v_mov_b32_e32 v38, v112
	v_mov_b32_e32 v39, v112
	v_mov_b32_e32 v40, v112
	v_mov_b32_e32 v41, v112
	v_mov_b32_e32 v42, v112
	v_mov_b32_e32 v43, v112
	v_mov_b32_e32 v44, v112
	v_mov_b32_e32 v45, v112
	v_mov_b32_e32 v46, v112
	v_mov_b32_e32 v47, v112
	v_mov_b32_e32 v48, v112
	v_mov_b32_e32 v49, v112
	v_mov_b32_e32 v50, v112
	v_mov_b32_e32 v51, v112
	v_mov_b32_e32 v52, v112
	v_mov_b32_e32 v53, v112
	v_mov_b32_e32 v54, v112
	v_mov_b32_e32 v55, v112
	v_mov_b32_e32 v56, v112
	v_mov_b32_e32 v57, v112
	v_mov_b32_e32 v58, v112
	v_mov_b32_e32 v59, v112
	v_mov_b32_e32 v60, v112
	v_mov_b32_e32 v61, v112
	v_mov_b32_e32 v62, v112
	v_mov_b32_e32 v63, v112
	v_mov_b32_e32 v64, v112
	v_mov_b32_e32 v65, v112
	v_mov_b32_e32 v66, v112
	v_mov_b32_e32 v67, v112
	v_mov_b32_e32 v76, v112
	v_mov_b32_e32 v77, v112
	v_mov_b32_e32 v78, v112
	v_mov_b32_e32 v79, v112
	v_mov_b32_e32 v80, v112
	v_mov_b32_e32 v81, v112
	v_mov_b32_e32 v82, v112
	v_mov_b32_e32 v83, v112
	v_mov_b32_e32 v84, v112
	v_mov_b32_e32 v85, v112
	v_mov_b32_e32 v86, v112
	v_mov_b32_e32 v87, v112
	v_mov_b32_e32 v92, v112
	v_mov_b32_e32 v93, v112
	v_mov_b32_e32 v94, v112
	v_mov_b32_e32 v95, v112
	v_mov_b32_e32 v100, v112
	v_mov_b32_e32 v101, v112
	v_mov_b32_e32 v102, v112
	v_mov_b32_e32 v103, v112
	v_mov_b32_e32 v104, v112
	v_mov_b32_e32 v105, v112
	v_mov_b32_e32 v106, v112
	v_mov_b32_e32 v107, v112
	v_mov_b32_e32 v116, v112
	v_mov_b32_e32 v117, v112
	v_mov_b32_e32 v118, v112
	v_mov_b32_e32 v119, v112
	v_mov_b32_e32 v124, v112
	v_mov_b32_e32 v125, v112
	v_mov_b32_e32 v126, v112
	v_mov_b32_e32 v127, v112
	v_mov_b32_e32 v128, v112
	v_mov_b32_e32 v129, v112
	v_mov_b32_e32 v130, v112
	v_mov_b32_e32 v131, v112
	v_mov_b32_e32 v140, v112
	v_mov_b32_e32 v141, v112
	v_mov_b32_e32 v142, v112
	v_mov_b32_e32 v143, v112
	v_mov_b32_e32 v144, v112
	v_mov_b32_e32 v145, v112
	v_mov_b32_e32 v146, v112
	v_mov_b32_e32 v147, v112
	v_mov_b32_e32 v156, v112
	v_mov_b32_e32 v157, v112
	v_mov_b32_e32 v158, v112
	v_mov_b32_e32 v159, v112
	v_mov_b32_e32 v164, v112
	v_mov_b32_e32 v165, v112
	v_mov_b32_e32 v166, v112
	v_mov_b32_e32 v167, v112
	v_mov_b32_e32 v172, v112
	v_mov_b32_e32 v173, v112
	v_mov_b32_e32 v174, v112
	v_mov_b32_e32 v175, v112
	s_setprio 2
	v_readlane_b32 s98, v253, 3
	v_readlane_b32 s99, v253, 4
	v_and_b32_e32 v224, 15, v188
	v_bfe_u32 v225, v188, 4, 2
	v_lshrrev_b32_e32 v226, 2, v224
	v_sub_u32_e32 v226, 0, v226
	v_and_b32_e32 v226, 3, v226
	v_xor_b32_e32 v225, v225, v226
	v_lshlrev_b32_e32 v225, 4, v225
	v_lshl_or_b32 v225, v224, 6, v225
	v_bfe_u32 v226, v188, 7, 1
	v_lshl_or_b32 v185, v226, 13, v225
	v_bfe_u32 v226, v188, 6, 1
	v_lshl_or_b32 v184, v226, 12, v225
	v_add_u32_e32 v184, 0x4000, v184
	v_lshrrev_b32_e32 v224, 3, v188
	v_bfe_u32 v225, v188, 2, 1
	v_lshrrev_b32_e32 v226, 2, v224
	v_sub_u32_e32 v226, 0, v226
	v_and_b32_e32 v226, 3, v226
	v_and_b32_e32 v227, 3, v188
	v_xor_b32_e32 v226, v227, v226
	v_lshlrev_b32_e32 v226, 4, v226
	v_xor_b32_e32 v224, v224, v225
	v_lshl_or_b32 v226, v224, 6, v226
	v_mul_u32_u24_e32 v225, 0x6000, v225
	v_add_u32_e32 v183, v225, v226
	s_mov_b32 m0, 0
	s_sub_u32 vcc_lo, s0, s98
	v_add_u32_e32 v186, vcc_lo, v178
	v_add_u32_e32 v187, vcc_lo, v180
	s_barrier
	s_waitcnt vmcnt(0)
	ds_write_b128 v183, v[168:171]
	ds_write_b128 v183, v[160:163] offset:2048
	ds_write_b128 v183, v[152:155] offset:4096
	ds_write_b128 v183, v[136:139] offset:6144
	ds_write_b128 v183, v[132:135] offset:8192
	ds_write_b128 v183, v[120:123] offset:10240
	ds_write_b128 v183, v[108:111] offset:12288
	ds_write_b128 v183, v[96:99] offset:14336
	ds_write_b128 v183, v[148:151] offset:16384
	ds_write_b128 v183, v[88:91] offset:18432
	ds_write_b128 v183, v[72:75] offset:20480
	ds_write_b128 v183, v[68:71] offset:22528
	v_cmp_gt_u32_e32 vcc, 0x6000, v183
	v_add_u32_e32 v182, 0xc000, v183
	v_add_u32_e32 v183, 0xffffa000, v183
	s_nop 0
	v_cndmask_b32_e32 v183, v183, v182, vcc
	v_add_u32_e32 v168, 0xa700000, v186
	global_load_dwordx4 v[168:171], v168, s[98:99] offset:128
	v_add_u32_e32 v160, 0xa706000, v186
	global_load_dwordx4 v[160:163], v160, s[98:99] offset:128
	v_add_u32_e32 v152, 0xa70c000, v186
	global_load_dwordx4 v[152:155], v152, s[98:99] offset:128
	v_add_u32_e32 v136, 0xa712000, v186
	global_load_dwordx4 v[136:139], v136, s[98:99] offset:128
	v_add_u32_e32 v132, 0xa718000, v186
	global_load_dwordx4 v[132:135], v132, s[98:99] offset:128
	v_add_u32_e32 v120, 0xa71e000, v186
	global_load_dwordx4 v[120:123], v120, s[98:99] offset:128
	v_add_u32_e32 v108, 0xa724000, v186
	global_load_dwordx4 v[108:111], v108, s[98:99] offset:128
	v_add_u32_e32 v96, 0xa72a000, v186
	global_load_dwordx4 v[96:99], v96, s[98:99] offset:128
	v_add_u32_e32 v148, 0x1f00000, v187
	global_load_dwordx4 v[148:151], v148, s[98:99] offset:128
	v_add_u32_e32 v88, 0x1f06000, v187
	global_load_dwordx4 v[88:91], v88, s[98:99] offset:128
	v_add_u32_e32 v72, 0x1f0c000, v187
	global_load_dwordx4 v[72:75], v72, s[98:99] offset:128
	v_add_u32_e32 v68, 0x1f12000, v187
	global_load_dwordx4 v[68:71], v68, s[98:99] offset:128
	s_add_u32 s0, s0, 0x80
	s_addc_u32 s1, s1, 0
.LBB0_400:
	s_waitcnt lgkmcnt(0)
	s_barrier
	ds_read_b128 v[224:227], v184
	ds_read_b128 v[228:231], v184 offset:1024
	ds_read_b128 v[232:235], v184 offset:2048
	ds_read_b128 v[236:239], v184 offset:3072
	ds_read_b128 v[190:193], v185
	ds_read_b128 v[194:197], v185 offset:1024
	ds_read_b128 v[198:201], v185 offset:2048
	ds_read_b128 v[204:207], v185 offset:3072
	ds_read_b128 v[208:211], v185 offset:4096
	ds_read_b128 v[212:215], v185 offset:5120
	ds_read_b128 v[216:219], v185 offset:6144
	ds_read_b128 v[220:223], v185 offset:7168
	s_movk_i32 vcc_lo, 0x6000
	s_cmp_eq_u32 m0, 2
	s_cselect_b32 vcc_lo, 0xffff4000, vcc_lo
	s_add_u32 m0, m0, 1
	s_cmp_eq_u32 m0, 3
	s_cselect_b32 m0, 0, m0
	v_add_u32_e32 v185, vcc_lo, v185
	v_add_u32_e32 v184, vcc_lo, v184
	v_xor_b32_e32 v185, 64, v185
	v_xor_b32_e32 v184, 64, v184
	s_waitcnt lgkmcnt(7)
	v_mfma_f32_16x16x32_bf16 v[172:175], v[224:227], v[190:193], v[172:175]
	v_mfma_f32_16x16x32_bf16 v[164:167], v[228:231], v[190:193], v[164:167]
	v_mfma_f32_16x16x32_bf16 v[156:159], v[232:235], v[190:193], v[156:159]
	v_mfma_f32_16x16x32_bf16 v[144:147], v[236:239], v[190:193], v[144:147]
	ds_read_b128 v[190:193], v185
	s_waitcnt lgkmcnt(7)
	v_mfma_f32_16x16x32_bf16 v[140:143], v[224:227], v[194:197], v[140:143]
	v_mfma_f32_16x16x32_bf16 v[128:131], v[228:231], v[194:197], v[128:131]
	v_mfma_f32_16x16x32_bf16 v[124:127], v[232:235], v[194:197], v[124:127]
	v_mfma_f32_16x16x32_bf16 v[116:119], v[236:239], v[194:197], v[116:119]
	ds_read_b128 v[194:197], v185 offset:1024
	s_waitcnt lgkmcnt(7)
	v_mfma_f32_16x16x32_bf16 v[104:107], v[224:227], v[198:201], v[104:107]
	v_mfma_f32_16x16x32_bf16 v[100:103], v[228:231], v[198:201], v[100:103]
	v_mfma_f32_16x16x32_bf16 v[92:95], v[232:235], v[198:201], v[92:95]
	v_mfma_f32_16x16x32_bf16 v[84:87], v[236:239], v[198:201], v[84:87]
	ds_read_b128 v[198:201], v185 offset:2048
	s_waitcnt lgkmcnt(7)
	v_mfma_f32_16x16x32_bf16 v[80:83], v[224:227], v[204:207], v[80:83]
	v_mfma_f32_16x16x32_bf16 v[76:79], v[228:231], v[204:207], v[76:79]
	v_mfma_f32_16x16x32_bf16 v[64:67], v[232:235], v[204:207], v[64:67]
	v_mfma_f32_16x16x32_bf16 v[60:63], v[236:239], v[204:207], v[60:63]
	ds_read_b128 v[204:207], v185 offset:3072
	s_waitcnt lgkmcnt(7)
	v_mfma_f32_16x16x32_bf16 v[56:59], v[224:227], v[208:211], v[56:59]
	v_mfma_f32_16x16x32_bf16 v[52:55], v[228:231], v[208:211], v[52:55]
	v_mfma_f32_16x16x32_bf16 v[48:51], v[232:235], v[208:211], v[48:51]
	v_mfma_f32_16x16x32_bf16 v[44:47], v[236:239], v[208:211], v[44:47]
	ds_read_b128 v[208:211], v185 offset:4096
	s_waitcnt lgkmcnt(7)
	v_mfma_f32_16x16x32_bf16 v[40:43], v[224:227], v[212:215], v[40:43]
	v_mfma_f32_16x16x32_bf16 v[36:39], v[228:231], v[212:215], v[36:39]
	v_mfma_f32_16x16x32_bf16 v[32:35], v[232:235], v[212:215], v[32:35]
	v_mfma_f32_16x16x32_bf16 v[28:31], v[236:239], v[212:215], v[28:31]
	ds_read_b128 v[212:215], v185 offset:5120
	s_waitcnt lgkmcnt(7)
	v_mfma_f32_16x16x32_bf16 v[24:27], v[224:227], v[216:219], v[24:27]
	v_mfma_f32_16x16x32_bf16 v[20:23], v[228:231], v[216:219], v[20:23]
	v_mfma_f32_16x16x32_bf16 v[16:19], v[232:235], v[216:219], v[16:19]
	v_mfma_f32_16x16x32_bf16 v[12:15], v[236:239], v[216:219], v[12:15]
	ds_read_b128 v[216:219], v185 offset:6144
	s_waitcnt lgkmcnt(7)
	v_mfma_f32_16x16x32_bf16 v[8:11], v[224:227], v[220:223], v[8:11]
	v_mfma_f32_16x16x32_bf16 v[4:7], v[228:231], v[220:223], v[4:7]
	v_mfma_f32_16x16x32_bf16 v[0:3], v[232:235], v[220:223], v[0:3]
	v_mfma_f32_16x16x32_bf16 v[112:115], v[236:239], v[220:223], v[112:115]
	ds_read_b128 v[220:223], v185 offset:7168
	ds_read_b128 v[224:227], v184
	ds_read_b128 v[228:231], v184 offset:1024
	ds_read_b128 v[232:235], v184 offset:2048
	ds_read_b128 v[236:239], v184 offset:3072
	s_movk_i32 vcc_lo, 0x6000
	s_cmp_eq_u32 m0, 2
	s_cselect_b32 vcc_lo, 0xffff4000, vcc_lo
	s_add_u32 m0, m0, 1
	s_cmp_eq_u32 m0, 3
	s_cselect_b32 m0, 0, m0
	v_add_u32_e32 v185, vcc_lo, v185
	v_add_u32_e32 v184, vcc_lo, v184
	v_xor_b32_e32 v185, 64, v185
	v_xor_b32_e32 v184, 64, v184
	s_sub_u32 vcc_lo, s0, s98
	v_add_u32_e32 v186, vcc_lo, v178
	v_add_u32_e32 v187, vcc_lo, v180
	s_barrier
	s_waitcnt lgkmcnt(0)
	v_mfma_f32_16x16x32_bf16 v[172:175], v[224:227], v[190:193], v[172:175]
	s_waitcnt vmcnt(11)
	v_mfma_f32_16x16x32_bf16 v[164:167], v[228:231], v[190:193], v[164:167]
	ds_write_b128 v183, v[168:171]
	v_add_u32_e32 v168, 0xa700000, v186
	v_mfma_f32_16x16x32_bf16 v[156:159], v[232:235], v[190:193], v[156:159]
	global_load_dwordx4 v[168:171], v168, s[98:99] offset:128
	v_mfma_f32_16x16x32_bf16 v[144:147], v[236:239], v[190:193], v[144:147]
	s_waitcnt vmcnt(11)
	ds_write_b128 v183, v[160:163] offset:2048
	v_mfma_f32_16x16x32_bf16 v[140:143], v[224:227], v[194:197], v[140:143]
	v_add_u32_e32 v160, 0xa706000, v186
	v_mfma_f32_16x16x32_bf16 v[128:131], v[228:231], v[194:197], v[128:131]
	global_load_dwordx4 v[160:163], v160, s[98:99] offset:128
	s_waitcnt vmcnt(11)
	v_mfma_f32_16x16x32_bf16 v[124:127], v[232:235], v[194:197], v[124:127]
	ds_write_b128 v183, v[152:155] offset:4096
	v_mfma_f32_16x16x32_bf16 v[116:119], v[236:239], v[194:197], v[116:119]
	v_add_u32_e32 v152, 0xa70c000, v186
	global_load_dwordx4 v[152:155], v152, s[98:99] offset:128
	v_mfma_f32_16x16x32_bf16 v[104:107], v[224:227], v[198:201], v[104:107]
	s_waitcnt vmcnt(11)
	v_mfma_f32_16x16x32_bf16 v[100:103], v[228:231], v[198:201], v[100:103]
	ds_write_b128 v183, v[136:139] offset:6144
	v_add_u32_e32 v136, 0xa712000, v186
	v_mfma_f32_16x16x32_bf16 v[92:95], v[232:235], v[198:201], v[92:95]
	global_load_dwordx4 v[136:139], v136, s[98:99] offset:128
	v_mfma_f32_16x16x32_bf16 v[84:87], v[236:239], v[198:201], v[84:87]
	s_waitcnt vmcnt(11)
	ds_write_b128 v183, v[132:135] offset:8192
	v_mfma_f32_16x16x32_bf16 v[80:83], v[224:227], v[204:207], v[80:83]
	v_add_u32_e32 v132, 0xa718000, v186
	v_mfma_f32_16x16x32_bf16 v[76:79], v[228:231], v[204:207], v[76:79]
	global_load_dwordx4 v[132:135], v132, s[98:99] offset:128
	s_waitcnt vmcnt(11)
	v_mfma_f32_16x16x32_bf16 v[64:67], v[232:235], v[204:207], v[64:67]
	ds_write_b128 v183, v[120:123] offset:10240
	v_mfma_f32_16x16x32_bf16 v[60:63], v[236:239], v[204:207], v[60:63]
	v_add_u32_e32 v120, 0xa71e000, v186
	global_load_dwordx4 v[120:123], v120, s[98:99] offset:128
	v_mfma_f32_16x16x32_bf16 v[56:59], v[224:227], v[208:211], v[56:59]
	s_waitcnt vmcnt(11)
	v_mfma_f32_16x16x32_bf16 v[52:55], v[228:231], v[208:211], v[52:55]
	ds_write_b128 v183, v[108:111] offset:12288
	v_add_u32_e32 v108, 0xa724000, v186
	v_mfma_f32_16x16x32_bf16 v[48:51], v[232:235], v[208:211], v[48:51]
	global_load_dwordx4 v[108:111], v108, s[98:99] offset:128
	v_mfma_f32_16x16x32_bf16 v[44:47], v[236:239], v[208:211], v[44:47]
	s_waitcnt vmcnt(11)
	ds_write_b128 v183, v[96:99] offset:14336
	v_mfma_f32_16x16x32_bf16 v[40:43], v[224:227], v[212:215], v[40:43]
	v_add_u32_e32 v96, 0xa72a000, v186
	v_mfma_f32_16x16x32_bf16 v[36:39], v[228:231], v[212:215], v[36:39]
	global_load_dwordx4 v[96:99], v96, s[98:99] offset:128
	s_waitcnt vmcnt(11)
	v_mfma_f32_16x16x32_bf16 v[32:35], v[232:235], v[212:215], v[32:35]
	ds_write_b128 v183, v[148:151] offset:16384
	v_mfma_f32_16x16x32_bf16 v[28:31], v[236:239], v[212:215], v[28:31]
	v_add_u32_e32 v148, 0x1f00000, v187
	global_load_dwordx4 v[148:151], v148, s[98:99] offset:128
	v_mfma_f32_16x16x32_bf16 v[24:27], v[224:227], v[216:219], v[24:27]
	s_waitcnt vmcnt(11)
	v_mfma_f32_16x16x32_bf16 v[20:23], v[228:231], v[216:219], v[20:23]
	ds_write_b128 v183, v[88:91] offset:18432
	v_add_u32_e32 v88, 0x1f06000, v187
	v_mfma_f32_16x16x32_bf16 v[16:19], v[232:235], v[216:219], v[16:19]
	global_load_dwordx4 v[88:91], v88, s[98:99] offset:128
	v_mfma_f32_16x16x32_bf16 v[12:15], v[236:239], v[216:219], v[12:15]
	s_waitcnt vmcnt(11)
	ds_write_b128 v183, v[72:75] offset:20480
	v_mfma_f32_16x16x32_bf16 v[8:11], v[224:227], v[220:223], v[8:11]
	v_add_u32_e32 v72, 0x1f0c000, v187
	v_mfma_f32_16x16x32_bf16 v[4:7], v[228:231], v[220:223], v[4:7]
	global_load_dwordx4 v[72:75], v72, s[98:99] offset:128
	s_waitcnt vmcnt(11)
	v_mfma_f32_16x16x32_bf16 v[0:3], v[232:235], v[220:223], v[0:3]
	ds_write_b128 v183, v[68:71] offset:22528
	v_mfma_f32_16x16x32_bf16 v[112:115], v[236:239], v[220:223], v[112:115]
	v_add_u32_e32 v68, 0x1f12000, v187
	global_load_dwordx4 v[68:71], v68, s[98:99] offset:128
	v_cmp_gt_u32_e32 vcc, 0x6000, v183
	v_add_u32_e32 v182, 0xc000, v183
	v_add_u32_e32 v183, 0xffffa000, v183
	s_nop 0
	v_cndmask_b32_e32 v183, v183, v182, vcc
	s_add_u32 s0, s0, 0x80
	s_addc_u32 s1, s1, 0
	s_cmpk_lg_i32 s0, 0x280
	s_cbranch_scc1 .LBB0_400
	s_waitcnt lgkmcnt(0)
	s_barrier
	ds_read_b128 v[224:227], v184
	ds_read_b128 v[228:231], v184 offset:1024
	ds_read_b128 v[232:235], v184 offset:2048
	ds_read_b128 v[236:239], v184 offset:3072
	ds_read_b128 v[190:193], v185
	ds_read_b128 v[194:197], v185 offset:1024
	ds_read_b128 v[198:201], v185 offset:2048
	ds_read_b128 v[204:207], v185 offset:3072
	ds_read_b128 v[208:211], v185 offset:4096
	ds_read_b128 v[212:215], v185 offset:5120
	ds_read_b128 v[216:219], v185 offset:6144
	ds_read_b128 v[220:223], v185 offset:7168
	s_movk_i32 vcc_lo, 0x6000
	s_cmp_eq_u32 m0, 2
	s_cselect_b32 vcc_lo, 0xffff4000, vcc_lo
	s_add_u32 m0, m0, 1
	s_cmp_eq_u32 m0, 3
	s_cselect_b32 m0, 0, m0
	v_add_u32_e32 v185, vcc_lo, v185
	v_add_u32_e32 v184, vcc_lo, v184
	v_xor_b32_e32 v185, 64, v185
	v_xor_b32_e32 v184, 64, v184
	s_waitcnt lgkmcnt(7)
	v_mfma_f32_16x16x32_bf16 v[172:175], v[224:227], v[190:193], v[172:175]
	v_mfma_f32_16x16x32_bf16 v[164:167], v[228:231], v[190:193], v[164:167]
	v_mfma_f32_16x16x32_bf16 v[156:159], v[232:235], v[190:193], v[156:159]
	v_mfma_f32_16x16x32_bf16 v[144:147], v[236:239], v[190:193], v[144:147]
	ds_read_b128 v[190:193], v185
	s_waitcnt lgkmcnt(7)
	v_mfma_f32_16x16x32_bf16 v[140:143], v[224:227], v[194:197], v[140:143]
	v_mfma_f32_16x16x32_bf16 v[128:131], v[228:231], v[194:197], v[128:131]
	v_mfma_f32_16x16x32_bf16 v[124:127], v[232:235], v[194:197], v[124:127]
	v_mfma_f32_16x16x32_bf16 v[116:119], v[236:239], v[194:197], v[116:119]
	ds_read_b128 v[194:197], v185 offset:1024
	s_waitcnt lgkmcnt(7)
	v_mfma_f32_16x16x32_bf16 v[104:107], v[224:227], v[198:201], v[104:107]
	v_mfma_f32_16x16x32_bf16 v[100:103], v[228:231], v[198:201], v[100:103]
	v_mfma_f32_16x16x32_bf16 v[92:95], v[232:235], v[198:201], v[92:95]
	v_mfma_f32_16x16x32_bf16 v[84:87], v[236:239], v[198:201], v[84:87]
	ds_read_b128 v[198:201], v185 offset:2048
	s_waitcnt lgkmcnt(7)
	v_mfma_f32_16x16x32_bf16 v[80:83], v[224:227], v[204:207], v[80:83]
	v_mfma_f32_16x16x32_bf16 v[76:79], v[228:231], v[204:207], v[76:79]
	v_mfma_f32_16x16x32_bf16 v[64:67], v[232:235], v[204:207], v[64:67]
	v_mfma_f32_16x16x32_bf16 v[60:63], v[236:239], v[204:207], v[60:63]
	ds_read_b128 v[204:207], v185 offset:3072
	s_waitcnt lgkmcnt(7)
	v_mfma_f32_16x16x32_bf16 v[56:59], v[224:227], v[208:211], v[56:59]
	v_mfma_f32_16x16x32_bf16 v[52:55], v[228:231], v[208:211], v[52:55]
	v_mfma_f32_16x16x32_bf16 v[48:51], v[232:235], v[208:211], v[48:51]
	v_mfma_f32_16x16x32_bf16 v[44:47], v[236:239], v[208:211], v[44:47]
	ds_read_b128 v[208:211], v185 offset:4096
	s_waitcnt lgkmcnt(7)
	v_mfma_f32_16x16x32_bf16 v[40:43], v[224:227], v[212:215], v[40:43]
	v_mfma_f32_16x16x32_bf16 v[36:39], v[228:231], v[212:215], v[36:39]
	v_mfma_f32_16x16x32_bf16 v[32:35], v[232:235], v[212:215], v[32:35]
	v_mfma_f32_16x16x32_bf16 v[28:31], v[236:239], v[212:215], v[28:31]
	ds_read_b128 v[212:215], v185 offset:5120
	s_waitcnt lgkmcnt(7)
	v_mfma_f32_16x16x32_bf16 v[24:27], v[224:227], v[216:219], v[24:27]
	v_mfma_f32_16x16x32_bf16 v[20:23], v[228:231], v[216:219], v[20:23]
	v_mfma_f32_16x16x32_bf16 v[16:19], v[232:235], v[216:219], v[16:19]
	v_mfma_f32_16x16x32_bf16 v[12:15], v[236:239], v[216:219], v[12:15]
	ds_read_b128 v[216:219], v185 offset:6144
	s_waitcnt lgkmcnt(7)
	v_mfma_f32_16x16x32_bf16 v[8:11], v[224:227], v[220:223], v[8:11]
	v_mfma_f32_16x16x32_bf16 v[4:7], v[228:231], v[220:223], v[4:7]
	v_mfma_f32_16x16x32_bf16 v[0:3], v[232:235], v[220:223], v[0:3]
	v_mfma_f32_16x16x32_bf16 v[112:115], v[236:239], v[220:223], v[112:115]
	ds_read_b128 v[220:223], v185 offset:7168
	ds_read_b128 v[224:227], v184
	ds_read_b128 v[228:231], v184 offset:1024
	ds_read_b128 v[232:235], v184 offset:2048
	ds_read_b128 v[236:239], v184 offset:3072
	s_movk_i32 vcc_lo, 0x6000
	s_cmp_eq_u32 m0, 2
	s_cselect_b32 vcc_lo, 0xffff4000, vcc_lo
	s_add_u32 m0, m0, 1
	s_cmp_eq_u32 m0, 3
	s_cselect_b32 m0, 0, m0
	v_add_u32_e32 v185, vcc_lo, v185
	v_add_u32_e32 v184, vcc_lo, v184
	v_xor_b32_e32 v185, 64, v185
	v_xor_b32_e32 v184, 64, v184
	s_waitcnt lgkmcnt(0)
	v_mfma_f32_16x16x32_bf16 v[172:175], v[224:227], v[190:193], v[172:175]
	v_mfma_f32_16x16x32_bf16 v[164:167], v[228:231], v[190:193], v[164:167]
	v_mfma_f32_16x16x32_bf16 v[156:159], v[232:235], v[190:193], v[156:159]
	v_mfma_f32_16x16x32_bf16 v[144:147], v[236:239], v[190:193], v[144:147]
	v_mfma_f32_16x16x32_bf16 v[140:143], v[224:227], v[194:197], v[140:143]
	v_mfma_f32_16x16x32_bf16 v[128:131], v[228:231], v[194:197], v[128:131]
	v_mfma_f32_16x16x32_bf16 v[124:127], v[232:235], v[194:197], v[124:127]
	v_mfma_f32_16x16x32_bf16 v[116:119], v[236:239], v[194:197], v[116:119]
	v_mfma_f32_16x16x32_bf16 v[104:107], v[224:227], v[198:201], v[104:107]
	v_mfma_f32_16x16x32_bf16 v[100:103], v[228:231], v[198:201], v[100:103]
	v_mfma_f32_16x16x32_bf16 v[92:95], v[232:235], v[198:201], v[92:95]
	v_mfma_f32_16x16x32_bf16 v[84:87], v[236:239], v[198:201], v[84:87]
	v_mfma_f32_16x16x32_bf16 v[80:83], v[224:227], v[204:207], v[80:83]
	v_mfma_f32_16x16x32_bf16 v[76:79], v[228:231], v[204:207], v[76:79]
	v_mfma_f32_16x16x32_bf16 v[64:67], v[232:235], v[204:207], v[64:67]
	v_mfma_f32_16x16x32_bf16 v[60:63], v[236:239], v[204:207], v[60:63]
	v_mfma_f32_16x16x32_bf16 v[56:59], v[224:227], v[208:211], v[56:59]
	v_mfma_f32_16x16x32_bf16 v[52:55], v[228:231], v[208:211], v[52:55]
	v_mfma_f32_16x16x32_bf16 v[48:51], v[232:235], v[208:211], v[48:51]
	v_mfma_f32_16x16x32_bf16 v[44:47], v[236:239], v[208:211], v[44:47]
	v_mfma_f32_16x16x32_bf16 v[40:43], v[224:227], v[212:215], v[40:43]
	v_mfma_f32_16x16x32_bf16 v[36:39], v[228:231], v[212:215], v[36:39]
	v_mfma_f32_16x16x32_bf16 v[32:35], v[232:235], v[212:215], v[32:35]
	v_mfma_f32_16x16x32_bf16 v[28:31], v[236:239], v[212:215], v[28:31]
	v_mfma_f32_16x16x32_bf16 v[24:27], v[224:227], v[216:219], v[24:27]
	v_mfma_f32_16x16x32_bf16 v[20:23], v[228:231], v[216:219], v[20:23]
	v_mfma_f32_16x16x32_bf16 v[16:19], v[232:235], v[216:219], v[16:19]
	v_mfma_f32_16x16x32_bf16 v[12:15], v[236:239], v[216:219], v[12:15]
	v_mfma_f32_16x16x32_bf16 v[8:11], v[224:227], v[220:223], v[8:11]
	v_mfma_f32_16x16x32_bf16 v[4:7], v[228:231], v[220:223], v[4:7]
	v_mfma_f32_16x16x32_bf16 v[0:3], v[232:235], v[220:223], v[0:3]
	v_mfma_f32_16x16x32_bf16 v[112:115], v[236:239], v[220:223], v[112:115]
	v_lshrrev_b32_e32 v224, 4, v188
	v_and_b32_e32 v225, 7, v188
	v_bitop3_b32 v226, v224, v225, 3 bitop3:0x6c
	v_lshlrev_b32_e32 v227, 7, v188
	v_bfe_u32 v228, v188, 4, 2
	v_and_b32_e32 v229, 0xffffc780, v227
	v_and_b32_e32 v227, 0x2780, v227
	v_bitop3_b32 v228, v228, v225, 4 bitop3:0x36
	v_lshlrev_b32_e32 v226, 4, v226
	v_lshlrev_b32_e32 v228, 4, v228
	v_or_b32_e32 v185, v229, v226
	v_or_b32_e32 v184, v227, v226
	v_or_b32_e32 v183, v229, v228
	v_or_b32_e32 v182, v227, v228
	s_waitcnt vmcnt(0)
	s_setprio 0
	s_barrier
	s_waitcnt vmcnt(11)
	ds_write_b128 v176, v[168:171]
	s_waitcnt vmcnt(10)
	ds_write_b128 v176, v[160:163] offset:4096
	s_waitcnt vmcnt(9)
	ds_write_b128 v176, v[152:155] offset:8192
	s_waitcnt vmcnt(8)
	ds_write_b128 v176, v[136:139] offset:12288
	s_waitcnt vmcnt(7)
	ds_write_b128 v176, v[132:135] offset:16384
	s_waitcnt vmcnt(6)
	ds_write_b128 v176, v[120:123] offset:20480
	s_waitcnt vmcnt(5)
	ds_write_b128 v176, v[108:111] offset:24576
	s_waitcnt vmcnt(4)
	ds_write_b128 v176, v[96:99] offset:28672
	s_waitcnt vmcnt(3)
	ds_write_b128 v176, v[148:151] offset:32768
	s_waitcnt vmcnt(2)
	ds_write_b128 v176, v[88:91] offset:36864
	s_waitcnt vmcnt(1)
	ds_write_b128 v176, v[72:75] offset:40960
	s_waitcnt vmcnt(0)
	ds_write_b128 v176, v[68:71] offset:45056
	s_waitcnt lgkmcnt(0)
	s_barrier
	ds_read_b128 v[68:71], v185
	ds_read_b128 v[72:75], v185 offset:2048
	ds_read_b128 v[88:91], v185 offset:4096
	ds_read_b128 v[96:99], v185 offset:6144
	ds_read_b128 v[108:111], v185 offset:8192
	ds_read_b128 v[120:123], v185 offset:10240
	ds_read_b128 v[132:135], v185 offset:12288
	ds_read_b128 v[136:139], v185 offset:14336
	ds_read_b128 v[148:151], v184 offset:32768
	ds_read_b128 v[152:155], v184 offset:34816
	ds_read_b128 v[160:163], v184 offset:36864
	ds_read_b128 v[168:171], v184 offset:38912
	s_waitcnt lgkmcnt(3)
	v_mfma_f32_16x16x32_bf16 v[172:175], v[148:151], v[68:71], v[172:175]
	s_waitcnt lgkmcnt(2)
	v_mfma_f32_16x16x32_bf16 v[164:167], v[152:155], v[68:71], v[164:167]
	s_waitcnt lgkmcnt(1)
	v_mfma_f32_16x16x32_bf16 v[156:159], v[160:163], v[68:71], v[156:159]
	s_waitcnt lgkmcnt(0)
	v_mfma_f32_16x16x32_bf16 v[68:71], v[168:171], v[68:71], v[144:147]
	v_mfma_f32_16x16x32_bf16 v[140:143], v[148:151], v[72:75], v[140:143]
	v_mfma_f32_16x16x32_bf16 v[128:131], v[152:155], v[72:75], v[128:131]
	v_mfma_f32_16x16x32_bf16 v[144:147], v[160:163], v[72:75], v[124:127]
	v_mfma_f32_16x16x32_bf16 v[72:75], v[168:171], v[72:75], v[116:119]
	v_mfma_f32_16x16x32_bf16 v[64:67], v[160:163], v[96:99], v[64:67]
	v_mfma_f32_16x16x32_bf16 v[60:63], v[168:171], v[96:99], v[60:63]
	v_mfma_f32_16x16x32_bf16 v[56:59], v[148:151], v[108:111], v[56:59]
	v_mfma_f32_16x16x32_bf16 v[52:55], v[152:155], v[108:111], v[52:55]
	v_mfma_f32_16x16x32_bf16 v[48:51], v[160:163], v[108:111], v[48:51]
	v_mfma_f32_16x16x32_bf16 v[44:47], v[168:171], v[108:111], v[44:47]
	v_mfma_f32_16x16x32_bf16 v[40:43], v[148:151], v[120:123], v[40:43]
	v_mfma_f32_16x16x32_bf16 v[36:39], v[152:155], v[120:123], v[36:39]
	v_mfma_f32_16x16x32_bf16 v[32:35], v[160:163], v[120:123], v[32:35]
	v_mfma_f32_16x16x32_bf16 v[28:31], v[168:171], v[120:123], v[28:31]
	v_mfma_f32_16x16x32_bf16 v[24:27], v[148:151], v[132:135], v[24:27]
	v_mfma_f32_16x16x32_bf16 v[20:23], v[152:155], v[132:135], v[20:23]
	v_mfma_f32_16x16x32_bf16 v[16:19], v[160:163], v[132:135], v[16:19]
	v_mfma_f32_16x16x32_bf16 v[12:15], v[168:171], v[132:135], v[12:15]
	v_mfma_f32_16x16x32_bf16 v[8:11], v[148:151], v[136:139], v[8:11]
	v_mfma_f32_16x16x32_bf16 v[4:7], v[152:155], v[136:139], v[4:7]
	v_mfma_f32_16x16x32_bf16 v[0:3], v[160:163], v[136:139], v[0:3]
	v_mfma_f32_16x16x32_bf16 v[178:181], v[148:151], v[88:91], v[104:107]
	v_mfma_f32_16x16x32_bf16 v[184:187], v[152:155], v[88:91], v[100:103]
	v_mfma_f32_16x16x32_bf16 v[190:193], v[160:163], v[88:91], v[92:95]
	v_mfma_f32_16x16x32_bf16 v[194:197], v[168:171], v[88:91], v[84:87]
	v_mfma_f32_16x16x32_bf16 v[198:201], v[148:151], v[96:99], v[80:83]
	v_mfma_f32_16x16x32_bf16 v[204:207], v[152:155], v[96:99], v[76:79]
	v_mfma_f32_16x16x32_bf16 v[148:151], v[168:171], v[136:139], v[112:115]
	s_nop 1
	ds_read_b128 v[76:79], v183
	ds_read_b128 v[80:83], v183 offset:2048
	ds_read_b128 v[132:135], v183 offset:4096
	ds_read_b128 v[136:139], v183 offset:6144
	ds_read_b128 v[152:155], v183 offset:8192
	ds_read_b128 v[160:163], v183 offset:10240
	ds_read_b128 v[168:171], v183 offset:12288
	ds_read_b128 v[208:211], v183 offset:14336
	ds_read_b128 v[212:215], v182 offset:32768
	ds_read_b128 v[216:219], v182 offset:34816
	ds_read_b128 v[220:223], v182 offset:36864
	ds_read_b128 v[224:227], v182 offset:38912
	s_waitcnt lgkmcnt(3)
	v_mfma_f32_16x16x32_bf16 v[124:127], v[212:215], v[76:79], v[172:175]
	s_movk_i32 s0, 0xfff
	s_waitcnt lgkmcnt(2)
	v_mfma_f32_16x16x32_bf16 v[120:123], v[216:219], v[76:79], v[164:167]
	s_waitcnt lgkmcnt(1)
	v_mfma_f32_16x16x32_bf16 v[116:119], v[220:223], v[76:79], v[156:159]
	s_waitcnt lgkmcnt(0)
	v_mfma_f32_16x16x32_bf16 v[112:115], v[224:227], v[76:79], v[68:71]
	v_mfma_f32_16x16x32_bf16 v[108:111], v[212:215], v[80:83], v[140:143]
	v_mfma_f32_16x16x32_bf16 v[104:107], v[216:219], v[80:83], v[128:131]
	v_mfma_f32_16x16x32_bf16 v[100:103], v[220:223], v[80:83], v[144:147]
	v_mfma_f32_16x16x32_bf16 v[96:99], v[224:227], v[80:83], v[72:75]
	v_mfma_f32_16x16x32_bf16 v[92:95], v[212:215], v[132:135], v[178:181]
	v_mfma_f32_16x16x32_bf16 v[88:91], v[216:219], v[132:135], v[184:187]
	v_mfma_f32_16x16x32_bf16 v[84:87], v[220:223], v[132:135], v[190:193]
	v_mfma_f32_16x16x32_bf16 v[80:83], v[224:227], v[132:135], v[194:197]
	v_mov_b32_e32 v132, v188
	v_mfma_f32_16x16x32_bf16 v[76:79], v[212:215], v[136:139], v[198:201]
	v_mfma_f32_16x16x32_bf16 v[72:75], v[216:219], v[136:139], v[204:207]
	v_mfma_f32_16x16x32_bf16 v[68:71], v[220:223], v[136:139], v[64:67]
	v_mfma_f32_16x16x32_bf16 v[64:67], v[224:227], v[136:139], v[60:63]
	v_mov_b32_e32 v137, v188
	v_mfma_f32_16x16x32_bf16 v[60:63], v[212:215], v[152:155], v[56:59]
	v_and_b32_e32 v143, 15, v137
	v_and_or_b32 v136, v132, 64, s8
	v_and_b32_e32 v176, 48, v137
	v_mfma_f32_16x16x32_bf16 v[56:59], v[216:219], v[152:155], v[52:55]
	v_mfma_f32_16x16x32_bf16 v[52:55], v[220:223], v[152:155], v[48:51]
	v_mfma_f32_16x16x32_bf16 v[48:51], v[224:227], v[152:155], v[44:47]
	v_mfma_f32_16x16x32_bf16 v[44:47], v[212:215], v[160:163], v[40:43]
	v_mfma_f32_16x16x32_bf16 v[40:43], v[216:219], v[160:163], v[36:39]
	v_mfma_f32_16x16x32_bf16 v[36:39], v[224:227], v[160:163], v[28:31]
	s_nop 2
	v_and_b32_e32 v28, 0xffffff80, v132
	v_add_u32_e32 v144, s9, v28
	v_or_b32_e32 v145, v144, v143
	v_mfma_f32_16x16x32_bf16 v[28:31], v[216:219], v[168:171], v[20:23]
	v_cmp_lt_i32_e32 vcc, s0, v144
	s_mov_b32 s0, 0x2aaaaaab
	v_and_b32_e32 v142, 0x380, v144
	v_lshlrev_b32_e32 v20, 3, v145
	v_ashrrev_i32_e32 v21, 31, v20
	v_lshl_add_u64 v[128:129], v[20:21], 2, s[4:5]
	global_load_dwordx2 v[138:139], v[128:129], off offset:16
	s_nop 0
	global_load_dwordx4 v[128:131], v[128:129], off
	v_mfma_f32_16x16x32_bf16 v[20:23], v[220:223], v[168:171], v[16:19]
	v_mfma_f32_16x16x32_bf16 v[16:19], v[224:227], v[168:171], v[12:15]
	s_nop 2
	v_mul_hi_i32 v12, v136, s0
	v_lshrrev_b32_e32 v13, 31, v12
	v_lshrrev_b32_e32 v12, 5, v12
	v_add_u32_e32 v132, v12, v13
	s_movk_i32 s0, 0xc0
	v_mfma_f32_16x16x32_bf16 v[12:15], v[216:219], v[208:211], v[4:7]
	s_nop 2
	v_mul_lo_u32 v4, v132, s0
	v_sub_u32_e32 v4, v136, v4
	v_cmp_eq_u32_e64 s[0:1], s19, v4
	s_and_b64 s[40:41], s[0:1], vcc
	v_readlane_b32 s0, v255, 45
	v_mfma_f32_16x16x32_bf16 v[32:35], v[220:223], v[160:163], v[32:35]
	v_readlane_b32 s1, v255, 46
	v_mfma_f32_16x16x32_bf16 v[24:27], v[212:215], v[168:171], v[24:27]
	s_nop 0
	v_lshl_add_u64 v[134:135], s[0:1], 0, v[176:177]
	v_readlane_b32 s0, v255, 47
	v_readlane_b32 s1, v255, 48
	v_mfma_f32_16x16x32_bf16 v[8:11], v[212:215], v[208:211], v[8:11]
	s_nop 0
	v_lshl_add_u64 v[132:133], s[0:1], 0, v[176:177]
	v_mfma_f32_16x16x32_bf16 v[0:3], v[220:223], v[208:211], v[0:3]
	v_mfma_f32_16x16x32_bf16 v[4:7], v[224:227], v[208:211], v[148:151]
	s_and_saveexec_b64 s[0:1], s[40:41]
	s_cbranch_execz .LBB0_403
	v_or_b32_e32 v140, v142, v143
	v_lshlrev_b32_e32 v176, 7, v140
	v_lshl_add_u64 v[154:155], v[134:135], 0, v[176:177]
	v_lshl_add_u64 v[156:157], v[132:133], 0, v[176:177]
	global_load_dwordx4 v[146:149], v[154:155], off
	global_load_dwordx4 v[150:153], v[156:157], off
	s_waitcnt vmcnt(0)
	v_pk_mul_f32 v[158:159], v[124:125], v[150:151]
	v_pk_mul_f32 v[140:141], v[116:117], v[150:151]
	v_mul_f32_e32 v150, v126, v148
	v_mul_f32_e32 v160, v118, v152
	v_mul_f32_e32 v162, v126, v152
	v_mul_f32_e32 v148, v118, v148
	v_mov_b32_e32 v118, v127
	v_mov_b32_e32 v152, v149
	v_mov_b32_e32 v126, v119
	v_pk_mul_f32 v[164:165], v[118:119], v[152:153]
	v_pk_mul_f32 v[118:119], v[126:127], v[152:153]
	v_mov_b32_e32 v151, v164
	v_mov_b32_e32 v161, v165
	v_mov_b32_e32 v149, v118
	v_mov_b32_e32 v163, v119
	v_pk_fma_f32 v[124:125], v[124:125], v[146:147], v[140:141] neg_lo:[0,0,1] neg_hi:[0,0,1]
	v_pk_add_f32 v[140:141], v[150:151], v[160:161] neg_lo:[0,1] neg_hi:[0,1]
	v_pk_fma_f32 v[116:117], v[116:117], v[146:147], v[158:159]
	v_pk_add_f32 v[118:119], v[148:149], v[162:163]
	global_load_dwordx4 v[146:149], v[154:155], off offset:64
	global_load_dwordx4 v[150:153], v[156:157], off offset:64
	s_waitcnt vmcnt(1)
	v_mul_f32_e32 v154, v122, v148
	s_waitcnt vmcnt(0)
	v_mul_f32_e32 v156, v114, v152
	v_mul_f32_e32 v158, v122, v152
	v_mul_f32_e32 v148, v114, v148
	v_mov_b32_e32 v114, v123
	v_mov_b32_e32 v152, v149
	v_pk_mul_f32 v[160:161], v[114:115], v[152:153]
	v_mov_b32_e32 v122, v115
	v_pk_mul_f32 v[126:127], v[120:121], v[150:151]
	v_pk_mul_f32 v[150:151], v[112:113], v[150:151]
	v_mov_b32_e32 v155, v160
	v_mov_b32_e32 v157, v161
	v_pk_mul_f32 v[114:115], v[122:123], v[152:153]
	v_pk_fma_f32 v[120:121], v[120:121], v[146:147], v[150:151] neg_lo:[0,0,1] neg_hi:[0,0,1]
	v_pk_add_f32 v[150:151], v[154:155], v[156:157] neg_lo:[0,1] neg_hi:[0,1]
	v_mov_b32_e32 v149, v114
	v_mov_b32_e32 v159, v115
	v_pk_fma_f32 v[112:113], v[112:113], v[146:147], v[126:127]
	v_pk_add_f32 v[114:115], v[148:149], v[158:159]
	v_mov_b32_e32 v122, v150
	v_mov_b32_e32 v123, v151
	v_mov_b32_e32 v126, v140
	v_mov_b32_e32 v127, v141

.LBB0_422:
	s_lshl_b32 s42, s42, 1
	s_ashr_i32 s9, s9, 5
	s_sub_i32 s42, s42, s43
	s_add_i32 s9, s9, s42
	s_lshl_b32 s9, s9, 3
	s_add_i32 s9, s9, s1
	s_lshl_b32 s94, s9, 7
	s_and_b64 s[42:43], s[92:93], exec
	s_mov_b32 s1, 0x2400000
	s_cselect_b32 s1, s1, 0x2200000
	s_add_u32 s42, s36, s1
	s_addc_u32 s43, s6, 0
	s_and_b32 s95, s0, 1
	s_bitcmp1_b32 s0, 0
	s_cselect_b64 s[0:1], -1, 0
	s_cmp_eq_u32 s95, 0
	s_cbranch_scc1 .LBB0_426
	v_mov_b32_e32 v6, v188
	s_mov_b32 s95, 0x8000
	v_ashrrev_i32_e32 v7, 3, v6
	v_lshlrev_b32_e32 v4, 4, v6
	v_and_b32_e32 v176, 0x70, v4
	v_add_u32_e32 v4, s94, v7
	v_ashrrev_i32_e32 v5, 31, v4
	v_add_u32_e32 v0, s8, v7
	v_lshlrev_b64 v[4:5], 9, v[4:5]
	v_ashrrev_i32_e32 v1, 31, v0
	v_lshl_add_u64 v[4:5], s[42:43], 0, v[4:5]
	v_xor_b32_e32 v8, v7, v6
	v_lshlrev_b64 v[0:1], 9, v[0:1]
	v_lshl_add_u64 v[178:179], v[4:5], 0, v[176:177]
	v_lshlrev_b32_e32 v4, 4, v8
	v_lshl_add_u64 v[2:3], s[46:47], 0, v[0:1]
	v_and_b32_e32 v4, 0x70, v4
	v_lshl_add_u64 v[2:3], v[2:3], 0, v[176:177]
	v_lshl_or_b32 v176, v7, 7, v4
	v_lshrrev_b32_e32 v4, 4, v6
	v_and_b32_e32 v11, 7, v6
	v_bitop3_b32 v12, v4, v11, 3 bitop3:0x6c
	v_add_co_u32_e32 v4, vcc, s28, v178
	v_lshlrev_b32_e32 v8, 7, v6
	s_nop 0
	v_addc_co_u32_e32 v5, vcc, 0, v179, vcc
	v_bfe_u32 v10, v6, 4, 2
	v_add_co_u32_e32 v6, vcc, s95, v178
	s_movk_i32 s16, 0x4000
	s_nop 0
	v_addc_co_u32_e32 v7, vcc, 0, v179, vcc
	global_load_dwordx4 v[20:23], v[4:5], off
	global_load_dwordx4 v[24:27], v[6:7], off
	v_add_co_u32_e32 v4, vcc, s16, v178
	s_mov_b32 s15, 0x1c000
	s_nop 0
	v_addc_co_u32_e32 v5, vcc, 0, v179, vcc
	v_add_co_u32_e32 v6, vcc, s15, v2
	s_mov_b32 s15, 0x18000
	s_nop 0
	v_addc_co_u32_e32 v7, vcc, 0, v3, vcc
	global_load_dwordx4 v[40:43], v[4:5], off
	global_load_dwordx4 v[48:51], v[6:7], off
	v_add_co_u32_e32 v4, vcc, s15, v2
	s_mov_b32 s15, 0x14000
	s_nop 0
	v_addc_co_u32_e32 v5, vcc, 0, v3, vcc
	v_add_co_u32_e32 v6, vcc, s15, v2
	v_and_b32_e32 v9, 0xffffc780, v8
	s_nop 0
	v_addc_co_u32_e32 v7, vcc, 0, v3, vcc
	global_load_dwordx4 v[68:71], v[4:5], off
	global_load_dwordx4 v[72:75], v[6:7], off
	v_add_co_u32_e32 v4, vcc, s14, v2
	v_and_b32_e32 v8, 0x2780, v8
	s_nop 0
	v_addc_co_u32_e32 v5, vcc, 0, v3, vcc
	v_add_co_u32_e32 v6, vcc, s28, v2
	v_bitop3_b32 v10, v10, v11, 4 bitop3:0x36
	s_nop 0
	v_addc_co_u32_e32 v7, vcc, 0, v3, vcc
	global_load_dwordx4 v[84:87], v[4:5], off
	global_load_dwordx4 v[92:95], v[6:7], off
	v_add_co_u32_e32 v4, vcc, s95, v2
	v_lshl_or_b32 v0, v11, 4, v0
	s_nop 0
	v_addc_co_u32_e32 v5, vcc, 0, v3, vcc
	v_add_co_u32_e32 v6, vcc, s16, v2
	v_mov_b32_e32 v140, 0
	s_nop 0
	v_addc_co_u32_e32 v7, vcc, 0, v3, vcc
	global_load_dwordx4 v[104:107], v[4:5], off
	global_load_dwordx4 v[112:115], v[6:7], off
	global_load_dwordx4 v[56:59], v[178:179], off
	global_load_dwordx4 v[116:119], v[2:3], off
	v_lshlrev_b32_e32 v2, 4, v12
	v_or_b32_e32 v185, v9, v2
	v_or_b32_e32 v184, v8, v2
	v_lshlrev_b32_e32 v2, 4, v10
	v_or_b32_e32 v183, v9, v2
	v_or_b32_e32 v182, v8, v2
	v_lshl_add_u64 v[180:181], s[58:59], 0, v[0:1]
	s_mov_b64 s[30:31], 0
	v_mov_b32_e32 v141, v140
	v_mov_b32_e32 v142, v140
	v_mov_b32_e32 v143, v140
	v_mov_b32_e32 v0, v140
	v_mov_b32_e32 v1, v140
	v_mov_b32_e32 v2, v140
	v_mov_b32_e32 v3, v140
	v_mov_b32_e32 v4, v140
	v_mov_b32_e32 v5, v140
	v_mov_b32_e32 v6, v140
	v_mov_b32_e32 v7, v140
	v_mov_b32_e32 v8, v140
	v_mov_b32_e32 v9, v140
	v_mov_b32_e32 v10, v140
	v_mov_b32_e32 v11, v140
	v_mov_b32_e32 v12, v140
	v_mov_b32_e32 v13, v140
	v_mov_b32_e32 v14, v140
	v_mov_b32_e32 v15, v140
	v_mov_b32_e32 v16, v140
	v_mov_b32_e32 v17, v140
	v_mov_b32_e32 v18, v140
	v_mov_b32_e32 v19, v140
	v_mov_b32_e32 v28, v140
	v_mov_b32_e32 v29, v140
	v_mov_b32_e32 v30, v140
	v_mov_b32_e32 v31, v140
	v_mov_b32_e32 v32, v140
	v_mov_b32_e32 v33, v140
	v_mov_b32_e32 v34, v140
	v_mov_b32_e32 v35, v140
	v_mov_b32_e32 v36, v140
	v_mov_b32_e32 v37, v140
	v_mov_b32_e32 v38, v140
	v_mov_b32_e32 v39, v140
	v_mov_b32_e32 v44, v140
	v_mov_b32_e32 v45, v140
	v_mov_b32_e32 v46, v140
	v_mov_b32_e32 v47, v140
	v_mov_b32_e32 v52, v140
	v_mov_b32_e32 v53, v140
	v_mov_b32_e32 v54, v140
	v_mov_b32_e32 v55, v140
	v_mov_b32_e32 v60, v140
	v_mov_b32_e32 v61, v140
	v_mov_b32_e32 v62, v140
	v_mov_b32_e32 v63, v140
	v_mov_b32_e32 v64, v140
	v_mov_b32_e32 v65, v140
	v_mov_b32_e32 v66, v140
	v_mov_b32_e32 v67, v140
	v_mov_b32_e32 v76, v140
	v_mov_b32_e32 v77, v140
	v_mov_b32_e32 v78, v140
	v_mov_b32_e32 v79, v140
	v_mov_b32_e32 v80, v140
	v_mov_b32_e32 v81, v140
	v_mov_b32_e32 v82, v140
	v_mov_b32_e32 v83, v140
	v_mov_b32_e32 v88, v140
	v_mov_b32_e32 v89, v140
	v_mov_b32_e32 v90, v140
	v_mov_b32_e32 v91, v140
	v_mov_b32_e32 v96, v140
	v_mov_b32_e32 v97, v140
	v_mov_b32_e32 v98, v140
	v_mov_b32_e32 v99, v140
	v_mov_b32_e32 v100, v140
	v_mov_b32_e32 v101, v140
	v_mov_b32_e32 v102, v140
	v_mov_b32_e32 v103, v140
	v_mov_b32_e32 v108, v140
	v_mov_b32_e32 v109, v140
	v_mov_b32_e32 v110, v140
	v_mov_b32_e32 v111, v140
	v_mov_b32_e32 v120, v140
	v_mov_b32_e32 v121, v140
	v_mov_b32_e32 v122, v140
	v_mov_b32_e32 v123, v140
	v_mov_b32_e32 v124, v140
	v_mov_b32_e32 v125, v140
	v_mov_b32_e32 v126, v140
	v_mov_b32_e32 v127, v140
	v_mov_b32_e32 v128, v140
	v_mov_b32_e32 v129, v140
	v_mov_b32_e32 v130, v140
	v_mov_b32_e32 v131, v140
	v_mov_b32_e32 v132, v140
	v_mov_b32_e32 v133, v140
	v_mov_b32_e32 v134, v140
	v_mov_b32_e32 v135, v140
	v_mov_b32_e32 v136, v140
	v_mov_b32_e32 v137, v140
	v_mov_b32_e32 v138, v140
	v_mov_b32_e32 v139, v140
	v_mov_b32_e32 v144, v140
	v_mov_b32_e32 v145, v140
	v_mov_b32_e32 v146, v140
	v_mov_b32_e32 v147, v140
	v_mov_b32_e32 v148, v140
	v_mov_b32_e32 v149, v140
	v_mov_b32_e32 v150, v140
	v_mov_b32_e32 v151, v140
	v_mov_b32_e32 v152, v140
	v_mov_b32_e32 v153, v140
	v_mov_b32_e32 v154, v140
	v_mov_b32_e32 v155, v140
	v_mov_b32_e32 v156, v140
	v_mov_b32_e32 v157, v140
	v_mov_b32_e32 v158, v140
	v_mov_b32_e32 v159, v140
	v_mov_b32_e32 v160, v140
	v_mov_b32_e32 v161, v140
	v_mov_b32_e32 v162, v140
	v_mov_b32_e32 v163, v140
	v_mov_b32_e32 v164, v140
	v_mov_b32_e32 v165, v140
	v_mov_b32_e32 v166, v140
	v_mov_b32_e32 v167, v140
	v_mov_b32_e32 v168, v140
	v_mov_b32_e32 v169, v140
	v_mov_b32_e32 v170, v140
	v_mov_b32_e32 v171, v140
	v_mov_b32_e32 v172, v140
	v_mov_b32_e32 v173, v140
	v_mov_b32_e32 v174, v140
	v_mov_b32_e32 v175, v140
	s_mov_b32 s15, 0xad00000
	s_mov_b32 s17, 0xad04000
	s_mov_b32 s52, 0xad08000
	s_mov_b32 s53, 0xad0c000
	s_mov_b32 s10, 0xad10000
	s_mov_b32 s11, 0xad14000
	s_mov_b32 s12, 0xad18000
	s_mov_b32 s13, 0xad1c000
	s_setprio 2
	v_readlane_b32 s98, v253, 3
	v_readlane_b32 s99, v253, 4
	v_and_b32_e32 v224, 15, v188
	v_bfe_u32 v225, v188, 4, 2
	v_lshrrev_b32_e32 v226, 2, v224
	v_sub_u32_e32 v226, 0, v226
	v_and_b32_e32 v226, 3, v226
	v_xor_b32_e32 v225, v225, v226
	v_lshlrev_b32_e32 v225, 4, v225
	v_lshl_or_b32 v225, v224, 6, v225
	v_bfe_u32 v226, v188, 7, 1
	v_lshl_or_b32 v185, v226, 13, v225
	v_bfe_u32 v226, v188, 6, 1
	v_lshl_or_b32 v184, v226, 12, v225
	v_add_u32_e32 v184, 0x4000, v184
	v_lshrrev_b32_e32 v224, 3, v188
	v_bfe_u32 v225, v188, 2, 1
	v_lshrrev_b32_e32 v226, 2, v224
	v_sub_u32_e32 v226, 0, v226
	v_and_b32_e32 v226, 3, v226
	v_and_b32_e32 v227, 3, v188
	v_xor_b32_e32 v226, v227, v226
	v_lshlrev_b32_e32 v226, 4, v226
	v_xor_b32_e32 v224, v224, v225
	v_lshl_or_b32 v226, v224, 6, v226
	v_mul_u32_u24_e32 v225, 0x6000, v225
	v_add_u32_e32 v183, v225, v226
	s_mov_b32 m0, 0
	s_sub_u32 vcc_lo, s30, s98
	v_add_u32_e32 v186, vcc_lo, v178
	v_add_u32_e32 v187, vcc_lo, v180
	s_barrier
	s_waitcnt vmcnt(0)
	ds_write_b128 v183, v[116:119]
	ds_write_b128 v183, v[112:115] offset:2048
	ds_write_b128 v183, v[104:107] offset:4096
	ds_write_b128 v183, v[92:95] offset:6144
	ds_write_b128 v183, v[84:87] offset:8192
	ds_write_b128 v183, v[72:75] offset:10240
	ds_write_b128 v183, v[68:71] offset:12288
	ds_write_b128 v183, v[48:51] offset:14336
	ds_write_b128 v183, v[56:59] offset:16384
	ds_write_b128 v183, v[40:43] offset:18432
	ds_write_b128 v183, v[24:27] offset:20480
	ds_write_b128 v183, v[20:23] offset:22528
	v_cmp_gt_u32_e32 vcc, 0x6000, v183
	v_add_u32_e32 v182, 0xc000, v183
	v_add_u32_e32 v183, 0xffffa000, v183
	s_nop 0
	v_cndmask_b32_e32 v183, v183, v182, vcc
	v_add_u32_e32 v116, s15, v187
	global_load_dwordx4 v[116:119], v116, s[98:99] offset:128
	v_add_u32_e32 v112, s17, v187
	global_load_dwordx4 v[112:115], v112, s[98:99] offset:128
	v_add_u32_e32 v104, s52, v187
	global_load_dwordx4 v[104:107], v104, s[98:99] offset:128
	v_add_u32_e32 v92, s53, v187
	global_load_dwordx4 v[92:95], v92, s[98:99] offset:128
	v_add_u32_e32 v84, s10, v187
	global_load_dwordx4 v[84:87], v84, s[98:99] offset:128
	v_add_u32_e32 v72, s11, v187
	global_load_dwordx4 v[72:75], v72, s[98:99] offset:128
	v_add_u32_e32 v68, s12, v187
	global_load_dwordx4 v[68:71], v68, s[98:99] offset:128
	v_add_u32_e32 v48, s13, v187
	global_load_dwordx4 v[48:51], v48, s[98:99] offset:128
	v_mov_b32_e32 v56, v186
	global_load_dwordx4 v[56:59], v56, s[98:99] offset:128
	v_add_u32_e32 v40, s16, v186
	global_load_dwordx4 v[40:43], v40, s[98:99] offset:128
	v_add_u32_e32 v24, s95, v186
	global_load_dwordx4 v[24:27], v24, s[98:99] offset:128
	v_add_u32_e32 v20, s28, v186
	global_load_dwordx4 v[20:23], v20, s[98:99] offset:128
	s_add_u32 s30, s30, 0x80
	s_addc_u32 s31, s31, 0
.LBB0_424:
	s_waitcnt lgkmcnt(0)
	s_barrier
	ds_read_b128 v[224:227], v184
	ds_read_b128 v[228:231], v184 offset:1024
	ds_read_b128 v[232:235], v184 offset:2048
	ds_read_b128 v[236:239], v184 offset:3072
	ds_read_b128 v[190:193], v185
	ds_read_b128 v[194:197], v185 offset:1024
	ds_read_b128 v[198:201], v185 offset:2048
	ds_read_b128 v[204:207], v185 offset:3072
	ds_read_b128 v[208:211], v185 offset:4096
	ds_read_b128 v[212:215], v185 offset:5120
	ds_read_b128 v[216:219], v185 offset:6144
	ds_read_b128 v[220:223], v185 offset:7168
	s_movk_i32 vcc_lo, 0x6000
	s_cmp_eq_u32 m0, 2
	s_cselect_b32 vcc_lo, 0xffff4000, vcc_lo
	s_add_u32 m0, m0, 1
	s_cmp_eq_u32 m0, 3
	s_cselect_b32 m0, 0, m0
	v_add_u32_e32 v185, vcc_lo, v185
	v_add_u32_e32 v184, vcc_lo, v184
	v_xor_b32_e32 v185, 64, v185
	v_xor_b32_e32 v184, 64, v184
	s_waitcnt lgkmcnt(7)
	v_mfma_f32_16x16x32_bf16 v[172:175], v[190:193], v[224:227], v[172:175]
	v_mfma_f32_16x16x32_bf16 v[168:171], v[190:193], v[228:231], v[168:171]
	v_mfma_f32_16x16x32_bf16 v[164:167], v[190:193], v[232:235], v[164:167]
	v_mfma_f32_16x16x32_bf16 v[160:163], v[190:193], v[236:239], v[160:163]
	ds_read_b128 v[190:193], v185
	s_waitcnt lgkmcnt(7)
	v_mfma_f32_16x16x32_bf16 v[156:159], v[194:197], v[224:227], v[156:159]
	v_mfma_f32_16x16x32_bf16 v[152:155], v[194:197], v[228:231], v[152:155]
	v_mfma_f32_16x16x32_bf16 v[148:151], v[194:197], v[232:235], v[148:151]
	v_mfma_f32_16x16x32_bf16 v[144:147], v[194:197], v[236:239], v[144:147]
	ds_read_b128 v[194:197], v185 offset:1024
	s_waitcnt lgkmcnt(7)
	v_mfma_f32_16x16x32_bf16 v[136:139], v[198:201], v[224:227], v[136:139]
	v_mfma_f32_16x16x32_bf16 v[132:135], v[198:201], v[228:231], v[132:135]
	v_mfma_f32_16x16x32_bf16 v[128:131], v[198:201], v[232:235], v[128:131]
	v_mfma_f32_16x16x32_bf16 v[124:127], v[198:201], v[236:239], v[124:127]
	ds_read_b128 v[198:201], v185 offset:2048
	s_waitcnt lgkmcnt(7)
	v_mfma_f32_16x16x32_bf16 v[120:123], v[204:207], v[224:227], v[120:123]
	v_mfma_f32_16x16x32_bf16 v[108:111], v[204:207], v[228:231], v[108:111]
	v_mfma_f32_16x16x32_bf16 v[100:103], v[204:207], v[232:235], v[100:103]
	v_mfma_f32_16x16x32_bf16 v[96:99], v[204:207], v[236:239], v[96:99]
	ds_read_b128 v[204:207], v185 offset:3072
	s_waitcnt lgkmcnt(7)
	v_mfma_f32_16x16x32_bf16 v[88:91], v[208:211], v[224:227], v[88:91]
	v_mfma_f32_16x16x32_bf16 v[80:83], v[208:211], v[228:231], v[80:83]
	v_mfma_f32_16x16x32_bf16 v[76:79], v[208:211], v[232:235], v[76:79]
	v_mfma_f32_16x16x32_bf16 v[64:67], v[208:211], v[236:239], v[64:67]
	ds_read_b128 v[208:211], v185 offset:4096
	s_waitcnt lgkmcnt(7)
	v_mfma_f32_16x16x32_bf16 v[60:63], v[212:215], v[224:227], v[60:63]
	v_mfma_f32_16x16x32_bf16 v[52:55], v[212:215], v[228:231], v[52:55]
	v_mfma_f32_16x16x32_bf16 v[44:47], v[212:215], v[232:235], v[44:47]
	v_mfma_f32_16x16x32_bf16 v[36:39], v[212:215], v[236:239], v[36:39]
	ds_read_b128 v[212:215], v185 offset:5120
	s_waitcnt lgkmcnt(7)
	v_mfma_f32_16x16x32_bf16 v[32:35], v[216:219], v[224:227], v[32:35]
	v_mfma_f32_16x16x32_bf16 v[28:31], v[216:219], v[228:231], v[28:31]
	v_mfma_f32_16x16x32_bf16 v[16:19], v[216:219], v[232:235], v[16:19]
	v_mfma_f32_16x16x32_bf16 v[12:15], v[216:219], v[236:239], v[12:15]
	ds_read_b128 v[216:219], v185 offset:6144
	s_waitcnt lgkmcnt(7)
	v_mfma_f32_16x16x32_bf16 v[8:11], v[220:223], v[224:227], v[8:11]
	v_mfma_f32_16x16x32_bf16 v[4:7], v[220:223], v[228:231], v[4:7]
	v_mfma_f32_16x16x32_bf16 v[0:3], v[220:223], v[232:235], v[0:3]
	v_mfma_f32_16x16x32_bf16 v[140:143], v[220:223], v[236:239], v[140:143]
	ds_read_b128 v[220:223], v185 offset:7168
	ds_read_b128 v[224:227], v184
	ds_read_b128 v[228:231], v184 offset:1024
	ds_read_b128 v[232:235], v184 offset:2048
	ds_read_b128 v[236:239], v184 offset:3072
	s_movk_i32 vcc_lo, 0x6000
	s_cmp_eq_u32 m0, 2
	s_cselect_b32 vcc_lo, 0xffff4000, vcc_lo
	s_add_u32 m0, m0, 1
	s_cmp_eq_u32 m0, 3
	s_cselect_b32 m0, 0, m0
	v_add_u32_e32 v185, vcc_lo, v185
	v_add_u32_e32 v184, vcc_lo, v184
	v_xor_b32_e32 v185, 64, v185
	v_xor_b32_e32 v184, 64, v184
	s_sub_u32 vcc_lo, s30, s98
	v_add_u32_e32 v186, vcc_lo, v178
	v_add_u32_e32 v187, vcc_lo, v180
	s_barrier
	s_waitcnt lgkmcnt(0)
	v_mfma_f32_16x16x32_bf16 v[172:175], v[190:193], v[224:227], v[172:175]
	s_waitcnt vmcnt(11)
	v_mfma_f32_16x16x32_bf16 v[168:171], v[190:193], v[228:231], v[168:171]
	ds_write_b128 v183, v[116:119]
	v_add_u32_e32 v116, s15, v187
	v_mfma_f32_16x16x32_bf16 v[164:167], v[190:193], v[232:235], v[164:167]
	global_load_dwordx4 v[116:119], v116, s[98:99] offset:128
	v_mfma_f32_16x16x32_bf16 v[160:163], v[190:193], v[236:239], v[160:163]
	s_waitcnt vmcnt(11)
	ds_write_b128 v183, v[112:115] offset:2048
	v_mfma_f32_16x16x32_bf16 v[156:159], v[194:197], v[224:227], v[156:159]
	v_add_u32_e32 v112, s17, v187
	v_mfma_f32_16x16x32_bf16 v[152:155], v[194:197], v[228:231], v[152:155]
	global_load_dwordx4 v[112:115], v112, s[98:99] offset:128
	s_waitcnt vmcnt(11)
	v_mfma_f32_16x16x32_bf16 v[148:151], v[194:197], v[232:235], v[148:151]
	ds_write_b128 v183, v[104:107] offset:4096
	v_mfma_f32_16x16x32_bf16 v[144:147], v[194:197], v[236:239], v[144:147]
	v_add_u32_e32 v104, s52, v187
	global_load_dwordx4 v[104:107], v104, s[98:99] offset:128
	v_mfma_f32_16x16x32_bf16 v[136:139], v[198:201], v[224:227], v[136:139]
	s_waitcnt vmcnt(11)
	v_mfma_f32_16x16x32_bf16 v[132:135], v[198:201], v[228:231], v[132:135]
	ds_write_b128 v183, v[92:95] offset:6144
	v_add_u32_e32 v92, s53, v187
	v_mfma_f32_16x16x32_bf16 v[128:131], v[198:201], v[232:235], v[128:131]
	global_load_dwordx4 v[92:95], v92, s[98:99] offset:128
	v_mfma_f32_16x16x32_bf16 v[124:127], v[198:201], v[236:239], v[124:127]
	s_waitcnt vmcnt(11)
	ds_write_b128 v183, v[84:87] offset:8192
	v_mfma_f32_16x16x32_bf16 v[120:123], v[204:207], v[224:227], v[120:123]
	v_add_u32_e32 v84, s10, v187
	v_mfma_f32_16x16x32_bf16 v[108:111], v[204:207], v[228:231], v[108:111]
	global_load_dwordx4 v[84:87], v84, s[98:99] offset:128
	s_waitcnt vmcnt(11)
	v_mfma_f32_16x16x32_bf16 v[100:103], v[204:207], v[232:235], v[100:103]
	ds_write_b128 v183, v[72:75] offset:10240
	v_mfma_f32_16x16x32_bf16 v[96:99], v[204:207], v[236:239], v[96:99]
	v_add_u32_e32 v72, s11, v187
	global_load_dwordx4 v[72:75], v72, s[98:99] offset:128
	v_mfma_f32_16x16x32_bf16 v[88:91], v[208:211], v[224:227], v[88:91]
	s_waitcnt vmcnt(11)
	v_mfma_f32_16x16x32_bf16 v[80:83], v[208:211], v[228:231], v[80:83]
	ds_write_b128 v183, v[68:71] offset:12288
	v_add_u32_e32 v68, s12, v187
	v_mfma_f32_16x16x32_bf16 v[76:79], v[208:211], v[232:235], v[76:79]
	global_load_dwordx4 v[68:71], v68, s[98:99] offset:128
	v_mfma_f32_16x16x32_bf16 v[64:67], v[208:211], v[236:239], v[64:67]
	s_waitcnt vmcnt(11)
	ds_write_b128 v183, v[48:51] offset:14336
	v_mfma_f32_16x16x32_bf16 v[60:63], v[212:215], v[224:227], v[60:63]
	v_add_u32_e32 v48, s13, v187
	v_mfma_f32_16x16x32_bf16 v[52:55], v[212:215], v[228:231], v[52:55]
	global_load_dwordx4 v[48:51], v48, s[98:99] offset:128
	s_waitcnt vmcnt(11)
	v_mfma_f32_16x16x32_bf16 v[44:47], v[212:215], v[232:235], v[44:47]
	ds_write_b128 v183, v[56:59] offset:16384
	v_mfma_f32_16x16x32_bf16 v[36:39], v[212:215], v[236:239], v[36:39]
	v_mov_b32_e32 v56, v186
	global_load_dwordx4 v[56:59], v56, s[98:99] offset:128
	v_mfma_f32_16x16x32_bf16 v[32:35], v[216:219], v[224:227], v[32:35]
	s_waitcnt vmcnt(11)
	v_mfma_f32_16x16x32_bf16 v[28:31], v[216:219], v[228:231], v[28:31]
	ds_write_b128 v183, v[40:43] offset:18432
	v_add_u32_e32 v40, s16, v186
	v_mfma_f32_16x16x32_bf16 v[16:19], v[216:219], v[232:235], v[16:19]
	global_load_dwordx4 v[40:43], v40, s[98:99] offset:128
	v_mfma_f32_16x16x32_bf16 v[12:15], v[216:219], v[236:239], v[12:15]
	s_waitcnt vmcnt(11)
	ds_write_b128 v183, v[24:27] offset:20480
	v_mfma_f32_16x16x32_bf16 v[8:11], v[220:223], v[224:227], v[8:11]
	v_add_u32_e32 v24, s95, v186
	v_mfma_f32_16x16x32_bf16 v[4:7], v[220:223], v[228:231], v[4:7]
	global_load_dwordx4 v[24:27], v24, s[98:99] offset:128
	s_waitcnt vmcnt(11)
	v_mfma_f32_16x16x32_bf16 v[0:3], v[220:223], v[232:235], v[0:3]
	ds_write_b128 v183, v[20:23] offset:22528
	v_mfma_f32_16x16x32_bf16 v[140:143], v[220:223], v[236:239], v[140:143]
	v_add_u32_e32 v20, s28, v186
	global_load_dwordx4 v[20:23], v20, s[98:99] offset:128
	v_cmp_gt_u32_e32 vcc, 0x6000, v183
	v_add_u32_e32 v182, 0xc000, v183
	v_add_u32_e32 v183, 0xffffa000, v183
	s_nop 0
	v_cndmask_b32_e32 v183, v183, v182, vcc
	s_add_u32 s30, s30, 0x80
	s_addc_u32 s31, s31, 0
	s_cmpk_eq_i32 s30, 0x180
	s_cbranch_scc0 .LBB0_424
	s_waitcnt lgkmcnt(0)
	s_barrier
	ds_read_b128 v[224:227], v184
	ds_read_b128 v[228:231], v184 offset:1024
	ds_read_b128 v[232:235], v184 offset:2048
	ds_read_b128 v[236:239], v184 offset:3072
	ds_read_b128 v[190:193], v185
	ds_read_b128 v[194:197], v185 offset:1024
	ds_read_b128 v[198:201], v185 offset:2048
	ds_read_b128 v[204:207], v185 offset:3072
	ds_read_b128 v[208:211], v185 offset:4096
	ds_read_b128 v[212:215], v185 offset:5120
	ds_read_b128 v[216:219], v185 offset:6144
	ds_read_b128 v[220:223], v185 offset:7168
	s_movk_i32 vcc_lo, 0x6000
	s_cmp_eq_u32 m0, 2
	s_cselect_b32 vcc_lo, 0xffff4000, vcc_lo
	s_add_u32 m0, m0, 1
	s_cmp_eq_u32 m0, 3
	s_cselect_b32 m0, 0, m0
	v_add_u32_e32 v185, vcc_lo, v185
	v_add_u32_e32 v184, vcc_lo, v184
	v_xor_b32_e32 v185, 64, v185
	v_xor_b32_e32 v184, 64, v184
	s_waitcnt lgkmcnt(7)
	v_mfma_f32_16x16x32_bf16 v[172:175], v[190:193], v[224:227], v[172:175]
	v_mfma_f32_16x16x32_bf16 v[168:171], v[190:193], v[228:231], v[168:171]
	v_mfma_f32_16x16x32_bf16 v[164:167], v[190:193], v[232:235], v[164:167]
	v_mfma_f32_16x16x32_bf16 v[160:163], v[190:193], v[236:239], v[160:163]
	ds_read_b128 v[190:193], v185
	s_waitcnt lgkmcnt(7)
	v_mfma_f32_16x16x32_bf16 v[156:159], v[194:197], v[224:227], v[156:159]
	v_mfma_f32_16x16x32_bf16 v[152:155], v[194:197], v[228:231], v[152:155]
	v_mfma_f32_16x16x32_bf16 v[148:151], v[194:197], v[232:235], v[148:151]
	v_mfma_f32_16x16x32_bf16 v[144:147], v[194:197], v[236:239], v[144:147]
	ds_read_b128 v[194:197], v185 offset:1024
	s_waitcnt lgkmcnt(7)
	v_mfma_f32_16x16x32_bf16 v[136:139], v[198:201], v[224:227], v[136:139]
	v_mfma_f32_16x16x32_bf16 v[132:135], v[198:201], v[228:231], v[132:135]
	v_mfma_f32_16x16x32_bf16 v[128:131], v[198:201], v[232:235], v[128:131]
	v_mfma_f32_16x16x32_bf16 v[124:127], v[198:201], v[236:239], v[124:127]
	ds_read_b128 v[198:201], v185 offset:2048
	s_waitcnt lgkmcnt(7)
	v_mfma_f32_16x16x32_bf16 v[120:123], v[204:207], v[224:227], v[120:123]
	v_mfma_f32_16x16x32_bf16 v[108:111], v[204:207], v[228:231], v[108:111]
	v_mfma_f32_16x16x32_bf16 v[100:103], v[204:207], v[232:235], v[100:103]
	v_mfma_f32_16x16x32_bf16 v[96:99], v[204:207], v[236:239], v[96:99]
	ds_read_b128 v[204:207], v185 offset:3072
	s_waitcnt lgkmcnt(7)
	v_mfma_f32_16x16x32_bf16 v[88:91], v[208:211], v[224:227], v[88:91]
	v_mfma_f32_16x16x32_bf16 v[80:83], v[208:211], v[228:231], v[80:83]
	v_mfma_f32_16x16x32_bf16 v[76:79], v[208:211], v[232:235], v[76:79]
	v_mfma_f32_16x16x32_bf16 v[64:67], v[208:211], v[236:239], v[64:67]
	ds_read_b128 v[208:211], v185 offset:4096
	s_waitcnt lgkmcnt(7)
	v_mfma_f32_16x16x32_bf16 v[60:63], v[212:215], v[224:227], v[60:63]
	v_mfma_f32_16x16x32_bf16 v[52:55], v[212:215], v[228:231], v[52:55]
	v_mfma_f32_16x16x32_bf16 v[44:47], v[212:215], v[232:235], v[44:47]
	v_mfma_f32_16x16x32_bf16 v[36:39], v[212:215], v[236:239], v[36:39]
	ds_read_b128 v[212:215], v185 offset:5120
	s_waitcnt lgkmcnt(7)
	v_mfma_f32_16x16x32_bf16 v[32:35], v[216:219], v[224:227], v[32:35]
	v_mfma_f32_16x16x32_bf16 v[28:31], v[216:219], v[228:231], v[28:31]
	v_mfma_f32_16x16x32_bf16 v[16:19], v[216:219], v[232:235], v[16:19]
	v_mfma_f32_16x16x32_bf16 v[12:15], v[216:219], v[236:239], v[12:15]
	ds_read_b128 v[216:219], v185 offset:6144
	s_waitcnt lgkmcnt(7)
	v_mfma_f32_16x16x32_bf16 v[8:11], v[220:223], v[224:227], v[8:11]
	v_mfma_f32_16x16x32_bf16 v[4:7], v[220:223], v[228:231], v[4:7]
	v_mfma_f32_16x16x32_bf16 v[0:3], v[220:223], v[232:235], v[0:3]
	v_mfma_f32_16x16x32_bf16 v[140:143], v[220:223], v[236:239], v[140:143]
	ds_read_b128 v[220:223], v185 offset:7168
	ds_read_b128 v[224:227], v184
	ds_read_b128 v[228:231], v184 offset:1024
	ds_read_b128 v[232:235], v184 offset:2048
	ds_read_b128 v[236:239], v184 offset:3072
	s_movk_i32 vcc_lo, 0x6000
	s_cmp_eq_u32 m0, 2
	s_cselect_b32 vcc_lo, 0xffff4000, vcc_lo
	s_add_u32 m0, m0, 1
	s_cmp_eq_u32 m0, 3
	s_cselect_b32 m0, 0, m0
	v_add_u32_e32 v185, vcc_lo, v185
	v_add_u32_e32 v184, vcc_lo, v184
	v_xor_b32_e32 v185, 64, v185
	v_xor_b32_e32 v184, 64, v184
	s_waitcnt lgkmcnt(0)
	v_mfma_f32_16x16x32_bf16 v[172:175], v[190:193], v[224:227], v[172:175]
	v_mfma_f32_16x16x32_bf16 v[168:171], v[190:193], v[228:231], v[168:171]
	v_mfma_f32_16x16x32_bf16 v[164:167], v[190:193], v[232:235], v[164:167]
	v_mfma_f32_16x16x32_bf16 v[160:163], v[190:193], v[236:239], v[160:163]
	v_mfma_f32_16x16x32_bf16 v[156:159], v[194:197], v[224:227], v[156:159]
	v_mfma_f32_16x16x32_bf16 v[152:155], v[194:197], v[228:231], v[152:155]
	v_mfma_f32_16x16x32_bf16 v[148:151], v[194:197], v[232:235], v[148:151]
	v_mfma_f32_16x16x32_bf16 v[144:147], v[194:197], v[236:239], v[144:147]
	v_mfma_f32_16x16x32_bf16 v[136:139], v[198:201], v[224:227], v[136:139]
	v_mfma_f32_16x16x32_bf16 v[132:135], v[198:201], v[228:231], v[132:135]
	v_mfma_f32_16x16x32_bf16 v[128:131], v[198:201], v[232:235], v[128:131]
	v_mfma_f32_16x16x32_bf16 v[124:127], v[198:201], v[236:239], v[124:127]
	v_mfma_f32_16x16x32_bf16 v[120:123], v[204:207], v[224:227], v[120:123]
	v_mfma_f32_16x16x32_bf16 v[108:111], v[204:207], v[228:231], v[108:111]
	v_mfma_f32_16x16x32_bf16 v[100:103], v[204:207], v[232:235], v[100:103]
	v_mfma_f32_16x16x32_bf16 v[96:99], v[204:207], v[236:239], v[96:99]
	v_mfma_f32_16x16x32_bf16 v[88:91], v[208:211], v[224:227], v[88:91]
	v_mfma_f32_16x16x32_bf16 v[80:83], v[208:211], v[228:231], v[80:83]
	v_mfma_f32_16x16x32_bf16 v[76:79], v[208:211], v[232:235], v[76:79]
	v_mfma_f32_16x16x32_bf16 v[64:67], v[208:211], v[236:239], v[64:67]
	v_mfma_f32_16x16x32_bf16 v[60:63], v[212:215], v[224:227], v[60:63]
	v_mfma_f32_16x16x32_bf16 v[52:55], v[212:215], v[228:231], v[52:55]
	v_mfma_f32_16x16x32_bf16 v[44:47], v[212:215], v[232:235], v[44:47]
	v_mfma_f32_16x16x32_bf16 v[36:39], v[212:215], v[236:239], v[36:39]
	v_mfma_f32_16x16x32_bf16 v[32:35], v[216:219], v[224:227], v[32:35]
	v_mfma_f32_16x16x32_bf16 v[28:31], v[216:219], v[228:231], v[28:31]
	v_mfma_f32_16x16x32_bf16 v[16:19], v[216:219], v[232:235], v[16:19]
	v_mfma_f32_16x16x32_bf16 v[12:15], v[216:219], v[236:239], v[12:15]
	v_mfma_f32_16x16x32_bf16 v[8:11], v[220:223], v[224:227], v[8:11]
	v_mfma_f32_16x16x32_bf16 v[4:7], v[220:223], v[228:231], v[4:7]
	v_mfma_f32_16x16x32_bf16 v[0:3], v[220:223], v[232:235], v[0:3]
	v_mfma_f32_16x16x32_bf16 v[140:143], v[220:223], v[236:239], v[140:143]
	v_lshrrev_b32_e32 v224, 4, v188
	v_and_b32_e32 v225, 7, v188
	v_bitop3_b32 v226, v224, v225, 3 bitop3:0x6c
	v_lshlrev_b32_e32 v227, 7, v188
	v_bfe_u32 v228, v188, 4, 2
	v_and_b32_e32 v229, 0xffffc780, v227
	v_and_b32_e32 v227, 0x2780, v227
	v_bitop3_b32 v228, v228, v225, 4 bitop3:0x36
	v_lshlrev_b32_e32 v226, 4, v226
	v_lshlrev_b32_e32 v228, 4, v228
	v_or_b32_e32 v185, v229, v226
	v_or_b32_e32 v184, v227, v226
	v_or_b32_e32 v183, v229, v228
	v_or_b32_e32 v182, v227, v228
	s_waitcnt vmcnt(0)
	s_setprio 0
	s_barrier
	s_waitcnt vmcnt(10)
	ds_write_b128 v176, v[116:119]
	s_waitcnt vmcnt(9)
	ds_write_b128 v176, v[112:115] offset:4096
	s_waitcnt vmcnt(8)
	ds_write_b128 v176, v[104:107] offset:8192
	s_waitcnt vmcnt(7)
	ds_write_b128 v176, v[92:95] offset:12288
	s_waitcnt vmcnt(6)
	ds_write_b128 v176, v[84:87] offset:16384
	s_waitcnt vmcnt(5)
	ds_write_b128 v176, v[72:75] offset:20480
	s_waitcnt vmcnt(4)
	ds_write_b128 v176, v[68:71] offset:24576
	s_waitcnt vmcnt(3)
	ds_write_b128 v176, v[48:51] offset:28672
	ds_write_b128 v176, v[56:59] offset:32768
	s_waitcnt vmcnt(2)
	ds_write_b128 v176, v[40:43] offset:36864
	s_waitcnt vmcnt(1)
	ds_write_b128 v176, v[24:27] offset:40960
	s_waitcnt vmcnt(0)
	ds_write_b128 v176, v[20:23] offset:45056
	s_waitcnt lgkmcnt(0)
	s_barrier
	ds_read_b128 v[20:23], v185
	ds_read_b128 v[24:27], v185 offset:2048
	ds_read_b128 v[40:43], v185 offset:4096
	ds_read_b128 v[48:51], v185 offset:6144
	ds_read_b128 v[56:59], v185 offset:8192
	ds_read_b128 v[68:71], v185 offset:10240
	ds_read_b128 v[72:75], v185 offset:12288
	ds_read_b128 v[84:87], v185 offset:14336
	ds_read_b128 v[92:95], v184 offset:32768
	ds_read_b128 v[104:107], v184 offset:34816
	ds_read_b128 v[112:115], v184 offset:36864
	ds_read_b128 v[116:119], v184 offset:38912
	s_waitcnt lgkmcnt(3)
	v_mfma_f32_16x16x32_bf16 v[172:175], v[20:23], v[92:95], v[172:175]
	s_waitcnt lgkmcnt(2)
	v_mfma_f32_16x16x32_bf16 v[168:171], v[20:23], v[104:107], v[168:171]
	s_waitcnt lgkmcnt(1)
	v_mfma_f32_16x16x32_bf16 v[164:167], v[20:23], v[112:115], v[164:167]
	s_waitcnt lgkmcnt(0)
	v_mfma_f32_16x16x32_bf16 v[20:23], v[20:23], v[116:119], v[160:163]
	v_mfma_f32_16x16x32_bf16 v[156:159], v[24:27], v[92:95], v[156:159]
	v_mfma_f32_16x16x32_bf16 v[152:155], v[24:27], v[104:107], v[152:155]
	v_mfma_f32_16x16x32_bf16 v[148:151], v[24:27], v[112:115], v[148:151]
	v_mfma_f32_16x16x32_bf16 v[24:27], v[24:27], v[116:119], v[144:147]
	v_mfma_f32_16x16x32_bf16 v[136:139], v[40:43], v[92:95], v[136:139]
	v_mfma_f32_16x16x32_bf16 v[132:135], v[40:43], v[104:107], v[132:135]
	v_mfma_f32_16x16x32_bf16 v[128:131], v[40:43], v[112:115], v[128:131]
	v_mfma_f32_16x16x32_bf16 v[40:43], v[40:43], v[116:119], v[124:127]
	v_mfma_f32_16x16x32_bf16 v[144:147], v[48:51], v[92:95], v[120:123]
	v_mfma_f32_16x16x32_bf16 v[160:163], v[48:51], v[104:107], v[108:111]
	v_mfma_f32_16x16x32_bf16 v[178:181], v[48:51], v[112:115], v[100:103]
	v_mfma_f32_16x16x32_bf16 v[48:51], v[48:51], v[116:119], v[96:99]
	v_mfma_f32_16x16x32_bf16 v[16:19], v[72:75], v[112:115], v[16:19]
	v_mfma_f32_16x16x32_bf16 v[12:15], v[72:75], v[116:119], v[12:15]
	v_mfma_f32_16x16x32_bf16 v[8:11], v[84:87], v[92:95], v[8:11]
	v_mfma_f32_16x16x32_bf16 v[4:7], v[84:87], v[104:107], v[4:7]
	v_mfma_f32_16x16x32_bf16 v[0:3], v[84:87], v[112:115], v[0:3]
	v_mfma_f32_16x16x32_bf16 v[184:187], v[56:59], v[92:95], v[88:91]
	v_mfma_f32_16x16x32_bf16 v[190:193], v[56:59], v[104:107], v[80:83]
	v_mfma_f32_16x16x32_bf16 v[194:197], v[56:59], v[112:115], v[76:79]
	v_mfma_f32_16x16x32_bf16 v[56:59], v[56:59], v[116:119], v[64:67]
	v_mfma_f32_16x16x32_bf16 v[198:201], v[68:71], v[92:95], v[60:63]
	v_mfma_f32_16x16x32_bf16 v[52:55], v[68:71], v[104:107], v[52:55]
	v_mfma_f32_16x16x32_bf16 v[204:207], v[68:71], v[112:115], v[44:47]
	v_mfma_f32_16x16x32_bf16 v[208:211], v[68:71], v[116:119], v[36:39]
	v_mfma_f32_16x16x32_bf16 v[212:215], v[72:75], v[92:95], v[32:35]
	v_mfma_f32_16x16x32_bf16 v[216:219], v[72:75], v[104:107], v[28:31]
	v_mfma_f32_16x16x32_bf16 v[140:143], v[84:87], v[116:119], v[140:143]
	s_nop 1
	ds_read_b128 v[28:31], v183
	ds_read_b128 v[32:35], v183 offset:2048
	ds_read_b128 v[36:39], v183 offset:4096
	ds_read_b128 v[44:47], v183 offset:6144
	ds_read_b128 v[220:223], v183 offset:8192
	ds_read_b128 v[224:227], v183 offset:10240
	ds_read_b128 v[228:231], v183 offset:12288
	ds_read_b128 v[232:235], v183 offset:14336
	ds_read_b128 v[236:239], v182 offset:32768
	ds_read_b128 v[240:243], v182 offset:34816
	ds_read_b128 v[244:247], v182 offset:36864
	ds_read_b128 v[248:251], v182 offset:38912
	s_waitcnt lgkmcnt(3)
	v_mfma_f32_16x16x32_bf16 v[124:127], v[28:31], v[236:239], v[172:175]
	v_readlane_b32 s16, v255, 27
	s_mov_b64 s[30:31], 0
	v_readlane_b32 s17, v255, 28
	s_waitcnt lgkmcnt(2)
	v_mfma_f32_16x16x32_bf16 v[120:123], v[28:31], v[240:243], v[168:171]
	v_readlane_b32 s11, v255, 16
	v_readlane_b32 s10, v255, 18
	s_waitcnt lgkmcnt(1)
	v_mfma_f32_16x16x32_bf16 v[116:119], v[28:31], v[244:247], v[164:167]
	s_waitcnt lgkmcnt(0)
	v_mfma_f32_16x16x32_bf16 v[112:115], v[28:31], v[248:251], v[20:23]
	v_mfma_f32_16x16x32_bf16 v[108:111], v[32:35], v[236:239], v[156:159]
	v_mfma_f32_16x16x32_bf16 v[104:107], v[32:35], v[240:243], v[152:155]
	v_mfma_f32_16x16x32_bf16 v[100:103], v[32:35], v[244:247], v[148:151]
	v_mfma_f32_16x16x32_bf16 v[96:99], v[32:35], v[248:251], v[24:27]
	v_mfma_f32_16x16x32_bf16 v[92:95], v[36:39], v[236:239], v[136:139]
	v_mfma_f32_16x16x32_bf16 v[88:91], v[36:39], v[240:243], v[132:135]
	v_mfma_f32_16x16x32_bf16 v[84:87], v[36:39], v[244:247], v[128:131]
	v_mfma_f32_16x16x32_bf16 v[80:83], v[36:39], v[248:251], v[40:43]
	v_mfma_f32_16x16x32_bf16 v[76:79], v[44:47], v[236:239], v[144:147]
	v_mfma_f32_16x16x32_bf16 v[72:75], v[44:47], v[240:243], v[160:163]
	v_mfma_f32_16x16x32_bf16 v[68:71], v[44:47], v[244:247], v[178:181]
	v_mfma_f32_16x16x32_bf16 v[64:67], v[44:47], v[248:251], v[48:51]
	v_mfma_f32_16x16x32_bf16 v[60:63], v[220:223], v[236:239], v[184:187]
	v_mfma_f32_16x16x32_bf16 v[156:159], v[220:223], v[240:243], v[190:193]
	v_mfma_f32_16x16x32_bf16 v[152:155], v[220:223], v[244:247], v[194:197]
	v_mfma_f32_16x16x32_bf16 v[48:51], v[220:223], v[248:251], v[56:59]
	v_mfma_f32_16x16x32_bf16 v[44:47], v[224:227], v[236:239], v[198:201]
	v_mfma_f32_16x16x32_bf16 v[40:43], v[224:227], v[240:243], v[52:55]
	v_mfma_f32_16x16x32_bf16 v[36:39], v[224:227], v[244:247], v[204:207]
	v_mfma_f32_16x16x32_bf16 v[32:35], v[224:227], v[248:251], v[208:211]
	v_mfma_f32_16x16x32_bf16 v[28:31], v[228:231], v[236:239], v[212:215]
	v_mfma_f32_16x16x32_bf16 v[24:27], v[228:231], v[240:243], v[216:219]
	v_mfma_f32_16x16x32_bf16 v[20:23], v[228:231], v[244:247], v[16:19]
	v_mfma_f32_16x16x32_bf16 v[16:19], v[228:231], v[248:251], v[12:15]
	v_mfma_f32_16x16x32_bf16 v[12:15], v[232:235], v[236:239], v[8:11]
	v_mfma_f32_16x16x32_bf16 v[8:11], v[232:235], v[240:243], v[4:7]
	v_xor_b32_e32 v240, 32, v203
	v_mfma_f32_16x16x32_bf16 v[0:3], v[232:235], v[244:247], v[0:3]
	v_mfma_f32_16x16x32_bf16 v[4:7], v[232:235], v[248:251], v[140:143]
.LBB0_426:
	s_and_b64 vcc, exec, s[30:31]
	s_cbranch_vccz .LBB0_430
	s_nop 5
	v_mov_b32_e32 v6, v188
	s_mov_b32 s15, 0x1c000
	v_ashrrev_i32_e32 v7, 3, v6
	v_lshlrev_b32_e32 v4, 4, v6
	v_and_b32_e32 v176, 0x70, v4
	v_add_u32_e32 v4, s94, v7
	v_ashrrev_i32_e32 v5, 31, v4
	v_add_u32_e32 v0, s8, v7
	v_lshlrev_b64 v[4:5], 9, v[4:5]
	v_ashrrev_i32_e32 v1, 31, v0
	v_lshl_add_u64 v[4:5], s[42:43], 0, v[4:5]
	v_xor_b32_e32 v8, v7, v6
	v_lshlrev_b64 v[0:1], 9, v[0:1]
	v_lshl_add_u64 v[178:179], v[4:5], 0, v[176:177]
	v_lshlrev_b32_e32 v4, 4, v8
	v_lshl_add_u64 v[2:3], s[46:47], 0, v[0:1]
	v_and_b32_e32 v4, 0x70, v4
	v_lshl_add_u64 v[2:3], v[2:3], 0, v[176:177]
	v_lshl_or_b32 v176, v7, 7, v4
	v_lshrrev_b32_e32 v4, 4, v6
	v_and_b32_e32 v11, 7, v6
	v_bitop3_b32 v12, v4, v11, 3 bitop3:0x6c
	v_add_co_u32_e32 v4, vcc, s28, v178
	s_mov_b32 s42, 0x8000
	s_nop 0
	v_addc_co_u32_e32 v5, vcc, 0, v179, vcc
	v_lshlrev_b32_e32 v8, 7, v6
	v_bfe_u32 v10, v6, 4, 2
	v_add_co_u32_e32 v6, vcc, s42, v178
	s_movk_i32 s43, 0x4000
	s_nop 0
	v_addc_co_u32_e32 v7, vcc, 0, v179, vcc
	global_load_dwordx4 v[20:23], v[4:5], off
	global_load_dwordx4 v[24:27], v[6:7], off
	v_add_co_u32_e32 v4, vcc, s43, v178
	v_and_b32_e32 v9, 0xffffc780, v8
	s_nop 0
	v_addc_co_u32_e32 v5, vcc, 0, v179, vcc
	v_add_co_u32_e32 v6, vcc, s15, v2
	s_mov_b32 s15, 0x18000
	s_nop 0
	v_addc_co_u32_e32 v7, vcc, 0, v3, vcc
	global_load_dwordx4 v[40:43], v[4:5], off
	global_load_dwordx4 v[48:51], v[6:7], off
	v_add_co_u32_e32 v4, vcc, s15, v2
	s_mov_b32 s15, 0x14000
	s_nop 0
	v_addc_co_u32_e32 v5, vcc, 0, v3, vcc
	v_add_co_u32_e32 v6, vcc, s15, v2
	v_and_b32_e32 v8, 0x2780, v8
	s_nop 0
	v_addc_co_u32_e32 v7, vcc, 0, v3, vcc
	global_load_dwordx4 v[68:71], v[4:5], off
	global_load_dwordx4 v[72:75], v[6:7], off
	v_add_co_u32_e32 v4, vcc, s14, v2
	v_bitop3_b32 v10, v10, v11, 4 bitop3:0x36
	s_nop 0
	v_addc_co_u32_e32 v5, vcc, 0, v3, vcc
	v_add_co_u32_e32 v6, vcc, s28, v2
	v_lshl_or_b32 v0, v11, 4, v0
	s_nop 0
	v_addc_co_u32_e32 v7, vcc, 0, v3, vcc
	global_load_dwordx4 v[84:87], v[4:5], off
	global_load_dwordx4 v[92:95], v[6:7], off
	v_add_co_u32_e32 v4, vcc, s42, v2
	v_mov_b32_e32 v140, 0
	s_nop 0
	v_addc_co_u32_e32 v5, vcc, 0, v3, vcc
	v_add_co_u32_e32 v6, vcc, s43, v2
	v_lshl_add_u64 v[180:181], s[58:59], 0, v[0:1]
	s_nop 0
	v_addc_co_u32_e32 v7, vcc, 0, v3, vcc
	global_load_dwordx4 v[104:107], v[4:5], off
	global_load_dwordx4 v[112:115], v[6:7], off
	global_load_dwordx4 v[56:59], v[178:179], off
	global_load_dwordx4 v[116:119], v[2:3], off
	v_lshlrev_b32_e32 v2, 4, v12
	v_or_b32_e32 v185, v9, v2
	v_or_b32_e32 v184, v8, v2
	v_lshlrev_b32_e32 v2, 4, v10
	v_or_b32_e32 v183, v9, v2
	v_or_b32_e32 v182, v8, v2
	s_mov_b64 s[30:31], 0
	v_mov_b32_e32 v141, v140
	v_mov_b32_e32 v142, v140
	v_mov_b32_e32 v143, v140
	v_mov_b32_e32 v0, v140
	v_mov_b32_e32 v1, v140
	v_mov_b32_e32 v2, v140
	v_mov_b32_e32 v3, v140
	v_mov_b32_e32 v4, v140
	v_mov_b32_e32 v5, v140
	v_mov_b32_e32 v6, v140
	v_mov_b32_e32 v7, v140
	v_mov_b32_e32 v8, v140
	v_mov_b32_e32 v9, v140
	v_mov_b32_e32 v10, v140
	v_mov_b32_e32 v11, v140
	v_mov_b32_e32 v12, v140
	v_mov_b32_e32 v13, v140
	v_mov_b32_e32 v14, v140
	v_mov_b32_e32 v15, v140
	v_mov_b32_e32 v16, v140
	v_mov_b32_e32 v17, v140
	v_mov_b32_e32 v18, v140
	v_mov_b32_e32 v19, v140
	v_mov_b32_e32 v28, v140
	v_mov_b32_e32 v29, v140
	v_mov_b32_e32 v30, v140
	v_mov_b32_e32 v31, v140
	v_mov_b32_e32 v32, v140
	v_mov_b32_e32 v33, v140
	v_mov_b32_e32 v34, v140
	v_mov_b32_e32 v35, v140
	v_mov_b32_e32 v36, v140
	v_mov_b32_e32 v37, v140
	v_mov_b32_e32 v38, v140
	v_mov_b32_e32 v39, v140
	v_mov_b32_e32 v44, v140
	v_mov_b32_e32 v45, v140
	v_mov_b32_e32 v46, v140
	v_mov_b32_e32 v47, v140
	v_mov_b32_e32 v52, v140
	v_mov_b32_e32 v53, v140
	v_mov_b32_e32 v54, v140
	v_mov_b32_e32 v55, v140
	v_mov_b32_e32 v60, v140
	v_mov_b32_e32 v61, v140
	v_mov_b32_e32 v62, v140
	v_mov_b32_e32 v63, v140
	v_mov_b32_e32 v64, v140
	v_mov_b32_e32 v65, v140
	v_mov_b32_e32 v66, v140
	v_mov_b32_e32 v67, v140
	v_mov_b32_e32 v76, v140
	v_mov_b32_e32 v77, v140
	v_mov_b32_e32 v78, v140
	v_mov_b32_e32 v79, v140
	v_mov_b32_e32 v80, v140
	v_mov_b32_e32 v81, v140
	v_mov_b32_e32 v82, v140
	v_mov_b32_e32 v83, v140
	v_mov_b32_e32 v88, v140
	v_mov_b32_e32 v89, v140
	v_mov_b32_e32 v90, v140
	v_mov_b32_e32 v91, v140
	v_mov_b32_e32 v96, v140
	v_mov_b32_e32 v97, v140
	v_mov_b32_e32 v98, v140
	v_mov_b32_e32 v99, v140
	v_mov_b32_e32 v100, v140
	v_mov_b32_e32 v101, v140
	v_mov_b32_e32 v102, v140
	v_mov_b32_e32 v103, v140
	v_mov_b32_e32 v108, v140
	v_mov_b32_e32 v109, v140
	v_mov_b32_e32 v110, v140
	v_mov_b32_e32 v111, v140
	v_mov_b32_e32 v120, v140
	v_mov_b32_e32 v121, v140
	v_mov_b32_e32 v122, v140
	v_mov_b32_e32 v123, v140
	v_mov_b32_e32 v124, v140
	v_mov_b32_e32 v125, v140
	v_mov_b32_e32 v126, v140
	v_mov_b32_e32 v127, v140
	v_mov_b32_e32 v128, v140
	v_mov_b32_e32 v129, v140
	v_mov_b32_e32 v130, v140
	v_mov_b32_e32 v131, v140
	v_mov_b32_e32 v132, v140
	v_mov_b32_e32 v133, v140
	v_mov_b32_e32 v134, v140
	v_mov_b32_e32 v135, v140
	v_mov_b32_e32 v136, v140
	v_mov_b32_e32 v137, v140
	v_mov_b32_e32 v138, v140
	v_mov_b32_e32 v139, v140
	v_mov_b32_e32 v144, v140
	v_mov_b32_e32 v145, v140
	v_mov_b32_e32 v146, v140
	v_mov_b32_e32 v147, v140
	v_mov_b32_e32 v148, v140
	v_mov_b32_e32 v149, v140
	v_mov_b32_e32 v150, v140
	v_mov_b32_e32 v151, v140
	v_mov_b32_e32 v152, v140
	v_mov_b32_e32 v153, v140
	v_mov_b32_e32 v154, v140
	v_mov_b32_e32 v155, v140
	v_mov_b32_e32 v156, v140
	v_mov_b32_e32 v157, v140
	v_mov_b32_e32 v158, v140
	v_mov_b32_e32 v159, v140
	v_mov_b32_e32 v160, v140
	v_mov_b32_e32 v161, v140
	v_mov_b32_e32 v162, v140
	v_mov_b32_e32 v163, v140
	v_mov_b32_e32 v164, v140
	v_mov_b32_e32 v165, v140
	v_mov_b32_e32 v166, v140
	v_mov_b32_e32 v167, v140
	v_mov_b32_e32 v168, v140
	v_mov_b32_e32 v169, v140
	v_mov_b32_e32 v170, v140
	v_mov_b32_e32 v171, v140
	v_mov_b32_e32 v172, v140
	v_mov_b32_e32 v173, v140
	v_mov_b32_e32 v174, v140
	v_mov_b32_e32 v175, v140
	s_mov_b32 s14, 0xad00000
	s_mov_b32 s15, 0xad04000
	s_mov_b32 s16, 0xad08000
	s_mov_b32 s17, 0xad0c000
	s_mov_b32 s10, 0xad10000
	s_mov_b32 s11, 0xad14000
	s_mov_b32 s12, 0xad18000
	s_mov_b32 s13, 0xad1c000
	s_setprio 2
	v_readlane_b32 s98, v253, 3
	v_readlane_b32 s99, v253, 4
	v_and_b32_e32 v224, 15, v188
	v_bfe_u32 v225, v188, 4, 2
	v_lshrrev_b32_e32 v226, 2, v224
	v_sub_u32_e32 v226, 0, v226
	v_and_b32_e32 v226, 3, v226
	v_xor_b32_e32 v225, v225, v226
	v_lshlrev_b32_e32 v225, 4, v225
	v_lshl_or_b32 v225, v224, 6, v225
	v_bfe_u32 v226, v188, 7, 1
	v_lshl_or_b32 v185, v226, 13, v225
	v_bfe_u32 v226, v188, 6, 1
	v_lshl_or_b32 v184, v226, 12, v225
	v_add_u32_e32 v184, 0x4000, v184
	v_lshrrev_b32_e32 v224, 3, v188
	v_bfe_u32 v225, v188, 2, 1
	v_lshrrev_b32_e32 v226, 2, v224
	v_sub_u32_e32 v226, 0, v226
	v_and_b32_e32 v226, 3, v226
	v_and_b32_e32 v227, 3, v188
	v_xor_b32_e32 v226, v227, v226
	v_lshlrev_b32_e32 v226, 4, v226
	v_xor_b32_e32 v224, v224, v225
	v_lshl_or_b32 v226, v224, 6, v226
	v_mul_u32_u24_e32 v225, 0x6000, v225
	v_add_u32_e32 v183, v225, v226
	s_mov_b32 m0, 0
	s_sub_u32 vcc_lo, s30, s98
	v_add_u32_e32 v186, vcc_lo, v178
	v_add_u32_e32 v187, vcc_lo, v180
	s_barrier
	s_waitcnt vmcnt(0)
	ds_write_b128 v183, v[116:119]
	ds_write_b128 v183, v[112:115] offset:2048
	ds_write_b128 v183, v[104:107] offset:4096
	ds_write_b128 v183, v[92:95] offset:6144
	ds_write_b128 v183, v[84:87] offset:8192
	ds_write_b128 v183, v[72:75] offset:10240
	ds_write_b128 v183, v[68:71] offset:12288
	ds_write_b128 v183, v[48:51] offset:14336
	ds_write_b128 v183, v[56:59] offset:16384
	ds_write_b128 v183, v[40:43] offset:18432
	ds_write_b128 v183, v[24:27] offset:20480
	ds_write_b128 v183, v[20:23] offset:22528
	v_cmp_gt_u32_e32 vcc, 0x6000, v183
	v_add_u32_e32 v182, 0xc000, v183
	v_add_u32_e32 v183, 0xffffa000, v183
	s_nop 0
	v_cndmask_b32_e32 v183, v183, v182, vcc
	v_add_u32_e32 v116, s14, v187
	global_load_dwordx4 v[116:119], v116, s[98:99] offset:128
	v_add_u32_e32 v112, s15, v187
	global_load_dwordx4 v[112:115], v112, s[98:99] offset:128
	v_add_u32_e32 v104, s16, v187
	global_load_dwordx4 v[104:107], v104, s[98:99] offset:128
	v_add_u32_e32 v92, s17, v187
	global_load_dwordx4 v[92:95], v92, s[98:99] offset:128
	v_add_u32_e32 v84, s10, v187
	global_load_dwordx4 v[84:87], v84, s[98:99] offset:128
	v_add_u32_e32 v72, s11, v187
	global_load_dwordx4 v[72:75], v72, s[98:99] offset:128
	v_add_u32_e32 v68, s12, v187
	global_load_dwordx4 v[68:71], v68, s[98:99] offset:128
	v_add_u32_e32 v48, s13, v187
	global_load_dwordx4 v[48:51], v48, s[98:99] offset:128
	v_mov_b32_e32 v56, v186
	global_load_dwordx4 v[56:59], v56, s[98:99] offset:128
	v_add_u32_e32 v40, s43, v186
	global_load_dwordx4 v[40:43], v40, s[98:99] offset:128
	v_add_u32_e32 v24, s42, v186
	global_load_dwordx4 v[24:27], v24, s[98:99] offset:128
	v_add_u32_e32 v20, s28, v186
	global_load_dwordx4 v[20:23], v20, s[98:99] offset:128
	s_add_u32 s30, s30, 0x80
	s_addc_u32 s31, s31, 0
.LBB0_428:
	s_waitcnt lgkmcnt(0)
	s_barrier
	ds_read_b128 v[224:227], v184
	ds_read_b128 v[228:231], v184 offset:1024
	ds_read_b128 v[232:235], v184 offset:2048
	ds_read_b128 v[236:239], v184 offset:3072
	ds_read_b128 v[190:193], v185
	ds_read_b128 v[194:197], v185 offset:1024
	ds_read_b128 v[198:201], v185 offset:2048
	ds_read_b128 v[204:207], v185 offset:3072
	ds_read_b128 v[208:211], v185 offset:4096
	ds_read_b128 v[212:215], v185 offset:5120
	ds_read_b128 v[216:219], v185 offset:6144
	ds_read_b128 v[220:223], v185 offset:7168
	s_movk_i32 vcc_lo, 0x6000
	s_cmp_eq_u32 m0, 2
	s_cselect_b32 vcc_lo, 0xffff4000, vcc_lo
	s_add_u32 m0, m0, 1
	s_cmp_eq_u32 m0, 3
	s_cselect_b32 m0, 0, m0
	v_add_u32_e32 v185, vcc_lo, v185
	v_add_u32_e32 v184, vcc_lo, v184
	v_xor_b32_e32 v185, 64, v185
	v_xor_b32_e32 v184, 64, v184
	s_waitcnt lgkmcnt(7)
	v_mfma_f32_16x16x32_bf16 v[172:175], v[224:227], v[190:193], v[172:175]
	v_mfma_f32_16x16x32_bf16 v[168:171], v[228:231], v[190:193], v[168:171]
	v_mfma_f32_16x16x32_bf16 v[164:167], v[232:235], v[190:193], v[164:167]
	v_mfma_f32_16x16x32_bf16 v[160:163], v[236:239], v[190:193], v[160:163]
	ds_read_b128 v[190:193], v185
	s_waitcnt lgkmcnt(7)
	v_mfma_f32_16x16x32_bf16 v[156:159], v[224:227], v[194:197], v[156:159]
	v_mfma_f32_16x16x32_bf16 v[152:155], v[228:231], v[194:197], v[152:155]
	v_mfma_f32_16x16x32_bf16 v[148:151], v[232:235], v[194:197], v[148:151]
	v_mfma_f32_16x16x32_bf16 v[144:147], v[236:239], v[194:197], v[144:147]
	ds_read_b128 v[194:197], v185 offset:1024
	s_waitcnt lgkmcnt(7)
	v_mfma_f32_16x16x32_bf16 v[136:139], v[224:227], v[198:201], v[136:139]
	v_mfma_f32_16x16x32_bf16 v[132:135], v[228:231], v[198:201], v[132:135]
	v_mfma_f32_16x16x32_bf16 v[128:131], v[232:235], v[198:201], v[128:131]
	v_mfma_f32_16x16x32_bf16 v[124:127], v[236:239], v[198:201], v[124:127]
	ds_read_b128 v[198:201], v185 offset:2048
	s_waitcnt lgkmcnt(7)
	v_mfma_f32_16x16x32_bf16 v[120:123], v[224:227], v[204:207], v[120:123]
	v_mfma_f32_16x16x32_bf16 v[108:111], v[228:231], v[204:207], v[108:111]
	v_mfma_f32_16x16x32_bf16 v[100:103], v[232:235], v[204:207], v[100:103]
	v_mfma_f32_16x16x32_bf16 v[96:99], v[236:239], v[204:207], v[96:99]
	ds_read_b128 v[204:207], v185 offset:3072
	s_waitcnt lgkmcnt(7)
	v_mfma_f32_16x16x32_bf16 v[88:91], v[224:227], v[208:211], v[88:91]
	v_mfma_f32_16x16x32_bf16 v[80:83], v[228:231], v[208:211], v[80:83]
	v_mfma_f32_16x16x32_bf16 v[76:79], v[232:235], v[208:211], v[76:79]
	v_mfma_f32_16x16x32_bf16 v[64:67], v[236:239], v[208:211], v[64:67]
	ds_read_b128 v[208:211], v185 offset:4096
	s_waitcnt lgkmcnt(7)
	v_mfma_f32_16x16x32_bf16 v[60:63], v[224:227], v[212:215], v[60:63]
	v_mfma_f32_16x16x32_bf16 v[52:55], v[228:231], v[212:215], v[52:55]
	v_mfma_f32_16x16x32_bf16 v[44:47], v[232:235], v[212:215], v[44:47]
	v_mfma_f32_16x16x32_bf16 v[36:39], v[236:239], v[212:215], v[36:39]
	ds_read_b128 v[212:215], v185 offset:5120
	s_waitcnt lgkmcnt(7)
	v_mfma_f32_16x16x32_bf16 v[32:35], v[224:227], v[216:219], v[32:35]
	v_mfma_f32_16x16x32_bf16 v[28:31], v[228:231], v[216:219], v[28:31]
	v_mfma_f32_16x16x32_bf16 v[16:19], v[232:235], v[216:219], v[16:19]
	v_mfma_f32_16x16x32_bf16 v[12:15], v[236:239], v[216:219], v[12:15]
	ds_read_b128 v[216:219], v185 offset:6144
	s_waitcnt lgkmcnt(7)
	v_mfma_f32_16x16x32_bf16 v[8:11], v[224:227], v[220:223], v[8:11]
	v_mfma_f32_16x16x32_bf16 v[4:7], v[228:231], v[220:223], v[4:7]
	v_mfma_f32_16x16x32_bf16 v[0:3], v[232:235], v[220:223], v[0:3]
	v_mfma_f32_16x16x32_bf16 v[140:143], v[236:239], v[220:223], v[140:143]
	ds_read_b128 v[220:223], v185 offset:7168
	ds_read_b128 v[224:227], v184
	ds_read_b128 v[228:231], v184 offset:1024
	ds_read_b128 v[232:235], v184 offset:2048
	ds_read_b128 v[236:239], v184 offset:3072
	s_movk_i32 vcc_lo, 0x6000
	s_cmp_eq_u32 m0, 2
	s_cselect_b32 vcc_lo, 0xffff4000, vcc_lo
	s_add_u32 m0, m0, 1
	s_cmp_eq_u32 m0, 3
	s_cselect_b32 m0, 0, m0
	v_add_u32_e32 v185, vcc_lo, v185
	v_add_u32_e32 v184, vcc_lo, v184
	v_xor_b32_e32 v185, 64, v185
	v_xor_b32_e32 v184, 64, v184
	s_sub_u32 vcc_lo, s30, s98
	v_add_u32_e32 v186, vcc_lo, v178
	v_add_u32_e32 v187, vcc_lo, v180
	s_barrier
	s_waitcnt lgkmcnt(0)
	v_mfma_f32_16x16x32_bf16 v[172:175], v[224:227], v[190:193], v[172:175]
	s_waitcnt vmcnt(11)
	v_mfma_f32_16x16x32_bf16 v[168:171], v[228:231], v[190:193], v[168:171]
	ds_write_b128 v183, v[116:119]
	v_add_u32_e32 v116, s14, v187
	v_mfma_f32_16x16x32_bf16 v[164:167], v[232:235], v[190:193], v[164:167]
	global_load_dwordx4 v[116:119], v116, s[98:99] offset:128
	v_mfma_f32_16x16x32_bf16 v[160:163], v[236:239], v[190:193], v[160:163]
	s_waitcnt vmcnt(11)
	ds_write_b128 v183, v[112:115] offset:2048
	v_mfma_f32_16x16x32_bf16 v[156:159], v[224:227], v[194:197], v[156:159]
	v_add_u32_e32 v112, s15, v187
	v_mfma_f32_16x16x32_bf16 v[152:155], v[228:231], v[194:197], v[152:155]
	global_load_dwordx4 v[112:115], v112, s[98:99] offset:128
	s_waitcnt vmcnt(11)
	v_mfma_f32_16x16x32_bf16 v[148:151], v[232:235], v[194:197], v[148:151]
	ds_write_b128 v183, v[104:107] offset:4096
	v_mfma_f32_16x16x32_bf16 v[144:147], v[236:239], v[194:197], v[144:147]
	v_add_u32_e32 v104, s16, v187
	global_load_dwordx4 v[104:107], v104, s[98:99] offset:128
	v_mfma_f32_16x16x32_bf16 v[136:139], v[224:227], v[198:201], v[136:139]
	s_waitcnt vmcnt(11)
	v_mfma_f32_16x16x32_bf16 v[132:135], v[228:231], v[198:201], v[132:135]
	ds_write_b128 v183, v[92:95] offset:6144
	v_add_u32_e32 v92, s17, v187
	v_mfma_f32_16x16x32_bf16 v[128:131], v[232:235], v[198:201], v[128:131]
	global_load_dwordx4 v[92:95], v92, s[98:99] offset:128
	v_mfma_f32_16x16x32_bf16 v[124:127], v[236:239], v[198:201], v[124:127]
	s_waitcnt vmcnt(11)
	ds_write_b128 v183, v[84:87] offset:8192
	v_mfma_f32_16x16x32_bf16 v[120:123], v[224:227], v[204:207], v[120:123]
	v_add_u32_e32 v84, s10, v187
	v_mfma_f32_16x16x32_bf16 v[108:111], v[228:231], v[204:207], v[108:111]
	global_load_dwordx4 v[84:87], v84, s[98:99] offset:128
	s_waitcnt vmcnt(11)
	v_mfma_f32_16x16x32_bf16 v[100:103], v[232:235], v[204:207], v[100:103]
	ds_write_b128 v183, v[72:75] offset:10240
	v_mfma_f32_16x16x32_bf16 v[96:99], v[236:239], v[204:207], v[96:99]
	v_add_u32_e32 v72, s11, v187
	global_load_dwordx4 v[72:75], v72, s[98:99] offset:128
	v_mfma_f32_16x16x32_bf16 v[88:91], v[224:227], v[208:211], v[88:91]
	s_waitcnt vmcnt(11)
	v_mfma_f32_16x16x32_bf16 v[80:83], v[228:231], v[208:211], v[80:83]
	ds_write_b128 v183, v[68:71] offset:12288
	v_add_u32_e32 v68, s12, v187
	v_mfma_f32_16x16x32_bf16 v[76:79], v[232:235], v[208:211], v[76:79]
	global_load_dwordx4 v[68:71], v68, s[98:99] offset:128
	v_mfma_f32_16x16x32_bf16 v[64:67], v[236:239], v[208:211], v[64:67]
	s_waitcnt vmcnt(11)
	ds_write_b128 v183, v[48:51] offset:14336
	v_mfma_f32_16x16x32_bf16 v[60:63], v[224:227], v[212:215], v[60:63]
	v_add_u32_e32 v48, s13, v187
	v_mfma_f32_16x16x32_bf16 v[52:55], v[228:231], v[212:215], v[52:55]
	global_load_dwordx4 v[48:51], v48, s[98:99] offset:128
	s_waitcnt vmcnt(11)
	v_mfma_f32_16x16x32_bf16 v[44:47], v[232:235], v[212:215], v[44:47]
	ds_write_b128 v183, v[56:59] offset:16384
	v_mfma_f32_16x16x32_bf16 v[36:39], v[236:239], v[212:215], v[36:39]
	v_mov_b32_e32 v56, v186
	global_load_dwordx4 v[56:59], v56, s[98:99] offset:128
	v_mfma_f32_16x16x32_bf16 v[32:35], v[224:227], v[216:219], v[32:35]
	s_waitcnt vmcnt(11)
	v_mfma_f32_16x16x32_bf16 v[28:31], v[228:231], v[216:219], v[28:31]
	ds_write_b128 v183, v[40:43] offset:18432
	v_add_u32_e32 v40, s43, v186
	v_mfma_f32_16x16x32_bf16 v[16:19], v[232:235], v[216:219], v[16:19]
	global_load_dwordx4 v[40:43], v40, s[98:99] offset:128
	v_mfma_f32_16x16x32_bf16 v[12:15], v[236:239], v[216:219], v[12:15]
	s_waitcnt vmcnt(11)
	ds_write_b128 v183, v[24:27] offset:20480
	v_mfma_f32_16x16x32_bf16 v[8:11], v[224:227], v[220:223], v[8:11]
	v_add_u32_e32 v24, s42, v186
	v_mfma_f32_16x16x32_bf16 v[4:7], v[228:231], v[220:223], v[4:7]
	global_load_dwordx4 v[24:27], v24, s[98:99] offset:128
	s_waitcnt vmcnt(11)
	v_mfma_f32_16x16x32_bf16 v[0:3], v[232:235], v[220:223], v[0:3]
	ds_write_b128 v183, v[20:23] offset:22528
	v_mfma_f32_16x16x32_bf16 v[140:143], v[236:239], v[220:223], v[140:143]
	v_add_u32_e32 v20, s28, v186
	global_load_dwordx4 v[20:23], v20, s[98:99] offset:128
	v_cmp_gt_u32_e32 vcc, 0x6000, v183
	v_add_u32_e32 v182, 0xc000, v183
	v_add_u32_e32 v183, 0xffffa000, v183
	s_nop 0
	v_cndmask_b32_e32 v183, v183, v182, vcc
	s_add_u32 s30, s30, 0x80
	s_addc_u32 s31, s31, 0
	s_cmpk_lg_i32 s30, 0x180
	s_cbranch_scc1 .LBB0_428
	s_waitcnt lgkmcnt(0)
	s_barrier
	ds_read_b128 v[224:227], v184
	ds_read_b128 v[228:231], v184 offset:1024
	ds_read_b128 v[232:235], v184 offset:2048
	ds_read_b128 v[236:239], v184 offset:3072
	ds_read_b128 v[190:193], v185
	ds_read_b128 v[194:197], v185 offset:1024
	ds_read_b128 v[198:201], v185 offset:2048
	ds_read_b128 v[204:207], v185 offset:3072
	ds_read_b128 v[208:211], v185 offset:4096
	ds_read_b128 v[212:215], v185 offset:5120
	ds_read_b128 v[216:219], v185 offset:6144
	ds_read_b128 v[220:223], v185 offset:7168
	s_movk_i32 vcc_lo, 0x6000
	s_cmp_eq_u32 m0, 2
	s_cselect_b32 vcc_lo, 0xffff4000, vcc_lo
	s_add_u32 m0, m0, 1
	s_cmp_eq_u32 m0, 3
	s_cselect_b32 m0, 0, m0
	v_add_u32_e32 v185, vcc_lo, v185
	v_add_u32_e32 v184, vcc_lo, v184
	v_xor_b32_e32 v185, 64, v185
	v_xor_b32_e32 v184, 64, v184
	s_waitcnt lgkmcnt(7)
	v_mfma_f32_16x16x32_bf16 v[172:175], v[224:227], v[190:193], v[172:175]
	v_mfma_f32_16x16x32_bf16 v[168:171], v[228:231], v[190:193], v[168:171]
	v_mfma_f32_16x16x32_bf16 v[164:167], v[232:235], v[190:193], v[164:167]
	v_mfma_f32_16x16x32_bf16 v[160:163], v[236:239], v[190:193], v[160:163]
	ds_read_b128 v[190:193], v185
	s_waitcnt lgkmcnt(7)
	v_mfma_f32_16x16x32_bf16 v[156:159], v[224:227], v[194:197], v[156:159]
	v_mfma_f32_16x16x32_bf16 v[152:155], v[228:231], v[194:197], v[152:155]
	v_mfma_f32_16x16x32_bf16 v[148:151], v[232:235], v[194:197], v[148:151]
	v_mfma_f32_16x16x32_bf16 v[144:147], v[236:239], v[194:197], v[144:147]
	ds_read_b128 v[194:197], v185 offset:1024
	s_waitcnt lgkmcnt(7)
	v_mfma_f32_16x16x32_bf16 v[136:139], v[224:227], v[198:201], v[136:139]
	v_mfma_f32_16x16x32_bf16 v[132:135], v[228:231], v[198:201], v[132:135]
	v_mfma_f32_16x16x32_bf16 v[128:131], v[232:235], v[198:201], v[128:131]
	v_mfma_f32_16x16x32_bf16 v[124:127], v[236:239], v[198:201], v[124:127]
	ds_read_b128 v[198:201], v185 offset:2048
	s_waitcnt lgkmcnt(7)
	v_mfma_f32_16x16x32_bf16 v[120:123], v[224:227], v[204:207], v[120:123]
	v_mfma_f32_16x16x32_bf16 v[108:111], v[228:231], v[204:207], v[108:111]
	v_mfma_f32_16x16x32_bf16 v[100:103], v[232:235], v[204:207], v[100:103]
	v_mfma_f32_16x16x32_bf16 v[96:99], v[236:239], v[204:207], v[96:99]
	ds_read_b128 v[204:207], v185 offset:3072
	s_waitcnt lgkmcnt(7)
	v_mfma_f32_16x16x32_bf16 v[88:91], v[224:227], v[208:211], v[88:91]
	v_mfma_f32_16x16x32_bf16 v[80:83], v[228:231], v[208:211], v[80:83]
	v_mfma_f32_16x16x32_bf16 v[76:79], v[232:235], v[208:211], v[76:79]
	v_mfma_f32_16x16x32_bf16 v[64:67], v[236:239], v[208:211], v[64:67]
	ds_read_b128 v[208:211], v185 offset:4096
	s_waitcnt lgkmcnt(7)
	v_mfma_f32_16x16x32_bf16 v[60:63], v[224:227], v[212:215], v[60:63]
	v_mfma_f32_16x16x32_bf16 v[52:55], v[228:231], v[212:215], v[52:55]
	v_mfma_f32_16x16x32_bf16 v[44:47], v[232:235], v[212:215], v[44:47]
	v_mfma_f32_16x16x32_bf16 v[36:39], v[236:239], v[212:215], v[36:39]
	ds_read_b128 v[212:215], v185 offset:5120
	s_waitcnt lgkmcnt(7)
	v_mfma_f32_16x16x32_bf16 v[32:35], v[224:227], v[216:219], v[32:35]
	v_mfma_f32_16x16x32_bf16 v[28:31], v[228:231], v[216:219], v[28:31]
	v_mfma_f32_16x16x32_bf16 v[16:19], v[232:235], v[216:219], v[16:19]
	v_mfma_f32_16x16x32_bf16 v[12:15], v[236:239], v[216:219], v[12:15]
	ds_read_b128 v[216:219], v185 offset:6144
	s_waitcnt lgkmcnt(7)
	v_mfma_f32_16x16x32_bf16 v[8:11], v[224:227], v[220:223], v[8:11]
	v_mfma_f32_16x16x32_bf16 v[4:7], v[228:231], v[220:223], v[4:7]
	v_mfma_f32_16x16x32_bf16 v[0:3], v[232:235], v[220:223], v[0:3]
	v_mfma_f32_16x16x32_bf16 v[140:143], v[236:239], v[220:223], v[140:143]
	ds_read_b128 v[220:223], v185 offset:7168
	ds_read_b128 v[224:227], v184
	ds_read_b128 v[228:231], v184 offset:1024
	ds_read_b128 v[232:235], v184 offset:2048
	ds_read_b128 v[236:239], v184 offset:3072
	s_movk_i32 vcc_lo, 0x6000
	s_cmp_eq_u32 m0, 2
	s_cselect_b32 vcc_lo, 0xffff4000, vcc_lo
	s_add_u32 m0, m0, 1
	s_cmp_eq_u32 m0, 3
	s_cselect_b32 m0, 0, m0
	v_add_u32_e32 v185, vcc_lo, v185
	v_add_u32_e32 v184, vcc_lo, v184
	v_xor_b32_e32 v185, 64, v185
	v_xor_b32_e32 v184, 64, v184
	s_waitcnt lgkmcnt(0)
	v_mfma_f32_16x16x32_bf16 v[172:175], v[224:227], v[190:193], v[172:175]
	v_mfma_f32_16x16x32_bf16 v[168:171], v[228:231], v[190:193], v[168:171]
	v_mfma_f32_16x16x32_bf16 v[164:167], v[232:235], v[190:193], v[164:167]
	v_mfma_f32_16x16x32_bf16 v[160:163], v[236:239], v[190:193], v[160:163]
	v_mfma_f32_16x16x32_bf16 v[156:159], v[224:227], v[194:197], v[156:159]
	v_mfma_f32_16x16x32_bf16 v[152:155], v[228:231], v[194:197], v[152:155]
	v_mfma_f32_16x16x32_bf16 v[148:151], v[232:235], v[194:197], v[148:151]
	v_mfma_f32_16x16x32_bf16 v[144:147], v[236:239], v[194:197], v[144:147]
	v_mfma_f32_16x16x32_bf16 v[136:139], v[224:227], v[198:201], v[136:139]
	v_mfma_f32_16x16x32_bf16 v[132:135], v[228:231], v[198:201], v[132:135]
	v_mfma_f32_16x16x32_bf16 v[128:131], v[232:235], v[198:201], v[128:131]
	v_mfma_f32_16x16x32_bf16 v[124:127], v[236:239], v[198:201], v[124:127]
	v_mfma_f32_16x16x32_bf16 v[120:123], v[224:227], v[204:207], v[120:123]
	v_mfma_f32_16x16x32_bf16 v[108:111], v[228:231], v[204:207], v[108:111]
	v_mfma_f32_16x16x32_bf16 v[100:103], v[232:235], v[204:207], v[100:103]
	v_mfma_f32_16x16x32_bf16 v[96:99], v[236:239], v[204:207], v[96:99]
	v_mfma_f32_16x16x32_bf16 v[88:91], v[224:227], v[208:211], v[88:91]
	v_mfma_f32_16x16x32_bf16 v[80:83], v[228:231], v[208:211], v[80:83]
	v_mfma_f32_16x16x32_bf16 v[76:79], v[232:235], v[208:211], v[76:79]
	v_mfma_f32_16x16x32_bf16 v[64:67], v[236:239], v[208:211], v[64:67]
	v_mfma_f32_16x16x32_bf16 v[60:63], v[224:227], v[212:215], v[60:63]
	v_mfma_f32_16x16x32_bf16 v[52:55], v[228:231], v[212:215], v[52:55]
	v_mfma_f32_16x16x32_bf16 v[44:47], v[232:235], v[212:215], v[44:47]
	v_mfma_f32_16x16x32_bf16 v[36:39], v[236:239], v[212:215], v[36:39]
	v_mfma_f32_16x16x32_bf16 v[32:35], v[224:227], v[216:219], v[32:35]
	v_mfma_f32_16x16x32_bf16 v[28:31], v[228:231], v[216:219], v[28:31]
	v_mfma_f32_16x16x32_bf16 v[16:19], v[232:235], v[216:219], v[16:19]
	v_mfma_f32_16x16x32_bf16 v[12:15], v[236:239], v[216:219], v[12:15]
	v_mfma_f32_16x16x32_bf16 v[8:11], v[224:227], v[220:223], v[8:11]
	v_mfma_f32_16x16x32_bf16 v[4:7], v[228:231], v[220:223], v[4:7]
	v_mfma_f32_16x16x32_bf16 v[0:3], v[232:235], v[220:223], v[0:3]
	v_mfma_f32_16x16x32_bf16 v[140:143], v[236:239], v[220:223], v[140:143]
	v_lshrrev_b32_e32 v224, 4, v188
	v_and_b32_e32 v225, 7, v188
	v_bitop3_b32 v226, v224, v225, 3 bitop3:0x6c
	v_lshlrev_b32_e32 v227, 7, v188
	v_bfe_u32 v228, v188, 4, 2
	v_and_b32_e32 v229, 0xffffc780, v227
	v_and_b32_e32 v227, 0x2780, v227
	v_bitop3_b32 v228, v228, v225, 4 bitop3:0x36
	v_lshlrev_b32_e32 v226, 4, v226
	v_lshlrev_b32_e32 v228, 4, v228
	v_or_b32_e32 v185, v229, v226
	v_or_b32_e32 v184, v227, v226
	v_or_b32_e32 v183, v229, v228
	v_or_b32_e32 v182, v227, v228
	s_waitcnt vmcnt(0)
	s_setprio 0
	s_barrier
	s_waitcnt vmcnt(10)
	ds_write_b128 v176, v[116:119]
	s_waitcnt vmcnt(9)
	ds_write_b128 v176, v[112:115] offset:4096
	s_waitcnt vmcnt(8)
	ds_write_b128 v176, v[104:107] offset:8192
	s_waitcnt vmcnt(7)
	ds_write_b128 v176, v[92:95] offset:12288
	s_waitcnt vmcnt(6)
	ds_write_b128 v176, v[84:87] offset:16384
	s_waitcnt vmcnt(5)
	ds_write_b128 v176, v[72:75] offset:20480
	s_waitcnt vmcnt(4)
	ds_write_b128 v176, v[68:71] offset:24576
	s_waitcnt vmcnt(3)
	ds_write_b128 v176, v[48:51] offset:28672
	ds_write_b128 v176, v[56:59] offset:32768
	s_waitcnt vmcnt(2)
	ds_write_b128 v176, v[40:43] offset:36864
	s_waitcnt vmcnt(1)
	ds_write_b128 v176, v[24:27] offset:40960
	s_waitcnt vmcnt(0)
	ds_write_b128 v176, v[20:23] offset:45056
	s_waitcnt lgkmcnt(0)
	s_barrier
	ds_read_b128 v[20:23], v185
	ds_read_b128 v[24:27], v185 offset:2048
	ds_read_b128 v[40:43], v185 offset:4096
	ds_read_b128 v[48:51], v185 offset:6144
	ds_read_b128 v[56:59], v185 offset:8192
	ds_read_b128 v[68:71], v185 offset:10240
	ds_read_b128 v[72:75], v185 offset:12288
	ds_read_b128 v[84:87], v185 offset:14336
	ds_read_b128 v[92:95], v184 offset:32768
	ds_read_b128 v[104:107], v184 offset:34816
	ds_read_b128 v[112:115], v184 offset:36864
	ds_read_b128 v[116:119], v184 offset:38912
	s_waitcnt lgkmcnt(3)
	v_mfma_f32_16x16x32_bf16 v[172:175], v[92:95], v[20:23], v[172:175]
	s_waitcnt lgkmcnt(2)
	v_mfma_f32_16x16x32_bf16 v[168:171], v[104:107], v[20:23], v[168:171]
	s_waitcnt lgkmcnt(1)
	v_mfma_f32_16x16x32_bf16 v[164:167], v[112:115], v[20:23], v[164:167]
	s_waitcnt lgkmcnt(0)
	v_mfma_f32_16x16x32_bf16 v[20:23], v[116:119], v[20:23], v[160:163]
	v_mfma_f32_16x16x32_bf16 v[156:159], v[92:95], v[24:27], v[156:159]
	v_mfma_f32_16x16x32_bf16 v[152:155], v[104:107], v[24:27], v[152:155]
	v_mfma_f32_16x16x32_bf16 v[148:151], v[112:115], v[24:27], v[148:151]
	v_mfma_f32_16x16x32_bf16 v[24:27], v[116:119], v[24:27], v[144:147]
	v_mfma_f32_16x16x32_bf16 v[136:139], v[92:95], v[40:43], v[136:139]
	v_mfma_f32_16x16x32_bf16 v[132:135], v[104:107], v[40:43], v[132:135]
	v_mfma_f32_16x16x32_bf16 v[128:131], v[112:115], v[40:43], v[128:131]
	v_mfma_f32_16x16x32_bf16 v[40:43], v[116:119], v[40:43], v[124:127]
	v_mfma_f32_16x16x32_bf16 v[144:147], v[92:95], v[48:51], v[120:123]
	v_mfma_f32_16x16x32_bf16 v[160:163], v[104:107], v[48:51], v[108:111]
	v_mfma_f32_16x16x32_bf16 v[178:181], v[112:115], v[48:51], v[100:103]
	v_mfma_f32_16x16x32_bf16 v[48:51], v[116:119], v[48:51], v[96:99]
	v_mfma_f32_16x16x32_bf16 v[16:19], v[112:115], v[72:75], v[16:19]
	v_mfma_f32_16x16x32_bf16 v[12:15], v[116:119], v[72:75], v[12:15]
	v_mfma_f32_16x16x32_bf16 v[8:11], v[92:95], v[84:87], v[8:11]
	v_mfma_f32_16x16x32_bf16 v[4:7], v[104:107], v[84:87], v[4:7]
	v_mfma_f32_16x16x32_bf16 v[0:3], v[112:115], v[84:87], v[0:3]
	v_mfma_f32_16x16x32_bf16 v[184:187], v[92:95], v[56:59], v[88:91]
	v_mfma_f32_16x16x32_bf16 v[190:193], v[104:107], v[56:59], v[80:83]
	v_mfma_f32_16x16x32_bf16 v[194:197], v[112:115], v[56:59], v[76:79]
	v_mfma_f32_16x16x32_bf16 v[198:201], v[116:119], v[56:59], v[64:67]
	v_mfma_f32_16x16x32_bf16 v[204:207], v[92:95], v[68:71], v[60:63]
	v_mfma_f32_16x16x32_bf16 v[208:211], v[104:107], v[68:71], v[52:55]
	v_mfma_f32_16x16x32_bf16 v[212:215], v[112:115], v[68:71], v[44:47]
	v_mfma_f32_16x16x32_bf16 v[216:219], v[116:119], v[68:71], v[36:39]
	v_mfma_f32_16x16x32_bf16 v[220:223], v[92:95], v[72:75], v[32:35]
	v_mfma_f32_16x16x32_bf16 v[224:227], v[104:107], v[72:75], v[28:31]
	v_mfma_f32_16x16x32_bf16 v[140:143], v[116:119], v[84:87], v[140:143]
	s_nop 1
	ds_read_b128 v[28:31], v183
	ds_read_b128 v[32:35], v183 offset:2048
	ds_read_b128 v[36:39], v183 offset:4096
	ds_read_b128 v[44:47], v183 offset:6144
	ds_read_b128 v[228:231], v183 offset:8192
	ds_read_b128 v[232:235], v183 offset:10240
	ds_read_b128 v[236:239], v183 offset:12288
	ds_read_b128 v[240:243], v183 offset:14336
	ds_read_b128 v[244:247], v182 offset:32768
	ds_read_b128 v[248:251], v182 offset:34816
	ds_read_b128 v[52:55], v182 offset:36864
	ds_read_b128 v[56:59], v182 offset:38912
	s_waitcnt lgkmcnt(3)
	v_mfma_f32_16x16x32_bf16 v[124:127], v[244:247], v[28:31], v[172:175]
	v_readlane_b32 s16, v255, 27
	v_readlane_b32 s17, v255, 28
	v_readlane_b32 s11, v255, 16
	s_waitcnt lgkmcnt(2)
	v_mfma_f32_16x16x32_bf16 v[120:123], v[248:251], v[28:31], v[168:171]
	v_readlane_b32 s10, v255, 18
	s_waitcnt lgkmcnt(1)
	v_mfma_f32_16x16x32_bf16 v[116:119], v[52:55], v[28:31], v[164:167]
	s_waitcnt lgkmcnt(0)
	v_mfma_f32_16x16x32_bf16 v[112:115], v[56:59], v[28:31], v[20:23]
	v_mfma_f32_16x16x32_bf16 v[108:111], v[244:247], v[32:35], v[156:159]
	v_mfma_f32_16x16x32_bf16 v[104:107], v[248:251], v[32:35], v[152:155]
	v_mfma_f32_16x16x32_bf16 v[100:103], v[52:55], v[32:35], v[148:151]
	v_mfma_f32_16x16x32_bf16 v[96:99], v[56:59], v[32:35], v[24:27]
	v_mfma_f32_16x16x32_bf16 v[92:95], v[244:247], v[36:39], v[136:139]
	v_mfma_f32_16x16x32_bf16 v[88:91], v[248:251], v[36:39], v[132:135]
	v_mfma_f32_16x16x32_bf16 v[84:87], v[52:55], v[36:39], v[128:131]
	v_mfma_f32_16x16x32_bf16 v[80:83], v[56:59], v[36:39], v[40:43]
	v_mfma_f32_16x16x32_bf16 v[76:79], v[244:247], v[44:47], v[144:147]
	v_mfma_f32_16x16x32_bf16 v[72:75], v[248:251], v[44:47], v[160:163]
	v_mfma_f32_16x16x32_bf16 v[68:71], v[52:55], v[44:47], v[178:181]
	v_mfma_f32_16x16x32_bf16 v[64:67], v[56:59], v[44:47], v[48:51]
	v_mfma_f32_16x16x32_bf16 v[60:63], v[244:247], v[228:231], v[184:187]
	v_mfma_f32_16x16x32_bf16 v[156:159], v[248:251], v[228:231], v[190:193]
	v_mfma_f32_16x16x32_bf16 v[152:155], v[52:55], v[228:231], v[194:197]
	v_mfma_f32_16x16x32_bf16 v[48:51], v[56:59], v[228:231], v[198:201]
	v_mfma_f32_16x16x32_bf16 v[44:47], v[244:247], v[232:235], v[204:207]
	v_mfma_f32_16x16x32_bf16 v[40:43], v[248:251], v[232:235], v[208:211]
	v_mfma_f32_16x16x32_bf16 v[36:39], v[52:55], v[232:235], v[212:215]
	v_mfma_f32_16x16x32_bf16 v[32:35], v[56:59], v[232:235], v[216:219]
	v_mfma_f32_16x16x32_bf16 v[28:31], v[244:247], v[236:239], v[220:223]
	v_mfma_f32_16x16x32_bf16 v[24:27], v[248:251], v[236:239], v[224:227]
	v_mfma_f32_16x16x32_bf16 v[20:23], v[52:55], v[236:239], v[16:19]
	v_mfma_f32_16x16x32_bf16 v[16:19], v[56:59], v[236:239], v[12:15]
	v_mfma_f32_16x16x32_bf16 v[12:15], v[244:247], v[240:243], v[8:11]
	v_mfma_f32_16x16x32_bf16 v[8:11], v[248:251], v[240:243], v[4:7]
	v_mfma_f32_16x16x32_bf16 v[0:3], v[52:55], v[240:243], v[0:3]
	v_mfma_f32_16x16x32_bf16 v[4:7], v[56:59], v[240:243], v[140:143]
	v_xor_b32_e32 v240, 32, v203

.LBB0_486:
	s_ashr_i32 s30, s36, 3
	s_lshl_b32 s40, s30, 1
	s_and_b32 s31, s30, -16
	s_and_b32 s40, s40, 14
	s_or_b32 s31, s40, s31
	s_bfe_u32 s40, s30, 0x10003
	s_or_b32 s31, s31, s40
	s_cmp_lt_i32 s30, 0
	s_cselect_b32 s30, s31, s30
	s_and_b32 s31, s36, 7
	s_mul_i32 s31, s31, 56
	s_add_i32 s30, s30, s31
	s_mul_hi_i32 s31, s30, 0x92492493
	s_add_i32 s31, s31, s30
	s_ashr_i32 s40, s31, 4
	s_lshr_b32 s41, s31, 31
	s_add_i32 s40, s40, s41
	s_mul_i32 s42, s40, 0xffffffe4
	s_add_i32 s42, s42, s30
	s_ashr_i32 s30, s31, 5
	s_mul_hi_i32 s31, s42, 0x92492493
	s_add_i32 s31, s31, s42
	s_add_i32 s30, s30, s41
	s_lshr_b32 s41, s31, 31
	s_ashr_i32 s31, s31, 2
	s_add_i32 s31, s31, s41
	s_lshl_b32 s41, s30, 1
	s_add_i32 s41, s41, s31
	s_sub_i32 s40, s40, s41
	s_mul_i32 s40, s40, 7
	s_add_i32 s41, s40, s42
	v_mov_b32_e32 v8, v188
	s_lshl_b32 s30, s30, 10
	s_lshl_b32 s40, s31, 8
	s_lshl_b32 s41, s41, 7
	s_add_i32 s40, s40, s30
	v_ashrrev_i32_e32 v9, 3, v8
	v_lshlrev_b32_e32 v4, 4, v8
	v_and_b32_e32 v176, 0x70, v4
	v_add_u32_e32 v4, s41, v9
	v_add_u32_e32 v0, s40, v9
	v_ashrrev_i32_e32 v5, 31, v4
	v_ashrrev_i32_e32 v1, 31, v0
	v_lshlrev_b64 v[4:5], 11, v[4:5]
	v_xor_b32_e32 v10, v9, v8
	v_lshlrev_b64 v[0:1], 11, v[0:1]
	v_lshl_add_u64 v[6:7], s[22:23], 0, v[4:5]
	v_lshlrev_b32_e32 v10, 4, v10
	v_lshl_add_u64 v[2:3], s[0:1], 0, v[0:1]
	v_lshl_add_u64 v[6:7], v[6:7], 0, v[176:177]
	v_and_b32_e32 v10, 0x70, v10
	s_mov_b32 s30, 0x30000
	v_lshl_add_u64 v[2:3], v[2:3], 0, v[176:177]
	v_lshl_or_b32 v176, v9, 7, v10
	v_lshlrev_b32_e32 v12, 7, v8
	v_lshrrev_b32_e32 v9, 4, v8
	v_bfe_u32 v14, v8, 4, 2
	v_and_b32_e32 v15, 7, v8
	v_add_co_u32_e32 v8, vcc, s30, v6
	v_bitop3_b32 v16, v9, v15, 3 bitop3:0x6c
	s_nop 0
	v_addc_co_u32_e32 v9, vcc, 0, v7, vcc
	s_mov_b32 s31, 0x20000
	v_add_co_u32_e32 v10, vcc, s31, v6
	s_mov_b32 s42, 0x10000
	s_nop 0
	v_addc_co_u32_e32 v11, vcc, 0, v7, vcc
	global_load_dwordx4 v[56:59], v[8:9], off
	global_load_dwordx4 v[64:67], v[10:11], off
	v_add_co_u32_e32 v8, vcc, s42, v6
	s_mov_b32 s43, 0x70000
	s_nop 0
	v_addc_co_u32_e32 v9, vcc, 0, v7, vcc
	v_add_co_u32_e32 v10, vcc, s43, v2
	s_mov_b32 s43, 0x60000
	s_nop 0
	v_addc_co_u32_e32 v11, vcc, 0, v3, vcc
	global_load_dwordx4 v[76:79], v[8:9], off
	global_load_dwordx4 v[84:87], v[10:11], off
	v_add_co_u32_e32 v8, vcc, s43, v2
	s_mov_b32 s43, 0x50000
	s_nop 0
	v_addc_co_u32_e32 v9, vcc, 0, v3, vcc
	v_add_co_u32_e32 v10, vcc, s43, v2
	s_mov_b32 s43, 0x40000
	s_nop 0
	v_addc_co_u32_e32 v11, vcc, 0, v3, vcc
	global_load_dwordx4 v[100:103], v[8:9], off
	global_load_dwordx4 v[104:107], v[10:11], off
	v_add_co_u32_e32 v8, vcc, s43, v2
	v_and_b32_e32 v13, 0xffffc780, v12
	s_nop 0
	v_addc_co_u32_e32 v9, vcc, 0, v3, vcc
	v_add_co_u32_e32 v10, vcc, s30, v2
	v_and_b32_e32 v12, 0x2780, v12
	s_nop 0
	v_addc_co_u32_e32 v11, vcc, 0, v3, vcc
	global_load_dwordx4 v[124:127], v[8:9], off
	global_load_dwordx4 v[128:131], v[10:11], off
	v_add_co_u32_e32 v8, vcc, s31, v2
	v_bitop3_b32 v14, v14, v15, 4 bitop3:0x36
	s_nop 0
	v_addc_co_u32_e32 v9, vcc, 0, v3, vcc
	v_add_co_u32_e32 v10, vcc, s42, v2
	v_mov_b32_e32 v116, 0
	s_nop 0
	v_addc_co_u32_e32 v11, vcc, 0, v3, vcc
	global_load_dwordx4 v[148:151], v[8:9], off
	global_load_dwordx4 v[152:155], v[10:11], off
	global_load_dwordx4 v[140:143], v[6:7], off
	global_load_dwordx4 v[160:163], v[2:3], off
	v_lshlrev_b32_e32 v2, 4, v16
	v_or_b32_e32 v185, v13, v2
	v_or_b32_e32 v184, v12, v2
	v_lshlrev_b32_e32 v2, 4, v14
	v_or_b32_e32 v183, v13, v2
	v_or_b32_e32 v182, v12, v2
	v_lshlrev_b32_e32 v2, 4, v15
	v_or_b32_e32 v0, v0, v2
	v_or_b32_e32 v4, v4, v2
	v_lshl_add_u64 v[178:179], s[34:35], 0, v[0:1]
	v_lshl_add_u64 v[180:181], s[2:3], 0, v[4:5]
	s_mov_b64 s[30:31], 0
	v_mov_b32_e32 v117, v116
	v_mov_b32_e32 v118, v116
	v_mov_b32_e32 v119, v116
	v_mov_b32_e32 v0, v116
	v_mov_b32_e32 v1, v116
	v_mov_b32_e32 v2, v116
	v_mov_b32_e32 v3, v116
	v_mov_b32_e32 v4, v116
	v_mov_b32_e32 v5, v116
	v_mov_b32_e32 v6, v116
	v_mov_b32_e32 v7, v116
	v_mov_b32_e32 v8, v116
	v_mov_b32_e32 v9, v116
	v_mov_b32_e32 v10, v116
	v_mov_b32_e32 v11, v116
	v_mov_b32_e32 v12, v116
	v_mov_b32_e32 v13, v116
	v_mov_b32_e32 v14, v116
	v_mov_b32_e32 v15, v116
	v_mov_b32_e32 v16, v116
	v_mov_b32_e32 v17, v116
	v_mov_b32_e32 v18, v116
	v_mov_b32_e32 v19, v116
	v_mov_b32_e32 v20, v116
	v_mov_b32_e32 v21, v116
	v_mov_b32_e32 v22, v116
	v_mov_b32_e32 v23, v116
	v_mov_b32_e32 v24, v116
	v_mov_b32_e32 v25, v116
	v_mov_b32_e32 v26, v116
	v_mov_b32_e32 v27, v116
	v_mov_b32_e32 v28, v116
	v_mov_b32_e32 v29, v116
	v_mov_b32_e32 v30, v116
	v_mov_b32_e32 v31, v116
	v_mov_b32_e32 v32, v116
	v_mov_b32_e32 v33, v116
	v_mov_b32_e32 v34, v116
	v_mov_b32_e32 v35, v116
	v_mov_b32_e32 v36, v116
	v_mov_b32_e32 v37, v116
	v_mov_b32_e32 v38, v116
	v_mov_b32_e32 v39, v116
	v_mov_b32_e32 v40, v116
	v_mov_b32_e32 v41, v116
	v_mov_b32_e32 v42, v116
	v_mov_b32_e32 v43, v116
	v_mov_b32_e32 v44, v116
	v_mov_b32_e32 v45, v116
	v_mov_b32_e32 v46, v116
	v_mov_b32_e32 v47, v116
	v_mov_b32_e32 v48, v116
	v_mov_b32_e32 v49, v116
	v_mov_b32_e32 v50, v116
	v_mov_b32_e32 v51, v116
	v_mov_b32_e32 v52, v116
	v_mov_b32_e32 v53, v116
	v_mov_b32_e32 v54, v116
	v_mov_b32_e32 v55, v116
	v_mov_b32_e32 v60, v116
	v_mov_b32_e32 v61, v116
	v_mov_b32_e32 v62, v116
	v_mov_b32_e32 v63, v116
	v_mov_b32_e32 v68, v116
	v_mov_b32_e32 v69, v116
	v_mov_b32_e32 v70, v116
	v_mov_b32_e32 v71, v116
	v_mov_b32_e32 v72, v116
	v_mov_b32_e32 v73, v116
	v_mov_b32_e32 v74, v116
	v_mov_b32_e32 v75, v116
	v_mov_b32_e32 v80, v116
	v_mov_b32_e32 v81, v116
	v_mov_b32_e32 v82, v116
	v_mov_b32_e32 v83, v116
	v_mov_b32_e32 v88, v116
	v_mov_b32_e32 v89, v116
	v_mov_b32_e32 v90, v116
	v_mov_b32_e32 v91, v116
	v_mov_b32_e32 v92, v116
	v_mov_b32_e32 v93, v116
	v_mov_b32_e32 v94, v116
	v_mov_b32_e32 v95, v116
	v_mov_b32_e32 v96, v116
	v_mov_b32_e32 v97, v116
	v_mov_b32_e32 v98, v116
	v_mov_b32_e32 v99, v116
	v_mov_b32_e32 v108, v116
	v_mov_b32_e32 v109, v116
	v_mov_b32_e32 v110, v116
	v_mov_b32_e32 v111, v116
	v_mov_b32_e32 v112, v116
	v_mov_b32_e32 v113, v116
	v_mov_b32_e32 v114, v116
	v_mov_b32_e32 v115, v116
	v_mov_b32_e32 v120, v116
	v_mov_b32_e32 v121, v116
	v_mov_b32_e32 v122, v116
	v_mov_b32_e32 v123, v116
	v_mov_b32_e32 v132, v116
	v_mov_b32_e32 v133, v116
	v_mov_b32_e32 v134, v116
	v_mov_b32_e32 v135, v116
	v_mov_b32_e32 v136, v116
	v_mov_b32_e32 v137, v116
	v_mov_b32_e32 v138, v116
	v_mov_b32_e32 v139, v116
	v_mov_b32_e32 v144, v116
	v_mov_b32_e32 v145, v116
	v_mov_b32_e32 v146, v116
	v_mov_b32_e32 v147, v116
	v_mov_b32_e32 v156, v116
	v_mov_b32_e32 v157, v116
	v_mov_b32_e32 v158, v116
	v_mov_b32_e32 v159, v116
	v_mov_b32_e32 v164, v116
	v_mov_b32_e32 v165, v116
	v_mov_b32_e32 v166, v116
	v_mov_b32_e32 v167, v116
	v_mov_b32_e32 v168, v116
	v_mov_b32_e32 v169, v116
	v_mov_b32_e32 v170, v116
	v_mov_b32_e32 v171, v116
	v_mov_b32_e32 v172, v116
	v_mov_b32_e32 v173, v116
	v_mov_b32_e32 v174, v116
	v_mov_b32_e32 v175, v116
	s_setprio 2
	v_readlane_b32 s98, v253, 3
	v_readlane_b32 s99, v253, 4
	v_and_b32_e32 v224, 15, v188
	v_bfe_u32 v225, v188, 4, 2
	v_lshrrev_b32_e32 v226, 2, v224
	v_sub_u32_e32 v226, 0, v226
	v_and_b32_e32 v226, 3, v226
	v_xor_b32_e32 v225, v225, v226
	v_lshlrev_b32_e32 v225, 4, v225
	v_lshl_or_b32 v225, v224, 6, v225
	v_bfe_u32 v226, v188, 7, 1
	v_lshl_or_b32 v185, v226, 13, v225
	v_bfe_u32 v226, v188, 6, 1
	v_lshl_or_b32 v184, v226, 12, v225
	v_add_u32_e32 v184, 0x4000, v184
	v_lshrrev_b32_e32 v224, 3, v188
	v_bfe_u32 v225, v188, 2, 1
	v_lshrrev_b32_e32 v226, 2, v224
	v_sub_u32_e32 v226, 0, v226
	v_and_b32_e32 v226, 3, v226
	v_and_b32_e32 v227, 3, v188
	v_xor_b32_e32 v226, v227, v226
	v_lshlrev_b32_e32 v226, 4, v226
	v_xor_b32_e32 v224, v224, v225
	v_lshl_or_b32 v226, v224, 6, v226
	v_mul_u32_u24_e32 v225, 0x6000, v225
	v_add_u32_e32 v183, v225, v226
	s_mov_b32 m0, 0
	s_sub_u32 vcc_lo, s30, s98
	v_add_u32_e32 v186, vcc_lo, v178
	v_add_u32_e32 v187, vcc_lo, v180
	s_barrier
	s_waitcnt vmcnt(0)
	ds_write_b128 v183, v[160:163]
	ds_write_b128 v183, v[152:155] offset:2048
	ds_write_b128 v183, v[148:151] offset:4096
	ds_write_b128 v183, v[128:131] offset:6144
	ds_write_b128 v183, v[124:127] offset:8192
	ds_write_b128 v183, v[104:107] offset:10240
	ds_write_b128 v183, v[100:103] offset:12288
	ds_write_b128 v183, v[84:87] offset:14336
	ds_write_b128 v183, v[140:143] offset:16384
	ds_write_b128 v183, v[76:79] offset:18432
	ds_write_b128 v183, v[64:67] offset:20480
	ds_write_b128 v183, v[56:59] offset:22528
	v_cmp_gt_u32_e32 vcc, 0x6000, v183
	v_add_u32_e32 v182, 0xc000, v183
	v_add_u32_e32 v183, 0xffffa000, v183
	s_nop 0
	v_cndmask_b32_e32 v183, v183, v182, vcc
	v_add_u32_e32 v160, s26, v186
	global_load_dwordx4 v[160:163], v160, s[98:99] offset:128
	v_add_u32_e32 v152, s27, v186
	global_load_dwordx4 v[152:155], v152, s[98:99] offset:128
	v_add_u32_e32 v148, s20, v186
	global_load_dwordx4 v[148:151], v148, s[98:99] offset:128
	v_add_u32_e32 v128, s21, v186
	global_load_dwordx4 v[128:131], v128, s[98:99] offset:128
	v_add_u32_e32 v124, s56, v186
	global_load_dwordx4 v[124:127], v124, s[98:99] offset:128
	v_add_u32_e32 v104, s57, v186
	global_load_dwordx4 v[104:107], v104, s[98:99] offset:128
	v_add_u32_e32 v100, s24, v186
	global_load_dwordx4 v[100:103], v100, s[98:99] offset:128
	v_add_u32_e32 v84, s96, v186
	global_load_dwordx4 v[84:87], v84, s[98:99] offset:128
	v_add_u32_e32 v140, 0x1800000, v187
	global_load_dwordx4 v[140:143], v140, s[98:99] offset:128
	v_add_u32_e32 v76, 0x1810000, v187
	global_load_dwordx4 v[76:79], v76, s[98:99] offset:128
	v_add_u32_e32 v64, 0x1820000, v187
	global_load_dwordx4 v[64:67], v64, s[98:99] offset:128
	v_add_u32_e32 v56, 0x1830000, v187
	global_load_dwordx4 v[56:59], v56, s[98:99] offset:128
	s_add_u32 s30, s30, 0x80
	s_addc_u32 s31, s31, 0
.LBB0_487:
	s_waitcnt lgkmcnt(0)
	s_barrier
	ds_read_b128 v[224:227], v184
	ds_read_b128 v[228:231], v184 offset:1024
	ds_read_b128 v[232:235], v184 offset:2048
	ds_read_b128 v[236:239], v184 offset:3072
	ds_read_b128 v[190:193], v185
	ds_read_b128 v[194:197], v185 offset:1024
	ds_read_b128 v[198:201], v185 offset:2048
	ds_read_b128 v[204:207], v185 offset:3072
	ds_read_b128 v[208:211], v185 offset:4096
	ds_read_b128 v[212:215], v185 offset:5120
	ds_read_b128 v[216:219], v185 offset:6144
	ds_read_b128 v[220:223], v185 offset:7168
	s_movk_i32 vcc_lo, 0x6000
	s_cmp_eq_u32 m0, 2
	s_cselect_b32 vcc_lo, 0xffff4000, vcc_lo
	s_add_u32 m0, m0, 1
	s_cmp_eq_u32 m0, 3
	s_cselect_b32 m0, 0, m0
	v_add_u32_e32 v185, vcc_lo, v185
	v_add_u32_e32 v184, vcc_lo, v184
	v_xor_b32_e32 v185, 64, v185
	v_xor_b32_e32 v184, 64, v184
	s_waitcnt lgkmcnt(7)
	v_mfma_f32_16x16x32_bf16 v[172:175], v[224:227], v[190:193], v[172:175]
	v_mfma_f32_16x16x32_bf16 v[168:171], v[228:231], v[190:193], v[168:171]
	v_mfma_f32_16x16x32_bf16 v[164:167], v[232:235], v[190:193], v[164:167]
	v_mfma_f32_16x16x32_bf16 v[156:159], v[236:239], v[190:193], v[156:159]
	ds_read_b128 v[190:193], v185
	s_waitcnt lgkmcnt(7)
	v_mfma_f32_16x16x32_bf16 v[144:147], v[224:227], v[194:197], v[144:147]
	v_mfma_f32_16x16x32_bf16 v[136:139], v[228:231], v[194:197], v[136:139]
	v_mfma_f32_16x16x32_bf16 v[132:135], v[232:235], v[194:197], v[132:135]
	v_mfma_f32_16x16x32_bf16 v[120:123], v[236:239], v[194:197], v[120:123]
	ds_read_b128 v[194:197], v185 offset:1024
	s_waitcnt lgkmcnt(7)
	v_mfma_f32_16x16x32_bf16 v[112:115], v[224:227], v[198:201], v[112:115]
	v_mfma_f32_16x16x32_bf16 v[108:111], v[228:231], v[198:201], v[108:111]
	v_mfma_f32_16x16x32_bf16 v[96:99], v[232:235], v[198:201], v[96:99]
	v_mfma_f32_16x16x32_bf16 v[92:95], v[236:239], v[198:201], v[92:95]
	ds_read_b128 v[198:201], v185 offset:2048
	s_waitcnt lgkmcnt(7)
	v_mfma_f32_16x16x32_bf16 v[88:91], v[224:227], v[204:207], v[88:91]
	v_mfma_f32_16x16x32_bf16 v[80:83], v[228:231], v[204:207], v[80:83]
	v_mfma_f32_16x16x32_bf16 v[72:75], v[232:235], v[204:207], v[72:75]
	v_mfma_f32_16x16x32_bf16 v[68:71], v[236:239], v[204:207], v[68:71]
	ds_read_b128 v[204:207], v185 offset:3072
	s_waitcnt lgkmcnt(7)
	v_mfma_f32_16x16x32_bf16 v[60:63], v[224:227], v[208:211], v[60:63]
	v_mfma_f32_16x16x32_bf16 v[52:55], v[228:231], v[208:211], v[52:55]
	v_mfma_f32_16x16x32_bf16 v[48:51], v[232:235], v[208:211], v[48:51]
	v_mfma_f32_16x16x32_bf16 v[44:47], v[236:239], v[208:211], v[44:47]
	ds_read_b128 v[208:211], v185 offset:4096
	s_waitcnt lgkmcnt(7)
	v_mfma_f32_16x16x32_bf16 v[40:43], v[224:227], v[212:215], v[40:43]
	v_mfma_f32_16x16x32_bf16 v[36:39], v[228:231], v[212:215], v[36:39]
	v_mfma_f32_16x16x32_bf16 v[32:35], v[232:235], v[212:215], v[32:35]
	v_mfma_f32_16x16x32_bf16 v[28:31], v[236:239], v[212:215], v[28:31]
	ds_read_b128 v[212:215], v185 offset:5120
	s_waitcnt lgkmcnt(7)
	v_mfma_f32_16x16x32_bf16 v[24:27], v[224:227], v[216:219], v[24:27]
	v_mfma_f32_16x16x32_bf16 v[20:23], v[228:231], v[216:219], v[20:23]
	v_mfma_f32_16x16x32_bf16 v[16:19], v[232:235], v[216:219], v[16:19]
	v_mfma_f32_16x16x32_bf16 v[12:15], v[236:239], v[216:219], v[12:15]
	ds_read_b128 v[216:219], v185 offset:6144
	s_waitcnt lgkmcnt(7)
	v_mfma_f32_16x16x32_bf16 v[8:11], v[224:227], v[220:223], v[8:11]
	v_mfma_f32_16x16x32_bf16 v[4:7], v[228:231], v[220:223], v[4:7]
	v_mfma_f32_16x16x32_bf16 v[0:3], v[232:235], v[220:223], v[0:3]
	v_mfma_f32_16x16x32_bf16 v[116:119], v[236:239], v[220:223], v[116:119]
	ds_read_b128 v[220:223], v185 offset:7168
	ds_read_b128 v[224:227], v184
	ds_read_b128 v[228:231], v184 offset:1024
	ds_read_b128 v[232:235], v184 offset:2048
	ds_read_b128 v[236:239], v184 offset:3072
	s_movk_i32 vcc_lo, 0x6000
	s_cmp_eq_u32 m0, 2
	s_cselect_b32 vcc_lo, 0xffff4000, vcc_lo
	s_add_u32 m0, m0, 1
	s_cmp_eq_u32 m0, 3
	s_cselect_b32 m0, 0, m0
	v_add_u32_e32 v185, vcc_lo, v185
	v_add_u32_e32 v184, vcc_lo, v184
	v_xor_b32_e32 v185, 64, v185
	v_xor_b32_e32 v184, 64, v184
	s_sub_u32 vcc_lo, s30, s98
	v_add_u32_e32 v186, vcc_lo, v178
	v_add_u32_e32 v187, vcc_lo, v180
	s_barrier
	s_waitcnt lgkmcnt(0)
	v_mfma_f32_16x16x32_bf16 v[172:175], v[224:227], v[190:193], v[172:175]
	s_waitcnt vmcnt(11)
	v_mfma_f32_16x16x32_bf16 v[168:171], v[228:231], v[190:193], v[168:171]
	ds_write_b128 v183, v[160:163]
	v_add_u32_e32 v160, s26, v186
	v_mfma_f32_16x16x32_bf16 v[164:167], v[232:235], v[190:193], v[164:167]
	global_load_dwordx4 v[160:163], v160, s[98:99] offset:128
	v_mfma_f32_16x16x32_bf16 v[156:159], v[236:239], v[190:193], v[156:159]
	s_waitcnt vmcnt(11)
	ds_write_b128 v183, v[152:155] offset:2048
	v_mfma_f32_16x16x32_bf16 v[144:147], v[224:227], v[194:197], v[144:147]
	v_add_u32_e32 v152, s27, v186
	v_mfma_f32_16x16x32_bf16 v[136:139], v[228:231], v[194:197], v[136:139]
	global_load_dwordx4 v[152:155], v152, s[98:99] offset:128
	s_waitcnt vmcnt(11)
	v_mfma_f32_16x16x32_bf16 v[132:135], v[232:235], v[194:197], v[132:135]
	ds_write_b128 v183, v[148:151] offset:4096
	v_mfma_f32_16x16x32_bf16 v[120:123], v[236:239], v[194:197], v[120:123]
	v_add_u32_e32 v148, s20, v186
	global_load_dwordx4 v[148:151], v148, s[98:99] offset:128
	v_mfma_f32_16x16x32_bf16 v[112:115], v[224:227], v[198:201], v[112:115]
	s_waitcnt vmcnt(11)
	v_mfma_f32_16x16x32_bf16 v[108:111], v[228:231], v[198:201], v[108:111]
	ds_write_b128 v183, v[128:131] offset:6144
	v_add_u32_e32 v128, s21, v186
	v_mfma_f32_16x16x32_bf16 v[96:99], v[232:235], v[198:201], v[96:99]
	global_load_dwordx4 v[128:131], v128, s[98:99] offset:128
	v_mfma_f32_16x16x32_bf16 v[92:95], v[236:239], v[198:201], v[92:95]
	s_waitcnt vmcnt(11)
	ds_write_b128 v183, v[124:127] offset:8192
	v_mfma_f32_16x16x32_bf16 v[88:91], v[224:227], v[204:207], v[88:91]
	v_add_u32_e32 v124, s56, v186
	v_mfma_f32_16x16x32_bf16 v[80:83], v[228:231], v[204:207], v[80:83]
	global_load_dwordx4 v[124:127], v124, s[98:99] offset:128
	s_waitcnt vmcnt(11)
	v_mfma_f32_16x16x32_bf16 v[72:75], v[232:235], v[204:207], v[72:75]
	ds_write_b128 v183, v[104:107] offset:10240
	v_mfma_f32_16x16x32_bf16 v[68:71], v[236:239], v[204:207], v[68:71]
	v_add_u32_e32 v104, s57, v186
	global_load_dwordx4 v[104:107], v104, s[98:99] offset:128
	v_mfma_f32_16x16x32_bf16 v[60:63], v[224:227], v[208:211], v[60:63]
	s_waitcnt vmcnt(11)
	v_mfma_f32_16x16x32_bf16 v[52:55], v[228:231], v[208:211], v[52:55]
	ds_write_b128 v183, v[100:103] offset:12288
	v_add_u32_e32 v100, s24, v186
	v_mfma_f32_16x16x32_bf16 v[48:51], v[232:235], v[208:211], v[48:51]
	global_load_dwordx4 v[100:103], v100, s[98:99] offset:128
	v_mfma_f32_16x16x32_bf16 v[44:47], v[236:239], v[208:211], v[44:47]
	s_waitcnt vmcnt(11)
	ds_write_b128 v183, v[84:87] offset:14336
	v_mfma_f32_16x16x32_bf16 v[40:43], v[224:227], v[212:215], v[40:43]
	v_add_u32_e32 v84, s96, v186
	v_mfma_f32_16x16x32_bf16 v[36:39], v[228:231], v[212:215], v[36:39]
	global_load_dwordx4 v[84:87], v84, s[98:99] offset:128
	s_waitcnt vmcnt(11)
	v_mfma_f32_16x16x32_bf16 v[32:35], v[232:235], v[212:215], v[32:35]
	ds_write_b128 v183, v[140:143] offset:16384
	v_mfma_f32_16x16x32_bf16 v[28:31], v[236:239], v[212:215], v[28:31]
	v_add_u32_e32 v140, 0x1800000, v187
	global_load_dwordx4 v[140:143], v140, s[98:99] offset:128
	v_mfma_f32_16x16x32_bf16 v[24:27], v[224:227], v[216:219], v[24:27]
	s_waitcnt vmcnt(11)
	v_mfma_f32_16x16x32_bf16 v[20:23], v[228:231], v[216:219], v[20:23]
	ds_write_b128 v183, v[76:79] offset:18432
	v_add_u32_e32 v76, 0x1810000, v187
	v_mfma_f32_16x16x32_bf16 v[16:19], v[232:235], v[216:219], v[16:19]
	global_load_dwordx4 v[76:79], v76, s[98:99] offset:128
	v_mfma_f32_16x16x32_bf16 v[12:15], v[236:239], v[216:219], v[12:15]
	s_waitcnt vmcnt(11)
	ds_write_b128 v183, v[64:67] offset:20480
	v_mfma_f32_16x16x32_bf16 v[8:11], v[224:227], v[220:223], v[8:11]
	v_add_u32_e32 v64, 0x1820000, v187
	v_mfma_f32_16x16x32_bf16 v[4:7], v[228:231], v[220:223], v[4:7]
	global_load_dwordx4 v[64:67], v64, s[98:99] offset:128
	s_waitcnt vmcnt(11)
	v_mfma_f32_16x16x32_bf16 v[0:3], v[232:235], v[220:223], v[0:3]
	ds_write_b128 v183, v[56:59] offset:22528
	v_mfma_f32_16x16x32_bf16 v[116:119], v[236:239], v[220:223], v[116:119]
	v_add_u32_e32 v56, 0x1830000, v187
	global_load_dwordx4 v[56:59], v56, s[98:99] offset:128
	v_cmp_gt_u32_e32 vcc, 0x6000, v183
	v_add_u32_e32 v182, 0xc000, v183
	v_add_u32_e32 v183, 0xffffa000, v183
	s_nop 0
	v_cndmask_b32_e32 v183, v183, v182, vcc
	s_add_u32 s30, s30, 0x80
	s_addc_u32 s31, s31, 0
	s_cmpk_lg_i32 s30, 0x780
	s_cbranch_scc1 .LBB0_487
	s_waitcnt lgkmcnt(0)
	s_barrier
	ds_read_b128 v[224:227], v184
	ds_read_b128 v[228:231], v184 offset:1024
	ds_read_b128 v[232:235], v184 offset:2048
	ds_read_b128 v[236:239], v184 offset:3072
	ds_read_b128 v[190:193], v185
	ds_read_b128 v[194:197], v185 offset:1024
	ds_read_b128 v[198:201], v185 offset:2048
	ds_read_b128 v[204:207], v185 offset:3072
	ds_read_b128 v[208:211], v185 offset:4096
	ds_read_b128 v[212:215], v185 offset:5120
	ds_read_b128 v[216:219], v185 offset:6144
	ds_read_b128 v[220:223], v185 offset:7168
	s_movk_i32 vcc_lo, 0x6000
	s_cmp_eq_u32 m0, 2
	s_cselect_b32 vcc_lo, 0xffff4000, vcc_lo
	s_add_u32 m0, m0, 1
	s_cmp_eq_u32 m0, 3
	s_cselect_b32 m0, 0, m0
	v_add_u32_e32 v185, vcc_lo, v185
	v_add_u32_e32 v184, vcc_lo, v184
	v_xor_b32_e32 v185, 64, v185
	v_xor_b32_e32 v184, 64, v184
	s_waitcnt lgkmcnt(7)
	v_mfma_f32_16x16x32_bf16 v[172:175], v[224:227], v[190:193], v[172:175]
	v_mfma_f32_16x16x32_bf16 v[168:171], v[228:231], v[190:193], v[168:171]
	v_mfma_f32_16x16x32_bf16 v[164:167], v[232:235], v[190:193], v[164:167]
	v_mfma_f32_16x16x32_bf16 v[156:159], v[236:239], v[190:193], v[156:159]
	ds_read_b128 v[190:193], v185
	s_waitcnt lgkmcnt(7)
	v_mfma_f32_16x16x32_bf16 v[144:147], v[224:227], v[194:197], v[144:147]
	v_mfma_f32_16x16x32_bf16 v[136:139], v[228:231], v[194:197], v[136:139]
	v_mfma_f32_16x16x32_bf16 v[132:135], v[232:235], v[194:197], v[132:135]
	v_mfma_f32_16x16x32_bf16 v[120:123], v[236:239], v[194:197], v[120:123]
	ds_read_b128 v[194:197], v185 offset:1024
	s_waitcnt lgkmcnt(7)
	v_mfma_f32_16x16x32_bf16 v[112:115], v[224:227], v[198:201], v[112:115]
	v_mfma_f32_16x16x32_bf16 v[108:111], v[228:231], v[198:201], v[108:111]
	v_mfma_f32_16x16x32_bf16 v[96:99], v[232:235], v[198:201], v[96:99]
	v_mfma_f32_16x16x32_bf16 v[92:95], v[236:239], v[198:201], v[92:95]
	ds_read_b128 v[198:201], v185 offset:2048
	s_waitcnt lgkmcnt(7)
	v_mfma_f32_16x16x32_bf16 v[88:91], v[224:227], v[204:207], v[88:91]
	v_mfma_f32_16x16x32_bf16 v[80:83], v[228:231], v[204:207], v[80:83]
	v_mfma_f32_16x16x32_bf16 v[72:75], v[232:235], v[204:207], v[72:75]
	v_mfma_f32_16x16x32_bf16 v[68:71], v[236:239], v[204:207], v[68:71]
	ds_read_b128 v[204:207], v185 offset:3072
	s_waitcnt lgkmcnt(7)
	v_mfma_f32_16x16x32_bf16 v[60:63], v[224:227], v[208:211], v[60:63]
	v_mfma_f32_16x16x32_bf16 v[52:55], v[228:231], v[208:211], v[52:55]
	v_mfma_f32_16x16x32_bf16 v[48:51], v[232:235], v[208:211], v[48:51]
	v_mfma_f32_16x16x32_bf16 v[44:47], v[236:239], v[208:211], v[44:47]
	ds_read_b128 v[208:211], v185 offset:4096
	s_waitcnt lgkmcnt(7)
	v_mfma_f32_16x16x32_bf16 v[40:43], v[224:227], v[212:215], v[40:43]
	v_mfma_f32_16x16x32_bf16 v[36:39], v[228:231], v[212:215], v[36:39]
	v_mfma_f32_16x16x32_bf16 v[32:35], v[232:235], v[212:215], v[32:35]
	v_mfma_f32_16x16x32_bf16 v[28:31], v[236:239], v[212:215], v[28:31]
	ds_read_b128 v[212:215], v185 offset:5120
	s_waitcnt lgkmcnt(7)
	v_mfma_f32_16x16x32_bf16 v[24:27], v[224:227], v[216:219], v[24:27]
	v_mfma_f32_16x16x32_bf16 v[20:23], v[228:231], v[216:219], v[20:23]
	v_mfma_f32_16x16x32_bf16 v[16:19], v[232:235], v[216:219], v[16:19]
	v_mfma_f32_16x16x32_bf16 v[12:15], v[236:239], v[216:219], v[12:15]
	ds_read_b128 v[216:219], v185 offset:6144
	s_waitcnt lgkmcnt(7)
	v_mfma_f32_16x16x32_bf16 v[8:11], v[224:227], v[220:223], v[8:11]
	v_mfma_f32_16x16x32_bf16 v[4:7], v[228:231], v[220:223], v[4:7]
	v_mfma_f32_16x16x32_bf16 v[0:3], v[232:235], v[220:223], v[0:3]
	v_mfma_f32_16x16x32_bf16 v[116:119], v[236:239], v[220:223], v[116:119]
	ds_read_b128 v[220:223], v185 offset:7168
	ds_read_b128 v[224:227], v184
	ds_read_b128 v[228:231], v184 offset:1024
	ds_read_b128 v[232:235], v184 offset:2048
	ds_read_b128 v[236:239], v184 offset:3072
	s_movk_i32 vcc_lo, 0x6000
	s_cmp_eq_u32 m0, 2
	s_cselect_b32 vcc_lo, 0xffff4000, vcc_lo
	s_add_u32 m0, m0, 1
	s_cmp_eq_u32 m0, 3
	s_cselect_b32 m0, 0, m0
	v_add_u32_e32 v185, vcc_lo, v185
	v_add_u32_e32 v184, vcc_lo, v184
	v_xor_b32_e32 v185, 64, v185
	v_xor_b32_e32 v184, 64, v184
	s_waitcnt lgkmcnt(0)
	v_mfma_f32_16x16x32_bf16 v[172:175], v[224:227], v[190:193], v[172:175]
	v_mfma_f32_16x16x32_bf16 v[168:171], v[228:231], v[190:193], v[168:171]
	v_mfma_f32_16x16x32_bf16 v[164:167], v[232:235], v[190:193], v[164:167]
	v_mfma_f32_16x16x32_bf16 v[156:159], v[236:239], v[190:193], v[156:159]
	v_mfma_f32_16x16x32_bf16 v[144:147], v[224:227], v[194:197], v[144:147]
	v_mfma_f32_16x16x32_bf16 v[136:139], v[228:231], v[194:197], v[136:139]
	v_mfma_f32_16x16x32_bf16 v[132:135], v[232:235], v[194:197], v[132:135]
	v_mfma_f32_16x16x32_bf16 v[120:123], v[236:239], v[194:197], v[120:123]
	v_mfma_f32_16x16x32_bf16 v[112:115], v[224:227], v[198:201], v[112:115]
	v_mfma_f32_16x16x32_bf16 v[108:111], v[228:231], v[198:201], v[108:111]
	v_mfma_f32_16x16x32_bf16 v[96:99], v[232:235], v[198:201], v[96:99]
	v_mfma_f32_16x16x32_bf16 v[92:95], v[236:239], v[198:201], v[92:95]
	v_mfma_f32_16x16x32_bf16 v[88:91], v[224:227], v[204:207], v[88:91]
	v_mfma_f32_16x16x32_bf16 v[80:83], v[228:231], v[204:207], v[80:83]
	v_mfma_f32_16x16x32_bf16 v[72:75], v[232:235], v[204:207], v[72:75]
	v_mfma_f32_16x16x32_bf16 v[68:71], v[236:239], v[204:207], v[68:71]
	v_mfma_f32_16x16x32_bf16 v[60:63], v[224:227], v[208:211], v[60:63]
	v_mfma_f32_16x16x32_bf16 v[52:55], v[228:231], v[208:211], v[52:55]
	v_mfma_f32_16x16x32_bf16 v[48:51], v[232:235], v[208:211], v[48:51]
	v_mfma_f32_16x16x32_bf16 v[44:47], v[236:239], v[208:211], v[44:47]
	v_mfma_f32_16x16x32_bf16 v[40:43], v[224:227], v[212:215], v[40:43]
	v_mfma_f32_16x16x32_bf16 v[36:39], v[228:231], v[212:215], v[36:39]
	v_mfma_f32_16x16x32_bf16 v[32:35], v[232:235], v[212:215], v[32:35]
	v_mfma_f32_16x16x32_bf16 v[28:31], v[236:239], v[212:215], v[28:31]
	v_mfma_f32_16x16x32_bf16 v[24:27], v[224:227], v[216:219], v[24:27]
	v_mfma_f32_16x16x32_bf16 v[20:23], v[228:231], v[216:219], v[20:23]
	v_mfma_f32_16x16x32_bf16 v[16:19], v[232:235], v[216:219], v[16:19]
	v_mfma_f32_16x16x32_bf16 v[12:15], v[236:239], v[216:219], v[12:15]
	v_mfma_f32_16x16x32_bf16 v[8:11], v[224:227], v[220:223], v[8:11]
	v_mfma_f32_16x16x32_bf16 v[4:7], v[228:231], v[220:223], v[4:7]
	v_mfma_f32_16x16x32_bf16 v[0:3], v[232:235], v[220:223], v[0:3]
	v_mfma_f32_16x16x32_bf16 v[116:119], v[236:239], v[220:223], v[116:119]
	v_lshrrev_b32_e32 v224, 4, v188
	v_and_b32_e32 v225, 7, v188
	v_bitop3_b32 v226, v224, v225, 3 bitop3:0x6c
	v_lshlrev_b32_e32 v227, 7, v188
	v_bfe_u32 v228, v188, 4, 2
	v_and_b32_e32 v229, 0xffffc780, v227
	v_and_b32_e32 v227, 0x2780, v227
	v_bitop3_b32 v228, v228, v225, 4 bitop3:0x36
	v_lshlrev_b32_e32 v226, 4, v226
	v_lshlrev_b32_e32 v228, 4, v228
	v_or_b32_e32 v185, v229, v226
	v_or_b32_e32 v184, v227, v226
	v_or_b32_e32 v183, v229, v228
	v_or_b32_e32 v182, v227, v228
	s_waitcnt vmcnt(0)
	s_setprio 0
	s_barrier
	s_waitcnt vmcnt(11)
	ds_write_b128 v176, v[160:163]
	s_waitcnt vmcnt(10)
	ds_write_b128 v176, v[152:155] offset:4096
	s_waitcnt vmcnt(9)
	ds_write_b128 v176, v[148:151] offset:8192
	s_waitcnt vmcnt(8)
	ds_write_b128 v176, v[128:131] offset:12288
	s_waitcnt vmcnt(7)
	ds_write_b128 v176, v[124:127] offset:16384
	s_waitcnt vmcnt(6)
	ds_write_b128 v176, v[104:107] offset:20480
	s_waitcnt vmcnt(5)
	ds_write_b128 v176, v[100:103] offset:24576
	s_waitcnt vmcnt(4)
	ds_write_b128 v176, v[84:87] offset:28672
	s_waitcnt vmcnt(3)
	ds_write_b128 v176, v[140:143] offset:32768
	s_waitcnt vmcnt(2)
	ds_write_b128 v176, v[76:79] offset:36864
	s_waitcnt vmcnt(1)
	ds_write_b128 v176, v[64:67] offset:40960
	s_waitcnt vmcnt(0)
	ds_write_b128 v176, v[56:59] offset:45056
	s_waitcnt lgkmcnt(0)
	s_barrier
	ds_read_b128 v[56:59], v185
	ds_read_b128 v[64:67], v185 offset:2048
	ds_read_b128 v[76:79], v185 offset:4096
	ds_read_b128 v[84:87], v185 offset:6144
	ds_read_b128 v[100:103], v185 offset:8192
	ds_read_b128 v[104:107], v185 offset:10240
	ds_read_b128 v[124:127], v185 offset:12288
	ds_read_b128 v[128:131], v185 offset:14336
	ds_read_b128 v[140:143], v184 offset:32768
	ds_read_b128 v[148:151], v184 offset:34816
	ds_read_b128 v[152:155], v184 offset:36864
	ds_read_b128 v[160:163], v184 offset:38912
	s_waitcnt lgkmcnt(3)
	v_mfma_f32_16x16x32_bf16 v[172:175], v[140:143], v[56:59], v[172:175]
	s_waitcnt lgkmcnt(2)
	v_mfma_f32_16x16x32_bf16 v[168:171], v[148:151], v[56:59], v[168:171]
	s_waitcnt lgkmcnt(1)
	v_mfma_f32_16x16x32_bf16 v[164:167], v[152:155], v[56:59], v[164:167]
	s_waitcnt lgkmcnt(0)
	v_mfma_f32_16x16x32_bf16 v[56:59], v[160:163], v[56:59], v[156:159]
	v_mfma_f32_16x16x32_bf16 v[144:147], v[140:143], v[64:67], v[144:147]
	v_mfma_f32_16x16x32_bf16 v[136:139], v[148:151], v[64:67], v[136:139]
	v_mfma_f32_16x16x32_bf16 v[132:135], v[152:155], v[64:67], v[132:135]
	v_mfma_f32_16x16x32_bf16 v[64:67], v[160:163], v[64:67], v[120:123]
	v_mfma_f32_16x16x32_bf16 v[156:159], v[140:143], v[76:79], v[112:115]
	v_mfma_f32_16x16x32_bf16 v[178:181], v[148:151], v[76:79], v[108:111]
	v_mfma_f32_16x16x32_bf16 v[184:187], v[152:155], v[76:79], v[96:99]
	v_mfma_f32_16x16x32_bf16 v[76:79], v[160:163], v[76:79], v[92:95]
	v_mfma_f32_16x16x32_bf16 v[60:63], v[140:143], v[100:103], v[60:63]
	v_mfma_f32_16x16x32_bf16 v[52:55], v[148:151], v[100:103], v[52:55]
	v_mfma_f32_16x16x32_bf16 v[48:51], v[152:155], v[100:103], v[48:51]
	v_mfma_f32_16x16x32_bf16 v[44:47], v[160:163], v[100:103], v[44:47]
	v_mfma_f32_16x16x32_bf16 v[40:43], v[140:143], v[104:107], v[40:43]
	v_mfma_f32_16x16x32_bf16 v[36:39], v[148:151], v[104:107], v[36:39]
	v_mfma_f32_16x16x32_bf16 v[32:35], v[152:155], v[104:107], v[32:35]
	v_mfma_f32_16x16x32_bf16 v[28:31], v[160:163], v[104:107], v[28:31]
	v_mfma_f32_16x16x32_bf16 v[24:27], v[140:143], v[124:127], v[24:27]
	v_mfma_f32_16x16x32_bf16 v[20:23], v[148:151], v[124:127], v[20:23]
	v_mfma_f32_16x16x32_bf16 v[16:19], v[152:155], v[124:127], v[16:19]
	v_mfma_f32_16x16x32_bf16 v[12:15], v[160:163], v[124:127], v[12:15]
	v_mfma_f32_16x16x32_bf16 v[8:11], v[140:143], v[128:131], v[8:11]
	v_mfma_f32_16x16x32_bf16 v[4:7], v[148:151], v[128:131], v[4:7]
	v_mfma_f32_16x16x32_bf16 v[0:3], v[152:155], v[128:131], v[0:3]
	v_mfma_f32_16x16x32_bf16 v[190:193], v[140:143], v[84:87], v[88:91]
	v_mfma_f32_16x16x32_bf16 v[194:197], v[148:151], v[84:87], v[80:83]
	v_mfma_f32_16x16x32_bf16 v[198:201], v[152:155], v[84:87], v[72:75]
	v_mfma_f32_16x16x32_bf16 v[204:207], v[160:163], v[84:87], v[68:71]
	v_mfma_f32_16x16x32_bf16 v[140:143], v[160:163], v[128:131], v[116:119]
	s_nop 1
	ds_read_b128 v[68:71], v183
	ds_read_b128 v[72:75], v183 offset:2048
	ds_read_b128 v[80:83], v183 offset:4096
	ds_read_b128 v[128:131], v183 offset:6144
	ds_read_b128 v[148:151], v183 offset:8192
	ds_read_b128 v[152:155], v183 offset:10240
	ds_read_b128 v[160:163], v183 offset:12288
	ds_read_b128 v[208:211], v183 offset:14336
	ds_read_b128 v[212:215], v182 offset:32768
	ds_read_b128 v[216:219], v182 offset:34816
	ds_read_b128 v[220:223], v182 offset:36864
	ds_read_b128 v[224:227], v182 offset:38912
	s_waitcnt lgkmcnt(3)
	v_mfma_f32_16x16x32_bf16 v[124:127], v[212:215], v[68:71], v[172:175]
	s_movk_i32 s30, 0x6c0
	s_waitcnt lgkmcnt(2)
	v_mfma_f32_16x16x32_bf16 v[120:123], v[216:219], v[68:71], v[168:171]
	s_waitcnt lgkmcnt(1)
	v_mfma_f32_16x16x32_bf16 v[116:119], v[220:223], v[68:71], v[164:167]
	s_waitcnt lgkmcnt(0)
	v_mfma_f32_16x16x32_bf16 v[112:115], v[224:227], v[68:71], v[56:59]
	v_mfma_f32_16x16x32_bf16 v[108:111], v[212:215], v[72:75], v[144:147]
	v_mfma_f32_16x16x32_bf16 v[104:107], v[216:219], v[72:75], v[136:139]
	v_mfma_f32_16x16x32_bf16 v[100:103], v[220:223], v[72:75], v[132:135]
	v_mfma_f32_16x16x32_bf16 v[96:99], v[224:227], v[72:75], v[64:67]
	v_mfma_f32_16x16x32_bf16 v[92:95], v[212:215], v[80:83], v[156:159]
	v_mfma_f32_16x16x32_bf16 v[88:91], v[216:219], v[80:83], v[178:181]
	v_mfma_f32_16x16x32_bf16 v[84:87], v[220:223], v[80:83], v[184:187]
	v_mfma_f32_16x16x32_bf16 v[80:83], v[224:227], v[80:83], v[76:79]
	v_mfma_f32_16x16x32_bf16 v[76:79], v[212:215], v[128:131], v[190:193]
	v_mfma_f32_16x16x32_bf16 v[72:75], v[216:219], v[128:131], v[194:197]
	v_mfma_f32_16x16x32_bf16 v[68:71], v[220:223], v[128:131], v[198:201]
	v_mfma_f32_16x16x32_bf16 v[64:67], v[224:227], v[128:131], v[204:207]
	v_mov_b32_e32 v128, v188
	v_mov_b32_e32 v129, v188
	v_mfma_f32_16x16x32_bf16 v[60:63], v[212:215], v[148:151], v[60:63]
	s_nop 0
	v_and_or_b32 v134, v129, 64, s41
	v_mfma_f32_16x16x32_bf16 v[56:59], v[216:219], v[148:151], v[52:55]
	v_cmp_gt_i32_e32 vcc, s30, v134
	v_mfma_f32_16x16x32_bf16 v[52:55], v[220:223], v[148:151], v[48:51]
	v_mfma_f32_16x16x32_bf16 v[48:51], v[224:227], v[148:151], v[44:47]
	v_mfma_f32_16x16x32_bf16 v[44:47], v[212:215], v[152:155], v[40:43]
	v_mfma_f32_16x16x32_bf16 v[40:43], v[216:219], v[152:155], v[36:39]
	v_mfma_f32_16x16x32_bf16 v[36:39], v[220:223], v[152:155], v[32:35]
	v_mfma_f32_16x16x32_bf16 v[32:35], v[224:227], v[152:155], v[28:31]
	v_mfma_f32_16x16x32_bf16 v[28:31], v[212:215], v[160:163], v[24:27]
	v_mfma_f32_16x16x32_bf16 v[24:27], v[216:219], v[160:163], v[20:23]
	v_mfma_f32_16x16x32_bf16 v[20:23], v[220:223], v[160:163], v[16:19]
	v_mfma_f32_16x16x32_bf16 v[16:19], v[224:227], v[160:163], v[12:15]
	v_mfma_f32_16x16x32_bf16 v[12:15], v[212:215], v[208:211], v[8:11]
	v_mfma_f32_16x16x32_bf16 v[8:11], v[216:219], v[208:211], v[4:7]
	v_mfma_f32_16x16x32_bf16 v[4:7], v[220:223], v[208:211], v[0:3]
	v_mfma_f32_16x16x32_bf16 v[0:3], v[224:227], v[208:211], v[140:143]
	s_and_saveexec_b64 s[92:93], vcc
	s_cbranch_execz .LBB0_485
	v_and_b32_e32 v130, 0xffffff80, v129
	v_add_u32_e32 v183, s40, v130
	s_movk_i32 s30, 0xfff
	v_cmp_lt_i32_e64 s[48:49], s30, v183
	s_movk_i32 s30, 0x1000
	v_cmp_gt_i32_e64 s[44:45], s30, v183
	v_add_u32_e32 v130, 0xfffff000, v183
	v_bfe_u32 v141, v128, 4, 2
	s_movk_i32 s30, 0x27f
	v_ashrrev_i32_e32 v135, 10, v130
	v_ashrrev_i32_e32 v132, 8, v183
	v_cmp_lt_i32_e64 s[52:53], s30, v134
	s_movk_i32 s30, 0x280
	v_lshlrev_b32_e32 v130, 4, v141
	v_mov_b32_e32 v131, v177
	v_and_b32_e32 v140, 0x80, v129
	v_cmp_ne_u32_e64 s[50:51], s30, v134
	v_lshl_add_u64 v[138:139], s[84:85], 0, v[130:131]
	v_lshl_add_u64 v[136:137], s[82:83], 0, v[130:131]
	v_lshlrev_b32_e32 v130, 9, v132
	v_readlane_b32 s30, v255, 49
	v_and_b32_e32 v182, 15, v128
	v_and_b32_e32 v181, 0x380, v183
	v_or3_b32 v178, v130, s30, v140
	v_lshlrev_b32_e32 v130, 3, v132
	v_ashrrev_i32_e32 v131, 31, v130
	v_lshlrev_b64 v[132:133], 8, v[130:131]
	v_lshlrev_b32_e32 v130, 3, v135
	s_movk_i32 s30, 0x500
	v_bfe_u32 v129, v128, 4, 1
	v_lshrrev_b32_e32 v128, 2, v128
	v_mad_i64_i32 v[130:131], s[30:31], v130, s30, 0
	v_mov_b32_e32 v176, v134
	v_cmp_eq_u32_e64 s[40:41], 0, v129
	v_lshlrev_b32_e32 v180, 4, v129
	v_and_b32_e32 v179, 8, v128
	v_lshlrev_b32_e32 v128, 2, v141
	v_mov_b32_e32 v129, v177
	v_or_b32_e32 v132, v132, v140
	v_or_b32_e32 v130, v130, v181
	v_cmp_lt_i32_e64 s[46:47], s97, v134
	v_cmp_eq_u32_e64 s[42:43], 0, v141
	v_or_b32_e32 v140, v183, v182
	s_and_saveexec_b64 s[30:31], s[52:53]
	s_xor_b64 s[94:95], exec, s[30:31]
	s_cbranch_execz .LBB0_513
	s_and_saveexec_b64 s[30:31], s[50:51]
	s_xor_b64 s[30:31], exec, s[30:31]
	s_cbranch_execz .LBB0_492
	v_mul_f32_e32 v142, 0xbfb8aa3b, v124
	v_mul_f32_e32 v144, 0xbfb8aa3b, v120
	v_mul_f32_e32 v145, 0xbfb8aa3b, v125
	v_exp_f32_e32 v142, v142
	v_exp_f32_e32 v144, v144
	v_exp_f32_e32 v145, v145
	v_mul_f32_e32 v146, 0xbfb8aa3b, v121
	v_add_f32_e32 v142, 1.0, v142
	v_add_f32_e32 v144, 1.0, v144
	v_add_f32_e32 v145, 1.0, v145
	v_rcp_f32_e32 v142, v142
	v_rcp_f32_e32 v144, v144
	v_rcp_f32_e32 v145, v145
	v_exp_f32_e32 v146, v146
	v_mul_f32_e32 v142, v124, v142
	v_mul_f32_e32 v144, v120, v144
	v_mul_f32_e32 v145, v125, v145
	v_add_f32_e32 v120, 1.0, v146
	v_mul_f32_e32 v124, 0xbfb8aa3b, v126
	v_mul_f32_e32 v125, 0xbfb8aa3b, v122
	v_rcp_f32_e32 v120, v120
	v_exp_f32_e32 v124, v124
	v_exp_f32_e32 v125, v125
	v_ashrrev_i32_e32 v141, 31, v140
	v_mul_f32_e32 v146, v121, v120
	v_add_f32_e32 v120, 1.0, v124
	v_add_f32_e32 v121, 1.0, v125
	v_mul_f32_e32 v124, 0xbfb8aa3b, v127
	v_mul_f32_e32 v125, 0xbfb8aa3b, v123
	v_exp_f32_e32 v124, v124
	v_exp_f32_e32 v125, v125
	v_rcp_f32_e32 v120, v120
	v_rcp_f32_e32 v121, v121
	v_add_f32_e32 v124, 1.0, v124
	v_add_f32_e32 v125, 1.0, v125
	v_rcp_f32_e32 v124, v124
	v_rcp_f32_e32 v125, v125
	v_lshlrev_b64 v[140:141], 11, v[140:141]
	v_cmp_lt_i32_e32 vcc, v189, v202
	v_mul_f32_e32 v126, v126, v120
	v_mul_f32_e32 v122, v122, v121
	v_cndmask_b32_e32 v143, v203, v189, vcc
	v_mul_f32_e32 v127, v127, v124
	v_mul_f32_e32 v123, v123, v125
	v_lshl_add_u64 v[120:121], s[34:35], 0, v[140:141]
	v_lshlrev_b32_e32 v143, 2, v143
	v_lshl_add_u64 v[124:125], v[176:177], 1, v[120:121]
	s_nop 0
	s_nop 0
	s_nop 0
	s_nop 0
	s_nop 0
	s_nop 0
	s_nop 0
	s_nop 0
	s_mov_b32 s58, 0x96ff000
	s_waitcnt lgkmcnt(0)
	s_nop 0
	s_nop 1
	v_permlane16_swap_b32_e32 v142, v144
	s_waitcnt lgkmcnt(0)
	s_nop 0
	v_mov_b32_e32 v120, v145
	v_mov_b32_e32 v145, v146
	s_nop 1
	v_permlane16_swap_b32_e32 v120, v145
	s_waitcnt lgkmcnt(0)
	s_nop 0
	v_mov_b32_e32 v121, v126
	v_mov_b32_e32 v126, v122
	s_nop 1
	v_permlane16_swap_b32_e32 v121, v126
	s_waitcnt lgkmcnt(0)
	s_nop 0
	v_mov_b32_e32 v122, v127
	s_nop 1
	v_permlane16_swap_b32_e32 v122, v123
	v_cvt_pk_bf16_f32 v123, v126, v123
	v_lshlrev_b32_e32 v126, 1, v180
	v_mov_b32_e32 v127, v177
	v_lshlrev_b32_e32 v140, 1, v179
	v_mov_b32_e32 v141, v177
	v_lshl_add_u64 v[124:125], v[124:125], 0, v[126:127]
	v_lshl_add_u64 v[124:125], v[124:125], 0, v[140:141]
	v_add_co_u32_e32 v124, vcc, s58, v124
	v_cvt_pk_bf16_f32 v120, v142, v120
	v_cvt_pk_bf16_f32 v121, v121, v122
	v_cvt_pk_bf16_f32 v122, v144, v145
	v_addc_co_u32_e32 v125, vcc, 0, v125, vcc
	v_mul_f32_e32 v126, 0xbfb8aa3b, v116
	global_store_dwordx4 v[124:125], v[120:123], off offset:2688
	v_exp_f32_e32 v126, v126
	s_nop 0
	v_mul_f32_e32 v121, 0xbfb8aa3b, v112
	v_mul_f32_e32 v122, 0xbfb8aa3b, v117
	v_exp_f32_e32 v121, v121
	v_exp_f32_e32 v122, v122
	v_add_f32_e32 v120, 1.0, v126
	v_mul_f32_e32 v123, 0xbfb8aa3b, v113
	v_add_f32_e32 v121, 1.0, v121
	v_add_f32_e32 v122, 1.0, v122
	v_rcp_f32_e32 v120, v120
	v_rcp_f32_e32 v121, v121
	v_rcp_f32_e32 v122, v122
	v_exp_f32_e32 v123, v123
	v_mul_f32_e32 v116, v116, v120
	v_mul_f32_e32 v112, v112, v121
	v_mul_f32_e32 v117, v117, v122
	v_add_f32_e32 v120, 1.0, v123
	v_mul_f32_e32 v121, 0xbfb8aa3b, v118
	v_mul_f32_e32 v122, 0xbfb8aa3b, v114
	v_rcp_f32_e32 v120, v120
	v_exp_f32_e32 v121, v121
	v_exp_f32_e32 v122, v122
	v_mul_f32_e32 v123, 0xbfb8aa3b, v115
	v_mul_f32_e32 v113, v113, v120
	v_add_f32_e32 v120, 1.0, v121
	v_add_f32_e32 v121, 1.0, v122
	v_mul_f32_e32 v122, 0xbfb8aa3b, v119
	v_exp_f32_e32 v122, v122
	v_exp_f32_e32 v123, v123
	v_rcp_f32_e32 v120, v120
	v_rcp_f32_e32 v121, v121
	v_add_f32_e32 v122, 1.0, v122
	v_add_f32_e32 v123, 1.0, v123
	v_rcp_f32_e32 v122, v122
	v_rcp_f32_e32 v123, v123
	v_mul_f32_e32 v118, v118, v120
	v_mul_f32_e32 v114, v114, v121
	v_mul_f32_e32 v119, v119, v122
	v_mul_f32_e32 v115, v115, v123
	s_nop 0
	s_nop 0
	s_nop 0
	s_nop 0
	s_nop 0
	s_nop 0
	s_nop 0
	s_nop 0
	s_waitcnt lgkmcnt(0)
	s_nop 0
	v_mov_b32_e32 v120, v112
	s_nop 1
	v_permlane16_swap_b32_e32 v116, v120
	s_waitcnt lgkmcnt(0)
	s_nop 0
	v_mov_b32_e32 v112, v117
	v_mov_b32_e32 v117, v113
	s_nop 1
	v_permlane16_swap_b32_e32 v112, v117
	s_waitcnt lgkmcnt(0)
	s_nop 0
	v_mov_b32_e32 v113, v118
	v_mov_b32_e32 v118, v114
	s_nop 1
	v_permlane16_swap_b32_e32 v113, v118
	s_waitcnt lgkmcnt(0)
	s_nop 0
	v_mov_b32_e32 v114, v119
	s_nop 1
	v_permlane16_swap_b32_e32 v114, v115
	v_cvt_pk_bf16_f32 v112, v116, v112
	v_cvt_pk_bf16_f32 v113, v113, v114
	v_cvt_pk_bf16_f32 v114, v120, v117
	v_cvt_pk_bf16_f32 v115, v118, v115
	global_store_dwordx4 v[124:125], v[112:115], off offset:2752

.LBB0_801:
	s_waitcnt lgkmcnt(0)
	s_ashr_i32 s6, s8, 3
	s_lshl_b32 s9, s6, 1
	s_and_b32 s7, s6, -16
	s_and_b32 s9, s9, 14
	s_or_b32 s7, s9, s7
	s_bfe_u32 s9, s6, 0x10003
	s_or_b32 s7, s7, s9
	s_cmp_lt_i32 s6, 0
	s_cselect_b32 s6, s7, s6
	s_lshl_b32 s7, s8, 5
	s_and_b32 s7, s7, 0xe0
	s_add_i32 s6, s6, s7
	s_ashr_i32 s7, s6, 31
	s_lshr_b32 s7, s7, 27
	s_add_i32 s7, s6, s7
	s_and_b32 s9, s7, 0xffffffe0
	s_sub_i32 s6, s6, s9
	s_ashr_i32 s9, s6, 31
	s_lshr_b32 s9, s9, 29
	s_add_i32 s9, s6, s9
	s_ashr_i32 s10, s9, 3
	s_lshl_b32 s7, s7, 5
	s_and_b32 s7, s7, 0xfffffc00
	s_lshl_b32 s9, s10, 8
	s_add_i32 s9, s9, s7
	s_lshl_b32 s7, s10, 10
	s_lshl_b32 s6, s6, 7
	v_mov_b32_e32 v6, v188
	s_sub_i32 s10, s6, s7
	s_mov_b32 s11, 0x30000
	v_ashrrev_i32_e32 v7, 3, v6
	v_lshlrev_b32_e32 v4, 4, v6
	v_and_b32_e32 v176, 0x70, v4
	v_add_u32_e32 v4, s10, v7
	v_ashrrev_i32_e32 v5, 31, v4
	v_add_u32_e32 v0, s9, v7
	v_lshlrev_b64 v[4:5], 11, v[4:5]
	v_ashrrev_i32_e32 v1, 31, v0
	v_lshl_add_u64 v[4:5], s[2:3], 0, v[4:5]
	v_xor_b32_e32 v8, v7, v6
	v_lshlrev_b64 v[0:1], 11, v[0:1]
	v_lshl_add_u64 v[178:179], v[4:5], 0, v[176:177]
	v_lshlrev_b32_e32 v4, 4, v8
	v_lshl_add_u64 v[2:3], s[0:1], 0, v[0:1]
	v_and_b32_e32 v4, 0x70, v4
	v_lshl_add_u64 v[2:3], v[2:3], 0, v[176:177]
	v_lshl_or_b32 v176, v7, 7, v4
	v_lshrrev_b32_e32 v4, 4, v6
	v_and_b32_e32 v15, 7, v6
	v_bitop3_b32 v20, v4, v15, 3 bitop3:0x6c
	v_add_co_u32_e32 v4, vcc, s11, v178
	v_lshlrev_b32_e32 v12, 7, v6
	s_nop 0
	v_addc_co_u32_e32 v5, vcc, 0, v179, vcc
	v_bfe_u32 v14, v6, 4, 2
	v_add_co_u32_e32 v6, vcc, s12, v178
	s_mov_b32 s6, 0x70000
	s_nop 0
	v_addc_co_u32_e32 v7, vcc, 0, v179, vcc
	global_load_dwordx4 v[8:11], v[4:5], off
	global_load_dwordx4 v[16:19], v[6:7], off
	v_add_co_u32_e32 v4, vcc, s13, v178
	v_and_b32_e32 v13, 0xffffc780, v12
	s_nop 0
	v_addc_co_u32_e32 v5, vcc, 0, v179, vcc
	v_add_co_u32_e32 v6, vcc, s6, v2
	s_mov_b32 s6, 0x60000
	s_nop 0
	v_addc_co_u32_e32 v7, vcc, 0, v3, vcc
	global_load_dwordx4 v[32:35], v[4:5], off
	global_load_dwordx4 v[40:43], v[6:7], off
	v_add_co_u32_e32 v4, vcc, s6, v2
	s_mov_b32 s6, 0x50000
	s_nop 0
	v_addc_co_u32_e32 v5, vcc, 0, v3, vcc
	v_add_co_u32_e32 v6, vcc, s6, v2
	v_and_b32_e32 v12, 0x2780, v12
	s_nop 0
	v_addc_co_u32_e32 v7, vcc, 0, v3, vcc
	global_load_dwordx4 v[60:63], v[4:5], off
	global_load_dwordx4 v[68:71], v[6:7], off
	v_add_co_u32_e32 v4, vcc, 0x40000, v2
	v_bitop3_b32 v14, v14, v15, 4 bitop3:0x36
	s_nop 0
	v_addc_co_u32_e32 v5, vcc, 0, v3, vcc
	v_add_co_u32_e32 v6, vcc, s11, v2
	v_lshl_or_b32 v0, v15, 4, v0
	s_nop 0
	v_addc_co_u32_e32 v7, vcc, 0, v3, vcc
	global_load_dwordx4 v[80:83], v[4:5], off
	global_load_dwordx4 v[88:91], v[6:7], off
	v_add_co_u32_e32 v4, vcc, s12, v2
	v_mov_b32_e32 v140, 0
	s_nop 0
	v_addc_co_u32_e32 v5, vcc, 0, v3, vcc
	v_add_co_u32_e32 v6, vcc, 0x10000, v2
	v_lshl_add_u64 v[180:181], s[34:35], 0, v[0:1]
	s_nop 0
	v_addc_co_u32_e32 v7, vcc, 0, v3, vcc
	global_load_dwordx4 v[104:107], v[4:5], off
	global_load_dwordx4 v[112:115], v[6:7], off
	global_load_dwordx4 v[56:59], v[178:179], off
	global_load_dwordx4 v[116:119], v[2:3], off
	v_lshlrev_b32_e32 v2, 4, v20
	v_or_b32_e32 v185, v13, v2
	v_or_b32_e32 v184, v12, v2
	v_lshlrev_b32_e32 v2, 4, v14
	v_or_b32_e32 v183, v13, v2
	v_or_b32_e32 v182, v12, v2
	s_mov_b64 s[6:7], 0
	v_mov_b32_e32 v141, v140
	v_mov_b32_e32 v142, v140
	v_mov_b32_e32 v143, v140
	v_mov_b32_e32 v0, v140
	v_mov_b32_e32 v1, v140
	v_mov_b32_e32 v2, v140
	v_mov_b32_e32 v3, v140
	v_mov_b32_e32 v4, v140
	v_mov_b32_e32 v5, v140
	v_mov_b32_e32 v6, v140
	v_mov_b32_e32 v7, v140
	v_mov_b32_e32 v12, v140
	v_mov_b32_e32 v13, v140
	v_mov_b32_e32 v14, v140
	v_mov_b32_e32 v15, v140
	v_mov_b32_e32 v20, v140
	v_mov_b32_e32 v21, v140
	v_mov_b32_e32 v22, v140
	v_mov_b32_e32 v23, v140
	v_mov_b32_e32 v24, v140
	v_mov_b32_e32 v25, v140
	v_mov_b32_e32 v26, v140
	v_mov_b32_e32 v27, v140
	v_mov_b32_e32 v28, v140
	v_mov_b32_e32 v29, v140
	v_mov_b32_e32 v30, v140
	v_mov_b32_e32 v31, v140
	v_mov_b32_e32 v36, v140
	v_mov_b32_e32 v37, v140
	v_mov_b32_e32 v38, v140
	v_mov_b32_e32 v39, v140
	v_mov_b32_e32 v44, v140
	v_mov_b32_e32 v45, v140
	v_mov_b32_e32 v46, v140
	v_mov_b32_e32 v47, v140
	v_mov_b32_e32 v48, v140
	v_mov_b32_e32 v49, v140
	v_mov_b32_e32 v50, v140
	v_mov_b32_e32 v51, v140
	v_mov_b32_e32 v52, v140
	v_mov_b32_e32 v53, v140
	v_mov_b32_e32 v54, v140
	v_mov_b32_e32 v55, v140
	v_mov_b32_e32 v64, v140
	v_mov_b32_e32 v65, v140
	v_mov_b32_e32 v66, v140
	v_mov_b32_e32 v67, v140
	v_mov_b32_e32 v72, v140
	v_mov_b32_e32 v73, v140
	v_mov_b32_e32 v74, v140
	v_mov_b32_e32 v75, v140
	v_mov_b32_e32 v76, v140
	v_mov_b32_e32 v77, v140
	v_mov_b32_e32 v78, v140
	v_mov_b32_e32 v79, v140
	v_mov_b32_e32 v84, v140
	v_mov_b32_e32 v85, v140
	v_mov_b32_e32 v86, v140
	v_mov_b32_e32 v87, v140
	v_mov_b32_e32 v92, v140
	v_mov_b32_e32 v93, v140
	v_mov_b32_e32 v94, v140
	v_mov_b32_e32 v95, v140
	v_mov_b32_e32 v96, v140
	v_mov_b32_e32 v97, v140
	v_mov_b32_e32 v98, v140
	v_mov_b32_e32 v99, v140
	v_mov_b32_e32 v100, v140
	v_mov_b32_e32 v101, v140
	v_mov_b32_e32 v102, v140
	v_mov_b32_e32 v103, v140
	v_mov_b32_e32 v108, v140
	v_mov_b32_e32 v109, v140
	v_mov_b32_e32 v110, v140
	v_mov_b32_e32 v111, v140
	v_mov_b32_e32 v120, v140
	v_mov_b32_e32 v121, v140
	v_mov_b32_e32 v122, v140
	v_mov_b32_e32 v123, v140
	v_mov_b32_e32 v124, v140
	v_mov_b32_e32 v125, v140
	v_mov_b32_e32 v126, v140
	v_mov_b32_e32 v127, v140
	v_mov_b32_e32 v128, v140
	v_mov_b32_e32 v129, v140
	v_mov_b32_e32 v130, v140
	v_mov_b32_e32 v131, v140
	v_mov_b32_e32 v132, v140
	v_mov_b32_e32 v133, v140
	v_mov_b32_e32 v134, v140
	v_mov_b32_e32 v135, v140
	v_mov_b32_e32 v136, v140
	v_mov_b32_e32 v137, v140
	v_mov_b32_e32 v138, v140
	v_mov_b32_e32 v139, v140
	v_mov_b32_e32 v144, v140
	v_mov_b32_e32 v145, v140
	v_mov_b32_e32 v146, v140
	v_mov_b32_e32 v147, v140
	v_mov_b32_e32 v148, v140
	v_mov_b32_e32 v149, v140
	v_mov_b32_e32 v150, v140
	v_mov_b32_e32 v151, v140
	v_mov_b32_e32 v152, v140
	v_mov_b32_e32 v153, v140
	v_mov_b32_e32 v154, v140
	v_mov_b32_e32 v155, v140
	v_mov_b32_e32 v156, v140
	v_mov_b32_e32 v157, v140
	v_mov_b32_e32 v158, v140
	v_mov_b32_e32 v159, v140
	v_mov_b32_e32 v160, v140
	v_mov_b32_e32 v161, v140
	v_mov_b32_e32 v162, v140
	v_mov_b32_e32 v163, v140
	v_mov_b32_e32 v164, v140
	v_mov_b32_e32 v165, v140
	v_mov_b32_e32 v166, v140
	v_mov_b32_e32 v167, v140
	v_mov_b32_e32 v168, v140
	v_mov_b32_e32 v169, v140
	v_mov_b32_e32 v170, v140
	v_mov_b32_e32 v171, v140
	v_mov_b32_e32 v172, v140
	v_mov_b32_e32 v173, v140
	v_mov_b32_e32 v174, v140
	v_mov_b32_e32 v175, v140
	s_setprio 2
	v_readlane_b32 s98, v253, 3
	v_readlane_b32 s99, v253, 4
	v_and_b32_e32 v224, 15, v188
	v_bfe_u32 v225, v188, 4, 2
	v_lshrrev_b32_e32 v226, 2, v224
	v_sub_u32_e32 v226, 0, v226
	v_and_b32_e32 v226, 3, v226
	v_xor_b32_e32 v225, v225, v226
	v_lshlrev_b32_e32 v225, 4, v225
	v_lshl_or_b32 v225, v224, 6, v225
	v_bfe_u32 v226, v188, 7, 1
	v_lshl_or_b32 v185, v226, 13, v225
	v_bfe_u32 v226, v188, 6, 1
	v_lshl_or_b32 v184, v226, 12, v225
	v_add_u32_e32 v184, 0x4000, v184
	v_lshrrev_b32_e32 v224, 3, v188
	v_bfe_u32 v225, v188, 2, 1
	v_lshrrev_b32_e32 v226, 2, v224
	v_sub_u32_e32 v226, 0, v226
	v_and_b32_e32 v226, 3, v226
	v_and_b32_e32 v227, 3, v188
	v_xor_b32_e32 v226, v227, v226
	v_lshlrev_b32_e32 v226, 4, v226
	v_xor_b32_e32 v224, v224, v225
	v_lshl_or_b32 v226, v224, 6, v226
	v_mul_u32_u24_e32 v225, 0x6000, v225
	v_add_u32_e32 v183, v225, v226
	s_mov_b32 m0, 0
	s_sub_u32 vcc_lo, s6, s98
	v_add_u32_e32 v186, vcc_lo, v178
	v_add_u32_e32 v187, vcc_lo, v180
	s_barrier
	s_waitcnt vmcnt(0)
	ds_write_b128 v183, v[116:119]
	ds_write_b128 v183, v[112:115] offset:2048
	ds_write_b128 v183, v[104:107] offset:4096
	ds_write_b128 v183, v[88:91] offset:6144
	ds_write_b128 v183, v[80:83] offset:8192
	ds_write_b128 v183, v[68:71] offset:10240
	ds_write_b128 v183, v[60:63] offset:12288
	ds_write_b128 v183, v[40:43] offset:14336
	ds_write_b128 v183, v[56:59] offset:16384
	ds_write_b128 v183, v[32:35] offset:18432
	ds_write_b128 v183, v[16:19] offset:20480
	ds_write_b128 v183, v[8:11] offset:22528
	v_cmp_gt_u32_e32 vcc, 0x6000, v183
	v_add_u32_e32 v182, 0xc000, v183
	v_add_u32_e32 v183, 0xffffa000, v183
	s_nop 0
	v_cndmask_b32_e32 v183, v183, v182, vcc
	v_add_u32_e32 v116, s26, v187
	global_load_dwordx4 v[116:119], v116, s[98:99] offset:128
	v_add_u32_e32 v112, s27, v187
	global_load_dwordx4 v[112:115], v112, s[98:99] offset:128
	v_add_u32_e32 v104, s20, v187
	global_load_dwordx4 v[104:107], v104, s[98:99] offset:128
	v_add_u32_e32 v88, s21, v187
	global_load_dwordx4 v[88:91], v88, s[98:99] offset:128
	v_add_u32_e32 v80, s56, v187
	global_load_dwordx4 v[80:83], v80, s[98:99] offset:128
	v_add_u32_e32 v68, s57, v187
	global_load_dwordx4 v[68:71], v68, s[98:99] offset:128
	v_add_u32_e32 v60, s24, v187
	global_load_dwordx4 v[60:63], v60, s[98:99] offset:128
	v_add_u32_e32 v40, s96, v187
	global_load_dwordx4 v[40:43], v40, s[98:99] offset:128
	v_mov_b32_e32 v56, v186
	global_load_dwordx4 v[56:59], v56, s[98:99] offset:128
	v_add_u32_e32 v32, s13, v186
	global_load_dwordx4 v[32:35], v32, s[98:99] offset:128
	v_add_u32_e32 v16, s12, v186
	global_load_dwordx4 v[16:19], v16, s[98:99] offset:128
	v_add_u32_e32 v8, s11, v186
	global_load_dwordx4 v[8:11], v8, s[98:99] offset:128
	s_add_u32 s6, s6, 0x80
	s_addc_u32 s7, s7, 0
.LBB0_802:
	s_waitcnt lgkmcnt(0)
	s_barrier
	ds_read_b128 v[224:227], v184
	ds_read_b128 v[228:231], v184 offset:1024
	ds_read_b128 v[232:235], v184 offset:2048
	ds_read_b128 v[236:239], v184 offset:3072
	ds_read_b128 v[190:193], v185
	ds_read_b128 v[194:197], v185 offset:1024
	ds_read_b128 v[198:201], v185 offset:2048
	ds_read_b128 v[204:207], v185 offset:3072
	ds_read_b128 v[208:211], v185 offset:4096
	ds_read_b128 v[212:215], v185 offset:5120
	ds_read_b128 v[216:219], v185 offset:6144
	ds_read_b128 v[220:223], v185 offset:7168
	s_movk_i32 vcc_lo, 0x6000
	s_cmp_eq_u32 m0, 2
	s_cselect_b32 vcc_lo, 0xffff4000, vcc_lo
	s_add_u32 m0, m0, 1
	s_cmp_eq_u32 m0, 3
	s_cselect_b32 m0, 0, m0
	v_add_u32_e32 v185, vcc_lo, v185
	v_add_u32_e32 v184, vcc_lo, v184
	v_xor_b32_e32 v185, 64, v185
	v_xor_b32_e32 v184, 64, v184
	s_waitcnt lgkmcnt(7)
	v_mfma_f32_16x16x32_bf16 v[172:175], v[224:227], v[190:193], v[172:175]
	v_mfma_f32_16x16x32_bf16 v[168:171], v[228:231], v[190:193], v[168:171]
	v_mfma_f32_16x16x32_bf16 v[164:167], v[232:235], v[190:193], v[164:167]
	v_mfma_f32_16x16x32_bf16 v[160:163], v[236:239], v[190:193], v[160:163]
	ds_read_b128 v[190:193], v185
	s_waitcnt lgkmcnt(7)
	v_mfma_f32_16x16x32_bf16 v[156:159], v[224:227], v[194:197], v[156:159]
	v_mfma_f32_16x16x32_bf16 v[152:155], v[228:231], v[194:197], v[152:155]
	v_mfma_f32_16x16x32_bf16 v[148:151], v[232:235], v[194:197], v[148:151]
	v_mfma_f32_16x16x32_bf16 v[144:147], v[236:239], v[194:197], v[144:147]
	ds_read_b128 v[194:197], v185 offset:1024
	s_waitcnt lgkmcnt(7)
	v_mfma_f32_16x16x32_bf16 v[136:139], v[224:227], v[198:201], v[136:139]
	v_mfma_f32_16x16x32_bf16 v[132:135], v[228:231], v[198:201], v[132:135]
	v_mfma_f32_16x16x32_bf16 v[128:131], v[232:235], v[198:201], v[128:131]
	v_mfma_f32_16x16x32_bf16 v[124:127], v[236:239], v[198:201], v[124:127]
	ds_read_b128 v[198:201], v185 offset:2048
	s_waitcnt lgkmcnt(7)
	v_mfma_f32_16x16x32_bf16 v[120:123], v[224:227], v[204:207], v[120:123]
	v_mfma_f32_16x16x32_bf16 v[108:111], v[228:231], v[204:207], v[108:111]
	v_mfma_f32_16x16x32_bf16 v[100:103], v[232:235], v[204:207], v[100:103]
	v_mfma_f32_16x16x32_bf16 v[96:99], v[236:239], v[204:207], v[96:99]
	ds_read_b128 v[204:207], v185 offset:3072
	s_waitcnt lgkmcnt(7)
	v_mfma_f32_16x16x32_bf16 v[92:95], v[224:227], v[208:211], v[92:95]
	v_mfma_f32_16x16x32_bf16 v[84:87], v[228:231], v[208:211], v[84:87]
	v_mfma_f32_16x16x32_bf16 v[76:79], v[232:235], v[208:211], v[76:79]
	v_mfma_f32_16x16x32_bf16 v[72:75], v[236:239], v[208:211], v[72:75]
	ds_read_b128 v[208:211], v185 offset:4096
	s_waitcnt lgkmcnt(7)
	v_mfma_f32_16x16x32_bf16 v[64:67], v[224:227], v[212:215], v[64:67]
	v_mfma_f32_16x16x32_bf16 v[52:55], v[228:231], v[212:215], v[52:55]
	v_mfma_f32_16x16x32_bf16 v[48:51], v[232:235], v[212:215], v[48:51]
	v_mfma_f32_16x16x32_bf16 v[44:47], v[236:239], v[212:215], v[44:47]
	ds_read_b128 v[212:215], v185 offset:5120
	s_waitcnt lgkmcnt(7)
	v_mfma_f32_16x16x32_bf16 v[36:39], v[224:227], v[216:219], v[36:39]
	v_mfma_f32_16x16x32_bf16 v[28:31], v[228:231], v[216:219], v[28:31]
	v_mfma_f32_16x16x32_bf16 v[24:27], v[232:235], v[216:219], v[24:27]
	v_mfma_f32_16x16x32_bf16 v[20:23], v[236:239], v[216:219], v[20:23]
	ds_read_b128 v[216:219], v185 offset:6144
	s_waitcnt lgkmcnt(7)
	v_mfma_f32_16x16x32_bf16 v[12:15], v[224:227], v[220:223], v[12:15]
	v_mfma_f32_16x16x32_bf16 v[4:7], v[228:231], v[220:223], v[4:7]
	v_mfma_f32_16x16x32_bf16 v[0:3], v[232:235], v[220:223], v[0:3]
	v_mfma_f32_16x16x32_bf16 v[140:143], v[236:239], v[220:223], v[140:143]
	ds_read_b128 v[220:223], v185 offset:7168
	ds_read_b128 v[224:227], v184
	ds_read_b128 v[228:231], v184 offset:1024
	ds_read_b128 v[232:235], v184 offset:2048
	ds_read_b128 v[236:239], v184 offset:3072
	s_movk_i32 vcc_lo, 0x6000
	s_cmp_eq_u32 m0, 2
	s_cselect_b32 vcc_lo, 0xffff4000, vcc_lo
	s_add_u32 m0, m0, 1
	s_cmp_eq_u32 m0, 3
	s_cselect_b32 m0, 0, m0
	v_add_u32_e32 v185, vcc_lo, v185
	v_add_u32_e32 v184, vcc_lo, v184
	v_xor_b32_e32 v185, 64, v185
	v_xor_b32_e32 v184, 64, v184
	s_sub_u32 vcc_lo, s6, s98
	v_add_u32_e32 v186, vcc_lo, v178
	v_add_u32_e32 v187, vcc_lo, v180
	s_barrier
	s_waitcnt lgkmcnt(0)
	v_mfma_f32_16x16x32_bf16 v[172:175], v[224:227], v[190:193], v[172:175]
	s_waitcnt vmcnt(11)
	v_mfma_f32_16x16x32_bf16 v[168:171], v[228:231], v[190:193], v[168:171]
	ds_write_b128 v183, v[116:119]
	v_add_u32_e32 v116, s26, v187
	v_mfma_f32_16x16x32_bf16 v[164:167], v[232:235], v[190:193], v[164:167]
	global_load_dwordx4 v[116:119], v116, s[98:99] offset:128
	v_mfma_f32_16x16x32_bf16 v[160:163], v[236:239], v[190:193], v[160:163]
	s_waitcnt vmcnt(11)
	ds_write_b128 v183, v[112:115] offset:2048
	v_mfma_f32_16x16x32_bf16 v[156:159], v[224:227], v[194:197], v[156:159]
	v_add_u32_e32 v112, s27, v187
	v_mfma_f32_16x16x32_bf16 v[152:155], v[228:231], v[194:197], v[152:155]
	global_load_dwordx4 v[112:115], v112, s[98:99] offset:128
	s_waitcnt vmcnt(11)
	v_mfma_f32_16x16x32_bf16 v[148:151], v[232:235], v[194:197], v[148:151]
	ds_write_b128 v183, v[104:107] offset:4096
	v_mfma_f32_16x16x32_bf16 v[144:147], v[236:239], v[194:197], v[144:147]
	v_add_u32_e32 v104, s20, v187
	global_load_dwordx4 v[104:107], v104, s[98:99] offset:128
	v_mfma_f32_16x16x32_bf16 v[136:139], v[224:227], v[198:201], v[136:139]
	s_waitcnt vmcnt(11)
	v_mfma_f32_16x16x32_bf16 v[132:135], v[228:231], v[198:201], v[132:135]
	ds_write_b128 v183, v[88:91] offset:6144
	v_add_u32_e32 v88, s21, v187
	v_mfma_f32_16x16x32_bf16 v[128:131], v[232:235], v[198:201], v[128:131]
	global_load_dwordx4 v[88:91], v88, s[98:99] offset:128
	v_mfma_f32_16x16x32_bf16 v[124:127], v[236:239], v[198:201], v[124:127]
	s_waitcnt vmcnt(11)
	ds_write_b128 v183, v[80:83] offset:8192
	v_mfma_f32_16x16x32_bf16 v[120:123], v[224:227], v[204:207], v[120:123]
	v_add_u32_e32 v80, s56, v187
	v_mfma_f32_16x16x32_bf16 v[108:111], v[228:231], v[204:207], v[108:111]
	global_load_dwordx4 v[80:83], v80, s[98:99] offset:128
	s_waitcnt vmcnt(11)
	v_mfma_f32_16x16x32_bf16 v[100:103], v[232:235], v[204:207], v[100:103]
	ds_write_b128 v183, v[68:71] offset:10240
	v_mfma_f32_16x16x32_bf16 v[96:99], v[236:239], v[204:207], v[96:99]
	v_add_u32_e32 v68, s57, v187
	global_load_dwordx4 v[68:71], v68, s[98:99] offset:128
	v_mfma_f32_16x16x32_bf16 v[92:95], v[224:227], v[208:211], v[92:95]
	s_waitcnt vmcnt(11)
	v_mfma_f32_16x16x32_bf16 v[84:87], v[228:231], v[208:211], v[84:87]
	ds_write_b128 v183, v[60:63] offset:12288
	v_add_u32_e32 v60, s24, v187
	v_mfma_f32_16x16x32_bf16 v[76:79], v[232:235], v[208:211], v[76:79]
	global_load_dwordx4 v[60:63], v60, s[98:99] offset:128
	v_mfma_f32_16x16x32_bf16 v[72:75], v[236:239], v[208:211], v[72:75]
	s_waitcnt vmcnt(11)
	ds_write_b128 v183, v[40:43] offset:14336
	v_mfma_f32_16x16x32_bf16 v[64:67], v[224:227], v[212:215], v[64:67]
	v_add_u32_e32 v40, s96, v187
	v_mfma_f32_16x16x32_bf16 v[52:55], v[228:231], v[212:215], v[52:55]
	global_load_dwordx4 v[40:43], v40, s[98:99] offset:128
	s_waitcnt vmcnt(11)
	v_mfma_f32_16x16x32_bf16 v[48:51], v[232:235], v[212:215], v[48:51]
	ds_write_b128 v183, v[56:59] offset:16384
	v_mfma_f32_16x16x32_bf16 v[44:47], v[236:239], v[212:215], v[44:47]
	v_mov_b32_e32 v56, v186
	global_load_dwordx4 v[56:59], v56, s[98:99] offset:128
	v_mfma_f32_16x16x32_bf16 v[36:39], v[224:227], v[216:219], v[36:39]
	s_waitcnt vmcnt(11)
	v_mfma_f32_16x16x32_bf16 v[28:31], v[228:231], v[216:219], v[28:31]
	ds_write_b128 v183, v[32:35] offset:18432
	v_add_u32_e32 v32, s13, v186
	v_mfma_f32_16x16x32_bf16 v[24:27], v[232:235], v[216:219], v[24:27]
	global_load_dwordx4 v[32:35], v32, s[98:99] offset:128
	v_mfma_f32_16x16x32_bf16 v[20:23], v[236:239], v[216:219], v[20:23]
	s_waitcnt vmcnt(11)
	ds_write_b128 v183, v[16:19] offset:20480
	v_mfma_f32_16x16x32_bf16 v[12:15], v[224:227], v[220:223], v[12:15]
	v_add_u32_e32 v16, s12, v186
	v_mfma_f32_16x16x32_bf16 v[4:7], v[228:231], v[220:223], v[4:7]
	global_load_dwordx4 v[16:19], v16, s[98:99] offset:128
	s_waitcnt vmcnt(11)
	v_mfma_f32_16x16x32_bf16 v[0:3], v[232:235], v[220:223], v[0:3]
	ds_write_b128 v183, v[8:11] offset:22528
	v_mfma_f32_16x16x32_bf16 v[140:143], v[236:239], v[220:223], v[140:143]
	v_add_u32_e32 v8, s11, v186
	global_load_dwordx4 v[8:11], v8, s[98:99] offset:128
	v_cmp_gt_u32_e32 vcc, 0x6000, v183
	v_add_u32_e32 v182, 0xc000, v183
	v_add_u32_e32 v183, 0xffffa000, v183
	s_nop 0
	v_cndmask_b32_e32 v183, v183, v182, vcc
	s_add_u32 s6, s6, 0x80
	s_addc_u32 s7, s7, 0
	s_cmpk_lg_i32 s6, 0x780
	s_cbranch_scc1 .LBB0_802
	s_waitcnt lgkmcnt(0)
	s_barrier
	ds_read_b128 v[224:227], v184
	ds_read_b128 v[228:231], v184 offset:1024
	ds_read_b128 v[232:235], v184 offset:2048
	ds_read_b128 v[236:239], v184 offset:3072
	ds_read_b128 v[190:193], v185
	ds_read_b128 v[194:197], v185 offset:1024
	ds_read_b128 v[198:201], v185 offset:2048
	ds_read_b128 v[204:207], v185 offset:3072
	ds_read_b128 v[208:211], v185 offset:4096
	ds_read_b128 v[212:215], v185 offset:5120
	ds_read_b128 v[216:219], v185 offset:6144
	ds_read_b128 v[220:223], v185 offset:7168
	s_movk_i32 vcc_lo, 0x6000
	s_cmp_eq_u32 m0, 2
	s_cselect_b32 vcc_lo, 0xffff4000, vcc_lo
	s_add_u32 m0, m0, 1
	s_cmp_eq_u32 m0, 3
	s_cselect_b32 m0, 0, m0
	v_add_u32_e32 v185, vcc_lo, v185
	v_add_u32_e32 v184, vcc_lo, v184
	v_xor_b32_e32 v185, 64, v185
	v_xor_b32_e32 v184, 64, v184
	s_waitcnt lgkmcnt(7)
	v_mfma_f32_16x16x32_bf16 v[172:175], v[224:227], v[190:193], v[172:175]
	v_mfma_f32_16x16x32_bf16 v[168:171], v[228:231], v[190:193], v[168:171]
	v_mfma_f32_16x16x32_bf16 v[164:167], v[232:235], v[190:193], v[164:167]
	v_mfma_f32_16x16x32_bf16 v[160:163], v[236:239], v[190:193], v[160:163]
	ds_read_b128 v[190:193], v185
	s_waitcnt lgkmcnt(7)
	v_mfma_f32_16x16x32_bf16 v[156:159], v[224:227], v[194:197], v[156:159]
	v_mfma_f32_16x16x32_bf16 v[152:155], v[228:231], v[194:197], v[152:155]
	v_mfma_f32_16x16x32_bf16 v[148:151], v[232:235], v[194:197], v[148:151]
	v_mfma_f32_16x16x32_bf16 v[144:147], v[236:239], v[194:197], v[144:147]
	ds_read_b128 v[194:197], v185 offset:1024
	s_waitcnt lgkmcnt(7)
	v_mfma_f32_16x16x32_bf16 v[136:139], v[224:227], v[198:201], v[136:139]
	v_mfma_f32_16x16x32_bf16 v[132:135], v[228:231], v[198:201], v[132:135]
	v_mfma_f32_16x16x32_bf16 v[128:131], v[232:235], v[198:201], v[128:131]
	v_mfma_f32_16x16x32_bf16 v[124:127], v[236:239], v[198:201], v[124:127]
	ds_read_b128 v[198:201], v185 offset:2048
	s_waitcnt lgkmcnt(7)
	v_mfma_f32_16x16x32_bf16 v[120:123], v[224:227], v[204:207], v[120:123]
	v_mfma_f32_16x16x32_bf16 v[108:111], v[228:231], v[204:207], v[108:111]
	v_mfma_f32_16x16x32_bf16 v[100:103], v[232:235], v[204:207], v[100:103]
	v_mfma_f32_16x16x32_bf16 v[96:99], v[236:239], v[204:207], v[96:99]
	ds_read_b128 v[204:207], v185 offset:3072
	s_waitcnt lgkmcnt(7)
	v_mfma_f32_16x16x32_bf16 v[92:95], v[224:227], v[208:211], v[92:95]
	v_mfma_f32_16x16x32_bf16 v[84:87], v[228:231], v[208:211], v[84:87]
	v_mfma_f32_16x16x32_bf16 v[76:79], v[232:235], v[208:211], v[76:79]
	v_mfma_f32_16x16x32_bf16 v[72:75], v[236:239], v[208:211], v[72:75]
	ds_read_b128 v[208:211], v185 offset:4096
	s_waitcnt lgkmcnt(7)
	v_mfma_f32_16x16x32_bf16 v[64:67], v[224:227], v[212:215], v[64:67]
	v_mfma_f32_16x16x32_bf16 v[52:55], v[228:231], v[212:215], v[52:55]
	v_mfma_f32_16x16x32_bf16 v[48:51], v[232:235], v[212:215], v[48:51]
	v_mfma_f32_16x16x32_bf16 v[44:47], v[236:239], v[212:215], v[44:47]
	ds_read_b128 v[212:215], v185 offset:5120
	s_waitcnt lgkmcnt(7)
	v_mfma_f32_16x16x32_bf16 v[36:39], v[224:227], v[216:219], v[36:39]
	v_mfma_f32_16x16x32_bf16 v[28:31], v[228:231], v[216:219], v[28:31]
	v_mfma_f32_16x16x32_bf16 v[24:27], v[232:235], v[216:219], v[24:27]
	v_mfma_f32_16x16x32_bf16 v[20:23], v[236:239], v[216:219], v[20:23]
	ds_read_b128 v[216:219], v185 offset:6144
	s_waitcnt lgkmcnt(7)
	v_mfma_f32_16x16x32_bf16 v[12:15], v[224:227], v[220:223], v[12:15]
	v_mfma_f32_16x16x32_bf16 v[4:7], v[228:231], v[220:223], v[4:7]
	v_mfma_f32_16x16x32_bf16 v[0:3], v[232:235], v[220:223], v[0:3]
	v_mfma_f32_16x16x32_bf16 v[140:143], v[236:239], v[220:223], v[140:143]
	ds_read_b128 v[220:223], v185 offset:7168
	ds_read_b128 v[224:227], v184
	ds_read_b128 v[228:231], v184 offset:1024
	ds_read_b128 v[232:235], v184 offset:2048
	ds_read_b128 v[236:239], v184 offset:3072
	s_movk_i32 vcc_lo, 0x6000
	s_cmp_eq_u32 m0, 2
	s_cselect_b32 vcc_lo, 0xffff4000, vcc_lo
	s_add_u32 m0, m0, 1
	s_cmp_eq_u32 m0, 3
	s_cselect_b32 m0, 0, m0
	v_add_u32_e32 v185, vcc_lo, v185
	v_add_u32_e32 v184, vcc_lo, v184
	v_xor_b32_e32 v185, 64, v185
	v_xor_b32_e32 v184, 64, v184
	s_waitcnt lgkmcnt(0)
	v_mfma_f32_16x16x32_bf16 v[172:175], v[224:227], v[190:193], v[172:175]
	v_mfma_f32_16x16x32_bf16 v[168:171], v[228:231], v[190:193], v[168:171]
	v_mfma_f32_16x16x32_bf16 v[164:167], v[232:235], v[190:193], v[164:167]
	v_mfma_f32_16x16x32_bf16 v[160:163], v[236:239], v[190:193], v[160:163]
	v_mfma_f32_16x16x32_bf16 v[156:159], v[224:227], v[194:197], v[156:159]
	v_mfma_f32_16x16x32_bf16 v[152:155], v[228:231], v[194:197], v[152:155]
	v_mfma_f32_16x16x32_bf16 v[148:151], v[232:235], v[194:197], v[148:151]
	v_mfma_f32_16x16x32_bf16 v[144:147], v[236:239], v[194:197], v[144:147]
	v_mfma_f32_16x16x32_bf16 v[136:139], v[224:227], v[198:201], v[136:139]
	v_mfma_f32_16x16x32_bf16 v[132:135], v[228:231], v[198:201], v[132:135]
	v_mfma_f32_16x16x32_bf16 v[128:131], v[232:235], v[198:201], v[128:131]
	v_mfma_f32_16x16x32_bf16 v[124:127], v[236:239], v[198:201], v[124:127]
	v_mfma_f32_16x16x32_bf16 v[120:123], v[224:227], v[204:207], v[120:123]
	v_mfma_f32_16x16x32_bf16 v[108:111], v[228:231], v[204:207], v[108:111]
	v_mfma_f32_16x16x32_bf16 v[100:103], v[232:235], v[204:207], v[100:103]
	v_mfma_f32_16x16x32_bf16 v[96:99], v[236:239], v[204:207], v[96:99]
	v_mfma_f32_16x16x32_bf16 v[92:95], v[224:227], v[208:211], v[92:95]
	v_mfma_f32_16x16x32_bf16 v[84:87], v[228:231], v[208:211], v[84:87]
	v_mfma_f32_16x16x32_bf16 v[76:79], v[232:235], v[208:211], v[76:79]
	v_mfma_f32_16x16x32_bf16 v[72:75], v[236:239], v[208:211], v[72:75]
	v_mfma_f32_16x16x32_bf16 v[64:67], v[224:227], v[212:215], v[64:67]
	v_mfma_f32_16x16x32_bf16 v[52:55], v[228:231], v[212:215], v[52:55]
	v_mfma_f32_16x16x32_bf16 v[48:51], v[232:235], v[212:215], v[48:51]
	v_mfma_f32_16x16x32_bf16 v[44:47], v[236:239], v[212:215], v[44:47]
	v_mfma_f32_16x16x32_bf16 v[36:39], v[224:227], v[216:219], v[36:39]
	v_mfma_f32_16x16x32_bf16 v[28:31], v[228:231], v[216:219], v[28:31]
	v_mfma_f32_16x16x32_bf16 v[24:27], v[232:235], v[216:219], v[24:27]
	v_mfma_f32_16x16x32_bf16 v[20:23], v[236:239], v[216:219], v[20:23]
	v_mfma_f32_16x16x32_bf16 v[12:15], v[224:227], v[220:223], v[12:15]
	v_mfma_f32_16x16x32_bf16 v[4:7], v[228:231], v[220:223], v[4:7]
	v_mfma_f32_16x16x32_bf16 v[0:3], v[232:235], v[220:223], v[0:3]
	v_mfma_f32_16x16x32_bf16 v[140:143], v[236:239], v[220:223], v[140:143]
	v_lshrrev_b32_e32 v224, 4, v188
	v_and_b32_e32 v225, 7, v188
	v_bitop3_b32 v226, v224, v225, 3 bitop3:0x6c
	v_lshlrev_b32_e32 v227, 7, v188
	v_bfe_u32 v228, v188, 4, 2
	v_and_b32_e32 v229, 0xffffc780, v227
	v_and_b32_e32 v227, 0x2780, v227
	v_bitop3_b32 v228, v228, v225, 4 bitop3:0x36
	v_lshlrev_b32_e32 v226, 4, v226
	v_lshlrev_b32_e32 v228, 4, v228
	v_or_b32_e32 v185, v229, v226
	v_or_b32_e32 v184, v227, v226
	v_or_b32_e32 v183, v229, v228
	v_or_b32_e32 v182, v227, v228
	s_waitcnt vmcnt(0)
	s_setprio 0
	s_barrier
	s_waitcnt vmcnt(10)
	ds_write_b128 v176, v[116:119]
	s_waitcnt vmcnt(9)
	ds_write_b128 v176, v[112:115] offset:4096
	s_waitcnt vmcnt(8)
	ds_write_b128 v176, v[104:107] offset:8192
	s_waitcnt vmcnt(7)
	ds_write_b128 v176, v[88:91] offset:12288
	s_waitcnt vmcnt(6)
	ds_write_b128 v176, v[80:83] offset:16384
	s_waitcnt vmcnt(5)
	ds_write_b128 v176, v[68:71] offset:20480
	s_waitcnt vmcnt(4)
	ds_write_b128 v176, v[60:63] offset:24576
	s_waitcnt vmcnt(3)
	ds_write_b128 v176, v[40:43] offset:28672
	ds_write_b128 v176, v[56:59] offset:32768
	s_waitcnt vmcnt(2)
	ds_write_b128 v176, v[32:35] offset:36864
	s_waitcnt vmcnt(1)
	ds_write_b128 v176, v[16:19] offset:40960
	s_waitcnt vmcnt(0)
	ds_write_b128 v176, v[8:11] offset:45056
	s_waitcnt lgkmcnt(0)
	s_barrier
	ds_read_b128 v[8:11], v185
	ds_read_b128 v[16:19], v185 offset:2048
	ds_read_b128 v[32:35], v185 offset:4096
	ds_read_b128 v[40:43], v185 offset:6144
	ds_read_b128 v[56:59], v185 offset:8192
	ds_read_b128 v[60:63], v185 offset:10240
	ds_read_b128 v[68:71], v185 offset:12288
	ds_read_b128 v[80:83], v185 offset:14336
	ds_read_b128 v[88:91], v184 offset:32768
	ds_read_b128 v[104:107], v184 offset:34816
	ds_read_b128 v[112:115], v184 offset:36864
	ds_read_b128 v[116:119], v184 offset:38912
	s_waitcnt lgkmcnt(3)
	v_mfma_f32_16x16x32_bf16 v[172:175], v[88:91], v[8:11], v[172:175]
	s_waitcnt lgkmcnt(2)
	v_mfma_f32_16x16x32_bf16 v[168:171], v[104:107], v[8:11], v[168:171]
	s_waitcnt lgkmcnt(1)
	v_mfma_f32_16x16x32_bf16 v[164:167], v[112:115], v[8:11], v[164:167]
	s_waitcnt lgkmcnt(0)
	v_mfma_f32_16x16x32_bf16 v[8:11], v[116:119], v[8:11], v[160:163]
	v_mfma_f32_16x16x32_bf16 v[156:159], v[88:91], v[16:19], v[156:159]
	v_mfma_f32_16x16x32_bf16 v[152:155], v[104:107], v[16:19], v[152:155]
	v_mfma_f32_16x16x32_bf16 v[148:151], v[112:115], v[16:19], v[148:151]
	v_mfma_f32_16x16x32_bf16 v[16:19], v[116:119], v[16:19], v[144:147]
	v_mfma_f32_16x16x32_bf16 v[136:139], v[88:91], v[32:35], v[136:139]
	v_mfma_f32_16x16x32_bf16 v[132:135], v[104:107], v[32:35], v[132:135]
	v_mfma_f32_16x16x32_bf16 v[128:131], v[112:115], v[32:35], v[128:131]
	v_mfma_f32_16x16x32_bf16 v[32:35], v[116:119], v[32:35], v[124:127]
	v_mfma_f32_16x16x32_bf16 v[120:123], v[88:91], v[40:43], v[120:123]
	v_mfma_f32_16x16x32_bf16 v[108:111], v[104:107], v[40:43], v[108:111]
	v_mfma_f32_16x16x32_bf16 v[100:103], v[112:115], v[40:43], v[100:103]
	v_mfma_f32_16x16x32_bf16 v[40:43], v[116:119], v[40:43], v[96:99]
	v_mfma_f32_16x16x32_bf16 v[92:95], v[88:91], v[56:59], v[92:95]
	v_mfma_f32_16x16x32_bf16 v[84:87], v[104:107], v[56:59], v[84:87]
	v_mfma_f32_16x16x32_bf16 v[76:79], v[112:115], v[56:59], v[76:79]
	v_mfma_f32_16x16x32_bf16 v[56:59], v[116:119], v[56:59], v[72:75]
	v_mfma_f32_16x16x32_bf16 v[64:67], v[88:91], v[60:63], v[64:67]
	v_mfma_f32_16x16x32_bf16 v[52:55], v[104:107], v[60:63], v[52:55]
	v_mfma_f32_16x16x32_bf16 v[72:75], v[112:115], v[60:63], v[48:51]
	v_mfma_f32_16x16x32_bf16 v[60:63], v[116:119], v[60:63], v[44:47]
	v_mfma_f32_16x16x32_bf16 v[96:99], v[88:91], v[68:71], v[36:39]
	v_mfma_f32_16x16x32_bf16 v[28:31], v[104:107], v[68:71], v[28:31]
	v_mfma_f32_16x16x32_bf16 v[124:127], v[112:115], v[68:71], v[24:27]
	v_mfma_f32_16x16x32_bf16 v[20:23], v[116:119], v[68:71], v[20:23]
	v_mfma_f32_16x16x32_bf16 v[12:15], v[88:91], v[80:83], v[12:15]
	v_mfma_f32_16x16x32_bf16 v[4:7], v[104:107], v[80:83], v[4:7]
	v_mfma_f32_16x16x32_bf16 v[0:3], v[112:115], v[80:83], v[0:3]
	v_mfma_f32_16x16x32_bf16 v[68:71], v[116:119], v[80:83], v[140:143]
	ds_read_b128 v[24:27], v183
	ds_read_b128 v[36:39], v183 offset:2048
	ds_read_b128 v[44:47], v183 offset:4096
	ds_read_b128 v[80:83], v183 offset:6144
	ds_read_b128 v[88:91], v183 offset:8192
	ds_read_b128 v[104:107], v183 offset:10240
	ds_read_b128 v[112:115], v183 offset:12288
	ds_read_b128 v[116:119], v183 offset:14336
	ds_read_b128 v[140:143], v182 offset:32768
	ds_read_b128 v[144:147], v182 offset:34816
	ds_read_b128 v[160:163], v182 offset:36864
	ds_read_b128 v[178:181], v182 offset:38912
	s_waitcnt lgkmcnt(3)
	v_mfma_f32_16x16x32_bf16 v[172:175], v[140:143], v[24:27], v[172:175]
	v_mov_b32_e32 v49, v188
	v_cmp_lt_i32_e32 vcc, v189, v202
	s_waitcnt lgkmcnt(2)
	v_mfma_f32_16x16x32_bf16 v[168:171], v[144:147], v[24:27], v[168:171]
	v_mov_b32_e32 v48, v188
	v_readlane_b32 s6, v253, 24
	s_waitcnt lgkmcnt(1)
	v_mfma_f32_16x16x32_bf16 v[164:167], v[160:163], v[24:27], v[164:167]
	v_and_b32_e32 v50, 0xffffff80, v48
	v_add_u32_e32 v51, s9, v50
	v_and_or_b32 v50, v48, 64, s10
	s_waitcnt lgkmcnt(0)
	v_mfma_f32_16x16x32_bf16 v[8:11], v[178:181], v[24:27], v[8:11]
	v_bfe_u32 v26, v49, 4, 1
	v_cndmask_b32_e32 v24, v203, v189, vcc
	v_cmp_eq_u32_e32 vcc, 0, v26
	v_lshlrev_b32_e32 v186, 2, v24
	v_mfma_f32_16x16x32_bf16 v[182:185], v[178:181], v[36:39], v[16:19]
	v_and_or_b32 v48, v49, 15, v51
	v_ashrrev_i32_e32 v51, 31, v50
	v_lshl_add_u64 v[50:51], v[50:51], 1, s[4:5]
	s_nop 0
	s_nop 0
	s_nop 0
	s_nop 0
	s_nop 0
	s_nop 0
	s_nop 0
	s_nop 0
	v_lshlrev_b32_e32 v176, 5, v26
	v_lshrrev_b32_e32 v27, 1, v49
	v_lshl_add_u64 v[24:25], v[50:51], 0, v[176:177]
	v_and_b32_e32 v176, 16, v27
	v_ashrrev_i32_e32 v49, 31, v48
	v_mfma_f32_16x16x32_bf16 v[156:159], v[140:143], v[36:39], v[156:159]
	v_lshl_add_u64 v[50:51], v[24:25], 0, v[176:177]
	v_lshlrev_b64 v[24:25], 11, v[48:49]
	s_waitcnt lgkmcnt(0)
	s_nop 0
	v_mfma_f32_16x16x32_bf16 v[152:155], v[144:147], v[36:39], v[152:155]
	v_mov_b32_e32 v26, v172
	v_mov_b32_e32 v27, v168
	s_nop 1
	v_permlane16_swap_b32_e32 v26, v27
	s_waitcnt lgkmcnt(0)
	s_nop 0
	v_lshl_add_u64 v[24:25], v[50:51], 0, v[24:25]
	v_mfma_f32_16x16x32_bf16 v[148:151], v[160:163], v[36:39], v[148:151]
	v_mov_b32_e32 v16, v173
	v_mov_b32_e32 v36, v169
	s_nop 1
	v_permlane16_swap_b32_e32 v16, v36
	s_waitcnt lgkmcnt(0)
	s_nop 0
	v_cvt_pk_bf16_f32 v16, v26, v16
	v_mfma_f32_16x16x32_bf16 v[190:193], v[178:181], v[44:47], v[32:35]
	v_readlane_b32 s7, v253, 25
	s_nop 1
	v_mov_b32_e32 v17, v174
	v_mov_b32_e32 v32, v170
	s_nop 1
	v_permlane16_swap_b32_e32 v17, v32
	s_waitcnt lgkmcnt(0)
	s_nop 0
	v_mov_b32_e32 v18, v175
	v_mov_b32_e32 v19, v171
	s_nop 1
	v_permlane16_swap_b32_e32 v18, v19
	v_cvt_pk_bf16_f32 v17, v17, v18
	v_cvt_pk_bf16_f32 v18, v27, v36
	v_cvt_pk_bf16_f32 v19, v32, v19
	global_store_dwordx4 v[24:25], v[16:19], off
	v_mfma_f32_16x16x32_bf16 v[120:123], v[140:143], v[80:83], v[120:123]
	s_nop 0
	s_nop 0
	s_nop 0
	s_nop 0
	s_nop 0
	s_nop 0
	s_nop 0
	s_nop 0
	s_nop 0
	v_mfma_f32_16x16x32_bf16 v[108:111], v[144:147], v[80:83], v[108:111]
	s_waitcnt lgkmcnt(0)
	s_nop 0
	v_mov_b32_e32 v26, v164
	v_mov_b32_e32 v16, v8
	s_nop 1
	v_permlane16_swap_b32_e32 v26, v16
	s_waitcnt lgkmcnt(0)
	s_nop 0
	v_mov_b32_e32 v8, v165
	v_mov_b32_e32 v17, v9
	s_nop 1
	v_permlane16_swap_b32_e32 v8, v17
	s_waitcnt lgkmcnt(0)
	s_nop 0
	v_mov_b32_e32 v9, v166
	v_mov_b32_e32 v18, v10
	s_nop 1
	v_permlane16_swap_b32_e32 v9, v18
	s_waitcnt lgkmcnt(0)
	s_nop 0
	v_mov_b32_e32 v10, v167
	s_nop 1
	v_permlane16_swap_b32_e32 v10, v11
	v_cvt_pk_bf16_f32 v8, v26, v8
	v_cvt_pk_bf16_f32 v9, v9, v10
	v_cvt_pk_bf16_f32 v10, v16, v17
	v_cvt_pk_bf16_f32 v11, v18, v11
	global_store_dwordx4 v[24:25], v[8:11], off offset:64
	v_mfma_f32_16x16x32_bf16 v[100:103], v[160:163], v[80:83], v[100:103]
	s_nop 0
	v_or_b32_e32 v8, 16, v48
	v_ashrrev_i32_e32 v9, 31, v8
	v_lshlrev_b64 v[8:9], 11, v[8:9]
	v_mfma_f32_16x16x32_bf16 v[80:83], v[178:181], v[80:83], v[40:43]
	s_nop 0
	s_nop 0
	s_nop 0
	v_mfma_f32_16x16x32_bf16 v[40:43], v[140:143], v[104:107], v[64:67]
	s_nop 0
	s_nop 1
	v_lshl_add_u64 v[64:65], v[50:51], 0, v[8:9]
	s_nop 0
	s_nop 0
	s_nop 0
	s_nop 0
	v_mfma_f32_16x16x32_bf16 v[136:139], v[140:143], v[44:47], v[136:139]
	s_waitcnt lgkmcnt(0)
	s_nop 0
	v_mfma_f32_16x16x32_bf16 v[132:135], v[144:147], v[44:47], v[132:135]
	v_mfma_f32_16x16x32_bf16 v[128:131], v[160:163], v[44:47], v[128:131]
	v_mfma_f32_16x16x32_bf16 v[44:47], v[144:147], v[104:107], v[52:55]
	v_mfma_f32_16x16x32_bf16 v[36:39], v[178:181], v[104:107], v[60:63]
	s_nop 1
	v_mov_b32_e32 v49, v156
	v_mov_b32_e32 v54, v152
	s_nop 1
	v_permlane16_swap_b32_e32 v49, v54
	s_waitcnt lgkmcnt(0)
	s_nop 0
	v_mov_b32_e32 v8, v157
	v_mov_b32_e32 v55, v153
	s_nop 1
	v_permlane16_swap_b32_e32 v8, v55
	s_nop 0
	v_mov_b32_e32 v53, v158
	v_mov_b32_e32 v60, v154
	s_nop 1
	v_permlane16_swap_b32_e32 v53, v60
	s_nop 0
	v_mov_b32_e32 v61, v159
	v_mov_b32_e32 v62, v155
	s_nop 1
	v_permlane16_swap_b32_e32 v61, v62
	v_cvt_pk_bf16_f32 v52, v49, v8
	v_cvt_pk_bf16_f32 v53, v53, v61
	v_cvt_pk_bf16_f32 v54, v54, v55
	v_cvt_pk_bf16_f32 v55, v60, v62
	v_mfma_f32_16x16x32_bf16 v[8:11], v[140:143], v[116:119], v[12:15]
	global_store_dwordx4 v[64:65], v[52:55], off
	s_nop 0
	s_nop 0
	v_mfma_f32_16x16x32_bf16 v[12:15], v[144:147], v[116:119], v[4:7]
	s_nop 0
	s_nop 0
	s_nop 0
	v_cndmask_b32_e32 v4, v148, v182, vcc
	ds_bpermute_b32 v54, v186, v4
	s_nop 0
	s_waitcnt lgkmcnt(1)
	s_nop 0
	v_mov_b32_e32 v60, v149
	v_mov_b32_e32 v49, v183
	s_nop 1
	v_permlane16_swap_b32_e32 v60, v49
	s_waitcnt lgkmcnt(1)
	s_nop 0
	s_waitcnt lgkmcnt(0)
	v_cndmask_b32_e32 v55, v54, v148, vcc
	v_cndmask_b32_e32 v54, v182, v54, vcc
	v_mov_b32_e32 v61, v150
	v_mov_b32_e32 v62, v184
	s_nop 1
	v_permlane16_swap_b32_e32 v61, v62
	s_waitcnt lgkmcnt(0)
	s_nop 0
	v_mov_b32_e32 v63, v151
	v_mov_b32_e32 v66, v185
	s_nop 1
	v_permlane16_swap_b32_e32 v63, v66
	v_cvt_pk_bf16_f32 v52, v55, v60
	v_cvt_pk_bf16_f32 v53, v61, v63
	v_cvt_pk_bf16_f32 v54, v54, v49
	v_cvt_pk_bf16_f32 v55, v62, v66
	global_store_dwordx4 v[64:65], v[52:55], off offset:64
	s_nop 0
	s_nop 0
	v_or_b32_e32 v52, 32, v48
	v_ashrrev_i32_e32 v53, 31, v52
	v_lshlrev_b64 v[52:53], 11, v[52:53]
	v_lshl_add_u64 v[60:61], v[50:51], 0, v[52:53]
	s_nop 0
	s_nop 0
	s_nop 0
	s_nop 0
	s_nop 0
	s_nop 0
	s_waitcnt lgkmcnt(0)
	s_nop 0
	v_mov_b32_e32 v55, v136
	v_mov_b32_e32 v49, v132
	s_nop 1
	v_permlane16_swap_b32_e32 v55, v49
	s_waitcnt lgkmcnt(0)
	s_nop 0
	v_mov_b32_e32 v62, v137
	v_mov_b32_e32 v63, v133
	s_nop 1
	v_permlane16_swap_b32_e32 v62, v63
	s_waitcnt lgkmcnt(0)
	s_nop 0
	v_mov_b32_e32 v64, v138
	v_mov_b32_e32 v65, v134
	s_nop 1
	v_permlane16_swap_b32_e32 v64, v65
	s_waitcnt lgkmcnt(0)
	s_nop 0
	v_mov_b32_e32 v53, v139
	v_mov_b32_e32 v66, v135
	s_nop 1
	v_permlane16_swap_b32_e32 v53, v66
	v_cvt_pk_bf16_f32 v52, v55, v62
	v_cvt_pk_bf16_f32 v53, v64, v53
	v_cvt_pk_bf16_f32 v54, v49, v63
	v_cvt_pk_bf16_f32 v55, v65, v66
	global_store_dwordx4 v[60:61], v[52:55], off
	s_nop 0
	s_nop 0
	s_nop 0
	s_nop 0
	s_nop 0
	s_nop 0
	s_nop 0
	s_nop 0
	s_waitcnt lgkmcnt(0)
	s_nop 0
	v_mov_b32_e32 v55, v128
	v_mov_b32_e32 v49, v190
	s_nop 1
	v_permlane16_swap_b32_e32 v55, v49
	s_waitcnt lgkmcnt(0)
	s_nop 0
	v_mov_b32_e32 v62, v129
	v_mov_b32_e32 v63, v191
	s_nop 1
	v_permlane16_swap_b32_e32 v62, v63
	s_waitcnt lgkmcnt(0)
	s_nop 0
	v_mov_b32_e32 v64, v130
	v_mov_b32_e32 v65, v192
	s_nop 1
	v_permlane16_swap_b32_e32 v64, v65
	s_waitcnt lgkmcnt(0)
	s_nop 0
	v_mov_b32_e32 v53, v131
	v_mov_b32_e32 v66, v193
	s_nop 1
	v_permlane16_swap_b32_e32 v53, v66
	v_cvt_pk_bf16_f32 v52, v55, v62
	v_cvt_pk_bf16_f32 v53, v64, v53
	v_cvt_pk_bf16_f32 v54, v49, v63
	v_cvt_pk_bf16_f32 v55, v65, v66
	global_store_dwordx4 v[60:61], v[52:55], off offset:64
	s_nop 0
	s_nop 0
	v_or_b32_e32 v52, 48, v48
	v_ashrrev_i32_e32 v53, 31, v52
	v_lshlrev_b64 v[52:53], 11, v[52:53]
	v_lshl_add_u64 v[60:61], v[50:51], 0, v[52:53]
	s_nop 0
	s_nop 0
	s_nop 0
	s_nop 0
	s_nop 0
	s_nop 0
	s_waitcnt lgkmcnt(0)
	s_nop 0
	v_mov_b32_e32 v55, v120
	v_mov_b32_e32 v49, v108
	s_nop 1
	v_permlane16_swap_b32_e32 v55, v49
	s_waitcnt lgkmcnt(0)
	s_nop 0
	v_mov_b32_e32 v62, v121
	v_mov_b32_e32 v63, v109
	s_nop 1
	v_permlane16_swap_b32_e32 v62, v63
	s_waitcnt lgkmcnt(0)
	s_nop 0
	v_mov_b32_e32 v64, v122
	v_mov_b32_e32 v65, v110
	s_nop 1
	v_permlane16_swap_b32_e32 v64, v65
	s_waitcnt lgkmcnt(0)
	s_nop 0
	v_mov_b32_e32 v53, v123
	v_mov_b32_e32 v66, v111
	s_nop 1
	v_permlane16_swap_b32_e32 v53, v66
	v_cvt_pk_bf16_f32 v52, v55, v62
	v_cvt_pk_bf16_f32 v53, v64, v53
	v_cvt_pk_bf16_f32 v54, v49, v63
	v_cvt_pk_bf16_f32 v55, v65, v66
	global_store_dwordx4 v[60:61], v[52:55], off
	s_nop 0
	s_nop 0
	s_nop 0
	s_nop 0
	s_nop 0
	s_nop 0
	s_nop 0
	s_nop 0
	s_waitcnt lgkmcnt(0)
	s_nop 0
	v_mov_b32_e32 v55, v100
	v_mov_b32_e32 v49, v80
	s_nop 1
	v_permlane16_swap_b32_e32 v55, v49
	s_waitcnt lgkmcnt(0)
	s_nop 0
	v_mov_b32_e32 v62, v101
	v_mov_b32_e32 v63, v81
	s_nop 1
	v_permlane16_swap_b32_e32 v62, v63
	s_waitcnt lgkmcnt(0)
	s_nop 0
	v_mov_b32_e32 v64, v102
	v_mov_b32_e32 v65, v82
	s_nop 1
	v_permlane16_swap_b32_e32 v64, v65
	s_waitcnt lgkmcnt(0)
	s_nop 0
	v_mov_b32_e32 v53, v103
	v_mov_b32_e32 v66, v83
	s_nop 1
	v_permlane16_swap_b32_e32 v53, v66
	v_mfma_f32_16x16x32_bf16 v[92:95], v[140:143], v[88:91], v[92:95]
	v_cvt_pk_bf16_f32 v52, v55, v62
	v_cvt_pk_bf16_f32 v53, v64, v53
	v_cvt_pk_bf16_f32 v54, v49, v63
	v_mfma_f32_16x16x32_bf16 v[84:87], v[144:147], v[88:91], v[84:87]
	v_cvt_pk_bf16_f32 v55, v65, v66
	global_store_dwordx4 v[60:61], v[52:55], off offset:64
	v_mfma_f32_16x16x32_bf16 v[76:79], v[160:163], v[88:91], v[76:79]
	s_nop 0
	v_or_b32_e32 v52, 64, v48
	v_ashrrev_i32_e32 v53, 31, v52
	v_lshlrev_b64 v[52:53], 11, v[52:53]
	v_lshl_add_u64 v[60:61], v[50:51], 0, v[52:53]
	s_nop 0
	s_nop 0
	s_nop 0
	s_nop 0
	s_nop 0
	s_nop 0
	s_nop 0
	s_nop 0
	v_mfma_f32_16x16x32_bf16 v[56:59], v[178:181], v[88:91], v[56:59]
	s_waitcnt lgkmcnt(0)
	s_nop 0
	v_mov_b32_e32 v55, v92
	v_mov_b32_e32 v49, v84
	s_nop 1
	v_permlane16_swap_b32_e32 v55, v49
	s_waitcnt lgkmcnt(0)
	s_nop 0
	v_mov_b32_e32 v62, v93
	v_mov_b32_e32 v63, v85
	s_nop 1
	v_permlane16_swap_b32_e32 v62, v63
	s_waitcnt lgkmcnt(0)
	s_nop 0
	v_mov_b32_e32 v64, v94
	v_mov_b32_e32 v65, v86
	s_nop 1
	v_permlane16_swap_b32_e32 v64, v65
	s_waitcnt lgkmcnt(0)
	s_nop 0
	v_mov_b32_e32 v53, v95
	v_mov_b32_e32 v66, v87
	s_nop 1
	v_permlane16_swap_b32_e32 v53, v66
	v_cvt_pk_bf16_f32 v52, v55, v62
	v_cvt_pk_bf16_f32 v53, v64, v53
	v_cvt_pk_bf16_f32 v54, v49, v63
	v_cvt_pk_bf16_f32 v55, v65, v66
	global_store_dwordx4 v[60:61], v[52:55], off
	s_nop 0
	s_nop 0
	s_nop 0
	s_nop 0
	s_nop 0
	s_nop 0
	s_nop 0
	s_nop 0
	s_waitcnt lgkmcnt(0)
	s_nop 0
	v_mov_b32_e32 v55, v76
	v_mov_b32_e32 v49, v56
	s_nop 1
	v_permlane16_swap_b32_e32 v55, v49
	s_waitcnt lgkmcnt(0)
	s_nop 0
	v_mov_b32_e32 v56, v77
	s_nop 1
	v_permlane16_swap_b32_e32 v56, v57
	s_waitcnt lgkmcnt(0)
	s_nop 0
	v_mov_b32_e32 v62, v78
	s_nop 1
	v_permlane16_swap_b32_e32 v62, v58
	s_waitcnt lgkmcnt(0)
	s_nop 0
	v_mov_b32_e32 v53, v79
	s_nop 1
	v_permlane16_swap_b32_e32 v53, v59
	v_cvt_pk_bf16_f32 v52, v55, v56
	v_cvt_pk_bf16_f32 v53, v62, v53
	v_cvt_pk_bf16_f32 v54, v49, v57
	v_cvt_pk_bf16_f32 v55, v58, v59
	global_store_dwordx4 v[60:61], v[52:55], off offset:64
	s_nop 0
	s_nop 0
	s_nop 0
	s_nop 0
	s_nop 0
	s_nop 0
	s_nop 0
	s_nop 0
	v_mfma_f32_16x16x32_bf16 v[32:35], v[160:163], v[104:107], v[72:75]
	v_or_b32_e32 v52, 0x50, v48
	v_ashrrev_i32_e32 v53, 31, v52
	v_lshlrev_b64 v[52:53], 11, v[52:53]
	s_waitcnt lgkmcnt(0)
	s_nop 0
	s_nop 1
	v_permlane16_swap_b32_e32 v40, v44
	s_waitcnt lgkmcnt(0)
	s_nop 0
	s_nop 1
	v_permlane16_swap_b32_e32 v41, v45
	s_waitcnt lgkmcnt(0)
	s_nop 0
	s_nop 1
	v_permlane16_swap_b32_e32 v42, v46
	s_waitcnt lgkmcnt(0)
	s_nop 0
	s_nop 1
	v_permlane16_swap_b32_e32 v43, v47
	v_lshl_add_u64 v[52:53], v[50:51], 0, v[52:53]
	v_cvt_pk_bf16_f32 v40, v40, v41
	v_cvt_pk_bf16_f32 v41, v42, v43
	v_cvt_pk_bf16_f32 v42, v44, v45
	v_cvt_pk_bf16_f32 v43, v46, v47
	global_store_dwordx4 v[52:53], v[40:43], off
	v_mfma_f32_16x16x32_bf16 v[24:27], v[140:143], v[112:115], v[96:99]
	s_nop 0
	s_nop 0
	s_nop 0
	s_nop 0
	s_nop 0
	s_nop 0
	s_nop 0
	s_nop 0
	s_nop 0
	v_mfma_f32_16x16x32_bf16 v[28:31], v[144:147], v[112:115], v[28:31]
	s_waitcnt lgkmcnt(0)
	s_nop 0
	s_nop 1
	v_permlane16_swap_b32_e32 v32, v36
	s_waitcnt lgkmcnt(0)
	s_nop 0
	s_nop 1
	v_permlane16_swap_b32_e32 v33, v37
	s_waitcnt lgkmcnt(0)
	s_nop 0
	s_nop 1
	v_permlane16_swap_b32_e32 v34, v38
	s_waitcnt lgkmcnt(0)
	s_nop 0
	s_nop 1
	v_permlane16_swap_b32_e32 v35, v39
	v_cvt_pk_bf16_f32 v32, v32, v33
	v_cvt_pk_bf16_f32 v33, v34, v35
	v_cvt_pk_bf16_f32 v34, v36, v37
	v_cvt_pk_bf16_f32 v35, v38, v39
	global_store_dwordx4 v[52:53], v[32:35], off offset:64
	s_nop 0
	s_nop 0
	s_nop 0
	s_nop 0
	s_nop 0
	s_nop 0
	s_nop 0
	s_nop 0
	v_mfma_f32_16x16x32_bf16 v[16:19], v[160:163], v[112:115], v[124:127]
	v_or_b32_e32 v32, 0x60, v48
	v_ashrrev_i32_e32 v33, 31, v32
	v_lshlrev_b64 v[32:33], 11, v[32:33]
	v_mfma_f32_16x16x32_bf16 v[20:23], v[178:181], v[112:115], v[20:23]
	s_waitcnt lgkmcnt(0)
	s_nop 0
	s_nop 1
	v_permlane16_swap_b32_e32 v24, v28
	s_waitcnt lgkmcnt(0)
	s_nop 0
	s_nop 1
	v_permlane16_swap_b32_e32 v25, v29
	s_waitcnt lgkmcnt(0)
	s_nop 0
	s_nop 1
	v_permlane16_swap_b32_e32 v26, v30
	s_waitcnt lgkmcnt(0)
	s_nop 0
	s_nop 1
	v_permlane16_swap_b32_e32 v27, v31
	v_lshl_add_u64 v[32:33], v[50:51], 0, v[32:33]
	v_cvt_pk_bf16_f32 v24, v24, v25
	v_cvt_pk_bf16_f32 v25, v26, v27
	v_cvt_pk_bf16_f32 v26, v28, v29
	v_cvt_pk_bf16_f32 v27, v30, v31
	global_store_dwordx4 v[32:33], v[24:27], off
	v_mfma_f32_16x16x32_bf16 v[0:3], v[160:163], v[116:119], v[0:3]
	s_nop 0
	s_nop 0
	s_nop 0
	s_nop 0
	s_nop 0
	s_nop 0
	s_nop 0
	s_nop 0
	s_nop 0
	v_mfma_f32_16x16x32_bf16 v[4:7], v[178:181], v[116:119], v[68:71]
	s_waitcnt lgkmcnt(0)
	s_nop 0
	s_nop 1
	v_permlane16_swap_b32_e32 v16, v20
	s_waitcnt lgkmcnt(0)
	s_nop 0
	s_nop 1
	v_permlane16_swap_b32_e32 v17, v21
	s_waitcnt lgkmcnt(0)
	s_nop 0
	s_nop 1
	v_permlane16_swap_b32_e32 v18, v22
	s_waitcnt lgkmcnt(0)
	s_nop 0
	s_nop 1
	v_permlane16_swap_b32_e32 v19, v23
	v_cvt_pk_bf16_f32 v16, v16, v17
	v_cvt_pk_bf16_f32 v17, v18, v19
	v_cvt_pk_bf16_f32 v18, v20, v21
	v_cvt_pk_bf16_f32 v19, v22, v23
	global_store_dwordx4 v[32:33], v[16:19], off offset:64
	s_nop 0
	s_nop 0
	s_nop 0
	s_nop 0
	s_nop 0
	s_nop 0
	s_nop 0
	s_nop 0
	v_or_b32_e32 v16, 0x70, v48
	v_ashrrev_i32_e32 v17, 31, v16
	v_lshlrev_b64 v[16:17], 11, v[16:17]
	s_waitcnt lgkmcnt(0)
	s_nop 0
	s_nop 1
	v_permlane16_swap_b32_e32 v8, v12
	s_waitcnt lgkmcnt(0)
	s_nop 0
	s_nop 1
	v_permlane16_swap_b32_e32 v9, v13
	s_waitcnt lgkmcnt(0)
	s_nop 0
	s_nop 1
	v_permlane16_swap_b32_e32 v10, v14
	s_waitcnt lgkmcnt(0)
	s_nop 0
	s_nop 1
	v_permlane16_swap_b32_e32 v11, v15
	v_lshl_add_u64 v[16:17], v[50:51], 0, v[16:17]
	v_cvt_pk_bf16_f32 v8, v8, v9
	v_cvt_pk_bf16_f32 v9, v10, v11
	v_cvt_pk_bf16_f32 v10, v12, v13
	v_cvt_pk_bf16_f32 v11, v14, v15
	global_store_dwordx4 v[16:17], v[8:11], off
	s_nop 1
	s_nop 0
	s_nop 0
	s_nop 0
	s_nop 0
	s_nop 0
	s_nop 0
	s_nop 0
	s_nop 0
	s_waitcnt lgkmcnt(0)
	s_nop 0
	s_nop 1
	v_permlane16_swap_b32_e32 v0, v4
	s_waitcnt lgkmcnt(0)
	s_nop 0
	s_nop 1
	v_permlane16_swap_b32_e32 v1, v5
	s_waitcnt lgkmcnt(0)
	s_nop 0
	s_nop 1
	v_permlane16_swap_b32_e32 v2, v6
	s_waitcnt lgkmcnt(0)
	s_nop 0
	s_nop 1
	v_permlane16_swap_b32_e32 v3, v7
	v_cvt_pk_bf16_f32 v0, v0, v1
	v_cvt_pk_bf16_f32 v1, v2, v3
	v_cvt_pk_bf16_f32 v2, v4, v5
	v_cvt_pk_bf16_f32 v3, v6, v7
	global_store_dwordx4 v[16:17], v[0:3], off offset:64
	s_load_dword s6, s[6:7], 0x0
	s_waitcnt lgkmcnt(0)
	s_add_i32 s8, s6, s8
	s_cmpk_gt_i32 s8, 0xff
	s_cbranch_scc0 .LBB0_801

.LBB0_1064:
	s_ashr_i32 s22, s52, 3
	s_lshl_b32 s31, s22, 1
	s_and_b32 s30, s22, -16
	s_and_b32 s31, s31, 14
	s_or_b32 s30, s31, s30
	s_bfe_u32 s31, s22, 0x10003
	s_or_b32 s23, s22, 63
	s_or_b32 s30, s30, s31
	s_cmpk_lt_i32 s23, 0x80
	s_cselect_b32 s22, s30, s22
	s_lshl_b32 s23, s52, 7
	s_and_b32 s23, s23, 0x380
	s_add_i32 s22, s22, s23
	s_ashr_i32 s23, s22, 31
	s_lshr_b32 s30, s23, 27
	s_add_i32 s30, s22, s30
	s_ashr_i32 s31, s30, 5
	s_andn2_b32 s30, s30, 31
	s_sub_i32 s30, s22, s30
	s_lshr_b32 s23, s23, 25
	s_add_i32 s22, s22, s23
	s_ashr_i32 s23, s30, 31
	s_lshr_b32 s23, s23, 29
	s_ashr_i32 s22, s22, 7
	s_add_i32 s23, s30, s23
	s_ashr_i32 s23, s23, 3
	s_lshl_b32 s38, s22, 2
	s_add_i32 s38, s38, s23
	s_sub_i32 s31, s31, s38
	s_lshl_b32 s42, s31, 3
	s_add_i32 s42, s42, s30
	s_lshl_b32 s22, s22, 10
	s_lshl_b32 s38, s23, 8
	s_add_i32 s38, s38, s22
	s_lshl_b32 s53, s42, 7
	s_ashr_i32 s44, s42, 3
	s_cmp_lg_u32 s44, 2
	s_cselect_b64 s[22:23], -1, 0
	s_mov_b64 s[30:31], -1
	s_and_b64 vcc, exec, s[22:23]
	s_mov_b32 s39, 0x30000
	s_cbranch_vccz .LBB0_1068
	v_mov_b32_e32 v8, v188
	s_mov_b32 s30, 0x20000
	v_ashrrev_i32_e32 v9, 3, v8
	v_lshlrev_b32_e32 v4, 4, v8
	v_and_b32_e32 v176, 0x70, v4
	v_add_u32_e32 v4, s53, v9
	v_add_u32_e32 v0, s38, v9
	v_ashrrev_i32_e32 v5, 31, v4
	v_ashrrev_i32_e32 v1, 31, v0
	v_lshlrev_b64 v[4:5], 11, v[4:5]
	v_xor_b32_e32 v10, v9, v8
	v_lshlrev_b64 v[0:1], 11, v[0:1]
	v_lshl_add_u64 v[6:7], s[2:3], 0, v[4:5]
	v_lshlrev_b32_e32 v10, 4, v10
	v_lshl_add_u64 v[2:3], s[0:1], 0, v[0:1]
	v_lshl_add_u64 v[6:7], v[6:7], 0, v[176:177]
	v_and_b32_e32 v10, 0x70, v10
	v_lshl_add_u64 v[2:3], v[2:3], 0, v[176:177]
	v_lshl_or_b32 v176, v9, 7, v10
	v_lshlrev_b32_e32 v12, 7, v8
	v_lshrrev_b32_e32 v9, 4, v8
	v_bfe_u32 v14, v8, 4, 2
	v_and_b32_e32 v15, 7, v8
	v_add_co_u32_e32 v8, vcc, s39, v6
	v_bitop3_b32 v16, v9, v15, 3 bitop3:0x6c
	s_nop 0
	v_addc_co_u32_e32 v9, vcc, 0, v7, vcc
	v_add_co_u32_e32 v10, vcc, s30, v6
	s_mov_b32 s31, 0x10000
	s_nop 0
	v_addc_co_u32_e32 v11, vcc, 0, v7, vcc
	global_load_dwordx4 v[20:23], v[8:9], off
	global_load_dwordx4 v[24:27], v[10:11], off
	v_add_co_u32_e32 v8, vcc, s31, v6
	s_mov_b32 s40, 0x70000
	s_nop 0
	v_addc_co_u32_e32 v9, vcc, 0, v7, vcc
	v_add_co_u32_e32 v10, vcc, s40, v2
	s_mov_b32 s40, 0x60000
	s_nop 0
	v_addc_co_u32_e32 v11, vcc, 0, v3, vcc
	global_load_dwordx4 v[40:43], v[8:9], off
	global_load_dwordx4 v[48:51], v[10:11], off
	v_add_co_u32_e32 v8, vcc, s40, v2
	s_mov_b32 s40, 0x50000
	s_nop 0
	v_addc_co_u32_e32 v9, vcc, 0, v3, vcc
	v_add_co_u32_e32 v10, vcc, s40, v2
	s_mov_b32 s40, 0x40000
	s_nop 0
	v_addc_co_u32_e32 v11, vcc, 0, v3, vcc
	global_load_dwordx4 v[60:63], v[8:9], off
	global_load_dwordx4 v[68:71], v[10:11], off
	v_add_co_u32_e32 v8, vcc, s40, v2
	v_and_b32_e32 v13, 0xffffc780, v12
	s_nop 0
	v_addc_co_u32_e32 v9, vcc, 0, v3, vcc
	v_add_co_u32_e32 v10, vcc, s39, v2
	v_and_b32_e32 v12, 0x2780, v12
	s_nop 0
	v_addc_co_u32_e32 v11, vcc, 0, v3, vcc
	global_load_dwordx4 v[80:83], v[8:9], off
	global_load_dwordx4 v[88:91], v[10:11], off
	v_add_co_u32_e32 v8, vcc, s30, v2
	v_bitop3_b32 v14, v14, v15, 4 bitop3:0x36
	s_nop 0
	v_addc_co_u32_e32 v9, vcc, 0, v3, vcc
	v_add_co_u32_e32 v10, vcc, s31, v2
	v_mov_b32_e32 v140, 0
	s_nop 0
	v_addc_co_u32_e32 v11, vcc, 0, v3, vcc
	global_load_dwordx4 v[104:107], v[8:9], off
	global_load_dwordx4 v[112:115], v[10:11], off
	global_load_dwordx4 v[100:103], v[6:7], off
	global_load_dwordx4 v[116:119], v[2:3], off
	v_lshlrev_b32_e32 v2, 4, v16
	v_or_b32_e32 v185, v13, v2
	v_or_b32_e32 v184, v12, v2
	v_lshlrev_b32_e32 v2, 4, v14
	v_or_b32_e32 v183, v13, v2
	v_or_b32_e32 v182, v12, v2
	v_lshlrev_b32_e32 v2, 4, v15
	v_or_b32_e32 v0, v0, v2
	v_or_b32_e32 v4, v4, v2
	v_lshl_add_u64 v[178:179], s[34:35], 0, v[0:1]
	v_lshl_add_u64 v[180:181], s[50:51], 0, v[4:5]
	s_mov_b64 s[30:31], 0
	v_mov_b32_e32 v141, v140
	v_mov_b32_e32 v142, v140
	v_mov_b32_e32 v143, v140
	v_mov_b32_e32 v0, v140
	v_mov_b32_e32 v1, v140
	v_mov_b32_e32 v2, v140
	v_mov_b32_e32 v3, v140
	v_mov_b32_e32 v4, v140
	v_mov_b32_e32 v5, v140
	v_mov_b32_e32 v6, v140
	v_mov_b32_e32 v7, v140
	v_mov_b32_e32 v8, v140
	v_mov_b32_e32 v9, v140
	v_mov_b32_e32 v10, v140
	v_mov_b32_e32 v11, v140
	v_mov_b32_e32 v12, v140
	v_mov_b32_e32 v13, v140
	v_mov_b32_e32 v14, v140
	v_mov_b32_e32 v15, v140
	v_mov_b32_e32 v16, v140
	v_mov_b32_e32 v17, v140
	v_mov_b32_e32 v18, v140
	v_mov_b32_e32 v19, v140
	v_mov_b32_e32 v28, v140
	v_mov_b32_e32 v29, v140
	v_mov_b32_e32 v30, v140
	v_mov_b32_e32 v31, v140
	v_mov_b32_e32 v32, v140
	v_mov_b32_e32 v33, v140
	v_mov_b32_e32 v34, v140
	v_mov_b32_e32 v35, v140
	v_mov_b32_e32 v36, v140
	v_mov_b32_e32 v37, v140
	v_mov_b32_e32 v38, v140
	v_mov_b32_e32 v39, v140
	v_mov_b32_e32 v44, v140
	v_mov_b32_e32 v45, v140
	v_mov_b32_e32 v46, v140
	v_mov_b32_e32 v47, v140
	v_mov_b32_e32 v52, v140
	v_mov_b32_e32 v53, v140
	v_mov_b32_e32 v54, v140
	v_mov_b32_e32 v55, v140
	v_mov_b32_e32 v56, v140
	v_mov_b32_e32 v57, v140
	v_mov_b32_e32 v58, v140
	v_mov_b32_e32 v59, v140
	v_mov_b32_e32 v64, v140
	v_mov_b32_e32 v65, v140
	v_mov_b32_e32 v66, v140
	v_mov_b32_e32 v67, v140
	v_mov_b32_e32 v72, v140
	v_mov_b32_e32 v73, v140
	v_mov_b32_e32 v74, v140
	v_mov_b32_e32 v75, v140
	v_mov_b32_e32 v76, v140
	v_mov_b32_e32 v77, v140
	v_mov_b32_e32 v78, v140
	v_mov_b32_e32 v79, v140
	v_mov_b32_e32 v84, v140
	v_mov_b32_e32 v85, v140
	v_mov_b32_e32 v86, v140
	v_mov_b32_e32 v87, v140
	v_mov_b32_e32 v92, v140
	v_mov_b32_e32 v93, v140
	v_mov_b32_e32 v94, v140
	v_mov_b32_e32 v95, v140
	v_mov_b32_e32 v96, v140
	v_mov_b32_e32 v97, v140
	v_mov_b32_e32 v98, v140
	v_mov_b32_e32 v99, v140
	v_mov_b32_e32 v108, v140
	v_mov_b32_e32 v109, v140
	v_mov_b32_e32 v110, v140
	v_mov_b32_e32 v111, v140
	v_mov_b32_e32 v120, v140
	v_mov_b32_e32 v121, v140
	v_mov_b32_e32 v122, v140
	v_mov_b32_e32 v123, v140
	v_mov_b32_e32 v124, v140
	v_mov_b32_e32 v125, v140
	v_mov_b32_e32 v126, v140
	v_mov_b32_e32 v127, v140
	v_mov_b32_e32 v128, v140
	v_mov_b32_e32 v129, v140
	v_mov_b32_e32 v130, v140
	v_mov_b32_e32 v131, v140
	v_mov_b32_e32 v132, v140
	v_mov_b32_e32 v133, v140
	v_mov_b32_e32 v134, v140
	v_mov_b32_e32 v135, v140
	v_mov_b32_e32 v136, v140
	v_mov_b32_e32 v137, v140
	v_mov_b32_e32 v138, v140
	v_mov_b32_e32 v139, v140
	v_mov_b32_e32 v144, v140
	v_mov_b32_e32 v145, v140
	v_mov_b32_e32 v146, v140
	v_mov_b32_e32 v147, v140
	v_mov_b32_e32 v148, v140
	v_mov_b32_e32 v149, v140
	v_mov_b32_e32 v150, v140
	v_mov_b32_e32 v151, v140
	v_mov_b32_e32 v152, v140
	v_mov_b32_e32 v153, v140
	v_mov_b32_e32 v154, v140
	v_mov_b32_e32 v155, v140
	v_mov_b32_e32 v156, v140
	v_mov_b32_e32 v157, v140
	v_mov_b32_e32 v158, v140
	v_mov_b32_e32 v159, v140
	v_mov_b32_e32 v160, v140
	v_mov_b32_e32 v161, v140
	v_mov_b32_e32 v162, v140
	v_mov_b32_e32 v163, v140
	v_mov_b32_e32 v164, v140
	v_mov_b32_e32 v165, v140
	v_mov_b32_e32 v166, v140
	v_mov_b32_e32 v167, v140
	v_mov_b32_e32 v168, v140
	v_mov_b32_e32 v169, v140
	v_mov_b32_e32 v170, v140
	v_mov_b32_e32 v171, v140
	v_mov_b32_e32 v172, v140
	v_mov_b32_e32 v173, v140
	v_mov_b32_e32 v174, v140
	v_mov_b32_e32 v175, v140
	s_mov_b32 s40, 0x820000
	s_mov_b32 s41, 0x830000
	s_setprio 2
	v_readlane_b32 s98, v253, 3
	v_readlane_b32 s99, v253, 4
	v_and_b32_e32 v236, 15, v188
	v_bfe_u32 v237, v188, 4, 2
	v_lshrrev_b32_e32 v238, 2, v236
	v_sub_u32_e32 v238, 0, v238
	v_and_b32_e32 v238, 3, v238
	v_xor_b32_e32 v237, v237, v238
	v_lshlrev_b32_e32 v237, 4, v237
	v_lshl_or_b32 v237, v236, 6, v237
	v_bfe_u32 v238, v188, 7, 1
	v_lshl_or_b32 v185, v238, 13, v237
	v_bfe_u32 v238, v188, 6, 1
	v_lshl_or_b32 v184, v238, 12, v237
	v_add_u32_e32 v184, 0x4000, v184
	v_lshrrev_b32_e32 v236, 3, v188
	v_bfe_u32 v237, v188, 2, 1
	v_lshrrev_b32_e32 v238, 2, v236
	v_sub_u32_e32 v238, 0, v238
	v_and_b32_e32 v238, 3, v238
	v_and_b32_e32 v239, 3, v188
	v_xor_b32_e32 v238, v239, v238
	v_lshlrev_b32_e32 v238, 4, v238
	v_xor_b32_e32 v236, v236, v237
	v_lshl_or_b32 v238, v236, 6, v238
	v_mul_u32_u24_e32 v237, 0x6000, v237
	v_add_u32_e32 v183, v237, v238
	s_mov_b32 m0, 0
	s_sub_u32 vcc_lo, s30, s98
	v_add_u32_e32 v186, vcc_lo, v178
	v_add_u32_e32 v187, vcc_lo, v180
	s_barrier
	s_waitcnt vmcnt(0)
	ds_write_b128 v183, v[116:119]
	ds_write_b128 v183, v[112:115] offset:2048
	ds_write_b128 v183, v[104:107] offset:4096
	ds_write_b128 v183, v[88:91] offset:6144
	ds_write_b128 v183, v[80:83] offset:8192
	ds_write_b128 v183, v[68:71] offset:10240
	ds_write_b128 v183, v[60:63] offset:12288
	ds_write_b128 v183, v[48:51] offset:14336
	ds_write_b128 v183, v[100:103] offset:16384
	ds_write_b128 v183, v[40:43] offset:18432
	ds_write_b128 v183, v[24:27] offset:20480
	ds_write_b128 v183, v[20:23] offset:22528
	v_cmp_gt_u32_e32 vcc, 0x6000, v183
	v_add_u32_e32 v182, 0xc000, v183
	v_add_u32_e32 v183, 0xffffa000, v183
	s_nop 0
	v_cndmask_b32_e32 v183, v183, v182, vcc
	v_add_u32_e32 v116, s26, v186
	global_load_dwordx4 v[116:119], v116, s[98:99] offset:128
	v_add_u32_e32 v112, s27, v186
	global_load_dwordx4 v[112:115], v112, s[98:99] offset:128
	v_add_u32_e32 v104, s20, v186
	global_load_dwordx4 v[104:107], v104, s[98:99] offset:128
	v_add_u32_e32 v88, s21, v186
	global_load_dwordx4 v[88:91], v88, s[98:99] offset:128
	v_add_u32_e32 v80, s56, v186
	global_load_dwordx4 v[80:83], v80, s[98:99] offset:128
	v_add_u32_e32 v68, s57, v186
	global_load_dwordx4 v[68:71], v68, s[98:99] offset:128
	v_add_u32_e32 v60, s24, v186
	global_load_dwordx4 v[60:63], v60, s[98:99] offset:128
	v_add_u32_e32 v48, s96, v186
	global_load_dwordx4 v[48:51], v48, s[98:99] offset:128
	v_add_u32_e32 v100, s25, v187
	global_load_dwordx4 v[100:103], v100, s[98:99] offset:128
	v_add_u32_e32 v40, s33, v187
	global_load_dwordx4 v[40:43], v40, s[98:99] offset:128
	v_add_u32_e32 v24, s40, v187
	global_load_dwordx4 v[24:27], v24, s[98:99] offset:128
	v_add_u32_e32 v20, s41, v187
	global_load_dwordx4 v[20:23], v20, s[98:99] offset:128
	s_add_u32 s30, s30, 0x80
	s_addc_u32 s31, s31, 0
.LBB0_1066:
	s_waitcnt lgkmcnt(0)
	s_barrier
	ds_read_b128 v[236:239], v184
	ds_read_b128 v[240:243], v184 offset:1024
	ds_read_b128 v[244:247], v184 offset:2048
	ds_read_b128 v[248:251], v184 offset:3072
	ds_read_b128 v[204:207], v185
	ds_read_b128 v[208:211], v185 offset:1024
	ds_read_b128 v[212:215], v185 offset:2048
	ds_read_b128 v[216:219], v185 offset:3072
	ds_read_b128 v[220:223], v185 offset:4096
	ds_read_b128 v[224:227], v185 offset:5120
	ds_read_b128 v[228:231], v185 offset:6144
	ds_read_b128 v[232:235], v185 offset:7168
	s_movk_i32 vcc_lo, 0x6000
	s_cmp_eq_u32 m0, 2
	s_cselect_b32 vcc_lo, 0xffff4000, vcc_lo
	s_add_u32 m0, m0, 1
	s_cmp_eq_u32 m0, 3
	s_cselect_b32 m0, 0, m0
	v_add_u32_e32 v185, vcc_lo, v185
	v_add_u32_e32 v184, vcc_lo, v184
	v_xor_b32_e32 v185, 64, v185
	v_xor_b32_e32 v184, 64, v184
	s_waitcnt lgkmcnt(7)
	v_mfma_f32_16x16x32_bf16 v[172:175], v[236:239], v[204:207], v[172:175]
	v_mfma_f32_16x16x32_bf16 v[168:171], v[240:243], v[204:207], v[168:171]
	v_mfma_f32_16x16x32_bf16 v[164:167], v[244:247], v[204:207], v[164:167]
	v_mfma_f32_16x16x32_bf16 v[160:163], v[248:251], v[204:207], v[160:163]
	ds_read_b128 v[204:207], v185
	s_waitcnt lgkmcnt(7)
	v_mfma_f32_16x16x32_bf16 v[156:159], v[236:239], v[208:211], v[156:159]
	v_mfma_f32_16x16x32_bf16 v[152:155], v[240:243], v[208:211], v[152:155]
	v_mfma_f32_16x16x32_bf16 v[148:151], v[244:247], v[208:211], v[148:151]
	v_mfma_f32_16x16x32_bf16 v[144:147], v[248:251], v[208:211], v[144:147]
	ds_read_b128 v[208:211], v185 offset:1024
	s_waitcnt lgkmcnt(7)
	v_mfma_f32_16x16x32_bf16 v[136:139], v[236:239], v[212:215], v[136:139]
	v_mfma_f32_16x16x32_bf16 v[132:135], v[240:243], v[212:215], v[132:135]
	v_mfma_f32_16x16x32_bf16 v[128:131], v[244:247], v[212:215], v[128:131]
	v_mfma_f32_16x16x32_bf16 v[124:127], v[248:251], v[212:215], v[124:127]
	ds_read_b128 v[212:215], v185 offset:2048
	s_waitcnt lgkmcnt(7)
	v_mfma_f32_16x16x32_bf16 v[120:123], v[236:239], v[216:219], v[120:123]
	v_mfma_f32_16x16x32_bf16 v[108:111], v[240:243], v[216:219], v[108:111]
	v_mfma_f32_16x16x32_bf16 v[96:99], v[244:247], v[216:219], v[96:99]
	v_mfma_f32_16x16x32_bf16 v[92:95], v[248:251], v[216:219], v[92:95]
	ds_read_b128 v[216:219], v185 offset:3072
	s_waitcnt lgkmcnt(7)
	v_mfma_f32_16x16x32_bf16 v[84:87], v[236:239], v[220:223], v[84:87]
	v_mfma_f32_16x16x32_bf16 v[76:79], v[240:243], v[220:223], v[76:79]
	v_mfma_f32_16x16x32_bf16 v[72:75], v[244:247], v[220:223], v[72:75]
	v_mfma_f32_16x16x32_bf16 v[64:67], v[248:251], v[220:223], v[64:67]
	ds_read_b128 v[220:223], v185 offset:4096
	s_waitcnt lgkmcnt(7)
	v_mfma_f32_16x16x32_bf16 v[56:59], v[236:239], v[224:227], v[56:59]
	v_mfma_f32_16x16x32_bf16 v[52:55], v[240:243], v[224:227], v[52:55]
	v_mfma_f32_16x16x32_bf16 v[44:47], v[244:247], v[224:227], v[44:47]
	v_mfma_f32_16x16x32_bf16 v[36:39], v[248:251], v[224:227], v[36:39]
	ds_read_b128 v[224:227], v185 offset:5120
	s_waitcnt lgkmcnt(7)
	v_mfma_f32_16x16x32_bf16 v[32:35], v[236:239], v[228:231], v[32:35]
	v_mfma_f32_16x16x32_bf16 v[28:31], v[240:243], v[228:231], v[28:31]
	v_mfma_f32_16x16x32_bf16 v[16:19], v[244:247], v[228:231], v[16:19]
	v_mfma_f32_16x16x32_bf16 v[12:15], v[248:251], v[228:231], v[12:15]
	ds_read_b128 v[228:231], v185 offset:6144
	s_waitcnt lgkmcnt(7)
	v_mfma_f32_16x16x32_bf16 v[8:11], v[236:239], v[232:235], v[8:11]
	v_mfma_f32_16x16x32_bf16 v[4:7], v[240:243], v[232:235], v[4:7]
	v_mfma_f32_16x16x32_bf16 v[0:3], v[244:247], v[232:235], v[0:3]
	v_mfma_f32_16x16x32_bf16 v[140:143], v[248:251], v[232:235], v[140:143]
	ds_read_b128 v[232:235], v185 offset:7168
	ds_read_b128 v[236:239], v184
	ds_read_b128 v[240:243], v184 offset:1024
	ds_read_b128 v[244:247], v184 offset:2048
	ds_read_b128 v[248:251], v184 offset:3072
	s_movk_i32 vcc_lo, 0x6000
	s_cmp_eq_u32 m0, 2
	s_cselect_b32 vcc_lo, 0xffff4000, vcc_lo
	s_add_u32 m0, m0, 1
	s_cmp_eq_u32 m0, 3
	s_cselect_b32 m0, 0, m0
	v_add_u32_e32 v185, vcc_lo, v185
	v_add_u32_e32 v184, vcc_lo, v184
	v_xor_b32_e32 v185, 64, v185
	v_xor_b32_e32 v184, 64, v184
	s_sub_u32 vcc_lo, s30, s98
	v_add_u32_e32 v186, vcc_lo, v178
	v_add_u32_e32 v187, vcc_lo, v180
	s_barrier
	s_waitcnt lgkmcnt(0)
	v_mfma_f32_16x16x32_bf16 v[172:175], v[236:239], v[204:207], v[172:175]
	s_waitcnt vmcnt(11)
	v_mfma_f32_16x16x32_bf16 v[168:171], v[240:243], v[204:207], v[168:171]
	ds_write_b128 v183, v[116:119]
	v_add_u32_e32 v116, s26, v186
	v_mfma_f32_16x16x32_bf16 v[164:167], v[244:247], v[204:207], v[164:167]
	global_load_dwordx4 v[116:119], v116, s[98:99] offset:128
	v_mfma_f32_16x16x32_bf16 v[160:163], v[248:251], v[204:207], v[160:163]
	s_waitcnt vmcnt(11)
	ds_write_b128 v183, v[112:115] offset:2048
	v_mfma_f32_16x16x32_bf16 v[156:159], v[236:239], v[208:211], v[156:159]
	v_add_u32_e32 v112, s27, v186
	v_mfma_f32_16x16x32_bf16 v[152:155], v[240:243], v[208:211], v[152:155]
	global_load_dwordx4 v[112:115], v112, s[98:99] offset:128
	s_waitcnt vmcnt(11)
	v_mfma_f32_16x16x32_bf16 v[148:151], v[244:247], v[208:211], v[148:151]
	ds_write_b128 v183, v[104:107] offset:4096
	v_mfma_f32_16x16x32_bf16 v[144:147], v[248:251], v[208:211], v[144:147]
	v_add_u32_e32 v104, s20, v186
	global_load_dwordx4 v[104:107], v104, s[98:99] offset:128
	v_mfma_f32_16x16x32_bf16 v[136:139], v[236:239], v[212:215], v[136:139]
	s_waitcnt vmcnt(11)
	v_mfma_f32_16x16x32_bf16 v[132:135], v[240:243], v[212:215], v[132:135]
	ds_write_b128 v183, v[88:91] offset:6144
	v_add_u32_e32 v88, s21, v186
	v_mfma_f32_16x16x32_bf16 v[128:131], v[244:247], v[212:215], v[128:131]
	global_load_dwordx4 v[88:91], v88, s[98:99] offset:128
	v_mfma_f32_16x16x32_bf16 v[124:127], v[248:251], v[212:215], v[124:127]
	s_waitcnt vmcnt(11)
	ds_write_b128 v183, v[80:83] offset:8192
	v_mfma_f32_16x16x32_bf16 v[120:123], v[236:239], v[216:219], v[120:123]
	v_add_u32_e32 v80, s56, v186
	v_mfma_f32_16x16x32_bf16 v[108:111], v[240:243], v[216:219], v[108:111]
	global_load_dwordx4 v[80:83], v80, s[98:99] offset:128
	s_waitcnt vmcnt(11)
	v_mfma_f32_16x16x32_bf16 v[96:99], v[244:247], v[216:219], v[96:99]
	ds_write_b128 v183, v[68:71] offset:10240
	v_mfma_f32_16x16x32_bf16 v[92:95], v[248:251], v[216:219], v[92:95]
	v_add_u32_e32 v68, s57, v186
	global_load_dwordx4 v[68:71], v68, s[98:99] offset:128
	v_mfma_f32_16x16x32_bf16 v[84:87], v[236:239], v[220:223], v[84:87]
	s_waitcnt vmcnt(11)
	v_mfma_f32_16x16x32_bf16 v[76:79], v[240:243], v[220:223], v[76:79]
	ds_write_b128 v183, v[60:63] offset:12288
	v_add_u32_e32 v60, s24, v186
	v_mfma_f32_16x16x32_bf16 v[72:75], v[244:247], v[220:223], v[72:75]
	global_load_dwordx4 v[60:63], v60, s[98:99] offset:128
	v_mfma_f32_16x16x32_bf16 v[64:67], v[248:251], v[220:223], v[64:67]
	s_waitcnt vmcnt(11)
	ds_write_b128 v183, v[48:51] offset:14336
	v_mfma_f32_16x16x32_bf16 v[56:59], v[236:239], v[224:227], v[56:59]
	v_add_u32_e32 v48, s96, v186
	v_mfma_f32_16x16x32_bf16 v[52:55], v[240:243], v[224:227], v[52:55]
	global_load_dwordx4 v[48:51], v48, s[98:99] offset:128
	s_waitcnt vmcnt(11)
	v_mfma_f32_16x16x32_bf16 v[44:47], v[244:247], v[224:227], v[44:47]
	ds_write_b128 v183, v[100:103] offset:16384
	v_mfma_f32_16x16x32_bf16 v[36:39], v[248:251], v[224:227], v[36:39]
	v_add_u32_e32 v100, s25, v187
	global_load_dwordx4 v[100:103], v100, s[98:99] offset:128
	v_mfma_f32_16x16x32_bf16 v[32:35], v[236:239], v[228:231], v[32:35]
	s_waitcnt vmcnt(11)
	v_mfma_f32_16x16x32_bf16 v[28:31], v[240:243], v[228:231], v[28:31]
	ds_write_b128 v183, v[40:43] offset:18432
	v_add_u32_e32 v40, s33, v187
	v_mfma_f32_16x16x32_bf16 v[16:19], v[244:247], v[228:231], v[16:19]
	global_load_dwordx4 v[40:43], v40, s[98:99] offset:128
	v_mfma_f32_16x16x32_bf16 v[12:15], v[248:251], v[228:231], v[12:15]
	s_waitcnt vmcnt(11)
	ds_write_b128 v183, v[24:27] offset:20480
	v_mfma_f32_16x16x32_bf16 v[8:11], v[236:239], v[232:235], v[8:11]
	v_add_u32_e32 v24, s40, v187
	v_mfma_f32_16x16x32_bf16 v[4:7], v[240:243], v[232:235], v[4:7]
	global_load_dwordx4 v[24:27], v24, s[98:99] offset:128
	s_waitcnt vmcnt(11)
	v_mfma_f32_16x16x32_bf16 v[0:3], v[244:247], v[232:235], v[0:3]
	ds_write_b128 v183, v[20:23] offset:22528
	v_mfma_f32_16x16x32_bf16 v[140:143], v[248:251], v[232:235], v[140:143]
	v_add_u32_e32 v20, s41, v187
	global_load_dwordx4 v[20:23], v20, s[98:99] offset:128
	v_cmp_gt_u32_e32 vcc, 0x6000, v183
	v_add_u32_e32 v182, 0xc000, v183
	v_add_u32_e32 v183, 0xffffa000, v183
	s_nop 0
	v_cndmask_b32_e32 v183, v183, v182, vcc
	s_add_u32 s30, s30, 0x80
	s_addc_u32 s31, s31, 0
	s_cmpk_eq_i32 s30, 0x780
	s_cbranch_scc0 .LBB0_1066
	s_waitcnt lgkmcnt(0)
	s_barrier
	ds_read_b128 v[236:239], v184
	ds_read_b128 v[240:243], v184 offset:1024
	ds_read_b128 v[244:247], v184 offset:2048
	ds_read_b128 v[248:251], v184 offset:3072
	ds_read_b128 v[204:207], v185
	ds_read_b128 v[208:211], v185 offset:1024
	ds_read_b128 v[212:215], v185 offset:2048
	ds_read_b128 v[216:219], v185 offset:3072
	ds_read_b128 v[220:223], v185 offset:4096
	ds_read_b128 v[224:227], v185 offset:5120
	ds_read_b128 v[228:231], v185 offset:6144
	ds_read_b128 v[232:235], v185 offset:7168
	s_movk_i32 vcc_lo, 0x6000
	s_cmp_eq_u32 m0, 2
	s_cselect_b32 vcc_lo, 0xffff4000, vcc_lo
	s_add_u32 m0, m0, 1
	s_cmp_eq_u32 m0, 3
	s_cselect_b32 m0, 0, m0
	v_add_u32_e32 v185, vcc_lo, v185
	v_add_u32_e32 v184, vcc_lo, v184
	v_xor_b32_e32 v185, 64, v185
	v_xor_b32_e32 v184, 64, v184
	s_waitcnt lgkmcnt(7)
	v_mfma_f32_16x16x32_bf16 v[172:175], v[236:239], v[204:207], v[172:175]
	v_mfma_f32_16x16x32_bf16 v[168:171], v[240:243], v[204:207], v[168:171]
	v_mfma_f32_16x16x32_bf16 v[164:167], v[244:247], v[204:207], v[164:167]
	v_mfma_f32_16x16x32_bf16 v[160:163], v[248:251], v[204:207], v[160:163]
	ds_read_b128 v[204:207], v185
	s_waitcnt lgkmcnt(7)
	v_mfma_f32_16x16x32_bf16 v[156:159], v[236:239], v[208:211], v[156:159]
	v_mfma_f32_16x16x32_bf16 v[152:155], v[240:243], v[208:211], v[152:155]
	v_mfma_f32_16x16x32_bf16 v[148:151], v[244:247], v[208:211], v[148:151]
	v_mfma_f32_16x16x32_bf16 v[144:147], v[248:251], v[208:211], v[144:147]
	ds_read_b128 v[208:211], v185 offset:1024
	s_waitcnt lgkmcnt(7)
	v_mfma_f32_16x16x32_bf16 v[136:139], v[236:239], v[212:215], v[136:139]
	v_mfma_f32_16x16x32_bf16 v[132:135], v[240:243], v[212:215], v[132:135]
	v_mfma_f32_16x16x32_bf16 v[128:131], v[244:247], v[212:215], v[128:131]
	v_mfma_f32_16x16x32_bf16 v[124:127], v[248:251], v[212:215], v[124:127]
	ds_read_b128 v[212:215], v185 offset:2048
	s_waitcnt lgkmcnt(7)
	v_mfma_f32_16x16x32_bf16 v[120:123], v[236:239], v[216:219], v[120:123]
	v_mfma_f32_16x16x32_bf16 v[108:111], v[240:243], v[216:219], v[108:111]
	v_mfma_f32_16x16x32_bf16 v[96:99], v[244:247], v[216:219], v[96:99]
	v_mfma_f32_16x16x32_bf16 v[92:95], v[248:251], v[216:219], v[92:95]
	ds_read_b128 v[216:219], v185 offset:3072
	s_waitcnt lgkmcnt(7)
	v_mfma_f32_16x16x32_bf16 v[84:87], v[236:239], v[220:223], v[84:87]
	v_mfma_f32_16x16x32_bf16 v[76:79], v[240:243], v[220:223], v[76:79]
	v_mfma_f32_16x16x32_bf16 v[72:75], v[244:247], v[220:223], v[72:75]
	v_mfma_f32_16x16x32_bf16 v[64:67], v[248:251], v[220:223], v[64:67]
	ds_read_b128 v[220:223], v185 offset:4096
	s_waitcnt lgkmcnt(7)
	v_mfma_f32_16x16x32_bf16 v[56:59], v[236:239], v[224:227], v[56:59]
	v_mfma_f32_16x16x32_bf16 v[52:55], v[240:243], v[224:227], v[52:55]
	v_mfma_f32_16x16x32_bf16 v[44:47], v[244:247], v[224:227], v[44:47]
	v_mfma_f32_16x16x32_bf16 v[36:39], v[248:251], v[224:227], v[36:39]
	ds_read_b128 v[224:227], v185 offset:5120
	s_waitcnt lgkmcnt(7)
	v_mfma_f32_16x16x32_bf16 v[32:35], v[236:239], v[228:231], v[32:35]
	v_mfma_f32_16x16x32_bf16 v[28:31], v[240:243], v[228:231], v[28:31]
	v_mfma_f32_16x16x32_bf16 v[16:19], v[244:247], v[228:231], v[16:19]
	v_mfma_f32_16x16x32_bf16 v[12:15], v[248:251], v[228:231], v[12:15]
	ds_read_b128 v[228:231], v185 offset:6144
	s_waitcnt lgkmcnt(7)
	v_mfma_f32_16x16x32_bf16 v[8:11], v[236:239], v[232:235], v[8:11]
	v_mfma_f32_16x16x32_bf16 v[4:7], v[240:243], v[232:235], v[4:7]
	v_mfma_f32_16x16x32_bf16 v[0:3], v[244:247], v[232:235], v[0:3]
	v_mfma_f32_16x16x32_bf16 v[140:143], v[248:251], v[232:235], v[140:143]
	ds_read_b128 v[232:235], v185 offset:7168
	ds_read_b128 v[236:239], v184
	ds_read_b128 v[240:243], v184 offset:1024
	ds_read_b128 v[244:247], v184 offset:2048
	ds_read_b128 v[248:251], v184 offset:3072
	s_movk_i32 vcc_lo, 0x6000
	s_cmp_eq_u32 m0, 2
	s_cselect_b32 vcc_lo, 0xffff4000, vcc_lo
	s_add_u32 m0, m0, 1
	s_cmp_eq_u32 m0, 3
	s_cselect_b32 m0, 0, m0
	v_add_u32_e32 v185, vcc_lo, v185
	v_add_u32_e32 v184, vcc_lo, v184
	v_xor_b32_e32 v185, 64, v185
	v_xor_b32_e32 v184, 64, v184
	s_waitcnt lgkmcnt(0)
	v_mfma_f32_16x16x32_bf16 v[172:175], v[236:239], v[204:207], v[172:175]
	v_mfma_f32_16x16x32_bf16 v[168:171], v[240:243], v[204:207], v[168:171]
	v_mfma_f32_16x16x32_bf16 v[164:167], v[244:247], v[204:207], v[164:167]
	v_mfma_f32_16x16x32_bf16 v[160:163], v[248:251], v[204:207], v[160:163]
	v_mfma_f32_16x16x32_bf16 v[156:159], v[236:239], v[208:211], v[156:159]
	v_mfma_f32_16x16x32_bf16 v[152:155], v[240:243], v[208:211], v[152:155]
	v_mfma_f32_16x16x32_bf16 v[148:151], v[244:247], v[208:211], v[148:151]
	v_mfma_f32_16x16x32_bf16 v[144:147], v[248:251], v[208:211], v[144:147]
	v_mfma_f32_16x16x32_bf16 v[136:139], v[236:239], v[212:215], v[136:139]
	v_mfma_f32_16x16x32_bf16 v[132:135], v[240:243], v[212:215], v[132:135]
	v_mfma_f32_16x16x32_bf16 v[128:131], v[244:247], v[212:215], v[128:131]
	v_mfma_f32_16x16x32_bf16 v[124:127], v[248:251], v[212:215], v[124:127]
	v_mfma_f32_16x16x32_bf16 v[120:123], v[236:239], v[216:219], v[120:123]
	v_mfma_f32_16x16x32_bf16 v[108:111], v[240:243], v[216:219], v[108:111]
	v_mfma_f32_16x16x32_bf16 v[96:99], v[244:247], v[216:219], v[96:99]
	v_mfma_f32_16x16x32_bf16 v[92:95], v[248:251], v[216:219], v[92:95]
	v_mfma_f32_16x16x32_bf16 v[84:87], v[236:239], v[220:223], v[84:87]
	v_mfma_f32_16x16x32_bf16 v[76:79], v[240:243], v[220:223], v[76:79]
	v_mfma_f32_16x16x32_bf16 v[72:75], v[244:247], v[220:223], v[72:75]
	v_mfma_f32_16x16x32_bf16 v[64:67], v[248:251], v[220:223], v[64:67]
	v_mfma_f32_16x16x32_bf16 v[56:59], v[236:239], v[224:227], v[56:59]
	v_mfma_f32_16x16x32_bf16 v[52:55], v[240:243], v[224:227], v[52:55]
	v_mfma_f32_16x16x32_bf16 v[44:47], v[244:247], v[224:227], v[44:47]
	v_mfma_f32_16x16x32_bf16 v[36:39], v[248:251], v[224:227], v[36:39]
	v_mfma_f32_16x16x32_bf16 v[32:35], v[236:239], v[228:231], v[32:35]
	v_mfma_f32_16x16x32_bf16 v[28:31], v[240:243], v[228:231], v[28:31]
	v_mfma_f32_16x16x32_bf16 v[16:19], v[244:247], v[228:231], v[16:19]
	v_mfma_f32_16x16x32_bf16 v[12:15], v[248:251], v[228:231], v[12:15]
	v_mfma_f32_16x16x32_bf16 v[8:11], v[236:239], v[232:235], v[8:11]
	v_mfma_f32_16x16x32_bf16 v[4:7], v[240:243], v[232:235], v[4:7]
	v_mfma_f32_16x16x32_bf16 v[0:3], v[244:247], v[232:235], v[0:3]
	v_mfma_f32_16x16x32_bf16 v[140:143], v[248:251], v[232:235], v[140:143]
	v_lshrrev_b32_e32 v236, 4, v188
	v_and_b32_e32 v237, 7, v188
	v_bitop3_b32 v238, v236, v237, 3 bitop3:0x6c
	v_lshlrev_b32_e32 v239, 7, v188
	v_bfe_u32 v240, v188, 4, 2
	v_and_b32_e32 v241, 0xffffc780, v239
	v_and_b32_e32 v239, 0x2780, v239
	v_bitop3_b32 v240, v240, v237, 4 bitop3:0x36
	v_lshlrev_b32_e32 v238, 4, v238
	v_lshlrev_b32_e32 v240, 4, v240
	v_or_b32_e32 v185, v241, v238
	v_or_b32_e32 v184, v239, v238
	v_or_b32_e32 v183, v241, v240
	v_or_b32_e32 v182, v239, v240
	s_waitcnt vmcnt(0)
	s_setprio 0
	s_barrier
	s_waitcnt vmcnt(11)
	ds_write_b128 v176, v[116:119]
	s_waitcnt vmcnt(10)
	ds_write_b128 v176, v[112:115] offset:4096
	s_waitcnt vmcnt(9)
	ds_write_b128 v176, v[104:107] offset:8192
	s_waitcnt vmcnt(8)
	ds_write_b128 v176, v[88:91] offset:12288
	s_waitcnt vmcnt(7)
	ds_write_b128 v176, v[80:83] offset:16384
	s_waitcnt vmcnt(6)
	ds_write_b128 v176, v[68:71] offset:20480
	s_waitcnt vmcnt(5)
	ds_write_b128 v176, v[60:63] offset:24576
	s_waitcnt vmcnt(4)
	ds_write_b128 v176, v[48:51] offset:28672
	s_waitcnt vmcnt(3)
	ds_write_b128 v176, v[100:103] offset:32768
	s_waitcnt vmcnt(2)
	ds_write_b128 v176, v[40:43] offset:36864
	s_waitcnt vmcnt(1)
	ds_write_b128 v176, v[24:27] offset:40960
	s_waitcnt vmcnt(0)
	ds_write_b128 v176, v[20:23] offset:45056
	s_waitcnt lgkmcnt(0)
	s_barrier
	ds_read_b128 v[20:23], v185
	ds_read_b128 v[24:27], v185 offset:2048
	ds_read_b128 v[40:43], v185 offset:4096
	ds_read_b128 v[48:51], v185 offset:6144
	ds_read_b128 v[60:63], v185 offset:8192
	ds_read_b128 v[68:71], v185 offset:10240
	ds_read_b128 v[80:83], v185 offset:12288
	ds_read_b128 v[88:91], v185 offset:14336
	ds_read_b128 v[100:103], v184 offset:32768
	ds_read_b128 v[104:107], v184 offset:34816
	ds_read_b128 v[112:115], v184 offset:36864
	ds_read_b128 v[116:119], v184 offset:38912
	s_waitcnt lgkmcnt(3)
	v_mfma_f32_16x16x32_bf16 v[172:175], v[100:103], v[20:23], v[172:175]
	s_waitcnt lgkmcnt(2)
	v_mfma_f32_16x16x32_bf16 v[168:171], v[104:107], v[20:23], v[168:171]
	s_waitcnt lgkmcnt(1)
	v_mfma_f32_16x16x32_bf16 v[164:167], v[112:115], v[20:23], v[164:167]
	s_waitcnt lgkmcnt(0)
	v_mfma_f32_16x16x32_bf16 v[20:23], v[116:119], v[20:23], v[160:163]
	v_mfma_f32_16x16x32_bf16 v[156:159], v[100:103], v[24:27], v[156:159]
	v_mfma_f32_16x16x32_bf16 v[152:155], v[104:107], v[24:27], v[152:155]
	v_mfma_f32_16x16x32_bf16 v[148:151], v[112:115], v[24:27], v[148:151]
	v_mfma_f32_16x16x32_bf16 v[24:27], v[116:119], v[24:27], v[144:147]
	v_mfma_f32_16x16x32_bf16 v[136:139], v[100:103], v[40:43], v[136:139]
	v_mfma_f32_16x16x32_bf16 v[132:135], v[104:107], v[40:43], v[132:135]
	v_mfma_f32_16x16x32_bf16 v[128:131], v[112:115], v[40:43], v[128:131]
	v_mfma_f32_16x16x32_bf16 v[40:43], v[116:119], v[40:43], v[124:127]
	v_mfma_f32_16x16x32_bf16 v[144:147], v[100:103], v[48:51], v[120:123]
	v_mfma_f32_16x16x32_bf16 v[160:163], v[104:107], v[48:51], v[108:111]
	v_mfma_f32_16x16x32_bf16 v[178:181], v[112:115], v[48:51], v[96:99]
	v_mfma_f32_16x16x32_bf16 v[48:51], v[116:119], v[48:51], v[92:95]
	v_mfma_f32_16x16x32_bf16 v[184:187], v[100:103], v[60:63], v[84:87]
	v_mfma_f32_16x16x32_bf16 v[16:19], v[112:115], v[80:83], v[16:19]
	v_mfma_f32_16x16x32_bf16 v[12:15], v[116:119], v[80:83], v[12:15]
	v_mfma_f32_16x16x32_bf16 v[8:11], v[100:103], v[88:91], v[8:11]
	v_mfma_f32_16x16x32_bf16 v[4:7], v[104:107], v[88:91], v[4:7]
	v_mfma_f32_16x16x32_bf16 v[0:3], v[112:115], v[88:91], v[0:3]
	v_mfma_f32_16x16x32_bf16 v[190:193], v[104:107], v[60:63], v[76:79]
	v_mfma_f32_16x16x32_bf16 v[194:197], v[112:115], v[60:63], v[72:75]
	v_mfma_f32_16x16x32_bf16 v[198:201], v[116:119], v[60:63], v[64:67]
	v_mfma_f32_16x16x32_bf16 v[56:59], v[100:103], v[68:71], v[56:59]
	v_mfma_f32_16x16x32_bf16 v[52:55], v[104:107], v[68:71], v[52:55]
	v_mfma_f32_16x16x32_bf16 v[204:207], v[112:115], v[68:71], v[44:47]
	v_mfma_f32_16x16x32_bf16 v[208:211], v[116:119], v[68:71], v[36:39]
	v_mfma_f32_16x16x32_bf16 v[212:215], v[100:103], v[80:83], v[32:35]
	v_mfma_f32_16x16x32_bf16 v[216:219], v[104:107], v[80:83], v[28:31]
	v_mfma_f32_16x16x32_bf16 v[140:143], v[116:119], v[88:91], v[140:143]
	s_nop 1
	ds_read_b128 v[28:31], v183
	ds_read_b128 v[32:35], v183 offset:2048
	ds_read_b128 v[36:39], v183 offset:4096
	ds_read_b128 v[44:47], v183 offset:6144
	ds_read_b128 v[220:223], v183 offset:8192
	ds_read_b128 v[224:227], v183 offset:10240
	ds_read_b128 v[228:231], v183 offset:12288
	ds_read_b128 v[232:235], v183 offset:14336
	ds_read_b128 v[236:239], v182 offset:32768
	ds_read_b128 v[240:243], v182 offset:34816
	ds_read_b128 v[244:247], v182 offset:36864
	ds_read_b128 v[248:251], v182 offset:38912
	s_waitcnt lgkmcnt(3)
	v_mfma_f32_16x16x32_bf16 v[124:127], v[236:239], v[28:31], v[172:175]
	s_mov_b64 s[30:31], 0
	s_waitcnt lgkmcnt(2)
	v_mfma_f32_16x16x32_bf16 v[120:123], v[240:243], v[28:31], v[168:171]
	s_waitcnt lgkmcnt(1)
	v_mfma_f32_16x16x32_bf16 v[116:119], v[244:247], v[28:31], v[164:167]
	s_waitcnt lgkmcnt(0)
	v_mfma_f32_16x16x32_bf16 v[112:115], v[248:251], v[28:31], v[20:23]
	v_mfma_f32_16x16x32_bf16 v[108:111], v[236:239], v[32:35], v[156:159]
	v_mfma_f32_16x16x32_bf16 v[104:107], v[240:243], v[32:35], v[152:155]
	v_mfma_f32_16x16x32_bf16 v[100:103], v[244:247], v[32:35], v[148:151]
	v_mfma_f32_16x16x32_bf16 v[96:99], v[248:251], v[32:35], v[24:27]
	v_mfma_f32_16x16x32_bf16 v[92:95], v[236:239], v[36:39], v[136:139]
	v_mfma_f32_16x16x32_bf16 v[88:91], v[240:243], v[36:39], v[132:135]
	v_mfma_f32_16x16x32_bf16 v[84:87], v[244:247], v[36:39], v[128:131]
	v_mfma_f32_16x16x32_bf16 v[80:83], v[248:251], v[36:39], v[40:43]
	v_mfma_f32_16x16x32_bf16 v[76:79], v[236:239], v[44:47], v[144:147]
	v_mfma_f32_16x16x32_bf16 v[72:75], v[240:243], v[44:47], v[160:163]
	v_mfma_f32_16x16x32_bf16 v[68:71], v[244:247], v[44:47], v[178:181]
	v_mfma_f32_16x16x32_bf16 v[64:67], v[248:251], v[44:47], v[48:51]
	v_mfma_f32_16x16x32_bf16 v[60:63], v[236:239], v[220:223], v[184:187]
	v_mfma_f32_16x16x32_bf16 v[184:187], v[240:243], v[220:223], v[190:193]
	v_mfma_f32_16x16x32_bf16 v[180:183], v[244:247], v[220:223], v[194:197]
	v_mfma_f32_16x16x32_bf16 v[48:51], v[248:251], v[220:223], v[198:201]
	v_mfma_f32_16x16x32_bf16 v[44:47], v[236:239], v[224:227], v[56:59]
	v_mfma_f32_16x16x32_bf16 v[40:43], v[240:243], v[224:227], v[52:55]
	v_mfma_f32_16x16x32_bf16 v[36:39], v[244:247], v[224:227], v[204:207]
	v_mfma_f32_16x16x32_bf16 v[32:35], v[248:251], v[224:227], v[208:211]
	v_mfma_f32_16x16x32_bf16 v[28:31], v[236:239], v[228:231], v[212:215]
	v_mfma_f32_16x16x32_bf16 v[24:27], v[240:243], v[228:231], v[216:219]
	v_mfma_f32_16x16x32_bf16 v[20:23], v[244:247], v[228:231], v[16:19]
	v_mfma_f32_16x16x32_bf16 v[16:19], v[248:251], v[228:231], v[12:15]
	v_mfma_f32_16x16x32_bf16 v[12:15], v[236:239], v[232:235], v[8:11]
	v_mfma_f32_16x16x32_bf16 v[8:11], v[240:243], v[232:235], v[4:7]
	v_xor_b32_e32 v240, 32, v203
	v_mfma_f32_16x16x32_bf16 v[4:7], v[244:247], v[232:235], v[0:3]
	v_mfma_f32_16x16x32_bf16 v[0:3], v[248:251], v[232:235], v[140:143]
.LBB0_1068:
	s_and_b64 vcc, exec, s[30:31]
	s_cbranch_vccz .LBB0_1072
	s_nop 2
	v_mov_b32_e32 v8, v188
	s_mov_b32 s30, 0x20000
	v_ashrrev_i32_e32 v9, 3, v8
	v_lshlrev_b32_e32 v4, 4, v8
	v_and_b32_e32 v176, 0x70, v4
	v_add_u32_e32 v4, s53, v9
	v_add_u32_e32 v0, s38, v9
	v_ashrrev_i32_e32 v5, 31, v4
	v_ashrrev_i32_e32 v1, 31, v0
	v_lshlrev_b64 v[4:5], 11, v[4:5]
	v_xor_b32_e32 v10, v9, v8
	v_lshlrev_b64 v[0:1], 11, v[0:1]
	v_lshl_add_u64 v[6:7], s[2:3], 0, v[4:5]
	v_lshlrev_b32_e32 v10, 4, v10
	v_lshl_add_u64 v[2:3], s[0:1], 0, v[0:1]
	v_lshl_add_u64 v[6:7], v[6:7], 0, v[176:177]
	v_and_b32_e32 v10, 0x70, v10
	v_lshl_add_u64 v[2:3], v[2:3], 0, v[176:177]
	v_lshl_or_b32 v176, v9, 7, v10
	v_lshlrev_b32_e32 v12, 7, v8
	v_lshrrev_b32_e32 v9, 4, v8
	v_bfe_u32 v14, v8, 4, 2
	v_and_b32_e32 v15, 7, v8
	v_add_co_u32_e32 v8, vcc, s39, v6
	v_bitop3_b32 v16, v9, v15, 3 bitop3:0x6c
	s_nop 0
	v_addc_co_u32_e32 v9, vcc, 0, v7, vcc
	v_add_co_u32_e32 v10, vcc, s30, v6
	s_mov_b32 s31, 0x10000
	s_nop 0
	v_addc_co_u32_e32 v11, vcc, 0, v7, vcc
	global_load_dwordx4 v[20:23], v[8:9], off
	global_load_dwordx4 v[24:27], v[10:11], off
	v_add_co_u32_e32 v8, vcc, s31, v6
	s_mov_b32 s40, 0x70000
	s_nop 0
	v_addc_co_u32_e32 v9, vcc, 0, v7, vcc
	v_add_co_u32_e32 v10, vcc, s40, v2
	s_mov_b32 s40, 0x60000
	s_nop 0
	v_addc_co_u32_e32 v11, vcc, 0, v3, vcc
	global_load_dwordx4 v[40:43], v[8:9], off
	global_load_dwordx4 v[48:51], v[10:11], off
	v_add_co_u32_e32 v8, vcc, s40, v2
	s_mov_b32 s40, 0x50000
	s_nop 0
	v_addc_co_u32_e32 v9, vcc, 0, v3, vcc
	v_add_co_u32_e32 v10, vcc, s40, v2
	s_mov_b32 s40, 0x40000
	s_nop 0
	v_addc_co_u32_e32 v11, vcc, 0, v3, vcc
	global_load_dwordx4 v[60:63], v[8:9], off
	global_load_dwordx4 v[68:71], v[10:11], off
	v_add_co_u32_e32 v8, vcc, s40, v2
	v_and_b32_e32 v13, 0xffffc780, v12
	s_nop 0
	v_addc_co_u32_e32 v9, vcc, 0, v3, vcc
	v_add_co_u32_e32 v10, vcc, s39, v2
	v_and_b32_e32 v12, 0x2780, v12
	s_nop 0
	v_addc_co_u32_e32 v11, vcc, 0, v3, vcc
	global_load_dwordx4 v[80:83], v[8:9], off
	global_load_dwordx4 v[88:91], v[10:11], off
	v_add_co_u32_e32 v8, vcc, s30, v2
	v_bitop3_b32 v14, v14, v15, 4 bitop3:0x36
	s_nop 0
	v_addc_co_u32_e32 v9, vcc, 0, v3, vcc
	v_add_co_u32_e32 v10, vcc, s31, v2
	v_mov_b32_e32 v140, 0
	s_nop 0
	v_addc_co_u32_e32 v11, vcc, 0, v3, vcc
	global_load_dwordx4 v[104:107], v[8:9], off
	global_load_dwordx4 v[112:115], v[10:11], off
	global_load_dwordx4 v[100:103], v[6:7], off
	global_load_dwordx4 v[116:119], v[2:3], off
	v_lshlrev_b32_e32 v2, 4, v16
	v_or_b32_e32 v185, v13, v2
	v_or_b32_e32 v184, v12, v2
	v_lshlrev_b32_e32 v2, 4, v14
	v_or_b32_e32 v183, v13, v2
	v_or_b32_e32 v182, v12, v2
	v_lshlrev_b32_e32 v2, 4, v15
	v_or_b32_e32 v0, v0, v2
	v_or_b32_e32 v4, v4, v2
	v_lshl_add_u64 v[178:179], s[34:35], 0, v[0:1]
	v_lshl_add_u64 v[180:181], s[50:51], 0, v[4:5]
	s_mov_b64 s[30:31], 0
	v_mov_b32_e32 v141, v140
	v_mov_b32_e32 v142, v140
	v_mov_b32_e32 v143, v140
	v_mov_b32_e32 v0, v140
	v_mov_b32_e32 v1, v140
	v_mov_b32_e32 v2, v140
	v_mov_b32_e32 v3, v140
	v_mov_b32_e32 v4, v140
	v_mov_b32_e32 v5, v140
	v_mov_b32_e32 v6, v140
	v_mov_b32_e32 v7, v140
	v_mov_b32_e32 v8, v140
	v_mov_b32_e32 v9, v140
	v_mov_b32_e32 v10, v140
	v_mov_b32_e32 v11, v140
	v_mov_b32_e32 v12, v140
	v_mov_b32_e32 v13, v140
	v_mov_b32_e32 v14, v140
	v_mov_b32_e32 v15, v140
	v_mov_b32_e32 v16, v140
	v_mov_b32_e32 v17, v140
	v_mov_b32_e32 v18, v140
	v_mov_b32_e32 v19, v140
	v_mov_b32_e32 v28, v140
	v_mov_b32_e32 v29, v140
	v_mov_b32_e32 v30, v140
	v_mov_b32_e32 v31, v140
	v_mov_b32_e32 v32, v140
	v_mov_b32_e32 v33, v140
	v_mov_b32_e32 v34, v140
	v_mov_b32_e32 v35, v140
	v_mov_b32_e32 v36, v140
	v_mov_b32_e32 v37, v140
	v_mov_b32_e32 v38, v140
	v_mov_b32_e32 v39, v140
	v_mov_b32_e32 v44, v140
	v_mov_b32_e32 v45, v140
	v_mov_b32_e32 v46, v140
	v_mov_b32_e32 v47, v140
	v_mov_b32_e32 v52, v140
	v_mov_b32_e32 v53, v140
	v_mov_b32_e32 v54, v140
	v_mov_b32_e32 v55, v140
	v_mov_b32_e32 v56, v140
	v_mov_b32_e32 v57, v140
	v_mov_b32_e32 v58, v140
	v_mov_b32_e32 v59, v140
	v_mov_b32_e32 v64, v140
	v_mov_b32_e32 v65, v140
	v_mov_b32_e32 v66, v140
	v_mov_b32_e32 v67, v140
	v_mov_b32_e32 v72, v140
	v_mov_b32_e32 v73, v140
	v_mov_b32_e32 v74, v140
	v_mov_b32_e32 v75, v140
	v_mov_b32_e32 v76, v140
	v_mov_b32_e32 v77, v140
	v_mov_b32_e32 v78, v140
	v_mov_b32_e32 v79, v140
	v_mov_b32_e32 v84, v140
	v_mov_b32_e32 v85, v140
	v_mov_b32_e32 v86, v140
	v_mov_b32_e32 v87, v140
	v_mov_b32_e32 v92, v140
	v_mov_b32_e32 v93, v140
	v_mov_b32_e32 v94, v140
	v_mov_b32_e32 v95, v140
	v_mov_b32_e32 v96, v140
	v_mov_b32_e32 v97, v140
	v_mov_b32_e32 v98, v140
	v_mov_b32_e32 v99, v140
	v_mov_b32_e32 v108, v140
	v_mov_b32_e32 v109, v140
	v_mov_b32_e32 v110, v140
	v_mov_b32_e32 v111, v140
	v_mov_b32_e32 v120, v140
	v_mov_b32_e32 v121, v140
	v_mov_b32_e32 v122, v140
	v_mov_b32_e32 v123, v140
	v_mov_b32_e32 v124, v140
	v_mov_b32_e32 v125, v140
	v_mov_b32_e32 v126, v140
	v_mov_b32_e32 v127, v140
	v_mov_b32_e32 v128, v140
	v_mov_b32_e32 v129, v140
	v_mov_b32_e32 v130, v140
	v_mov_b32_e32 v131, v140
	v_mov_b32_e32 v132, v140
	v_mov_b32_e32 v133, v140
	v_mov_b32_e32 v134, v140
	v_mov_b32_e32 v135, v140
	v_mov_b32_e32 v136, v140
	v_mov_b32_e32 v137, v140
	v_mov_b32_e32 v138, v140
	v_mov_b32_e32 v139, v140
	v_mov_b32_e32 v144, v140
	v_mov_b32_e32 v145, v140
	v_mov_b32_e32 v146, v140
	v_mov_b32_e32 v147, v140
	v_mov_b32_e32 v148, v140
	v_mov_b32_e32 v149, v140
	v_mov_b32_e32 v150, v140
	v_mov_b32_e32 v151, v140
	v_mov_b32_e32 v152, v140
	v_mov_b32_e32 v153, v140
	v_mov_b32_e32 v154, v140
	v_mov_b32_e32 v155, v140
	v_mov_b32_e32 v156, v140
	v_mov_b32_e32 v157, v140
	v_mov_b32_e32 v158, v140
	v_mov_b32_e32 v159, v140
	v_mov_b32_e32 v160, v140
	v_mov_b32_e32 v161, v140
	v_mov_b32_e32 v162, v140
	v_mov_b32_e32 v163, v140
	v_mov_b32_e32 v164, v140
	v_mov_b32_e32 v165, v140
	v_mov_b32_e32 v166, v140
	v_mov_b32_e32 v167, v140
	v_mov_b32_e32 v168, v140
	v_mov_b32_e32 v169, v140
	v_mov_b32_e32 v170, v140
	v_mov_b32_e32 v171, v140
	v_mov_b32_e32 v172, v140
	v_mov_b32_e32 v173, v140
	v_mov_b32_e32 v174, v140
	v_mov_b32_e32 v175, v140
	s_mov_b32 s39, 0x820000
	s_mov_b32 s40, 0x830000
	s_setprio 2
	v_readlane_b32 s98, v253, 3
	v_readlane_b32 s99, v253, 4
	v_and_b32_e32 v240, 15, v188
	v_bfe_u32 v241, v188, 4, 2
	v_lshrrev_b32_e32 v242, 2, v240
	v_sub_u32_e32 v242, 0, v242
	v_and_b32_e32 v242, 3, v242
	v_xor_b32_e32 v241, v241, v242
	v_lshlrev_b32_e32 v241, 4, v241
	v_lshl_or_b32 v241, v240, 6, v241
	v_bfe_u32 v242, v188, 7, 1
	v_lshl_or_b32 v185, v242, 13, v241
	v_bfe_u32 v242, v188, 6, 1
	v_lshl_or_b32 v184, v242, 12, v241
	v_add_u32_e32 v184, 0x4000, v184
	v_lshrrev_b32_e32 v240, 3, v188
	v_bfe_u32 v241, v188, 2, 1
	v_lshrrev_b32_e32 v242, 2, v240
	v_sub_u32_e32 v242, 0, v242
	v_and_b32_e32 v242, 3, v242
	v_and_b32_e32 v243, 3, v188
	v_xor_b32_e32 v242, v243, v242
	v_lshlrev_b32_e32 v242, 4, v242
	v_xor_b32_e32 v240, v240, v241
	v_lshl_or_b32 v242, v240, 6, v242
	v_mul_u32_u24_e32 v241, 0x6000, v241
	v_add_u32_e32 v183, v241, v242
	s_mov_b32 m0, 0
	s_sub_u32 vcc_lo, s30, s98
	v_add_u32_e32 v186, vcc_lo, v178
	v_add_u32_e32 v187, vcc_lo, v180
	s_barrier
	s_waitcnt vmcnt(0)
	ds_write_b128 v183, v[116:119]
	ds_write_b128 v183, v[112:115] offset:2048
	ds_write_b128 v183, v[104:107] offset:4096
	ds_write_b128 v183, v[88:91] offset:6144
	ds_write_b128 v183, v[80:83] offset:8192
	ds_write_b128 v183, v[68:71] offset:10240
	ds_write_b128 v183, v[60:63] offset:12288
	ds_write_b128 v183, v[48:51] offset:14336
	ds_write_b128 v183, v[100:103] offset:16384
	ds_write_b128 v183, v[40:43] offset:18432
	ds_write_b128 v183, v[24:27] offset:20480
	ds_write_b128 v183, v[20:23] offset:22528
	v_cmp_gt_u32_e32 vcc, 0x6000, v183
	v_add_u32_e32 v182, 0xc000, v183
	v_add_u32_e32 v183, 0xffffa000, v183
	s_nop 0
	v_cndmask_b32_e32 v183, v183, v182, vcc
	v_add_u32_e32 v116, s26, v186
	global_load_dwordx4 v[116:119], v116, s[98:99] offset:128
	v_add_u32_e32 v112, s27, v186
	global_load_dwordx4 v[112:115], v112, s[98:99] offset:128
	v_add_u32_e32 v104, s20, v186
	global_load_dwordx4 v[104:107], v104, s[98:99] offset:128
	v_add_u32_e32 v88, s21, v186
	global_load_dwordx4 v[88:91], v88, s[98:99] offset:128
	v_add_u32_e32 v80, s56, v186
	global_load_dwordx4 v[80:83], v80, s[98:99] offset:128
	v_add_u32_e32 v68, s57, v186
	global_load_dwordx4 v[68:71], v68, s[98:99] offset:128
	v_add_u32_e32 v60, s24, v186
	global_load_dwordx4 v[60:63], v60, s[98:99] offset:128
	v_add_u32_e32 v48, s96, v186
	global_load_dwordx4 v[48:51], v48, s[98:99] offset:128
	v_add_u32_e32 v100, s25, v187
	global_load_dwordx4 v[100:103], v100, s[98:99] offset:128
	v_add_u32_e32 v40, s33, v187
	global_load_dwordx4 v[40:43], v40, s[98:99] offset:128
	v_add_u32_e32 v24, s39, v187
	global_load_dwordx4 v[24:27], v24, s[98:99] offset:128
	v_add_u32_e32 v20, s40, v187
	global_load_dwordx4 v[20:23], v20, s[98:99] offset:128
	s_add_u32 s30, s30, 0x80
	s_addc_u32 s31, s31, 0
.LBB0_1070:
	s_waitcnt lgkmcnt(0)
	s_barrier
	ds_read_b128 v[240:243], v184
	ds_read_b128 v[244:247], v184 offset:1024
	ds_read_b128 v[248:251], v184 offset:2048
	ds_read_b128 v[204:207], v184 offset:3072
	ds_read_b128 v[208:211], v185
	ds_read_b128 v[212:215], v185 offset:1024
	ds_read_b128 v[216:219], v185 offset:2048
	ds_read_b128 v[220:223], v185 offset:3072
	ds_read_b128 v[224:227], v185 offset:4096
	ds_read_b128 v[228:231], v185 offset:5120
	ds_read_b128 v[232:235], v185 offset:6144
	ds_read_b128 v[236:239], v185 offset:7168
	s_movk_i32 vcc_lo, 0x6000
	s_cmp_eq_u32 m0, 2
	s_cselect_b32 vcc_lo, 0xffff4000, vcc_lo
	s_add_u32 m0, m0, 1
	s_cmp_eq_u32 m0, 3
	s_cselect_b32 m0, 0, m0
	v_add_u32_e32 v185, vcc_lo, v185
	v_add_u32_e32 v184, vcc_lo, v184
	v_xor_b32_e32 v185, 64, v185
	v_xor_b32_e32 v184, 64, v184
	s_waitcnt lgkmcnt(7)
	v_mfma_f32_16x16x32_bf16 v[172:175], v[208:211], v[240:243], v[172:175]
	v_mfma_f32_16x16x32_bf16 v[168:171], v[208:211], v[244:247], v[168:171]
	v_mfma_f32_16x16x32_bf16 v[164:167], v[208:211], v[248:251], v[164:167]
	v_mfma_f32_16x16x32_bf16 v[160:163], v[208:211], v[204:207], v[160:163]
	ds_read_b128 v[208:211], v185
	s_waitcnt lgkmcnt(7)
	v_mfma_f32_16x16x32_bf16 v[156:159], v[212:215], v[240:243], v[156:159]
	v_mfma_f32_16x16x32_bf16 v[152:155], v[212:215], v[244:247], v[152:155]
	v_mfma_f32_16x16x32_bf16 v[148:151], v[212:215], v[248:251], v[148:151]
	v_mfma_f32_16x16x32_bf16 v[144:147], v[212:215], v[204:207], v[144:147]
	ds_read_b128 v[212:215], v185 offset:1024
	s_waitcnt lgkmcnt(7)
	v_mfma_f32_16x16x32_bf16 v[136:139], v[216:219], v[240:243], v[136:139]
	v_mfma_f32_16x16x32_bf16 v[132:135], v[216:219], v[244:247], v[132:135]
	v_mfma_f32_16x16x32_bf16 v[128:131], v[216:219], v[248:251], v[128:131]
	v_mfma_f32_16x16x32_bf16 v[124:127], v[216:219], v[204:207], v[124:127]
	ds_read_b128 v[216:219], v185 offset:2048
	s_waitcnt lgkmcnt(7)
	v_mfma_f32_16x16x32_bf16 v[120:123], v[220:223], v[240:243], v[120:123]
	v_mfma_f32_16x16x32_bf16 v[108:111], v[220:223], v[244:247], v[108:111]
	v_mfma_f32_16x16x32_bf16 v[96:99], v[220:223], v[248:251], v[96:99]
	v_mfma_f32_16x16x32_bf16 v[92:95], v[220:223], v[204:207], v[92:95]
	ds_read_b128 v[220:223], v185 offset:3072
	s_waitcnt lgkmcnt(7)
	v_mfma_f32_16x16x32_bf16 v[84:87], v[224:227], v[240:243], v[84:87]
	v_mfma_f32_16x16x32_bf16 v[76:79], v[224:227], v[244:247], v[76:79]
	v_mfma_f32_16x16x32_bf16 v[72:75], v[224:227], v[248:251], v[72:75]
	v_mfma_f32_16x16x32_bf16 v[64:67], v[224:227], v[204:207], v[64:67]
	ds_read_b128 v[224:227], v185 offset:4096
	s_waitcnt lgkmcnt(7)
	v_mfma_f32_16x16x32_bf16 v[56:59], v[228:231], v[240:243], v[56:59]
	v_mfma_f32_16x16x32_bf16 v[52:55], v[228:231], v[244:247], v[52:55]
	v_mfma_f32_16x16x32_bf16 v[44:47], v[228:231], v[248:251], v[44:47]
	v_mfma_f32_16x16x32_bf16 v[36:39], v[228:231], v[204:207], v[36:39]
	ds_read_b128 v[228:231], v185 offset:5120
	s_waitcnt lgkmcnt(7)
	v_mfma_f32_16x16x32_bf16 v[32:35], v[232:235], v[240:243], v[32:35]
	v_mfma_f32_16x16x32_bf16 v[28:31], v[232:235], v[244:247], v[28:31]
	v_mfma_f32_16x16x32_bf16 v[16:19], v[232:235], v[248:251], v[16:19]
	v_mfma_f32_16x16x32_bf16 v[12:15], v[232:235], v[204:207], v[12:15]
	ds_read_b128 v[232:235], v185 offset:6144
	s_waitcnt lgkmcnt(7)
	v_mfma_f32_16x16x32_bf16 v[8:11], v[236:239], v[240:243], v[8:11]
	v_mfma_f32_16x16x32_bf16 v[4:7], v[236:239], v[244:247], v[4:7]
	v_mfma_f32_16x16x32_bf16 v[0:3], v[236:239], v[248:251], v[0:3]
	v_mfma_f32_16x16x32_bf16 v[140:143], v[236:239], v[204:207], v[140:143]
	ds_read_b128 v[236:239], v185 offset:7168
	ds_read_b128 v[240:243], v184
	ds_read_b128 v[244:247], v184 offset:1024
	ds_read_b128 v[248:251], v184 offset:2048
	ds_read_b128 v[204:207], v184 offset:3072
	s_movk_i32 vcc_lo, 0x6000
	s_cmp_eq_u32 m0, 2
	s_cselect_b32 vcc_lo, 0xffff4000, vcc_lo
	s_add_u32 m0, m0, 1
	s_cmp_eq_u32 m0, 3
	s_cselect_b32 m0, 0, m0
	v_add_u32_e32 v185, vcc_lo, v185
	v_add_u32_e32 v184, vcc_lo, v184
	v_xor_b32_e32 v185, 64, v185
	v_xor_b32_e32 v184, 64, v184
	s_sub_u32 vcc_lo, s30, s98
	v_add_u32_e32 v186, vcc_lo, v178
	v_add_u32_e32 v187, vcc_lo, v180
	s_barrier
	s_waitcnt lgkmcnt(0)
	v_mfma_f32_16x16x32_bf16 v[172:175], v[208:211], v[240:243], v[172:175]
	s_waitcnt vmcnt(11)
	v_mfma_f32_16x16x32_bf16 v[168:171], v[208:211], v[244:247], v[168:171]
	ds_write_b128 v183, v[116:119]
	v_add_u32_e32 v116, s26, v186
	v_mfma_f32_16x16x32_bf16 v[164:167], v[208:211], v[248:251], v[164:167]
	global_load_dwordx4 v[116:119], v116, s[98:99] offset:128
	v_mfma_f32_16x16x32_bf16 v[160:163], v[208:211], v[204:207], v[160:163]
	s_waitcnt vmcnt(11)
	ds_write_b128 v183, v[112:115] offset:2048
	v_mfma_f32_16x16x32_bf16 v[156:159], v[212:215], v[240:243], v[156:159]
	v_add_u32_e32 v112, s27, v186
	v_mfma_f32_16x16x32_bf16 v[152:155], v[212:215], v[244:247], v[152:155]
	global_load_dwordx4 v[112:115], v112, s[98:99] offset:128
	s_waitcnt vmcnt(11)
	v_mfma_f32_16x16x32_bf16 v[148:151], v[212:215], v[248:251], v[148:151]
	ds_write_b128 v183, v[104:107] offset:4096
	v_mfma_f32_16x16x32_bf16 v[144:147], v[212:215], v[204:207], v[144:147]
	v_add_u32_e32 v104, s20, v186
	global_load_dwordx4 v[104:107], v104, s[98:99] offset:128
	v_mfma_f32_16x16x32_bf16 v[136:139], v[216:219], v[240:243], v[136:139]
	s_waitcnt vmcnt(11)
	v_mfma_f32_16x16x32_bf16 v[132:135], v[216:219], v[244:247], v[132:135]
	ds_write_b128 v183, v[88:91] offset:6144
	v_add_u32_e32 v88, s21, v186
	v_mfma_f32_16x16x32_bf16 v[128:131], v[216:219], v[248:251], v[128:131]
	global_load_dwordx4 v[88:91], v88, s[98:99] offset:128
	v_mfma_f32_16x16x32_bf16 v[124:127], v[216:219], v[204:207], v[124:127]
	s_waitcnt vmcnt(11)
	ds_write_b128 v183, v[80:83] offset:8192
	v_mfma_f32_16x16x32_bf16 v[120:123], v[220:223], v[240:243], v[120:123]
	v_add_u32_e32 v80, s56, v186
	v_mfma_f32_16x16x32_bf16 v[108:111], v[220:223], v[244:247], v[108:111]
	global_load_dwordx4 v[80:83], v80, s[98:99] offset:128
	s_waitcnt vmcnt(11)
	v_mfma_f32_16x16x32_bf16 v[96:99], v[220:223], v[248:251], v[96:99]
	ds_write_b128 v183, v[68:71] offset:10240
	v_mfma_f32_16x16x32_bf16 v[92:95], v[220:223], v[204:207], v[92:95]
	v_add_u32_e32 v68, s57, v186
	global_load_dwordx4 v[68:71], v68, s[98:99] offset:128
	v_mfma_f32_16x16x32_bf16 v[84:87], v[224:227], v[240:243], v[84:87]
	s_waitcnt vmcnt(11)
	v_mfma_f32_16x16x32_bf16 v[76:79], v[224:227], v[244:247], v[76:79]
	ds_write_b128 v183, v[60:63] offset:12288
	v_add_u32_e32 v60, s24, v186
	v_mfma_f32_16x16x32_bf16 v[72:75], v[224:227], v[248:251], v[72:75]
	global_load_dwordx4 v[60:63], v60, s[98:99] offset:128
	v_mfma_f32_16x16x32_bf16 v[64:67], v[224:227], v[204:207], v[64:67]
	s_waitcnt vmcnt(11)
	ds_write_b128 v183, v[48:51] offset:14336
	v_mfma_f32_16x16x32_bf16 v[56:59], v[228:231], v[240:243], v[56:59]
	v_add_u32_e32 v48, s96, v186
	v_mfma_f32_16x16x32_bf16 v[52:55], v[228:231], v[244:247], v[52:55]
	global_load_dwordx4 v[48:51], v48, s[98:99] offset:128
	s_waitcnt vmcnt(11)
	v_mfma_f32_16x16x32_bf16 v[44:47], v[228:231], v[248:251], v[44:47]
	ds_write_b128 v183, v[100:103] offset:16384
	v_mfma_f32_16x16x32_bf16 v[36:39], v[228:231], v[204:207], v[36:39]
	v_add_u32_e32 v100, s25, v187
	global_load_dwordx4 v[100:103], v100, s[98:99] offset:128
	v_mfma_f32_16x16x32_bf16 v[32:35], v[232:235], v[240:243], v[32:35]
	s_waitcnt vmcnt(11)
	v_mfma_f32_16x16x32_bf16 v[28:31], v[232:235], v[244:247], v[28:31]
	ds_write_b128 v183, v[40:43] offset:18432
	v_add_u32_e32 v40, s33, v187
	v_mfma_f32_16x16x32_bf16 v[16:19], v[232:235], v[248:251], v[16:19]
	global_load_dwordx4 v[40:43], v40, s[98:99] offset:128
	v_mfma_f32_16x16x32_bf16 v[12:15], v[232:235], v[204:207], v[12:15]
	s_waitcnt vmcnt(11)
	ds_write_b128 v183, v[24:27] offset:20480
	v_mfma_f32_16x16x32_bf16 v[8:11], v[236:239], v[240:243], v[8:11]
	v_add_u32_e32 v24, s39, v187
	v_mfma_f32_16x16x32_bf16 v[4:7], v[236:239], v[244:247], v[4:7]
	global_load_dwordx4 v[24:27], v24, s[98:99] offset:128
	s_waitcnt vmcnt(11)
	v_mfma_f32_16x16x32_bf16 v[0:3], v[236:239], v[248:251], v[0:3]
	ds_write_b128 v183, v[20:23] offset:22528
	v_mfma_f32_16x16x32_bf16 v[140:143], v[236:239], v[204:207], v[140:143]
	v_add_u32_e32 v20, s40, v187
	global_load_dwordx4 v[20:23], v20, s[98:99] offset:128
	v_cmp_gt_u32_e32 vcc, 0x6000, v183
	v_add_u32_e32 v182, 0xc000, v183
	v_add_u32_e32 v183, 0xffffa000, v183
	s_nop 0
	v_cndmask_b32_e32 v183, v183, v182, vcc
	s_add_u32 s30, s30, 0x80
	s_addc_u32 s31, s31, 0
	s_cmpk_eq_i32 s30, 0x780
	s_cbranch_scc0 .LBB0_1070
	s_waitcnt lgkmcnt(0)
	s_barrier
	ds_read_b128 v[240:243], v184
	ds_read_b128 v[244:247], v184 offset:1024
	ds_read_b128 v[248:251], v184 offset:2048
	ds_read_b128 v[204:207], v184 offset:3072
	ds_read_b128 v[208:211], v185
	ds_read_b128 v[212:215], v185 offset:1024
	ds_read_b128 v[216:219], v185 offset:2048
	ds_read_b128 v[220:223], v185 offset:3072
	ds_read_b128 v[224:227], v185 offset:4096
	ds_read_b128 v[228:231], v185 offset:5120
	ds_read_b128 v[232:235], v185 offset:6144
	ds_read_b128 v[236:239], v185 offset:7168
	s_movk_i32 vcc_lo, 0x6000
	s_cmp_eq_u32 m0, 2
	s_cselect_b32 vcc_lo, 0xffff4000, vcc_lo
	s_add_u32 m0, m0, 1
	s_cmp_eq_u32 m0, 3
	s_cselect_b32 m0, 0, m0
	v_add_u32_e32 v185, vcc_lo, v185
	v_add_u32_e32 v184, vcc_lo, v184
	v_xor_b32_e32 v185, 64, v185
	v_xor_b32_e32 v184, 64, v184
	s_waitcnt lgkmcnt(7)
	v_mfma_f32_16x16x32_bf16 v[172:175], v[208:211], v[240:243], v[172:175]
	v_mfma_f32_16x16x32_bf16 v[168:171], v[208:211], v[244:247], v[168:171]
	v_mfma_f32_16x16x32_bf16 v[164:167], v[208:211], v[248:251], v[164:167]
	v_mfma_f32_16x16x32_bf16 v[160:163], v[208:211], v[204:207], v[160:163]
	ds_read_b128 v[208:211], v185
	s_waitcnt lgkmcnt(7)
	v_mfma_f32_16x16x32_bf16 v[156:159], v[212:215], v[240:243], v[156:159]
	v_mfma_f32_16x16x32_bf16 v[152:155], v[212:215], v[244:247], v[152:155]
	v_mfma_f32_16x16x32_bf16 v[148:151], v[212:215], v[248:251], v[148:151]
	v_mfma_f32_16x16x32_bf16 v[144:147], v[212:215], v[204:207], v[144:147]
	ds_read_b128 v[212:215], v185 offset:1024
	s_waitcnt lgkmcnt(7)
	v_mfma_f32_16x16x32_bf16 v[136:139], v[216:219], v[240:243], v[136:139]
	v_mfma_f32_16x16x32_bf16 v[132:135], v[216:219], v[244:247], v[132:135]
	v_mfma_f32_16x16x32_bf16 v[128:131], v[216:219], v[248:251], v[128:131]
	v_mfma_f32_16x16x32_bf16 v[124:127], v[216:219], v[204:207], v[124:127]
	ds_read_b128 v[216:219], v185 offset:2048
	s_waitcnt lgkmcnt(7)
	v_mfma_f32_16x16x32_bf16 v[120:123], v[220:223], v[240:243], v[120:123]
	v_mfma_f32_16x16x32_bf16 v[108:111], v[220:223], v[244:247], v[108:111]
	v_mfma_f32_16x16x32_bf16 v[96:99], v[220:223], v[248:251], v[96:99]
	v_mfma_f32_16x16x32_bf16 v[92:95], v[220:223], v[204:207], v[92:95]
	ds_read_b128 v[220:223], v185 offset:3072
	s_waitcnt lgkmcnt(7)
	v_mfma_f32_16x16x32_bf16 v[84:87], v[224:227], v[240:243], v[84:87]
	v_mfma_f32_16x16x32_bf16 v[76:79], v[224:227], v[244:247], v[76:79]
	v_mfma_f32_16x16x32_bf16 v[72:75], v[224:227], v[248:251], v[72:75]
	v_mfma_f32_16x16x32_bf16 v[64:67], v[224:227], v[204:207], v[64:67]
	ds_read_b128 v[224:227], v185 offset:4096
	s_waitcnt lgkmcnt(7)
	v_mfma_f32_16x16x32_bf16 v[56:59], v[228:231], v[240:243], v[56:59]
	v_mfma_f32_16x16x32_bf16 v[52:55], v[228:231], v[244:247], v[52:55]
	v_mfma_f32_16x16x32_bf16 v[44:47], v[228:231], v[248:251], v[44:47]
	v_mfma_f32_16x16x32_bf16 v[36:39], v[228:231], v[204:207], v[36:39]
	ds_read_b128 v[228:231], v185 offset:5120
	s_waitcnt lgkmcnt(7)
	v_mfma_f32_16x16x32_bf16 v[32:35], v[232:235], v[240:243], v[32:35]
	v_mfma_f32_16x16x32_bf16 v[28:31], v[232:235], v[244:247], v[28:31]
	v_mfma_f32_16x16x32_bf16 v[16:19], v[232:235], v[248:251], v[16:19]
	v_mfma_f32_16x16x32_bf16 v[12:15], v[232:235], v[204:207], v[12:15]
	ds_read_b128 v[232:235], v185 offset:6144
	s_waitcnt lgkmcnt(7)
	v_mfma_f32_16x16x32_bf16 v[8:11], v[236:239], v[240:243], v[8:11]
	v_mfma_f32_16x16x32_bf16 v[4:7], v[236:239], v[244:247], v[4:7]
	v_mfma_f32_16x16x32_bf16 v[0:3], v[236:239], v[248:251], v[0:3]
	v_mfma_f32_16x16x32_bf16 v[140:143], v[236:239], v[204:207], v[140:143]
	ds_read_b128 v[236:239], v185 offset:7168
	ds_read_b128 v[240:243], v184
	ds_read_b128 v[244:247], v184 offset:1024
	ds_read_b128 v[248:251], v184 offset:2048
	ds_read_b128 v[204:207], v184 offset:3072
	s_movk_i32 vcc_lo, 0x6000
	s_cmp_eq_u32 m0, 2
	s_cselect_b32 vcc_lo, 0xffff4000, vcc_lo
	s_add_u32 m0, m0, 1
	s_cmp_eq_u32 m0, 3
	s_cselect_b32 m0, 0, m0
	v_add_u32_e32 v185, vcc_lo, v185
	v_add_u32_e32 v184, vcc_lo, v184
	v_xor_b32_e32 v185, 64, v185
	v_xor_b32_e32 v184, 64, v184
	s_waitcnt lgkmcnt(0)
	v_mfma_f32_16x16x32_bf16 v[172:175], v[208:211], v[240:243], v[172:175]
	v_mfma_f32_16x16x32_bf16 v[168:171], v[208:211], v[244:247], v[168:171]
	v_mfma_f32_16x16x32_bf16 v[164:167], v[208:211], v[248:251], v[164:167]
	v_mfma_f32_16x16x32_bf16 v[160:163], v[208:211], v[204:207], v[160:163]
	v_mfma_f32_16x16x32_bf16 v[156:159], v[212:215], v[240:243], v[156:159]
	v_mfma_f32_16x16x32_bf16 v[152:155], v[212:215], v[244:247], v[152:155]
	v_mfma_f32_16x16x32_bf16 v[148:151], v[212:215], v[248:251], v[148:151]
	v_mfma_f32_16x16x32_bf16 v[144:147], v[212:215], v[204:207], v[144:147]
	v_mfma_f32_16x16x32_bf16 v[136:139], v[216:219], v[240:243], v[136:139]
	v_mfma_f32_16x16x32_bf16 v[132:135], v[216:219], v[244:247], v[132:135]
	v_mfma_f32_16x16x32_bf16 v[128:131], v[216:219], v[248:251], v[128:131]
	v_mfma_f32_16x16x32_bf16 v[124:127], v[216:219], v[204:207], v[124:127]
	v_mfma_f32_16x16x32_bf16 v[120:123], v[220:223], v[240:243], v[120:123]
	v_mfma_f32_16x16x32_bf16 v[108:111], v[220:223], v[244:247], v[108:111]
	v_mfma_f32_16x16x32_bf16 v[96:99], v[220:223], v[248:251], v[96:99]
	v_mfma_f32_16x16x32_bf16 v[92:95], v[220:223], v[204:207], v[92:95]
	v_mfma_f32_16x16x32_bf16 v[84:87], v[224:227], v[240:243], v[84:87]
	v_mfma_f32_16x16x32_bf16 v[76:79], v[224:227], v[244:247], v[76:79]
	v_mfma_f32_16x16x32_bf16 v[72:75], v[224:227], v[248:251], v[72:75]
	v_mfma_f32_16x16x32_bf16 v[64:67], v[224:227], v[204:207], v[64:67]
	v_mfma_f32_16x16x32_bf16 v[56:59], v[228:231], v[240:243], v[56:59]
	v_mfma_f32_16x16x32_bf16 v[52:55], v[228:231], v[244:247], v[52:55]
	v_mfma_f32_16x16x32_bf16 v[44:47], v[228:231], v[248:251], v[44:47]
	v_mfma_f32_16x16x32_bf16 v[36:39], v[228:231], v[204:207], v[36:39]
	v_mfma_f32_16x16x32_bf16 v[32:35], v[232:235], v[240:243], v[32:35]
	v_mfma_f32_16x16x32_bf16 v[28:31], v[232:235], v[244:247], v[28:31]
	v_mfma_f32_16x16x32_bf16 v[16:19], v[232:235], v[248:251], v[16:19]
	v_mfma_f32_16x16x32_bf16 v[12:15], v[232:235], v[204:207], v[12:15]
	v_mfma_f32_16x16x32_bf16 v[8:11], v[236:239], v[240:243], v[8:11]
	v_mfma_f32_16x16x32_bf16 v[4:7], v[236:239], v[244:247], v[4:7]
	v_mfma_f32_16x16x32_bf16 v[0:3], v[236:239], v[248:251], v[0:3]
	v_mfma_f32_16x16x32_bf16 v[140:143], v[236:239], v[204:207], v[140:143]
	v_lshrrev_b32_e32 v240, 4, v188
	v_and_b32_e32 v241, 7, v188
	v_bitop3_b32 v242, v240, v241, 3 bitop3:0x6c
	v_lshlrev_b32_e32 v243, 7, v188
	v_bfe_u32 v244, v188, 4, 2
	v_and_b32_e32 v245, 0xffffc780, v243
	v_and_b32_e32 v243, 0x2780, v243
	v_bitop3_b32 v244, v244, v241, 4 bitop3:0x36
	v_lshlrev_b32_e32 v242, 4, v242
	v_lshlrev_b32_e32 v244, 4, v244
	v_or_b32_e32 v185, v245, v242
	v_or_b32_e32 v184, v243, v242
	v_or_b32_e32 v183, v245, v244
	v_or_b32_e32 v182, v243, v244
	s_waitcnt vmcnt(0)
	s_setprio 0
	s_barrier
	s_waitcnt vmcnt(11)
	ds_write_b128 v176, v[116:119]
	s_waitcnt vmcnt(10)
	ds_write_b128 v176, v[112:115] offset:4096
	s_waitcnt vmcnt(9)
	ds_write_b128 v176, v[104:107] offset:8192
	s_waitcnt vmcnt(8)
	ds_write_b128 v176, v[88:91] offset:12288
	s_waitcnt vmcnt(7)
	ds_write_b128 v176, v[80:83] offset:16384
	s_waitcnt vmcnt(6)
	ds_write_b128 v176, v[68:71] offset:20480
	s_waitcnt vmcnt(5)
	ds_write_b128 v176, v[60:63] offset:24576
	s_waitcnt vmcnt(4)
	ds_write_b128 v176, v[48:51] offset:28672
	s_waitcnt vmcnt(3)
	ds_write_b128 v176, v[100:103] offset:32768
	s_waitcnt vmcnt(2)
	ds_write_b128 v176, v[40:43] offset:36864
	s_waitcnt vmcnt(1)
	ds_write_b128 v176, v[24:27] offset:40960
	s_waitcnt vmcnt(0)
	ds_write_b128 v176, v[20:23] offset:45056
	s_waitcnt lgkmcnt(0)
	s_barrier
	ds_read_b128 v[20:23], v185
	ds_read_b128 v[24:27], v185 offset:2048
	ds_read_b128 v[40:43], v185 offset:4096
	ds_read_b128 v[48:51], v185 offset:6144
	ds_read_b128 v[60:63], v185 offset:8192
	ds_read_b128 v[68:71], v185 offset:10240
	ds_read_b128 v[80:83], v185 offset:12288
	ds_read_b128 v[88:91], v185 offset:14336
	ds_read_b128 v[100:103], v184 offset:32768
	ds_read_b128 v[104:107], v184 offset:34816
	ds_read_b128 v[112:115], v184 offset:36864
	ds_read_b128 v[116:119], v184 offset:38912
	s_waitcnt lgkmcnt(3)
	v_mfma_f32_16x16x32_bf16 v[172:175], v[20:23], v[100:103], v[172:175]
	s_waitcnt lgkmcnt(2)
	v_mfma_f32_16x16x32_bf16 v[168:171], v[20:23], v[104:107], v[168:171]
	s_waitcnt lgkmcnt(1)
	v_mfma_f32_16x16x32_bf16 v[164:167], v[20:23], v[112:115], v[164:167]
	s_waitcnt lgkmcnt(0)
	v_mfma_f32_16x16x32_bf16 v[20:23], v[20:23], v[116:119], v[160:163]
	v_mfma_f32_16x16x32_bf16 v[156:159], v[24:27], v[100:103], v[156:159]
	v_mfma_f32_16x16x32_bf16 v[152:155], v[24:27], v[104:107], v[152:155]
	v_mfma_f32_16x16x32_bf16 v[148:151], v[24:27], v[112:115], v[148:151]
	v_mfma_f32_16x16x32_bf16 v[24:27], v[24:27], v[116:119], v[144:147]
	v_mfma_f32_16x16x32_bf16 v[136:139], v[40:43], v[100:103], v[136:139]
	v_mfma_f32_16x16x32_bf16 v[132:135], v[40:43], v[104:107], v[132:135]
	v_mfma_f32_16x16x32_bf16 v[128:131], v[40:43], v[112:115], v[128:131]
	v_mfma_f32_16x16x32_bf16 v[40:43], v[40:43], v[116:119], v[124:127]
	v_mfma_f32_16x16x32_bf16 v[144:147], v[48:51], v[100:103], v[120:123]
	v_mfma_f32_16x16x32_bf16 v[160:163], v[48:51], v[104:107], v[108:111]
	v_mfma_f32_16x16x32_bf16 v[178:181], v[48:51], v[112:115], v[96:99]
	v_mfma_f32_16x16x32_bf16 v[48:51], v[48:51], v[116:119], v[92:95]
	v_mfma_f32_16x16x32_bf16 v[184:187], v[60:63], v[100:103], v[84:87]
	v_mfma_f32_16x16x32_bf16 v[16:19], v[80:83], v[112:115], v[16:19]
	v_mfma_f32_16x16x32_bf16 v[12:15], v[80:83], v[116:119], v[12:15]
	v_mfma_f32_16x16x32_bf16 v[8:11], v[88:91], v[100:103], v[8:11]
	v_mfma_f32_16x16x32_bf16 v[4:7], v[88:91], v[104:107], v[4:7]
	v_mfma_f32_16x16x32_bf16 v[0:3], v[88:91], v[112:115], v[0:3]
	v_mfma_f32_16x16x32_bf16 v[204:207], v[60:63], v[104:107], v[76:79]
	v_mfma_f32_16x16x32_bf16 v[208:211], v[60:63], v[112:115], v[72:75]
	v_mfma_f32_16x16x32_bf16 v[212:215], v[60:63], v[116:119], v[64:67]
	v_mfma_f32_16x16x32_bf16 v[216:219], v[68:71], v[100:103], v[56:59]
	v_mfma_f32_16x16x32_bf16 v[220:223], v[68:71], v[104:107], v[52:55]
	v_mfma_f32_16x16x32_bf16 v[224:227], v[68:71], v[112:115], v[44:47]
	v_mfma_f32_16x16x32_bf16 v[228:231], v[68:71], v[116:119], v[36:39]
	v_mfma_f32_16x16x32_bf16 v[232:235], v[80:83], v[100:103], v[32:35]
	v_mfma_f32_16x16x32_bf16 v[236:239], v[80:83], v[104:107], v[28:31]
	v_mfma_f32_16x16x32_bf16 v[140:143], v[88:91], v[116:119], v[140:143]
	s_nop 1
	ds_read_b128 v[28:31], v183
	ds_read_b128 v[32:35], v183 offset:2048
	ds_read_b128 v[36:39], v183 offset:4096
	ds_read_b128 v[44:47], v183 offset:6144
	ds_read_b128 v[240:243], v183 offset:8192
	ds_read_b128 v[244:247], v183 offset:10240
	ds_read_b128 v[248:251], v183 offset:12288
	ds_read_b128 v[190:193], v183 offset:14336
	ds_read_b128 v[198:201], v182 offset:32768
	ds_read_b128 v[194:197], v182 offset:34816
	ds_read_b128 v[52:55], v182 offset:36864
	ds_read_b128 v[56:59], v182 offset:38912
	s_waitcnt lgkmcnt(3)
	v_mfma_f32_16x16x32_bf16 v[124:127], v[28:31], v[198:201], v[172:175]
	s_waitcnt lgkmcnt(2)
	v_mfma_f32_16x16x32_bf16 v[120:123], v[28:31], v[194:197], v[168:171]
	s_waitcnt lgkmcnt(1)
	v_mfma_f32_16x16x32_bf16 v[116:119], v[28:31], v[52:55], v[164:167]
	s_waitcnt lgkmcnt(0)
	v_mfma_f32_16x16x32_bf16 v[112:115], v[28:31], v[56:59], v[20:23]
	v_mfma_f32_16x16x32_bf16 v[108:111], v[32:35], v[198:201], v[156:159]
	v_mfma_f32_16x16x32_bf16 v[104:107], v[32:35], v[194:197], v[152:155]
	v_mfma_f32_16x16x32_bf16 v[100:103], v[32:35], v[52:55], v[148:151]
	v_mfma_f32_16x16x32_bf16 v[96:99], v[32:35], v[56:59], v[24:27]
	v_mfma_f32_16x16x32_bf16 v[92:95], v[36:39], v[198:201], v[136:139]
	v_mfma_f32_16x16x32_bf16 v[88:91], v[36:39], v[194:197], v[132:135]
	v_mfma_f32_16x16x32_bf16 v[84:87], v[36:39], v[52:55], v[128:131]
	v_mfma_f32_16x16x32_bf16 v[80:83], v[36:39], v[56:59], v[40:43]
	v_mfma_f32_16x16x32_bf16 v[76:79], v[44:47], v[198:201], v[144:147]
	v_mfma_f32_16x16x32_bf16 v[72:75], v[44:47], v[194:197], v[160:163]
	v_mfma_f32_16x16x32_bf16 v[68:71], v[44:47], v[52:55], v[178:181]
	v_mfma_f32_16x16x32_bf16 v[64:67], v[44:47], v[56:59], v[48:51]
	v_mfma_f32_16x16x32_bf16 v[60:63], v[240:243], v[198:201], v[184:187]
	v_mfma_f32_16x16x32_bf16 v[184:187], v[240:243], v[194:197], v[204:207]
	v_mfma_f32_16x16x32_bf16 v[180:183], v[240:243], v[52:55], v[208:211]
	v_mfma_f32_16x16x32_bf16 v[48:51], v[240:243], v[56:59], v[212:215]
	v_xor_b32_e32 v240, 32, v203
	v_mfma_f32_16x16x32_bf16 v[44:47], v[244:247], v[198:201], v[216:219]
	v_mfma_f32_16x16x32_bf16 v[40:43], v[244:247], v[194:197], v[220:223]
	v_mfma_f32_16x16x32_bf16 v[36:39], v[244:247], v[52:55], v[224:227]
	v_mfma_f32_16x16x32_bf16 v[32:35], v[244:247], v[56:59], v[228:231]
	v_mfma_f32_16x16x32_bf16 v[28:31], v[248:251], v[198:201], v[232:235]
	v_mfma_f32_16x16x32_bf16 v[24:27], v[248:251], v[194:197], v[236:239]
	v_mfma_f32_16x16x32_bf16 v[20:23], v[248:251], v[52:55], v[16:19]
	v_mfma_f32_16x16x32_bf16 v[16:19], v[248:251], v[56:59], v[12:15]
	v_mfma_f32_16x16x32_bf16 v[12:15], v[190:193], v[198:201], v[8:11]
	v_mfma_f32_16x16x32_bf16 v[8:11], v[190:193], v[194:197], v[4:7]
	v_mfma_f32_16x16x32_bf16 v[4:7], v[190:193], v[52:55], v[0:3]
	v_mfma_f32_16x16x32_bf16 v[0:3], v[190:193], v[56:59], v[140:143]
